# GEMM compute segments run at priority 2 (set before the pre-MMA barrier) so the computing wave outranks the just-released loader wave, which is still at priority 1 until its first instruction
# speedup vs baseline: 1.0015x; 1.0015x over previous
.Lpk354_peel:
	ds_read_b128 v[166:169], v139
	ds_read_b128 v[170:173], v139 offset:1024
	ds_read_b128 v[178:181], v139 offset:2048
	ds_read_b128 v[182:185], v139 offset:3072
	ds_read_b128 v[186:189], v164
	ds_read_b128 v[190:193], v164 offset:1024
	ds_read_b128 v[194:197], v164 offset:2048
	ds_read_b128 v[198:201], v164 offset:3072
	s_add_u32 s2, s26, 0xfffc0080
	s_addc_u32 s3, s27, -1
	s_cmp_eq_u32 s52, 12
	s_cselect_b32 s3, s11, s3
	s_cselect_b32 s2, s13, s2
	s_cselect_b32 s29, s44, s47
	s_cselect_b32 s28, s45, s46
	v_lshl_add_u64 v[148:149], s[26:27], 0, v[142:143]
	s_add_i32 m0, s34, 0xc000
	ds_read_b128 v[202:205], v165
	ds_read_b128 v[206:209], v165 offset:1024
	ds_read_b128 v[210:213], v165 offset:2048
	ds_read_b128 v[214:217], v165 offset:3072
	ds_read_b128 v[218:221], v165 offset:4096
	ds_read_b128 v[222:225], v165 offset:5120
	ds_read_b128 v[226:229], v165 offset:6144
	ds_read_b128 v[230:233], v165 offset:7168
	global_load_lds_dwordx4 v[148:149], off
	v_lshl_add_u64 v[148:149], s[26:27], 0, v[144:145]
	s_add_i32 m0, s34, 0xe000
	s_nop 0
	global_load_lds_dwordx4 v[148:149], off
	s_waitcnt vmcnt(8)
	s_waitcnt lgkmcnt(0)
	s_setprio 2
	s_barrier
	v_mfma_f32_16x16x32_bf16 v[126:129], v[166:169], v[202:205], 0
	v_mfma_f32_16x16x32_bf16 v[122:125], v[178:181], v[202:205], 0
	v_mfma_f32_16x16x32_bf16 v[110:113], v[166:169], v[210:213], 0
	v_mfma_f32_16x16x32_bf16 v[106:109], v[178:181], v[210:213], 0
	v_mfma_f32_16x16x32_bf16 v[94:97], v[166:169], v[218:221], 0
	v_mfma_f32_16x16x32_bf16 v[90:93], v[178:181], v[218:221], 0
	v_mfma_f32_16x16x32_bf16 v[78:81], v[166:169], v[226:229], 0
	v_mfma_f32_16x16x32_bf16 v[74:77], v[178:181], v[226:229], 0
	v_mfma_f32_16x16x32_bf16 v[126:129], v[170:173], v[206:209], v[126:129]
	v_mfma_f32_16x16x32_bf16 v[122:125], v[182:185], v[206:209], v[122:125]
	v_mfma_f32_16x16x32_bf16 v[110:113], v[170:173], v[214:217], v[110:113]
	v_mfma_f32_16x16x32_bf16 v[106:109], v[182:185], v[214:217], v[106:109]
	v_mfma_f32_16x16x32_bf16 v[94:97], v[170:173], v[222:225], v[94:97]
	v_mfma_f32_16x16x32_bf16 v[90:93], v[182:185], v[222:225], v[90:93]
	v_mfma_f32_16x16x32_bf16 v[78:81], v[170:173], v[230:233], v[78:81]
	v_mfma_f32_16x16x32_bf16 v[74:77], v[182:185], v[230:233], v[74:77]
	v_mfma_f32_16x16x32_bf16 v[118:121], v[186:189], v[202:205], 0
	v_mfma_f32_16x16x32_bf16 v[114:117], v[194:197], v[202:205], 0
	v_mfma_f32_16x16x32_bf16 v[102:105], v[186:189], v[210:213], 0
	v_mfma_f32_16x16x32_bf16 v[98:101], v[194:197], v[210:213], 0
	v_mfma_f32_16x16x32_bf16 v[86:89], v[186:189], v[218:221], 0
	v_mfma_f32_16x16x32_bf16 v[82:85], v[194:197], v[218:221], 0
	v_mfma_f32_16x16x32_bf16 v[70:73], v[186:189], v[226:229], 0
	v_mfma_f32_16x16x32_bf16 v[66:69], v[194:197], v[226:229], 0
	v_mfma_f32_16x16x32_bf16 v[118:121], v[190:193], v[206:209], v[118:121]
	v_mfma_f32_16x16x32_bf16 v[114:117], v[198:201], v[206:209], v[114:117]
	v_mfma_f32_16x16x32_bf16 v[102:105], v[190:193], v[214:217], v[102:105]
	v_mfma_f32_16x16x32_bf16 v[98:101], v[198:201], v[214:217], v[98:101]
	v_mfma_f32_16x16x32_bf16 v[86:89], v[190:193], v[222:225], v[86:89]
	v_mfma_f32_16x16x32_bf16 v[82:85], v[198:201], v[222:225], v[82:85]
	v_mfma_f32_16x16x32_bf16 v[70:73], v[190:193], v[230:233], v[70:73]
	v_mfma_f32_16x16x32_bf16 v[66:69], v[198:201], v[230:233], v[66:69]
	s_barrier
	s_setprio 0
	s_add_i32 s53, s41, s30
	v_lshl_add_u64 v[148:149], s[28:29], 0, v[132:133]
	s_mov_b32 m0, s53
	ds_read_b128 v[202:205], v165 offset:16384
	ds_read_b128 v[206:209], v165 offset:17408
	ds_read_b128 v[210:213], v165 offset:18432
	ds_read_b128 v[214:217], v165 offset:19456
	ds_read_b128 v[218:221], v165 offset:20480
	ds_read_b128 v[222:225], v165 offset:21504
	ds_read_b128 v[226:229], v165 offset:22528
	ds_read_b128 v[230:233], v165 offset:23552
	global_load_lds_dwordx4 v[148:149], off
	s_add_i32 m0, s53, 0x2000
	s_add_u32 s54, s28, 0x40000
	v_lshl_add_u64 v[174:175], s[28:29], 0, v[136:137]
	s_addc_u32 s55, s29, 0
	s_add_i32 s53, s42, s30
	global_load_lds_dwordx4 v[174:175], off
	v_lshl_add_u64 v[234:235], s[54:55], 0, v[132:133]
	s_mov_b32 m0, s53
	v_lshl_add_u64 v[236:237], s[2:3], 0, v[134:135]
	global_load_lds_dwordx4 v[234:235], off
	v_lshl_add_u64 v[234:235], s[54:55], 0, v[136:137]
	s_add_i32 m0, s53, 0x2000
	s_nop 0
	global_load_lds_dwordx4 v[234:235], off
	v_lshl_add_u64 v[234:235], s[2:3], 0, v[130:131]
	s_mov_b32 m0, s34
	s_nop 0
	global_load_lds_dwordx4 v[234:235], off
	s_mov_b32 m0, s25
	s_nop 0
	global_load_lds_dwordx4 v[236:237], off
	s_waitcnt vmcnt(8)
	s_waitcnt lgkmcnt(0)
	s_setprio 2
	s_barrier
	v_mfma_f32_16x16x32_bf16 v[62:65], v[166:169], v[202:205], 0
	v_mfma_f32_16x16x32_bf16 v[58:61], v[178:181], v[202:205], 0
	v_mfma_f32_16x16x32_bf16 v[46:49], v[166:169], v[210:213], 0
	v_mfma_f32_16x16x32_bf16 v[42:45], v[178:181], v[210:213], 0
	v_mfma_f32_16x16x32_bf16 v[30:33], v[166:169], v[218:221], 0
	v_mfma_f32_16x16x32_bf16 v[26:29], v[178:181], v[218:221], 0
	v_mfma_f32_16x16x32_bf16 v[14:17], v[166:169], v[226:229], 0
	v_mfma_f32_16x16x32_bf16 v[10:13], v[178:181], v[226:229], 0
	v_mfma_f32_16x16x32_bf16 v[62:65], v[170:173], v[206:209], v[62:65]
	v_mfma_f32_16x16x32_bf16 v[58:61], v[182:185], v[206:209], v[58:61]
	v_mfma_f32_16x16x32_bf16 v[46:49], v[170:173], v[214:217], v[46:49]
	v_mfma_f32_16x16x32_bf16 v[42:45], v[182:185], v[214:217], v[42:45]
	v_mfma_f32_16x16x32_bf16 v[30:33], v[170:173], v[222:225], v[30:33]
	v_mfma_f32_16x16x32_bf16 v[26:29], v[182:185], v[222:225], v[26:29]
	v_mfma_f32_16x16x32_bf16 v[14:17], v[170:173], v[230:233], v[14:17]
	v_mfma_f32_16x16x32_bf16 v[10:13], v[182:185], v[230:233], v[10:13]
	v_mfma_f32_16x16x32_bf16 v[54:57], v[186:189], v[202:205], 0
	v_mfma_f32_16x16x32_bf16 v[50:53], v[194:197], v[202:205], 0
	v_mfma_f32_16x16x32_bf16 v[38:41], v[186:189], v[210:213], 0
	v_mfma_f32_16x16x32_bf16 v[34:37], v[194:197], v[210:213], 0
	v_mfma_f32_16x16x32_bf16 v[22:25], v[186:189], v[218:221], 0
	v_mfma_f32_16x16x32_bf16 v[18:21], v[194:197], v[218:221], 0
	v_mfma_f32_16x16x32_bf16 v[6:9], v[186:189], v[226:229], 0
	v_mfma_f32_16x16x32_bf16 v[2:5], v[194:197], v[226:229], 0
	v_mfma_f32_16x16x32_bf16 v[54:57], v[190:193], v[206:209], v[54:57]
	v_mfma_f32_16x16x32_bf16 v[50:53], v[198:201], v[206:209], v[50:53]
	v_mfma_f32_16x16x32_bf16 v[38:41], v[190:193], v[214:217], v[38:41]
	v_mfma_f32_16x16x32_bf16 v[34:37], v[198:201], v[214:217], v[34:37]
	v_mfma_f32_16x16x32_bf16 v[22:25], v[190:193], v[222:225], v[22:25]
	v_mfma_f32_16x16x32_bf16 v[18:21], v[198:201], v[222:225], v[18:21]
	v_mfma_f32_16x16x32_bf16 v[6:9], v[190:193], v[230:233], v[6:9]
	v_mfma_f32_16x16x32_bf16 v[2:5], v[198:201], v[230:233], v[2:5]
	s_barrier
	s_setprio 0
	s_add_i32 s53, 0, 0x18000
	v_add_u32_e32 v176, s53, v163
	s_add_i32 s54, 0, 0x1c000
	ds_read_b128 v[166:169], v176
	ds_read_b128 v[170:173], v176 offset:1024
	ds_read_b128 v[178:181], v176 offset:2048
	ds_read_b128 v[182:185], v176 offset:3072
	v_add_u32_e32 v176, s54, v163
	ds_read_b128 v[186:189], v176
	ds_read_b128 v[190:193], v176 offset:1024
	ds_read_b128 v[194:197], v176 offset:2048
	ds_read_b128 v[198:201], v176 offset:3072
	s_add_u32 s2, s2, 0x40000
	s_addc_u32 s3, s3, 0
	s_mov_b32 m0, s35
	v_lshl_add_u64 v[238:239], s[2:3], 0, v[130:131]
	ds_read_b128 v[202:205], v165 offset:32768
	ds_read_b128 v[206:209], v165 offset:33792
	ds_read_b128 v[210:213], v165 offset:34816
	ds_read_b128 v[214:217], v165 offset:35840
	ds_read_b128 v[218:221], v165 offset:36864
	ds_read_b128 v[222:225], v165 offset:37888
	ds_read_b128 v[226:229], v165 offset:38912
	ds_read_b128 v[230:233], v165 offset:39936
	global_load_lds_dwordx4 v[238:239], off
	v_lshl_add_u64 v[238:239], s[2:3], 0, v[134:135]
	s_mov_b32 m0, s36
	s_nop 0
	global_load_lds_dwordx4 v[238:239], off
	s_waitcnt vmcnt(8)
	s_waitcnt lgkmcnt(0)
	s_setprio 2
	s_barrier
	v_mfma_f32_16x16x32_bf16 v[126:129], v[166:169], v[202:205], v[126:129]
	v_mfma_f32_16x16x32_bf16 v[122:125], v[178:181], v[202:205], v[122:125]
	v_mfma_f32_16x16x32_bf16 v[110:113], v[166:169], v[210:213], v[110:113]
	v_mfma_f32_16x16x32_bf16 v[106:109], v[178:181], v[210:213], v[106:109]
	v_mfma_f32_16x16x32_bf16 v[94:97], v[166:169], v[218:221], v[94:97]
	v_mfma_f32_16x16x32_bf16 v[90:93], v[178:181], v[218:221], v[90:93]
	v_mfma_f32_16x16x32_bf16 v[78:81], v[166:169], v[226:229], v[78:81]
	v_mfma_f32_16x16x32_bf16 v[74:77], v[178:181], v[226:229], v[74:77]
	v_mfma_f32_16x16x32_bf16 v[126:129], v[170:173], v[206:209], v[126:129]
	v_mfma_f32_16x16x32_bf16 v[122:125], v[182:185], v[206:209], v[122:125]
	v_mfma_f32_16x16x32_bf16 v[110:113], v[170:173], v[214:217], v[110:113]
	v_mfma_f32_16x16x32_bf16 v[106:109], v[182:185], v[214:217], v[106:109]
	v_mfma_f32_16x16x32_bf16 v[94:97], v[170:173], v[222:225], v[94:97]
	v_mfma_f32_16x16x32_bf16 v[90:93], v[182:185], v[222:225], v[90:93]
	v_mfma_f32_16x16x32_bf16 v[78:81], v[170:173], v[230:233], v[78:81]
	v_mfma_f32_16x16x32_bf16 v[74:77], v[182:185], v[230:233], v[74:77]
	v_mfma_f32_16x16x32_bf16 v[118:121], v[186:189], v[202:205], v[118:121]
	v_mfma_f32_16x16x32_bf16 v[114:117], v[194:197], v[202:205], v[114:117]
	v_mfma_f32_16x16x32_bf16 v[102:105], v[186:189], v[210:213], v[102:105]
	v_mfma_f32_16x16x32_bf16 v[98:101], v[194:197], v[210:213], v[98:101]
	v_mfma_f32_16x16x32_bf16 v[86:89], v[186:189], v[218:221], v[86:89]
	v_mfma_f32_16x16x32_bf16 v[82:85], v[194:197], v[218:221], v[82:85]
	v_mfma_f32_16x16x32_bf16 v[70:73], v[186:189], v[226:229], v[70:73]
	v_mfma_f32_16x16x32_bf16 v[66:69], v[194:197], v[226:229], v[66:69]
	v_mfma_f32_16x16x32_bf16 v[118:121], v[190:193], v[206:209], v[118:121]
	v_mfma_f32_16x16x32_bf16 v[114:117], v[198:201], v[206:209], v[114:117]
	v_mfma_f32_16x16x32_bf16 v[102:105], v[190:193], v[214:217], v[102:105]
	v_mfma_f32_16x16x32_bf16 v[98:101], v[198:201], v[214:217], v[98:101]
	v_mfma_f32_16x16x32_bf16 v[86:89], v[190:193], v[222:225], v[86:89]
	v_mfma_f32_16x16x32_bf16 v[82:85], v[198:201], v[222:225], v[82:85]
	v_mfma_f32_16x16x32_bf16 v[70:73], v[190:193], v[230:233], v[70:73]
	v_mfma_f32_16x16x32_bf16 v[66:69], v[198:201], v[230:233], v[66:69]
	s_barrier
	s_setprio 0
	s_add_i32 s2, s53, s30
	v_lshl_add_u64 v[148:149], v[148:149], 0, s[6:7]
	s_mov_b32 m0, s2
	ds_read_b128 v[202:205], v165 offset:49152
	ds_read_b128 v[206:209], v165 offset:50176
	ds_read_b128 v[210:213], v165 offset:51200
	ds_read_b128 v[214:217], v165 offset:52224
	ds_read_b128 v[218:221], v165 offset:53248
	ds_read_b128 v[222:225], v165 offset:54272
	ds_read_b128 v[226:229], v165 offset:55296
	ds_read_b128 v[230:233], v165 offset:56320
	global_load_lds_dwordx4 v[148:149], off
	s_add_i32 m0, s2, 0x2000
	s_add_u32 s2, s28, 0x40080
	v_lshl_add_u64 v[148:149], v[174:175], 0, s[6:7]
	s_addc_u32 s3, s29, 0
	s_add_i32 s28, s54, s30
	global_load_lds_dwordx4 v[148:149], off
	v_lshl_add_u64 v[148:149], s[2:3], 0, v[132:133]
	s_mov_b32 m0, s28
	s_nop 0
	global_load_lds_dwordx4 v[148:149], off
	v_lshl_add_u64 v[148:149], s[2:3], 0, v[136:137]
	s_add_i32 m0, s28, 0x2000
	s_nop 0
	global_load_lds_dwordx4 v[148:149], off
	v_lshl_add_u64 v[148:149], v[234:235], 0, s[6:7]
	s_mov_b32 m0, s38
	s_nop 0
	global_load_lds_dwordx4 v[148:149], off
	v_lshl_add_u64 v[148:149], v[236:237], 0, s[6:7]
	s_mov_b32 m0, s39
	s_nop 0
	global_load_lds_dwordx4 v[148:149], off
	s_waitcnt vmcnt(8)
	s_waitcnt lgkmcnt(0)
	s_setprio 2
	s_barrier
	v_mfma_f32_16x16x32_bf16 v[62:65], v[166:169], v[202:205], v[62:65]
	v_mfma_f32_16x16x32_bf16 v[58:61], v[178:181], v[202:205], v[58:61]
	v_mfma_f32_16x16x32_bf16 v[46:49], v[166:169], v[210:213], v[46:49]
	v_mfma_f32_16x16x32_bf16 v[42:45], v[178:181], v[210:213], v[42:45]
	v_mfma_f32_16x16x32_bf16 v[30:33], v[166:169], v[218:221], v[30:33]
	v_mfma_f32_16x16x32_bf16 v[26:29], v[178:181], v[218:221], v[26:29]
	v_mfma_f32_16x16x32_bf16 v[14:17], v[166:169], v[226:229], v[14:17]
	v_mfma_f32_16x16x32_bf16 v[10:13], v[178:181], v[226:229], v[10:13]
	v_mfma_f32_16x16x32_bf16 v[62:65], v[170:173], v[206:209], v[62:65]
	v_mfma_f32_16x16x32_bf16 v[58:61], v[182:185], v[206:209], v[58:61]
	v_mfma_f32_16x16x32_bf16 v[46:49], v[170:173], v[214:217], v[46:49]
	v_mfma_f32_16x16x32_bf16 v[42:45], v[182:185], v[214:217], v[42:45]
	v_mfma_f32_16x16x32_bf16 v[30:33], v[170:173], v[222:225], v[30:33]
	v_mfma_f32_16x16x32_bf16 v[26:29], v[182:185], v[222:225], v[26:29]
	v_mfma_f32_16x16x32_bf16 v[14:17], v[170:173], v[230:233], v[14:17]
	v_mfma_f32_16x16x32_bf16 v[10:13], v[182:185], v[230:233], v[10:13]
	v_mfma_f32_16x16x32_bf16 v[54:57], v[186:189], v[202:205], v[54:57]
	v_mfma_f32_16x16x32_bf16 v[50:53], v[194:197], v[202:205], v[50:53]
	v_mfma_f32_16x16x32_bf16 v[38:41], v[186:189], v[210:213], v[38:41]
	v_mfma_f32_16x16x32_bf16 v[34:37], v[194:197], v[210:213], v[34:37]
	v_mfma_f32_16x16x32_bf16 v[22:25], v[186:189], v[218:221], v[22:25]
	v_mfma_f32_16x16x32_bf16 v[18:21], v[194:197], v[218:221], v[18:21]
	v_mfma_f32_16x16x32_bf16 v[6:9], v[186:189], v[226:229], v[6:9]
	v_mfma_f32_16x16x32_bf16 v[2:5], v[194:197], v[226:229], v[2:5]
	v_mfma_f32_16x16x32_bf16 v[54:57], v[190:193], v[206:209], v[54:57]
	v_mfma_f32_16x16x32_bf16 v[50:53], v[198:201], v[206:209], v[50:53]
	v_mfma_f32_16x16x32_bf16 v[38:41], v[190:193], v[214:217], v[38:41]
	v_mfma_f32_16x16x32_bf16 v[34:37], v[198:201], v[214:217], v[34:37]
	v_mfma_f32_16x16x32_bf16 v[22:25], v[190:193], v[222:225], v[22:25]
	v_mfma_f32_16x16x32_bf16 v[18:21], v[198:201], v[222:225], v[18:21]
	v_mfma_f32_16x16x32_bf16 v[6:9], v[190:193], v[230:233], v[6:9]
	v_mfma_f32_16x16x32_bf16 v[2:5], v[198:201], v[230:233], v[2:5]
	s_barrier
	s_setprio 0
	s_add_i32 s52, s52, 2
	s_add_u32 s26, s26, 0x100
	s_addc_u32 s27, s27, 0
	s_add_u32 s46, s46, 0x100
	s_addc_u32 s47, s47, 0
	s_cmp_gt_u32 s52, 13
	s_cbranch_scc0 .LBB0_354
	s_branch .Lpk354_exit
.LBB0_354:
	ds_read_b128 v[166:169], v139
	ds_read_b128 v[170:173], v139 offset:1024
	ds_read_b128 v[178:181], v139 offset:2048
	ds_read_b128 v[182:185], v139 offset:3072
	ds_read_b128 v[186:189], v164
	ds_read_b128 v[190:193], v164 offset:1024
	ds_read_b128 v[194:197], v164 offset:2048
	ds_read_b128 v[198:201], v164 offset:3072
	s_add_u32 s2, s26, 0xfffc0080
	s_addc_u32 s3, s27, -1
	s_cmp_eq_u32 s52, 12
	s_cselect_b32 s3, s11, s3
	s_cselect_b32 s2, s13, s2
	s_cselect_b32 s29, s44, s47
	s_cselect_b32 s28, s45, s46
	v_lshl_add_u64 v[148:149], s[26:27], 0, v[142:143]
	s_add_i32 m0, s34, 0xc000
	ds_read_b128 v[202:205], v165
	ds_read_b128 v[206:209], v165 offset:1024
	ds_read_b128 v[210:213], v165 offset:2048
	ds_read_b128 v[214:217], v165 offset:3072
	ds_read_b128 v[218:221], v165 offset:4096
	ds_read_b128 v[222:225], v165 offset:5120
	ds_read_b128 v[226:229], v165 offset:6144
	ds_read_b128 v[230:233], v165 offset:7168
	global_load_lds_dwordx4 v[148:149], off
	v_lshl_add_u64 v[148:149], s[26:27], 0, v[144:145]
	s_add_i32 m0, s34, 0xe000
	s_nop 0
	global_load_lds_dwordx4 v[148:149], off
	s_waitcnt vmcnt(8)
	s_waitcnt lgkmcnt(0)
	s_setprio 2
	s_barrier
	v_mfma_f32_16x16x32_bf16 v[126:129], v[166:169], v[202:205], v[126:129]
	v_mfma_f32_16x16x32_bf16 v[122:125], v[178:181], v[202:205], v[122:125]
	v_mfma_f32_16x16x32_bf16 v[110:113], v[166:169], v[210:213], v[110:113]
	v_mfma_f32_16x16x32_bf16 v[106:109], v[178:181], v[210:213], v[106:109]
	v_mfma_f32_16x16x32_bf16 v[94:97], v[166:169], v[218:221], v[94:97]
	v_mfma_f32_16x16x32_bf16 v[90:93], v[178:181], v[218:221], v[90:93]
	v_mfma_f32_16x16x32_bf16 v[78:81], v[166:169], v[226:229], v[78:81]
	v_mfma_f32_16x16x32_bf16 v[74:77], v[178:181], v[226:229], v[74:77]
	v_mfma_f32_16x16x32_bf16 v[126:129], v[170:173], v[206:209], v[126:129]
	v_mfma_f32_16x16x32_bf16 v[122:125], v[182:185], v[206:209], v[122:125]
	v_mfma_f32_16x16x32_bf16 v[110:113], v[170:173], v[214:217], v[110:113]
	v_mfma_f32_16x16x32_bf16 v[106:109], v[182:185], v[214:217], v[106:109]
	v_mfma_f32_16x16x32_bf16 v[94:97], v[170:173], v[222:225], v[94:97]
	v_mfma_f32_16x16x32_bf16 v[90:93], v[182:185], v[222:225], v[90:93]
	v_mfma_f32_16x16x32_bf16 v[78:81], v[170:173], v[230:233], v[78:81]
	v_mfma_f32_16x16x32_bf16 v[74:77], v[182:185], v[230:233], v[74:77]
	v_mfma_f32_16x16x32_bf16 v[118:121], v[186:189], v[202:205], v[118:121]
	v_mfma_f32_16x16x32_bf16 v[114:117], v[194:197], v[202:205], v[114:117]
	v_mfma_f32_16x16x32_bf16 v[102:105], v[186:189], v[210:213], v[102:105]
	v_mfma_f32_16x16x32_bf16 v[98:101], v[194:197], v[210:213], v[98:101]
	v_mfma_f32_16x16x32_bf16 v[86:89], v[186:189], v[218:221], v[86:89]
	v_mfma_f32_16x16x32_bf16 v[82:85], v[194:197], v[218:221], v[82:85]
	v_mfma_f32_16x16x32_bf16 v[70:73], v[186:189], v[226:229], v[70:73]
	v_mfma_f32_16x16x32_bf16 v[66:69], v[194:197], v[226:229], v[66:69]
	v_mfma_f32_16x16x32_bf16 v[118:121], v[190:193], v[206:209], v[118:121]
	v_mfma_f32_16x16x32_bf16 v[114:117], v[198:201], v[206:209], v[114:117]
	v_mfma_f32_16x16x32_bf16 v[102:105], v[190:193], v[214:217], v[102:105]
	v_mfma_f32_16x16x32_bf16 v[98:101], v[198:201], v[214:217], v[98:101]
	v_mfma_f32_16x16x32_bf16 v[86:89], v[190:193], v[222:225], v[86:89]
	v_mfma_f32_16x16x32_bf16 v[82:85], v[198:201], v[222:225], v[82:85]
	v_mfma_f32_16x16x32_bf16 v[70:73], v[190:193], v[230:233], v[70:73]
	v_mfma_f32_16x16x32_bf16 v[66:69], v[198:201], v[230:233], v[66:69]
	s_barrier
	s_setprio 0
	s_add_i32 s53, s41, s30
	v_lshl_add_u64 v[148:149], s[28:29], 0, v[132:133]
	s_mov_b32 m0, s53
	ds_read_b128 v[202:205], v165 offset:16384
	ds_read_b128 v[206:209], v165 offset:17408
	ds_read_b128 v[210:213], v165 offset:18432
	ds_read_b128 v[214:217], v165 offset:19456
	ds_read_b128 v[218:221], v165 offset:20480
	ds_read_b128 v[222:225], v165 offset:21504
	ds_read_b128 v[226:229], v165 offset:22528
	ds_read_b128 v[230:233], v165 offset:23552
	global_load_lds_dwordx4 v[148:149], off
	s_add_i32 m0, s53, 0x2000
	s_add_u32 s54, s28, 0x40000
	v_lshl_add_u64 v[174:175], s[28:29], 0, v[136:137]
	s_addc_u32 s55, s29, 0
	s_add_i32 s53, s42, s30
	global_load_lds_dwordx4 v[174:175], off
	v_lshl_add_u64 v[234:235], s[54:55], 0, v[132:133]
	s_mov_b32 m0, s53
	v_lshl_add_u64 v[236:237], s[2:3], 0, v[134:135]
	global_load_lds_dwordx4 v[234:235], off
	v_lshl_add_u64 v[234:235], s[54:55], 0, v[136:137]
	s_add_i32 m0, s53, 0x2000
	s_nop 0
	global_load_lds_dwordx4 v[234:235], off
	v_lshl_add_u64 v[234:235], s[2:3], 0, v[130:131]
	s_mov_b32 m0, s34
	s_nop 0
	global_load_lds_dwordx4 v[234:235], off
	s_mov_b32 m0, s25
	s_nop 0
	global_load_lds_dwordx4 v[236:237], off
	s_waitcnt vmcnt(8)
	s_waitcnt lgkmcnt(0)
	s_setprio 2
	s_barrier
	v_mfma_f32_16x16x32_bf16 v[62:65], v[166:169], v[202:205], v[62:65]
	v_mfma_f32_16x16x32_bf16 v[58:61], v[178:181], v[202:205], v[58:61]
	v_mfma_f32_16x16x32_bf16 v[46:49], v[166:169], v[210:213], v[46:49]
	v_mfma_f32_16x16x32_bf16 v[42:45], v[178:181], v[210:213], v[42:45]
	v_mfma_f32_16x16x32_bf16 v[30:33], v[166:169], v[218:221], v[30:33]
	v_mfma_f32_16x16x32_bf16 v[26:29], v[178:181], v[218:221], v[26:29]
	v_mfma_f32_16x16x32_bf16 v[14:17], v[166:169], v[226:229], v[14:17]
	v_mfma_f32_16x16x32_bf16 v[10:13], v[178:181], v[226:229], v[10:13]
	v_mfma_f32_16x16x32_bf16 v[62:65], v[170:173], v[206:209], v[62:65]
	v_mfma_f32_16x16x32_bf16 v[58:61], v[182:185], v[206:209], v[58:61]
	v_mfma_f32_16x16x32_bf16 v[46:49], v[170:173], v[214:217], v[46:49]
	v_mfma_f32_16x16x32_bf16 v[42:45], v[182:185], v[214:217], v[42:45]
	v_mfma_f32_16x16x32_bf16 v[30:33], v[170:173], v[222:225], v[30:33]
	v_mfma_f32_16x16x32_bf16 v[26:29], v[182:185], v[222:225], v[26:29]
	v_mfma_f32_16x16x32_bf16 v[14:17], v[170:173], v[230:233], v[14:17]
	v_mfma_f32_16x16x32_bf16 v[10:13], v[182:185], v[230:233], v[10:13]
	v_mfma_f32_16x16x32_bf16 v[54:57], v[186:189], v[202:205], v[54:57]
	v_mfma_f32_16x16x32_bf16 v[50:53], v[194:197], v[202:205], v[50:53]
	v_mfma_f32_16x16x32_bf16 v[38:41], v[186:189], v[210:213], v[38:41]
	v_mfma_f32_16x16x32_bf16 v[34:37], v[194:197], v[210:213], v[34:37]
	v_mfma_f32_16x16x32_bf16 v[22:25], v[186:189], v[218:221], v[22:25]
	v_mfma_f32_16x16x32_bf16 v[18:21], v[194:197], v[218:221], v[18:21]
	v_mfma_f32_16x16x32_bf16 v[6:9], v[186:189], v[226:229], v[6:9]
	v_mfma_f32_16x16x32_bf16 v[2:5], v[194:197], v[226:229], v[2:5]
	v_mfma_f32_16x16x32_bf16 v[54:57], v[190:193], v[206:209], v[54:57]
	v_mfma_f32_16x16x32_bf16 v[50:53], v[198:201], v[206:209], v[50:53]
	v_mfma_f32_16x16x32_bf16 v[38:41], v[190:193], v[214:217], v[38:41]
	v_mfma_f32_16x16x32_bf16 v[34:37], v[198:201], v[214:217], v[34:37]
	v_mfma_f32_16x16x32_bf16 v[22:25], v[190:193], v[222:225], v[22:25]
	v_mfma_f32_16x16x32_bf16 v[18:21], v[198:201], v[222:225], v[18:21]
	v_mfma_f32_16x16x32_bf16 v[6:9], v[190:193], v[230:233], v[6:9]
	v_mfma_f32_16x16x32_bf16 v[2:5], v[198:201], v[230:233], v[2:5]
	s_barrier
	s_setprio 0
	s_add_i32 s53, 0, 0x18000
	v_add_u32_e32 v176, s53, v163
	s_add_i32 s54, 0, 0x1c000
	ds_read_b128 v[166:169], v176
	ds_read_b128 v[170:173], v176 offset:1024
	ds_read_b128 v[178:181], v176 offset:2048
	ds_read_b128 v[182:185], v176 offset:3072
	v_add_u32_e32 v176, s54, v163
	ds_read_b128 v[186:189], v176
	ds_read_b128 v[190:193], v176 offset:1024
	ds_read_b128 v[194:197], v176 offset:2048
	ds_read_b128 v[198:201], v176 offset:3072
	s_add_u32 s2, s2, 0x40000
	s_addc_u32 s3, s3, 0
	s_mov_b32 m0, s35
	v_lshl_add_u64 v[238:239], s[2:3], 0, v[130:131]
	ds_read_b128 v[202:205], v165 offset:32768
	ds_read_b128 v[206:209], v165 offset:33792
	ds_read_b128 v[210:213], v165 offset:34816
	ds_read_b128 v[214:217], v165 offset:35840
	ds_read_b128 v[218:221], v165 offset:36864
	ds_read_b128 v[222:225], v165 offset:37888
	ds_read_b128 v[226:229], v165 offset:38912
	ds_read_b128 v[230:233], v165 offset:39936
	global_load_lds_dwordx4 v[238:239], off
	v_lshl_add_u64 v[238:239], s[2:3], 0, v[134:135]
	s_mov_b32 m0, s36
	s_nop 0
	global_load_lds_dwordx4 v[238:239], off
	s_waitcnt vmcnt(8)
	s_waitcnt lgkmcnt(0)
	s_setprio 2
	s_barrier
	v_mfma_f32_16x16x32_bf16 v[126:129], v[166:169], v[202:205], v[126:129]
	v_mfma_f32_16x16x32_bf16 v[122:125], v[178:181], v[202:205], v[122:125]
	v_mfma_f32_16x16x32_bf16 v[110:113], v[166:169], v[210:213], v[110:113]
	v_mfma_f32_16x16x32_bf16 v[106:109], v[178:181], v[210:213], v[106:109]
	v_mfma_f32_16x16x32_bf16 v[94:97], v[166:169], v[218:221], v[94:97]
	v_mfma_f32_16x16x32_bf16 v[90:93], v[178:181], v[218:221], v[90:93]
	v_mfma_f32_16x16x32_bf16 v[78:81], v[166:169], v[226:229], v[78:81]
	v_mfma_f32_16x16x32_bf16 v[74:77], v[178:181], v[226:229], v[74:77]
	v_mfma_f32_16x16x32_bf16 v[126:129], v[170:173], v[206:209], v[126:129]
	v_mfma_f32_16x16x32_bf16 v[122:125], v[182:185], v[206:209], v[122:125]
	v_mfma_f32_16x16x32_bf16 v[110:113], v[170:173], v[214:217], v[110:113]
	v_mfma_f32_16x16x32_bf16 v[106:109], v[182:185], v[214:217], v[106:109]
	v_mfma_f32_16x16x32_bf16 v[94:97], v[170:173], v[222:225], v[94:97]
	v_mfma_f32_16x16x32_bf16 v[90:93], v[182:185], v[222:225], v[90:93]
	v_mfma_f32_16x16x32_bf16 v[78:81], v[170:173], v[230:233], v[78:81]
	v_mfma_f32_16x16x32_bf16 v[74:77], v[182:185], v[230:233], v[74:77]
	v_mfma_f32_16x16x32_bf16 v[118:121], v[186:189], v[202:205], v[118:121]
	v_mfma_f32_16x16x32_bf16 v[114:117], v[194:197], v[202:205], v[114:117]
	v_mfma_f32_16x16x32_bf16 v[102:105], v[186:189], v[210:213], v[102:105]
	v_mfma_f32_16x16x32_bf16 v[98:101], v[194:197], v[210:213], v[98:101]
	v_mfma_f32_16x16x32_bf16 v[86:89], v[186:189], v[218:221], v[86:89]
	v_mfma_f32_16x16x32_bf16 v[82:85], v[194:197], v[218:221], v[82:85]
	v_mfma_f32_16x16x32_bf16 v[70:73], v[186:189], v[226:229], v[70:73]
	v_mfma_f32_16x16x32_bf16 v[66:69], v[194:197], v[226:229], v[66:69]
	v_mfma_f32_16x16x32_bf16 v[118:121], v[190:193], v[206:209], v[118:121]
	v_mfma_f32_16x16x32_bf16 v[114:117], v[198:201], v[206:209], v[114:117]
	v_mfma_f32_16x16x32_bf16 v[102:105], v[190:193], v[214:217], v[102:105]
	v_mfma_f32_16x16x32_bf16 v[98:101], v[198:201], v[214:217], v[98:101]
	v_mfma_f32_16x16x32_bf16 v[86:89], v[190:193], v[222:225], v[86:89]
	v_mfma_f32_16x16x32_bf16 v[82:85], v[198:201], v[222:225], v[82:85]
	v_mfma_f32_16x16x32_bf16 v[70:73], v[190:193], v[230:233], v[70:73]
	v_mfma_f32_16x16x32_bf16 v[66:69], v[198:201], v[230:233], v[66:69]
	s_barrier
	s_setprio 0
	s_add_i32 s2, s53, s30
	v_lshl_add_u64 v[148:149], v[148:149], 0, s[6:7]
	s_mov_b32 m0, s2
	ds_read_b128 v[202:205], v165 offset:49152
	ds_read_b128 v[206:209], v165 offset:50176
	ds_read_b128 v[210:213], v165 offset:51200
	ds_read_b128 v[214:217], v165 offset:52224
	ds_read_b128 v[218:221], v165 offset:53248
	ds_read_b128 v[222:225], v165 offset:54272
	ds_read_b128 v[226:229], v165 offset:55296
	ds_read_b128 v[230:233], v165 offset:56320
	global_load_lds_dwordx4 v[148:149], off
	s_add_i32 m0, s2, 0x2000
	s_add_u32 s2, s28, 0x40080
	v_lshl_add_u64 v[148:149], v[174:175], 0, s[6:7]
	s_addc_u32 s3, s29, 0
	s_add_i32 s28, s54, s30
	global_load_lds_dwordx4 v[148:149], off
	v_lshl_add_u64 v[148:149], s[2:3], 0, v[132:133]
	s_mov_b32 m0, s28
	s_nop 0
	global_load_lds_dwordx4 v[148:149], off
	v_lshl_add_u64 v[148:149], s[2:3], 0, v[136:137]
	s_add_i32 m0, s28, 0x2000
	s_nop 0
	global_load_lds_dwordx4 v[148:149], off
	v_lshl_add_u64 v[148:149], v[234:235], 0, s[6:7]
	s_mov_b32 m0, s38
	s_nop 0
	global_load_lds_dwordx4 v[148:149], off
	v_lshl_add_u64 v[148:149], v[236:237], 0, s[6:7]
	s_mov_b32 m0, s39
	s_nop 0
	global_load_lds_dwordx4 v[148:149], off
	s_waitcnt vmcnt(8)
	s_waitcnt lgkmcnt(0)
	s_setprio 2
	s_barrier
	v_mfma_f32_16x16x32_bf16 v[62:65], v[166:169], v[202:205], v[62:65]
	v_mfma_f32_16x16x32_bf16 v[58:61], v[178:181], v[202:205], v[58:61]
	v_mfma_f32_16x16x32_bf16 v[46:49], v[166:169], v[210:213], v[46:49]
	v_mfma_f32_16x16x32_bf16 v[42:45], v[178:181], v[210:213], v[42:45]
	v_mfma_f32_16x16x32_bf16 v[30:33], v[166:169], v[218:221], v[30:33]
	v_mfma_f32_16x16x32_bf16 v[26:29], v[178:181], v[218:221], v[26:29]
	v_mfma_f32_16x16x32_bf16 v[14:17], v[166:169], v[226:229], v[14:17]
	v_mfma_f32_16x16x32_bf16 v[10:13], v[178:181], v[226:229], v[10:13]
	v_mfma_f32_16x16x32_bf16 v[62:65], v[170:173], v[206:209], v[62:65]
	v_mfma_f32_16x16x32_bf16 v[58:61], v[182:185], v[206:209], v[58:61]
	v_mfma_f32_16x16x32_bf16 v[46:49], v[170:173], v[214:217], v[46:49]
	v_mfma_f32_16x16x32_bf16 v[42:45], v[182:185], v[214:217], v[42:45]
	v_mfma_f32_16x16x32_bf16 v[30:33], v[170:173], v[222:225], v[30:33]
	v_mfma_f32_16x16x32_bf16 v[26:29], v[182:185], v[222:225], v[26:29]
	v_mfma_f32_16x16x32_bf16 v[14:17], v[170:173], v[230:233], v[14:17]
	v_mfma_f32_16x16x32_bf16 v[10:13], v[182:185], v[230:233], v[10:13]
	v_mfma_f32_16x16x32_bf16 v[54:57], v[186:189], v[202:205], v[54:57]
	v_mfma_f32_16x16x32_bf16 v[50:53], v[194:197], v[202:205], v[50:53]
	v_mfma_f32_16x16x32_bf16 v[38:41], v[186:189], v[210:213], v[38:41]
	v_mfma_f32_16x16x32_bf16 v[34:37], v[194:197], v[210:213], v[34:37]
	v_mfma_f32_16x16x32_bf16 v[22:25], v[186:189], v[218:221], v[22:25]
	v_mfma_f32_16x16x32_bf16 v[18:21], v[194:197], v[218:221], v[18:21]
	v_mfma_f32_16x16x32_bf16 v[6:9], v[186:189], v[226:229], v[6:9]
	v_mfma_f32_16x16x32_bf16 v[2:5], v[194:197], v[226:229], v[2:5]
	v_mfma_f32_16x16x32_bf16 v[54:57], v[190:193], v[206:209], v[54:57]
	v_mfma_f32_16x16x32_bf16 v[50:53], v[198:201], v[206:209], v[50:53]
	v_mfma_f32_16x16x32_bf16 v[38:41], v[190:193], v[214:217], v[38:41]
	v_mfma_f32_16x16x32_bf16 v[34:37], v[198:201], v[214:217], v[34:37]
	v_mfma_f32_16x16x32_bf16 v[22:25], v[190:193], v[222:225], v[22:25]
	v_mfma_f32_16x16x32_bf16 v[18:21], v[198:201], v[222:225], v[18:21]
	v_mfma_f32_16x16x32_bf16 v[6:9], v[190:193], v[230:233], v[6:9]
	v_mfma_f32_16x16x32_bf16 v[2:5], v[198:201], v[230:233], v[2:5]
	s_barrier
	s_setprio 0
	s_add_i32 s52, s52, 2
	s_add_u32 s26, s26, 0x100
	s_addc_u32 s27, s27, 0
	s_add_u32 s46, s46, 0x100
	s_addc_u32 s47, s47, 0
	s_cmp_gt_u32 s52, 13
	s_cbranch_scc0 .LBB0_354

.LBB0_437:
	ds_read_b128 v[160:163], v133
	ds_read_b128 v[164:167], v133 offset:1024
	ds_read_b128 v[168:171], v133 offset:2048
	ds_read_b128 v[172:175], v133 offset:3072
	ds_read_b128 v[178:181], v135
	ds_read_b128 v[182:185], v135 offset:1024
	ds_read_b128 v[186:189], v135 offset:2048
	ds_read_b128 v[190:193], v135 offset:3072
	s_cmp_lg_u32 s8, 0x160000
	s_cselect_b32 s13, s8, 0
	s_cselect_b32 s12, s9, 0
	s_add_u32 s2, s6, s13
	s_addc_u32 s3, s7, s12
	s_add_u32 s14, s0, s13
	s_addc_u32 s15, s1, s12
	s_add_u32 s12, s2, 0x8000
	s_addc_u32 s13, s3, 0
	v_lshl_add_u64 v[226:227], v[148:149], 0, s[8:9]
	s_mov_b32 m0, s27
	v_lshl_add_u64 v[226:227], v[226:227], 0, s[10:11]
	ds_read_b128 v[194:197], v137
	ds_read_b128 v[198:201], v137 offset:1024
	ds_read_b128 v[202:205], v137 offset:2048
	ds_read_b128 v[206:209], v137 offset:3072
	ds_read_b128 v[210:213], v137 offset:4096
	ds_read_b128 v[214:217], v137 offset:5120
	ds_read_b128 v[218:221], v137 offset:6144
	ds_read_b128 v[222:225], v137 offset:7168
	global_load_lds_dwordx4 v[226:227], off
	v_lshl_add_u64 v[226:227], v[150:151], 0, s[8:9]
	v_lshl_add_u64 v[226:227], v[226:227], 0, s[10:11]
	s_mov_b32 m0, s28
	s_nop 0
	global_load_lds_dwordx4 v[226:227], off
	s_waitcnt vmcnt(8)
	s_waitcnt lgkmcnt(0)
	s_setprio 2
	s_barrier
	v_mfma_f32_16x16x32_bf16 v[126:129], v[160:163], v[194:197], v[126:129]
	v_mfma_f32_16x16x32_bf16 v[122:125], v[168:171], v[194:197], v[122:125]
	v_mfma_f32_16x16x32_bf16 v[114:117], v[160:163], v[202:205], v[114:117]
	v_mfma_f32_16x16x32_bf16 v[106:109], v[168:171], v[202:205], v[106:109]
	v_mfma_f32_16x16x32_bf16 v[98:101], v[160:163], v[210:213], v[98:101]
	v_mfma_f32_16x16x32_bf16 v[90:93], v[168:171], v[210:213], v[90:93]
	v_mfma_f32_16x16x32_bf16 v[82:85], v[160:163], v[218:221], v[82:85]
	v_mfma_f32_16x16x32_bf16 v[74:77], v[168:171], v[218:221], v[74:77]
	v_mfma_f32_16x16x32_bf16 v[126:129], v[164:167], v[198:201], v[126:129]
	v_mfma_f32_16x16x32_bf16 v[122:125], v[172:175], v[198:201], v[122:125]
	v_mfma_f32_16x16x32_bf16 v[114:117], v[164:167], v[206:209], v[114:117]
	v_mfma_f32_16x16x32_bf16 v[106:109], v[172:175], v[206:209], v[106:109]
	v_mfma_f32_16x16x32_bf16 v[98:101], v[164:167], v[214:217], v[98:101]
	v_mfma_f32_16x16x32_bf16 v[90:93], v[172:175], v[214:217], v[90:93]
	v_mfma_f32_16x16x32_bf16 v[82:85], v[164:167], v[222:225], v[82:85]
	v_mfma_f32_16x16x32_bf16 v[74:77], v[172:175], v[222:225], v[74:77]
	v_mfma_f32_16x16x32_bf16 v[118:121], v[178:181], v[194:197], v[118:121]
	v_mfma_f32_16x16x32_bf16 v[110:113], v[186:189], v[194:197], v[110:113]
	v_mfma_f32_16x16x32_bf16 v[102:105], v[178:181], v[202:205], v[102:105]
	v_mfma_f32_16x16x32_bf16 v[94:97], v[186:189], v[202:205], v[94:97]
	v_mfma_f32_16x16x32_bf16 v[86:89], v[178:181], v[210:213], v[86:89]
	v_mfma_f32_16x16x32_bf16 v[78:81], v[186:189], v[210:213], v[78:81]
	v_mfma_f32_16x16x32_bf16 v[70:73], v[178:181], v[218:221], v[70:73]
	v_mfma_f32_16x16x32_bf16 v[66:69], v[186:189], v[218:221], v[66:69]
	v_mfma_f32_16x16x32_bf16 v[118:121], v[182:185], v[198:201], v[118:121]
	v_mfma_f32_16x16x32_bf16 v[110:113], v[190:193], v[198:201], v[110:113]
	v_mfma_f32_16x16x32_bf16 v[102:105], v[182:185], v[206:209], v[102:105]
	v_mfma_f32_16x16x32_bf16 v[94:97], v[190:193], v[206:209], v[94:97]
	v_mfma_f32_16x16x32_bf16 v[86:89], v[182:185], v[214:217], v[86:89]
	v_mfma_f32_16x16x32_bf16 v[78:81], v[190:193], v[214:217], v[78:81]
	v_mfma_f32_16x16x32_bf16 v[70:73], v[182:185], v[222:225], v[70:73]
	v_mfma_f32_16x16x32_bf16 v[66:69], v[190:193], v[222:225], v[66:69]
	s_barrier
	s_setprio 0
	s_mov_b32 m0, s29
	v_lshl_add_u64 v[226:227], s[14:15], 0, v[142:143]
	s_add_u32 s40, s14, 0x4000
	ds_read_b128 v[194:197], v137 offset:16384
	ds_read_b128 v[198:201], v137 offset:17408
	ds_read_b128 v[202:205], v137 offset:18432
	ds_read_b128 v[206:209], v137 offset:19456
	ds_read_b128 v[210:213], v137 offset:20480
	ds_read_b128 v[214:217], v137 offset:21504
	ds_read_b128 v[218:221], v137 offset:22528
	ds_read_b128 v[222:225], v137 offset:23552
	global_load_lds_dwordx4 v[226:227], off
	v_lshl_add_u64 v[226:227], s[14:15], 0, v[146:147]
	s_mov_b32 m0, s30
	s_addc_u32 s41, s15, 0
	global_load_lds_dwordx4 v[226:227], off
	v_lshl_add_u64 v[226:227], s[40:41], 0, v[142:143]
	s_mov_b32 m0, s31
	s_nop 0
	global_load_lds_dwordx4 v[226:227], off
	v_lshl_add_u64 v[226:227], s[40:41], 0, v[146:147]
	s_mov_b32 m0, s34
	s_nop 0
	global_load_lds_dwordx4 v[226:227], off
	v_lshl_add_u64 v[226:227], s[2:3], 0, v[140:141]
	s_mov_b32 m0, s19
	s_nop 0
	global_load_lds_dwordx4 v[226:227], off
	v_lshl_add_u64 v[226:227], s[2:3], 0, v[144:145]
	s_mov_b32 m0, s20
	s_nop 0
	global_load_lds_dwordx4 v[226:227], off
	s_waitcnt vmcnt(8)
	s_waitcnt lgkmcnt(0)
	s_setprio 2
	s_barrier
	v_mfma_f32_16x16x32_bf16 v[62:65], v[160:163], v[194:197], v[62:65]
	v_mfma_f32_16x16x32_bf16 v[58:61], v[168:171], v[194:197], v[58:61]
	v_mfma_f32_16x16x32_bf16 v[50:53], v[160:163], v[202:205], v[50:53]
	v_mfma_f32_16x16x32_bf16 v[42:45], v[168:171], v[202:205], v[42:45]
	v_mfma_f32_16x16x32_bf16 v[34:37], v[160:163], v[210:213], v[34:37]
	v_mfma_f32_16x16x32_bf16 v[26:29], v[168:171], v[210:213], v[26:29]
	v_mfma_f32_16x16x32_bf16 v[18:21], v[160:163], v[218:221], v[18:21]
	v_mfma_f32_16x16x32_bf16 v[10:13], v[168:171], v[218:221], v[10:13]
	v_mfma_f32_16x16x32_bf16 v[62:65], v[164:167], v[198:201], v[62:65]
	v_mfma_f32_16x16x32_bf16 v[58:61], v[172:175], v[198:201], v[58:61]
	v_mfma_f32_16x16x32_bf16 v[50:53], v[164:167], v[206:209], v[50:53]
	v_mfma_f32_16x16x32_bf16 v[42:45], v[172:175], v[206:209], v[42:45]
	v_mfma_f32_16x16x32_bf16 v[34:37], v[164:167], v[214:217], v[34:37]
	v_mfma_f32_16x16x32_bf16 v[26:29], v[172:175], v[214:217], v[26:29]
	v_mfma_f32_16x16x32_bf16 v[18:21], v[164:167], v[222:225], v[18:21]
	v_mfma_f32_16x16x32_bf16 v[10:13], v[172:175], v[222:225], v[10:13]
	v_mfma_f32_16x16x32_bf16 v[54:57], v[178:181], v[194:197], v[54:57]
	v_mfma_f32_16x16x32_bf16 v[46:49], v[186:189], v[194:197], v[46:49]
	v_mfma_f32_16x16x32_bf16 v[38:41], v[178:181], v[202:205], v[38:41]
	v_mfma_f32_16x16x32_bf16 v[30:33], v[186:189], v[202:205], v[30:33]
	v_mfma_f32_16x16x32_bf16 v[22:25], v[178:181], v[210:213], v[22:25]
	v_mfma_f32_16x16x32_bf16 v[14:17], v[186:189], v[210:213], v[14:17]
	v_mfma_f32_16x16x32_bf16 v[6:9], v[178:181], v[218:221], v[6:9]
	v_mfma_f32_16x16x32_bf16 v[2:5], v[186:189], v[218:221], v[2:5]
	v_mfma_f32_16x16x32_bf16 v[54:57], v[182:185], v[198:201], v[54:57]
	v_mfma_f32_16x16x32_bf16 v[46:49], v[190:193], v[198:201], v[46:49]
	v_mfma_f32_16x16x32_bf16 v[38:41], v[182:185], v[206:209], v[38:41]
	v_mfma_f32_16x16x32_bf16 v[30:33], v[190:193], v[206:209], v[30:33]
	v_mfma_f32_16x16x32_bf16 v[22:25], v[182:185], v[214:217], v[22:25]
	v_mfma_f32_16x16x32_bf16 v[14:17], v[190:193], v[214:217], v[14:17]
	v_mfma_f32_16x16x32_bf16 v[6:9], v[182:185], v[222:225], v[6:9]
	v_mfma_f32_16x16x32_bf16 v[2:5], v[190:193], v[222:225], v[2:5]
	s_barrier
	s_setprio 0
	ds_read_b128 v[160:163], v139
	ds_read_b128 v[164:167], v139 offset:1024
	ds_read_b128 v[168:171], v139 offset:2048
	ds_read_b128 v[172:175], v139 offset:3072
	ds_read_b128 v[178:181], v159
	ds_read_b128 v[182:185], v159 offset:1024
	ds_read_b128 v[186:189], v159 offset:2048
	ds_read_b128 v[190:193], v159 offset:3072
	s_add_u32 s2, s2, 0x4000
	s_addc_u32 s3, s3, 0
	s_mov_b32 m0, s21
	v_lshl_add_u64 v[226:227], s[2:3], 0, v[140:141]
	ds_read_b128 v[194:197], v137 offset:32768
	ds_read_b128 v[198:201], v137 offset:33792
	ds_read_b128 v[202:205], v137 offset:34816
	ds_read_b128 v[206:209], v137 offset:35840
	ds_read_b128 v[210:213], v137 offset:36864
	ds_read_b128 v[214:217], v137 offset:37888
	ds_read_b128 v[218:221], v137 offset:38912
	ds_read_b128 v[222:225], v137 offset:39936
	global_load_lds_dwordx4 v[226:227], off
	v_lshl_add_u64 v[226:227], s[2:3], 0, v[144:145]
	s_mov_b32 m0, s22
	s_nop 0
	global_load_lds_dwordx4 v[226:227], off
	s_waitcnt vmcnt(8)
	s_waitcnt lgkmcnt(0)
	s_setprio 2
	s_barrier
	v_mfma_f32_16x16x32_bf16 v[126:129], v[160:163], v[194:197], v[126:129]
	v_mfma_f32_16x16x32_bf16 v[122:125], v[168:171], v[194:197], v[122:125]
	v_mfma_f32_16x16x32_bf16 v[114:117], v[160:163], v[202:205], v[114:117]
	v_mfma_f32_16x16x32_bf16 v[106:109], v[168:171], v[202:205], v[106:109]
	v_mfma_f32_16x16x32_bf16 v[98:101], v[160:163], v[210:213], v[98:101]
	v_mfma_f32_16x16x32_bf16 v[90:93], v[168:171], v[210:213], v[90:93]
	v_mfma_f32_16x16x32_bf16 v[82:85], v[160:163], v[218:221], v[82:85]
	v_mfma_f32_16x16x32_bf16 v[74:77], v[168:171], v[218:221], v[74:77]
	v_mfma_f32_16x16x32_bf16 v[126:129], v[164:167], v[198:201], v[126:129]
	v_mfma_f32_16x16x32_bf16 v[122:125], v[172:175], v[198:201], v[122:125]
	v_mfma_f32_16x16x32_bf16 v[114:117], v[164:167], v[206:209], v[114:117]
	v_mfma_f32_16x16x32_bf16 v[106:109], v[172:175], v[206:209], v[106:109]
	v_mfma_f32_16x16x32_bf16 v[98:101], v[164:167], v[214:217], v[98:101]
	v_mfma_f32_16x16x32_bf16 v[90:93], v[172:175], v[214:217], v[90:93]
	v_mfma_f32_16x16x32_bf16 v[82:85], v[164:167], v[222:225], v[82:85]
	v_mfma_f32_16x16x32_bf16 v[74:77], v[172:175], v[222:225], v[74:77]
	v_mfma_f32_16x16x32_bf16 v[118:121], v[178:181], v[194:197], v[118:121]
	v_mfma_f32_16x16x32_bf16 v[110:113], v[186:189], v[194:197], v[110:113]
	v_mfma_f32_16x16x32_bf16 v[102:105], v[178:181], v[202:205], v[102:105]
	v_mfma_f32_16x16x32_bf16 v[94:97], v[186:189], v[202:205], v[94:97]
	v_mfma_f32_16x16x32_bf16 v[86:89], v[178:181], v[210:213], v[86:89]
	v_mfma_f32_16x16x32_bf16 v[78:81], v[186:189], v[210:213], v[78:81]
	v_mfma_f32_16x16x32_bf16 v[70:73], v[178:181], v[218:221], v[70:73]
	v_mfma_f32_16x16x32_bf16 v[66:69], v[186:189], v[218:221], v[66:69]
	v_mfma_f32_16x16x32_bf16 v[118:121], v[182:185], v[198:201], v[118:121]
	v_mfma_f32_16x16x32_bf16 v[110:113], v[190:193], v[198:201], v[110:113]
	v_mfma_f32_16x16x32_bf16 v[102:105], v[182:185], v[206:209], v[102:105]
	v_mfma_f32_16x16x32_bf16 v[94:97], v[190:193], v[206:209], v[94:97]
	v_mfma_f32_16x16x32_bf16 v[86:89], v[182:185], v[214:217], v[86:89]
	v_mfma_f32_16x16x32_bf16 v[78:81], v[190:193], v[214:217], v[78:81]
	v_mfma_f32_16x16x32_bf16 v[70:73], v[182:185], v[222:225], v[70:73]
	v_mfma_f32_16x16x32_bf16 v[66:69], v[190:193], v[222:225], v[66:69]
	s_barrier
	s_setprio 0
	s_add_u32 s2, s14, 0x8000
	s_addc_u32 s3, s15, 0
	s_mov_b32 m0, s35
	v_lshl_add_u64 v[226:227], s[2:3], 0, v[142:143]
	ds_read_b128 v[194:197], v137 offset:49152
	ds_read_b128 v[198:201], v137 offset:50176
	ds_read_b128 v[202:205], v137 offset:51200
	ds_read_b128 v[206:209], v137 offset:52224
	ds_read_b128 v[210:213], v137 offset:53248
	ds_read_b128 v[214:217], v137 offset:54272
	ds_read_b128 v[218:221], v137 offset:55296
	ds_read_b128 v[222:225], v137 offset:56320
	global_load_lds_dwordx4 v[226:227], off
	v_lshl_add_u64 v[226:227], s[2:3], 0, v[146:147]
	s_add_u32 s2, s14, 0xc000
	s_mov_b32 m0, s36
	s_addc_u32 s3, s15, 0
	global_load_lds_dwordx4 v[226:227], off
	v_lshl_add_u64 v[226:227], s[2:3], 0, v[142:143]
	s_mov_b32 m0, s37
	s_nop 0
	global_load_lds_dwordx4 v[226:227], off
	v_lshl_add_u64 v[226:227], s[2:3], 0, v[146:147]
	s_mov_b32 m0, s38
	s_nop 0
	global_load_lds_dwordx4 v[226:227], off
	v_lshl_add_u64 v[226:227], s[12:13], 0, v[140:141]
	s_mov_b32 m0, s24
	s_nop 0
	global_load_lds_dwordx4 v[226:227], off
	v_lshl_add_u64 v[226:227], s[12:13], 0, v[144:145]
	s_mov_b32 m0, s25
	s_nop 0
	global_load_lds_dwordx4 v[226:227], off
	s_waitcnt vmcnt(8)
	s_waitcnt lgkmcnt(0)
	s_setprio 2
	s_barrier
	v_mfma_f32_16x16x32_bf16 v[62:65], v[160:163], v[194:197], v[62:65]
	v_mfma_f32_16x16x32_bf16 v[58:61], v[168:171], v[194:197], v[58:61]
	v_mfma_f32_16x16x32_bf16 v[50:53], v[160:163], v[202:205], v[50:53]
	v_mfma_f32_16x16x32_bf16 v[42:45], v[168:171], v[202:205], v[42:45]
	v_mfma_f32_16x16x32_bf16 v[34:37], v[160:163], v[210:213], v[34:37]
	v_mfma_f32_16x16x32_bf16 v[26:29], v[168:171], v[210:213], v[26:29]
	v_mfma_f32_16x16x32_bf16 v[18:21], v[160:163], v[218:221], v[18:21]
	v_mfma_f32_16x16x32_bf16 v[10:13], v[168:171], v[218:221], v[10:13]
	v_mfma_f32_16x16x32_bf16 v[62:65], v[164:167], v[198:201], v[62:65]
	v_mfma_f32_16x16x32_bf16 v[58:61], v[172:175], v[198:201], v[58:61]
	v_mfma_f32_16x16x32_bf16 v[50:53], v[164:167], v[206:209], v[50:53]
	v_mfma_f32_16x16x32_bf16 v[42:45], v[172:175], v[206:209], v[42:45]
	v_mfma_f32_16x16x32_bf16 v[34:37], v[164:167], v[214:217], v[34:37]
	v_mfma_f32_16x16x32_bf16 v[26:29], v[172:175], v[214:217], v[26:29]
	v_mfma_f32_16x16x32_bf16 v[18:21], v[164:167], v[222:225], v[18:21]
	v_mfma_f32_16x16x32_bf16 v[10:13], v[172:175], v[222:225], v[10:13]
	v_mfma_f32_16x16x32_bf16 v[54:57], v[178:181], v[194:197], v[54:57]
	v_mfma_f32_16x16x32_bf16 v[46:49], v[186:189], v[194:197], v[46:49]
	v_mfma_f32_16x16x32_bf16 v[38:41], v[178:181], v[202:205], v[38:41]
	v_mfma_f32_16x16x32_bf16 v[30:33], v[186:189], v[202:205], v[30:33]
	v_mfma_f32_16x16x32_bf16 v[22:25], v[178:181], v[210:213], v[22:25]
	v_mfma_f32_16x16x32_bf16 v[14:17], v[186:189], v[210:213], v[14:17]
	v_mfma_f32_16x16x32_bf16 v[6:9], v[178:181], v[218:221], v[6:9]
	v_mfma_f32_16x16x32_bf16 v[2:5], v[186:189], v[218:221], v[2:5]
	v_mfma_f32_16x16x32_bf16 v[54:57], v[182:185], v[198:201], v[54:57]
	v_mfma_f32_16x16x32_bf16 v[46:49], v[190:193], v[198:201], v[46:49]
	v_mfma_f32_16x16x32_bf16 v[38:41], v[182:185], v[206:209], v[38:41]
	v_mfma_f32_16x16x32_bf16 v[30:33], v[190:193], v[206:209], v[30:33]
	v_mfma_f32_16x16x32_bf16 v[22:25], v[182:185], v[214:217], v[22:25]
	v_mfma_f32_16x16x32_bf16 v[14:17], v[190:193], v[214:217], v[14:17]
	v_mfma_f32_16x16x32_bf16 v[6:9], v[182:185], v[222:225], v[6:9]
	v_mfma_f32_16x16x32_bf16 v[2:5], v[190:193], v[222:225], v[2:5]
	s_barrier
	s_setprio 0
	s_add_i32 s26, s26, 2
	s_add_u32 s8, s8, 0x10000
	s_addc_u32 s9, s9, 0
	s_cmp_gt_u32 s26, 41
	s_cbranch_scc0 .LBB0_437
	s_cmpk_lt_u32 s16, 0x100
	s_cbranch_scc0 .LBB0_440
	s_barrier

.Lpk451_peel:
	ds_read_b128 v[152:155], v149
	ds_read_b128 v[156:159], v149 offset:1024
	ds_read_b128 v[160:163], v149 offset:2048
	ds_read_b128 v[164:167], v149 offset:3072
	ds_read_b128 v[168:171], v150
	ds_read_b128 v[172:175], v150 offset:1024
	ds_read_b128 v[178:181], v150 offset:2048
	ds_read_b128 v[182:185], v150 offset:3072
	s_add_u32 s2, s28, 0xfffc0080
	s_addc_u32 s3, s29, -1
	s_cmp_eq_u32 s52, 12
	s_cselect_b32 s3, s11, s3
	s_cselect_b32 s2, s13, s2
	s_cselect_b32 s31, s44, s47
	s_cselect_b32 s30, s45, s46
	v_lshl_add_u64 v[146:147], s[28:29], 0, v[140:141]
	s_add_i32 m0, s25, 0xc000
	ds_read_b128 v[186:189], v151
	ds_read_b128 v[190:193], v151 offset:1024
	ds_read_b128 v[194:197], v151 offset:2048
	ds_read_b128 v[198:201], v151 offset:3072
	ds_read_b128 v[202:205], v151 offset:4096
	ds_read_b128 v[206:209], v151 offset:5120
	ds_read_b128 v[210:213], v151 offset:6144
	ds_read_b128 v[214:217], v151 offset:7168
	global_load_lds_dwordx4 v[146:147], off
	v_lshl_add_u64 v[146:147], s[28:29], 0, v[142:143]
	s_add_i32 m0, s25, 0xe000
	s_nop 0
	global_load_lds_dwordx4 v[146:147], off
	s_waitcnt vmcnt(8)
	s_waitcnt lgkmcnt(0)
	s_setprio 2
	s_barrier
	v_mfma_f32_16x16x32_bf16 v[126:129], v[152:155], v[186:189], 0
	v_mfma_f32_16x16x32_bf16 v[122:125], v[160:163], v[186:189], 0
	v_mfma_f32_16x16x32_bf16 v[110:113], v[152:155], v[194:197], 0
	v_mfma_f32_16x16x32_bf16 v[106:109], v[160:163], v[194:197], 0
	v_mfma_f32_16x16x32_bf16 v[94:97], v[152:155], v[202:205], 0
	v_mfma_f32_16x16x32_bf16 v[90:93], v[160:163], v[202:205], 0
	v_mfma_f32_16x16x32_bf16 v[78:81], v[152:155], v[210:213], 0
	v_mfma_f32_16x16x32_bf16 v[74:77], v[160:163], v[210:213], 0
	v_mfma_f32_16x16x32_bf16 v[126:129], v[156:159], v[190:193], v[126:129]
	v_mfma_f32_16x16x32_bf16 v[122:125], v[164:167], v[190:193], v[122:125]
	v_mfma_f32_16x16x32_bf16 v[110:113], v[156:159], v[198:201], v[110:113]
	v_mfma_f32_16x16x32_bf16 v[106:109], v[164:167], v[198:201], v[106:109]
	v_mfma_f32_16x16x32_bf16 v[94:97], v[156:159], v[206:209], v[94:97]
	v_mfma_f32_16x16x32_bf16 v[90:93], v[164:167], v[206:209], v[90:93]
	v_mfma_f32_16x16x32_bf16 v[78:81], v[156:159], v[214:217], v[78:81]
	v_mfma_f32_16x16x32_bf16 v[74:77], v[164:167], v[214:217], v[74:77]
	v_mfma_f32_16x16x32_bf16 v[118:121], v[168:171], v[186:189], 0
	v_mfma_f32_16x16x32_bf16 v[114:117], v[178:181], v[186:189], 0
	v_mfma_f32_16x16x32_bf16 v[102:105], v[168:171], v[194:197], 0
	v_mfma_f32_16x16x32_bf16 v[98:101], v[178:181], v[194:197], 0
	v_mfma_f32_16x16x32_bf16 v[86:89], v[168:171], v[202:205], 0
	v_mfma_f32_16x16x32_bf16 v[82:85], v[178:181], v[202:205], 0
	v_mfma_f32_16x16x32_bf16 v[70:73], v[168:171], v[210:213], 0
	v_mfma_f32_16x16x32_bf16 v[66:69], v[178:181], v[210:213], 0
	v_mfma_f32_16x16x32_bf16 v[118:121], v[172:175], v[190:193], v[118:121]
	v_mfma_f32_16x16x32_bf16 v[114:117], v[182:185], v[190:193], v[114:117]
	v_mfma_f32_16x16x32_bf16 v[102:105], v[172:175], v[198:201], v[102:105]
	v_mfma_f32_16x16x32_bf16 v[98:101], v[182:185], v[198:201], v[98:101]
	v_mfma_f32_16x16x32_bf16 v[86:89], v[172:175], v[206:209], v[86:89]
	v_mfma_f32_16x16x32_bf16 v[82:85], v[182:185], v[206:209], v[82:85]
	v_mfma_f32_16x16x32_bf16 v[70:73], v[172:175], v[214:217], v[70:73]
	v_mfma_f32_16x16x32_bf16 v[66:69], v[182:185], v[214:217], v[66:69]
	s_barrier
	s_setprio 0
	s_add_i32 s53, s42, s34
	v_lshl_add_u64 v[146:147], s[30:31], 0, v[132:133]
	s_mov_b32 m0, s53
	ds_read_b128 v[186:189], v151 offset:16384
	ds_read_b128 v[190:193], v151 offset:17408
	ds_read_b128 v[194:197], v151 offset:18432
	ds_read_b128 v[198:201], v151 offset:19456
	ds_read_b128 v[202:205], v151 offset:20480
	ds_read_b128 v[206:209], v151 offset:21504
	ds_read_b128 v[210:213], v151 offset:22528
	ds_read_b128 v[214:217], v151 offset:23552
	global_load_lds_dwordx4 v[146:147], off
	s_add_i32 m0, s53, 0x2000
	s_add_u32 s54, s30, 0x40000
	v_lshl_add_u64 v[218:219], s[30:31], 0, v[136:137]
	s_addc_u32 s55, s31, 0
	s_add_i32 s53, s43, s34
	global_load_lds_dwordx4 v[218:219], off
	v_lshl_add_u64 v[220:221], s[54:55], 0, v[132:133]
	s_mov_b32 m0, s53
	v_lshl_add_u64 v[222:223], s[2:3], 0, v[134:135]
	global_load_lds_dwordx4 v[220:221], off
	v_lshl_add_u64 v[220:221], s[54:55], 0, v[136:137]
	s_add_i32 m0, s53, 0x2000
	s_nop 0
	global_load_lds_dwordx4 v[220:221], off
	v_lshl_add_u64 v[220:221], s[2:3], 0, v[130:131]
	s_mov_b32 m0, s25
	s_nop 0
	global_load_lds_dwordx4 v[220:221], off
	s_mov_b32 m0, s27
	s_nop 0
	global_load_lds_dwordx4 v[222:223], off
	s_waitcnt vmcnt(8)
	s_waitcnt lgkmcnt(0)
	s_setprio 2
	s_barrier
	v_mfma_f32_16x16x32_bf16 v[62:65], v[152:155], v[186:189], 0
	v_mfma_f32_16x16x32_bf16 v[58:61], v[160:163], v[186:189], 0
	v_mfma_f32_16x16x32_bf16 v[46:49], v[152:155], v[194:197], 0
	v_mfma_f32_16x16x32_bf16 v[42:45], v[160:163], v[194:197], 0
	v_mfma_f32_16x16x32_bf16 v[30:33], v[152:155], v[202:205], 0
	v_mfma_f32_16x16x32_bf16 v[26:29], v[160:163], v[202:205], 0
	v_mfma_f32_16x16x32_bf16 v[14:17], v[152:155], v[210:213], 0
	v_mfma_f32_16x16x32_bf16 v[10:13], v[160:163], v[210:213], 0
	v_mfma_f32_16x16x32_bf16 v[62:65], v[156:159], v[190:193], v[62:65]
	v_mfma_f32_16x16x32_bf16 v[58:61], v[164:167], v[190:193], v[58:61]
	v_mfma_f32_16x16x32_bf16 v[46:49], v[156:159], v[198:201], v[46:49]
	v_mfma_f32_16x16x32_bf16 v[42:45], v[164:167], v[198:201], v[42:45]
	v_mfma_f32_16x16x32_bf16 v[30:33], v[156:159], v[206:209], v[30:33]
	v_mfma_f32_16x16x32_bf16 v[26:29], v[164:167], v[206:209], v[26:29]
	v_mfma_f32_16x16x32_bf16 v[14:17], v[156:159], v[214:217], v[14:17]
	v_mfma_f32_16x16x32_bf16 v[10:13], v[164:167], v[214:217], v[10:13]
	v_mfma_f32_16x16x32_bf16 v[54:57], v[168:171], v[186:189], 0
	v_mfma_f32_16x16x32_bf16 v[50:53], v[178:181], v[186:189], 0
	v_mfma_f32_16x16x32_bf16 v[38:41], v[168:171], v[194:197], 0
	v_mfma_f32_16x16x32_bf16 v[34:37], v[178:181], v[194:197], 0
	v_mfma_f32_16x16x32_bf16 v[22:25], v[168:171], v[202:205], 0
	v_mfma_f32_16x16x32_bf16 v[18:21], v[178:181], v[202:205], 0
	v_mfma_f32_16x16x32_bf16 v[6:9], v[168:171], v[210:213], 0
	v_mfma_f32_16x16x32_bf16 v[2:5], v[178:181], v[210:213], 0
	v_mfma_f32_16x16x32_bf16 v[54:57], v[172:175], v[190:193], v[54:57]
	v_mfma_f32_16x16x32_bf16 v[50:53], v[182:185], v[190:193], v[50:53]
	v_mfma_f32_16x16x32_bf16 v[38:41], v[172:175], v[198:201], v[38:41]
	v_mfma_f32_16x16x32_bf16 v[34:37], v[182:185], v[198:201], v[34:37]
	v_mfma_f32_16x16x32_bf16 v[22:25], v[172:175], v[206:209], v[22:25]
	v_mfma_f32_16x16x32_bf16 v[18:21], v[182:185], v[206:209], v[18:21]
	v_mfma_f32_16x16x32_bf16 v[6:9], v[172:175], v[214:217], v[6:9]
	v_mfma_f32_16x16x32_bf16 v[2:5], v[182:185], v[214:217], v[2:5]
	s_barrier
	s_setprio 0
	s_add_i32 s53, 0, 0x18000
	s_add_i32 s54, 0, 0x1c000
	v_add_u32_e32 v164, s53, v148
	v_add_u32_e32 v176, s54, v148
	ds_read_b128 v[152:155], v164
	ds_read_b128 v[156:159], v164 offset:1024
	ds_read_b128 v[160:163], v164 offset:2048
	ds_read_b128 v[164:167], v164 offset:3072
	ds_read_b128 v[168:171], v176
	ds_read_b128 v[172:175], v176 offset:1024
	ds_read_b128 v[178:181], v176 offset:2048
	ds_read_b128 v[182:185], v176 offset:3072
	s_add_u32 s2, s2, 0x40000
	s_addc_u32 s3, s3, 0
	s_mov_b32 m0, s36
	v_lshl_add_u64 v[224:225], s[2:3], 0, v[130:131]
	ds_read_b128 v[186:189], v151 offset:32768
	ds_read_b128 v[190:193], v151 offset:33792
	ds_read_b128 v[194:197], v151 offset:34816
	ds_read_b128 v[198:201], v151 offset:35840
	ds_read_b128 v[202:205], v151 offset:36864
	ds_read_b128 v[206:209], v151 offset:37888
	ds_read_b128 v[210:213], v151 offset:38912
	ds_read_b128 v[214:217], v151 offset:39936
	global_load_lds_dwordx4 v[224:225], off
	v_lshl_add_u64 v[224:225], s[2:3], 0, v[134:135]
	s_mov_b32 m0, s37
	s_nop 0
	global_load_lds_dwordx4 v[224:225], off
	s_waitcnt vmcnt(8)
	s_waitcnt lgkmcnt(0)
	s_setprio 2
	s_barrier
	v_mfma_f32_16x16x32_bf16 v[126:129], v[152:155], v[186:189], v[126:129]
	v_mfma_f32_16x16x32_bf16 v[122:125], v[160:163], v[186:189], v[122:125]
	v_mfma_f32_16x16x32_bf16 v[110:113], v[152:155], v[194:197], v[110:113]
	v_mfma_f32_16x16x32_bf16 v[106:109], v[160:163], v[194:197], v[106:109]
	v_mfma_f32_16x16x32_bf16 v[94:97], v[152:155], v[202:205], v[94:97]
	v_mfma_f32_16x16x32_bf16 v[90:93], v[160:163], v[202:205], v[90:93]
	v_mfma_f32_16x16x32_bf16 v[78:81], v[152:155], v[210:213], v[78:81]
	v_mfma_f32_16x16x32_bf16 v[74:77], v[160:163], v[210:213], v[74:77]
	v_mfma_f32_16x16x32_bf16 v[126:129], v[156:159], v[190:193], v[126:129]
	v_mfma_f32_16x16x32_bf16 v[122:125], v[164:167], v[190:193], v[122:125]
	v_mfma_f32_16x16x32_bf16 v[110:113], v[156:159], v[198:201], v[110:113]
	v_mfma_f32_16x16x32_bf16 v[106:109], v[164:167], v[198:201], v[106:109]
	v_mfma_f32_16x16x32_bf16 v[94:97], v[156:159], v[206:209], v[94:97]
	v_mfma_f32_16x16x32_bf16 v[90:93], v[164:167], v[206:209], v[90:93]
	v_mfma_f32_16x16x32_bf16 v[78:81], v[156:159], v[214:217], v[78:81]
	v_mfma_f32_16x16x32_bf16 v[74:77], v[164:167], v[214:217], v[74:77]
	v_mfma_f32_16x16x32_bf16 v[118:121], v[168:171], v[186:189], v[118:121]
	v_mfma_f32_16x16x32_bf16 v[114:117], v[178:181], v[186:189], v[114:117]
	v_mfma_f32_16x16x32_bf16 v[102:105], v[168:171], v[194:197], v[102:105]
	v_mfma_f32_16x16x32_bf16 v[98:101], v[178:181], v[194:197], v[98:101]
	v_mfma_f32_16x16x32_bf16 v[86:89], v[168:171], v[202:205], v[86:89]
	v_mfma_f32_16x16x32_bf16 v[82:85], v[178:181], v[202:205], v[82:85]
	v_mfma_f32_16x16x32_bf16 v[70:73], v[168:171], v[210:213], v[70:73]
	v_mfma_f32_16x16x32_bf16 v[66:69], v[178:181], v[210:213], v[66:69]
	v_mfma_f32_16x16x32_bf16 v[118:121], v[172:175], v[190:193], v[118:121]
	v_mfma_f32_16x16x32_bf16 v[114:117], v[182:185], v[190:193], v[114:117]
	v_mfma_f32_16x16x32_bf16 v[102:105], v[172:175], v[198:201], v[102:105]
	v_mfma_f32_16x16x32_bf16 v[98:101], v[182:185], v[198:201], v[98:101]
	v_mfma_f32_16x16x32_bf16 v[86:89], v[172:175], v[206:209], v[86:89]
	v_mfma_f32_16x16x32_bf16 v[82:85], v[182:185], v[206:209], v[82:85]
	v_mfma_f32_16x16x32_bf16 v[70:73], v[172:175], v[214:217], v[70:73]
	v_mfma_f32_16x16x32_bf16 v[66:69], v[182:185], v[214:217], v[66:69]
	s_barrier
	s_setprio 0
	s_add_i32 s2, s53, s34
	v_lshl_add_u64 v[146:147], v[146:147], 0, s[6:7]
	s_mov_b32 m0, s2
	ds_read_b128 v[186:189], v151 offset:49152
	ds_read_b128 v[190:193], v151 offset:50176
	ds_read_b128 v[194:197], v151 offset:51200
	ds_read_b128 v[198:201], v151 offset:52224
	ds_read_b128 v[202:205], v151 offset:53248
	ds_read_b128 v[206:209], v151 offset:54272
	ds_read_b128 v[210:213], v151 offset:55296
	ds_read_b128 v[214:217], v151 offset:56320
	global_load_lds_dwordx4 v[146:147], off
	s_add_i32 m0, s2, 0x2000
	s_add_u32 s2, s30, 0x40080
	v_lshl_add_u64 v[146:147], v[218:219], 0, s[6:7]
	s_addc_u32 s3, s31, 0
	s_add_i32 s30, s54, s34
	global_load_lds_dwordx4 v[146:147], off
	v_lshl_add_u64 v[146:147], s[2:3], 0, v[132:133]
	s_mov_b32 m0, s30
	s_nop 0
	global_load_lds_dwordx4 v[146:147], off
	v_lshl_add_u64 v[146:147], s[2:3], 0, v[136:137]
	s_add_i32 m0, s30, 0x2000
	s_nop 0
	global_load_lds_dwordx4 v[146:147], off
	v_lshl_add_u64 v[146:147], v[220:221], 0, s[6:7]
	s_mov_b32 m0, s39
	s_nop 0
	global_load_lds_dwordx4 v[146:147], off
	v_lshl_add_u64 v[146:147], v[222:223], 0, s[6:7]
	s_mov_b32 m0, s40
	s_nop 0
	global_load_lds_dwordx4 v[146:147], off
	s_waitcnt vmcnt(8)
	s_waitcnt lgkmcnt(0)
	s_setprio 2
	s_barrier
	v_mfma_f32_16x16x32_bf16 v[62:65], v[152:155], v[186:189], v[62:65]
	v_mfma_f32_16x16x32_bf16 v[58:61], v[160:163], v[186:189], v[58:61]
	v_mfma_f32_16x16x32_bf16 v[46:49], v[152:155], v[194:197], v[46:49]
	v_mfma_f32_16x16x32_bf16 v[42:45], v[160:163], v[194:197], v[42:45]
	v_mfma_f32_16x16x32_bf16 v[30:33], v[152:155], v[202:205], v[30:33]
	v_mfma_f32_16x16x32_bf16 v[26:29], v[160:163], v[202:205], v[26:29]
	v_mfma_f32_16x16x32_bf16 v[14:17], v[152:155], v[210:213], v[14:17]
	v_mfma_f32_16x16x32_bf16 v[10:13], v[160:163], v[210:213], v[10:13]
	v_mfma_f32_16x16x32_bf16 v[62:65], v[156:159], v[190:193], v[62:65]
	v_mfma_f32_16x16x32_bf16 v[58:61], v[164:167], v[190:193], v[58:61]
	v_mfma_f32_16x16x32_bf16 v[46:49], v[156:159], v[198:201], v[46:49]
	v_mfma_f32_16x16x32_bf16 v[42:45], v[164:167], v[198:201], v[42:45]
	v_mfma_f32_16x16x32_bf16 v[30:33], v[156:159], v[206:209], v[30:33]
	v_mfma_f32_16x16x32_bf16 v[26:29], v[164:167], v[206:209], v[26:29]
	v_mfma_f32_16x16x32_bf16 v[14:17], v[156:159], v[214:217], v[14:17]
	v_mfma_f32_16x16x32_bf16 v[10:13], v[164:167], v[214:217], v[10:13]
	v_mfma_f32_16x16x32_bf16 v[54:57], v[168:171], v[186:189], v[54:57]
	v_mfma_f32_16x16x32_bf16 v[50:53], v[178:181], v[186:189], v[50:53]
	v_mfma_f32_16x16x32_bf16 v[38:41], v[168:171], v[194:197], v[38:41]
	v_mfma_f32_16x16x32_bf16 v[34:37], v[178:181], v[194:197], v[34:37]
	v_mfma_f32_16x16x32_bf16 v[22:25], v[168:171], v[202:205], v[22:25]
	v_mfma_f32_16x16x32_bf16 v[18:21], v[178:181], v[202:205], v[18:21]
	v_mfma_f32_16x16x32_bf16 v[6:9], v[168:171], v[210:213], v[6:9]
	v_mfma_f32_16x16x32_bf16 v[2:5], v[178:181], v[210:213], v[2:5]
	v_mfma_f32_16x16x32_bf16 v[54:57], v[172:175], v[190:193], v[54:57]
	v_mfma_f32_16x16x32_bf16 v[50:53], v[182:185], v[190:193], v[50:53]
	v_mfma_f32_16x16x32_bf16 v[38:41], v[172:175], v[198:201], v[38:41]
	v_mfma_f32_16x16x32_bf16 v[34:37], v[182:185], v[198:201], v[34:37]
	v_mfma_f32_16x16x32_bf16 v[22:25], v[172:175], v[206:209], v[22:25]
	v_mfma_f32_16x16x32_bf16 v[18:21], v[182:185], v[206:209], v[18:21]
	v_mfma_f32_16x16x32_bf16 v[6:9], v[172:175], v[214:217], v[6:9]
	v_mfma_f32_16x16x32_bf16 v[2:5], v[182:185], v[214:217], v[2:5]
	s_barrier
	s_setprio 0
	s_add_i32 s52, s52, 2
	s_add_u32 s28, s28, 0x100
	s_addc_u32 s29, s29, 0
	s_add_u32 s46, s46, 0x100
	s_addc_u32 s47, s47, 0
	s_cmp_gt_u32 s52, 13
	s_cbranch_scc0 .LBB0_451
	s_branch .Lpk451_exit
.LBB0_451:
	ds_read_b128 v[152:155], v149
	ds_read_b128 v[156:159], v149 offset:1024
	ds_read_b128 v[160:163], v149 offset:2048
	ds_read_b128 v[164:167], v149 offset:3072
	ds_read_b128 v[168:171], v150
	ds_read_b128 v[172:175], v150 offset:1024
	ds_read_b128 v[178:181], v150 offset:2048
	ds_read_b128 v[182:185], v150 offset:3072
	s_add_u32 s2, s28, 0xfffc0080
	s_addc_u32 s3, s29, -1
	s_cmp_eq_u32 s52, 12
	s_cselect_b32 s3, s11, s3
	s_cselect_b32 s2, s13, s2
	s_cselect_b32 s31, s44, s47
	s_cselect_b32 s30, s45, s46
	v_lshl_add_u64 v[146:147], s[28:29], 0, v[140:141]
	s_add_i32 m0, s25, 0xc000
	ds_read_b128 v[186:189], v151
	ds_read_b128 v[190:193], v151 offset:1024
	ds_read_b128 v[194:197], v151 offset:2048
	ds_read_b128 v[198:201], v151 offset:3072
	ds_read_b128 v[202:205], v151 offset:4096
	ds_read_b128 v[206:209], v151 offset:5120
	ds_read_b128 v[210:213], v151 offset:6144
	ds_read_b128 v[214:217], v151 offset:7168
	global_load_lds_dwordx4 v[146:147], off
	v_lshl_add_u64 v[146:147], s[28:29], 0, v[142:143]
	s_add_i32 m0, s25, 0xe000
	s_nop 0
	global_load_lds_dwordx4 v[146:147], off
	s_waitcnt vmcnt(8)
	s_waitcnt lgkmcnt(0)
	s_setprio 2
	s_barrier
	v_mfma_f32_16x16x32_bf16 v[126:129], v[152:155], v[186:189], v[126:129]
	v_mfma_f32_16x16x32_bf16 v[122:125], v[160:163], v[186:189], v[122:125]
	v_mfma_f32_16x16x32_bf16 v[110:113], v[152:155], v[194:197], v[110:113]
	v_mfma_f32_16x16x32_bf16 v[106:109], v[160:163], v[194:197], v[106:109]
	v_mfma_f32_16x16x32_bf16 v[94:97], v[152:155], v[202:205], v[94:97]
	v_mfma_f32_16x16x32_bf16 v[90:93], v[160:163], v[202:205], v[90:93]
	v_mfma_f32_16x16x32_bf16 v[78:81], v[152:155], v[210:213], v[78:81]
	v_mfma_f32_16x16x32_bf16 v[74:77], v[160:163], v[210:213], v[74:77]
	v_mfma_f32_16x16x32_bf16 v[126:129], v[156:159], v[190:193], v[126:129]
	v_mfma_f32_16x16x32_bf16 v[122:125], v[164:167], v[190:193], v[122:125]
	v_mfma_f32_16x16x32_bf16 v[110:113], v[156:159], v[198:201], v[110:113]
	v_mfma_f32_16x16x32_bf16 v[106:109], v[164:167], v[198:201], v[106:109]
	v_mfma_f32_16x16x32_bf16 v[94:97], v[156:159], v[206:209], v[94:97]
	v_mfma_f32_16x16x32_bf16 v[90:93], v[164:167], v[206:209], v[90:93]
	v_mfma_f32_16x16x32_bf16 v[78:81], v[156:159], v[214:217], v[78:81]
	v_mfma_f32_16x16x32_bf16 v[74:77], v[164:167], v[214:217], v[74:77]
	v_mfma_f32_16x16x32_bf16 v[118:121], v[168:171], v[186:189], v[118:121]
	v_mfma_f32_16x16x32_bf16 v[114:117], v[178:181], v[186:189], v[114:117]
	v_mfma_f32_16x16x32_bf16 v[102:105], v[168:171], v[194:197], v[102:105]
	v_mfma_f32_16x16x32_bf16 v[98:101], v[178:181], v[194:197], v[98:101]
	v_mfma_f32_16x16x32_bf16 v[86:89], v[168:171], v[202:205], v[86:89]
	v_mfma_f32_16x16x32_bf16 v[82:85], v[178:181], v[202:205], v[82:85]
	v_mfma_f32_16x16x32_bf16 v[70:73], v[168:171], v[210:213], v[70:73]
	v_mfma_f32_16x16x32_bf16 v[66:69], v[178:181], v[210:213], v[66:69]
	v_mfma_f32_16x16x32_bf16 v[118:121], v[172:175], v[190:193], v[118:121]
	v_mfma_f32_16x16x32_bf16 v[114:117], v[182:185], v[190:193], v[114:117]
	v_mfma_f32_16x16x32_bf16 v[102:105], v[172:175], v[198:201], v[102:105]
	v_mfma_f32_16x16x32_bf16 v[98:101], v[182:185], v[198:201], v[98:101]
	v_mfma_f32_16x16x32_bf16 v[86:89], v[172:175], v[206:209], v[86:89]
	v_mfma_f32_16x16x32_bf16 v[82:85], v[182:185], v[206:209], v[82:85]
	v_mfma_f32_16x16x32_bf16 v[70:73], v[172:175], v[214:217], v[70:73]
	v_mfma_f32_16x16x32_bf16 v[66:69], v[182:185], v[214:217], v[66:69]
	s_barrier
	s_setprio 0
	s_add_i32 s53, s42, s34
	v_lshl_add_u64 v[146:147], s[30:31], 0, v[132:133]
	s_mov_b32 m0, s53
	ds_read_b128 v[186:189], v151 offset:16384
	ds_read_b128 v[190:193], v151 offset:17408
	ds_read_b128 v[194:197], v151 offset:18432
	ds_read_b128 v[198:201], v151 offset:19456
	ds_read_b128 v[202:205], v151 offset:20480
	ds_read_b128 v[206:209], v151 offset:21504
	ds_read_b128 v[210:213], v151 offset:22528
	ds_read_b128 v[214:217], v151 offset:23552
	global_load_lds_dwordx4 v[146:147], off
	s_add_i32 m0, s53, 0x2000
	s_add_u32 s54, s30, 0x40000
	v_lshl_add_u64 v[218:219], s[30:31], 0, v[136:137]
	s_addc_u32 s55, s31, 0
	s_add_i32 s53, s43, s34
	global_load_lds_dwordx4 v[218:219], off
	v_lshl_add_u64 v[220:221], s[54:55], 0, v[132:133]
	s_mov_b32 m0, s53
	v_lshl_add_u64 v[222:223], s[2:3], 0, v[134:135]
	global_load_lds_dwordx4 v[220:221], off
	v_lshl_add_u64 v[220:221], s[54:55], 0, v[136:137]
	s_add_i32 m0, s53, 0x2000
	s_nop 0
	global_load_lds_dwordx4 v[220:221], off
	v_lshl_add_u64 v[220:221], s[2:3], 0, v[130:131]
	s_mov_b32 m0, s25
	s_nop 0
	global_load_lds_dwordx4 v[220:221], off
	s_mov_b32 m0, s27
	s_nop 0
	global_load_lds_dwordx4 v[222:223], off
	s_waitcnt vmcnt(8)
	s_waitcnt lgkmcnt(0)
	s_setprio 2
	s_barrier
	v_mfma_f32_16x16x32_bf16 v[62:65], v[152:155], v[186:189], v[62:65]
	v_mfma_f32_16x16x32_bf16 v[58:61], v[160:163], v[186:189], v[58:61]
	v_mfma_f32_16x16x32_bf16 v[46:49], v[152:155], v[194:197], v[46:49]
	v_mfma_f32_16x16x32_bf16 v[42:45], v[160:163], v[194:197], v[42:45]
	v_mfma_f32_16x16x32_bf16 v[30:33], v[152:155], v[202:205], v[30:33]
	v_mfma_f32_16x16x32_bf16 v[26:29], v[160:163], v[202:205], v[26:29]
	v_mfma_f32_16x16x32_bf16 v[14:17], v[152:155], v[210:213], v[14:17]
	v_mfma_f32_16x16x32_bf16 v[10:13], v[160:163], v[210:213], v[10:13]
	v_mfma_f32_16x16x32_bf16 v[62:65], v[156:159], v[190:193], v[62:65]
	v_mfma_f32_16x16x32_bf16 v[58:61], v[164:167], v[190:193], v[58:61]
	v_mfma_f32_16x16x32_bf16 v[46:49], v[156:159], v[198:201], v[46:49]
	v_mfma_f32_16x16x32_bf16 v[42:45], v[164:167], v[198:201], v[42:45]
	v_mfma_f32_16x16x32_bf16 v[30:33], v[156:159], v[206:209], v[30:33]
	v_mfma_f32_16x16x32_bf16 v[26:29], v[164:167], v[206:209], v[26:29]
	v_mfma_f32_16x16x32_bf16 v[14:17], v[156:159], v[214:217], v[14:17]
	v_mfma_f32_16x16x32_bf16 v[10:13], v[164:167], v[214:217], v[10:13]
	v_mfma_f32_16x16x32_bf16 v[54:57], v[168:171], v[186:189], v[54:57]
	v_mfma_f32_16x16x32_bf16 v[50:53], v[178:181], v[186:189], v[50:53]
	v_mfma_f32_16x16x32_bf16 v[38:41], v[168:171], v[194:197], v[38:41]
	v_mfma_f32_16x16x32_bf16 v[34:37], v[178:181], v[194:197], v[34:37]
	v_mfma_f32_16x16x32_bf16 v[22:25], v[168:171], v[202:205], v[22:25]
	v_mfma_f32_16x16x32_bf16 v[18:21], v[178:181], v[202:205], v[18:21]
	v_mfma_f32_16x16x32_bf16 v[6:9], v[168:171], v[210:213], v[6:9]
	v_mfma_f32_16x16x32_bf16 v[2:5], v[178:181], v[210:213], v[2:5]
	v_mfma_f32_16x16x32_bf16 v[54:57], v[172:175], v[190:193], v[54:57]
	v_mfma_f32_16x16x32_bf16 v[50:53], v[182:185], v[190:193], v[50:53]
	v_mfma_f32_16x16x32_bf16 v[38:41], v[172:175], v[198:201], v[38:41]
	v_mfma_f32_16x16x32_bf16 v[34:37], v[182:185], v[198:201], v[34:37]
	v_mfma_f32_16x16x32_bf16 v[22:25], v[172:175], v[206:209], v[22:25]
	v_mfma_f32_16x16x32_bf16 v[18:21], v[182:185], v[206:209], v[18:21]
	v_mfma_f32_16x16x32_bf16 v[6:9], v[172:175], v[214:217], v[6:9]
	v_mfma_f32_16x16x32_bf16 v[2:5], v[182:185], v[214:217], v[2:5]
	s_barrier
	s_setprio 0
	s_add_i32 s53, 0, 0x18000
	s_add_i32 s54, 0, 0x1c000
	v_add_u32_e32 v164, s53, v148
	v_add_u32_e32 v176, s54, v148
	ds_read_b128 v[152:155], v164
	ds_read_b128 v[156:159], v164 offset:1024
	ds_read_b128 v[160:163], v164 offset:2048
	ds_read_b128 v[164:167], v164 offset:3072
	ds_read_b128 v[168:171], v176
	ds_read_b128 v[172:175], v176 offset:1024
	ds_read_b128 v[178:181], v176 offset:2048
	ds_read_b128 v[182:185], v176 offset:3072
	s_add_u32 s2, s2, 0x40000
	s_addc_u32 s3, s3, 0
	s_mov_b32 m0, s36
	v_lshl_add_u64 v[224:225], s[2:3], 0, v[130:131]
	ds_read_b128 v[186:189], v151 offset:32768
	ds_read_b128 v[190:193], v151 offset:33792
	ds_read_b128 v[194:197], v151 offset:34816
	ds_read_b128 v[198:201], v151 offset:35840
	ds_read_b128 v[202:205], v151 offset:36864
	ds_read_b128 v[206:209], v151 offset:37888
	ds_read_b128 v[210:213], v151 offset:38912
	ds_read_b128 v[214:217], v151 offset:39936
	global_load_lds_dwordx4 v[224:225], off
	v_lshl_add_u64 v[224:225], s[2:3], 0, v[134:135]
	s_mov_b32 m0, s37
	s_nop 0
	global_load_lds_dwordx4 v[224:225], off
	s_waitcnt vmcnt(8)
	s_waitcnt lgkmcnt(0)
	s_setprio 2
	s_barrier
	v_mfma_f32_16x16x32_bf16 v[126:129], v[152:155], v[186:189], v[126:129]
	v_mfma_f32_16x16x32_bf16 v[122:125], v[160:163], v[186:189], v[122:125]
	v_mfma_f32_16x16x32_bf16 v[110:113], v[152:155], v[194:197], v[110:113]
	v_mfma_f32_16x16x32_bf16 v[106:109], v[160:163], v[194:197], v[106:109]
	v_mfma_f32_16x16x32_bf16 v[94:97], v[152:155], v[202:205], v[94:97]
	v_mfma_f32_16x16x32_bf16 v[90:93], v[160:163], v[202:205], v[90:93]
	v_mfma_f32_16x16x32_bf16 v[78:81], v[152:155], v[210:213], v[78:81]
	v_mfma_f32_16x16x32_bf16 v[74:77], v[160:163], v[210:213], v[74:77]
	v_mfma_f32_16x16x32_bf16 v[126:129], v[156:159], v[190:193], v[126:129]
	v_mfma_f32_16x16x32_bf16 v[122:125], v[164:167], v[190:193], v[122:125]
	v_mfma_f32_16x16x32_bf16 v[110:113], v[156:159], v[198:201], v[110:113]
	v_mfma_f32_16x16x32_bf16 v[106:109], v[164:167], v[198:201], v[106:109]
	v_mfma_f32_16x16x32_bf16 v[94:97], v[156:159], v[206:209], v[94:97]
	v_mfma_f32_16x16x32_bf16 v[90:93], v[164:167], v[206:209], v[90:93]
	v_mfma_f32_16x16x32_bf16 v[78:81], v[156:159], v[214:217], v[78:81]
	v_mfma_f32_16x16x32_bf16 v[74:77], v[164:167], v[214:217], v[74:77]
	v_mfma_f32_16x16x32_bf16 v[118:121], v[168:171], v[186:189], v[118:121]
	v_mfma_f32_16x16x32_bf16 v[114:117], v[178:181], v[186:189], v[114:117]
	v_mfma_f32_16x16x32_bf16 v[102:105], v[168:171], v[194:197], v[102:105]
	v_mfma_f32_16x16x32_bf16 v[98:101], v[178:181], v[194:197], v[98:101]
	v_mfma_f32_16x16x32_bf16 v[86:89], v[168:171], v[202:205], v[86:89]
	v_mfma_f32_16x16x32_bf16 v[82:85], v[178:181], v[202:205], v[82:85]
	v_mfma_f32_16x16x32_bf16 v[70:73], v[168:171], v[210:213], v[70:73]
	v_mfma_f32_16x16x32_bf16 v[66:69], v[178:181], v[210:213], v[66:69]
	v_mfma_f32_16x16x32_bf16 v[118:121], v[172:175], v[190:193], v[118:121]
	v_mfma_f32_16x16x32_bf16 v[114:117], v[182:185], v[190:193], v[114:117]
	v_mfma_f32_16x16x32_bf16 v[102:105], v[172:175], v[198:201], v[102:105]
	v_mfma_f32_16x16x32_bf16 v[98:101], v[182:185], v[198:201], v[98:101]
	v_mfma_f32_16x16x32_bf16 v[86:89], v[172:175], v[206:209], v[86:89]
	v_mfma_f32_16x16x32_bf16 v[82:85], v[182:185], v[206:209], v[82:85]
	v_mfma_f32_16x16x32_bf16 v[70:73], v[172:175], v[214:217], v[70:73]
	v_mfma_f32_16x16x32_bf16 v[66:69], v[182:185], v[214:217], v[66:69]
	s_barrier
	s_setprio 0
	s_add_i32 s2, s53, s34
	v_lshl_add_u64 v[146:147], v[146:147], 0, s[6:7]
	s_mov_b32 m0, s2
	ds_read_b128 v[186:189], v151 offset:49152
	ds_read_b128 v[190:193], v151 offset:50176
	ds_read_b128 v[194:197], v151 offset:51200
	ds_read_b128 v[198:201], v151 offset:52224
	ds_read_b128 v[202:205], v151 offset:53248
	ds_read_b128 v[206:209], v151 offset:54272
	ds_read_b128 v[210:213], v151 offset:55296
	ds_read_b128 v[214:217], v151 offset:56320
	global_load_lds_dwordx4 v[146:147], off
	s_add_i32 m0, s2, 0x2000
	s_add_u32 s2, s30, 0x40080
	v_lshl_add_u64 v[146:147], v[218:219], 0, s[6:7]
	s_addc_u32 s3, s31, 0
	s_add_i32 s30, s54, s34
	global_load_lds_dwordx4 v[146:147], off
	v_lshl_add_u64 v[146:147], s[2:3], 0, v[132:133]
	s_mov_b32 m0, s30
	s_nop 0
	global_load_lds_dwordx4 v[146:147], off
	v_lshl_add_u64 v[146:147], s[2:3], 0, v[136:137]
	s_add_i32 m0, s30, 0x2000
	s_nop 0
	global_load_lds_dwordx4 v[146:147], off
	v_lshl_add_u64 v[146:147], v[220:221], 0, s[6:7]
	s_mov_b32 m0, s39
	s_nop 0
	global_load_lds_dwordx4 v[146:147], off
	v_lshl_add_u64 v[146:147], v[222:223], 0, s[6:7]
	s_mov_b32 m0, s40
	s_nop 0
	global_load_lds_dwordx4 v[146:147], off
	s_waitcnt vmcnt(8)
	s_waitcnt lgkmcnt(0)
	s_setprio 2
	s_barrier
	v_mfma_f32_16x16x32_bf16 v[62:65], v[152:155], v[186:189], v[62:65]
	v_mfma_f32_16x16x32_bf16 v[58:61], v[160:163], v[186:189], v[58:61]
	v_mfma_f32_16x16x32_bf16 v[46:49], v[152:155], v[194:197], v[46:49]
	v_mfma_f32_16x16x32_bf16 v[42:45], v[160:163], v[194:197], v[42:45]
	v_mfma_f32_16x16x32_bf16 v[30:33], v[152:155], v[202:205], v[30:33]
	v_mfma_f32_16x16x32_bf16 v[26:29], v[160:163], v[202:205], v[26:29]
	v_mfma_f32_16x16x32_bf16 v[14:17], v[152:155], v[210:213], v[14:17]
	v_mfma_f32_16x16x32_bf16 v[10:13], v[160:163], v[210:213], v[10:13]
	v_mfma_f32_16x16x32_bf16 v[62:65], v[156:159], v[190:193], v[62:65]
	v_mfma_f32_16x16x32_bf16 v[58:61], v[164:167], v[190:193], v[58:61]
	v_mfma_f32_16x16x32_bf16 v[46:49], v[156:159], v[198:201], v[46:49]
	v_mfma_f32_16x16x32_bf16 v[42:45], v[164:167], v[198:201], v[42:45]
	v_mfma_f32_16x16x32_bf16 v[30:33], v[156:159], v[206:209], v[30:33]
	v_mfma_f32_16x16x32_bf16 v[26:29], v[164:167], v[206:209], v[26:29]
	v_mfma_f32_16x16x32_bf16 v[14:17], v[156:159], v[214:217], v[14:17]
	v_mfma_f32_16x16x32_bf16 v[10:13], v[164:167], v[214:217], v[10:13]
	v_mfma_f32_16x16x32_bf16 v[54:57], v[168:171], v[186:189], v[54:57]
	v_mfma_f32_16x16x32_bf16 v[50:53], v[178:181], v[186:189], v[50:53]
	v_mfma_f32_16x16x32_bf16 v[38:41], v[168:171], v[194:197], v[38:41]
	v_mfma_f32_16x16x32_bf16 v[34:37], v[178:181], v[194:197], v[34:37]
	v_mfma_f32_16x16x32_bf16 v[22:25], v[168:171], v[202:205], v[22:25]
	v_mfma_f32_16x16x32_bf16 v[18:21], v[178:181], v[202:205], v[18:21]
	v_mfma_f32_16x16x32_bf16 v[6:9], v[168:171], v[210:213], v[6:9]
	v_mfma_f32_16x16x32_bf16 v[2:5], v[178:181], v[210:213], v[2:5]
	v_mfma_f32_16x16x32_bf16 v[54:57], v[172:175], v[190:193], v[54:57]
	v_mfma_f32_16x16x32_bf16 v[50:53], v[182:185], v[190:193], v[50:53]
	v_mfma_f32_16x16x32_bf16 v[38:41], v[172:175], v[198:201], v[38:41]
	v_mfma_f32_16x16x32_bf16 v[34:37], v[182:185], v[198:201], v[34:37]
	v_mfma_f32_16x16x32_bf16 v[22:25], v[172:175], v[206:209], v[22:25]
	v_mfma_f32_16x16x32_bf16 v[18:21], v[182:185], v[206:209], v[18:21]
	v_mfma_f32_16x16x32_bf16 v[6:9], v[172:175], v[214:217], v[6:9]
	v_mfma_f32_16x16x32_bf16 v[2:5], v[182:185], v[214:217], v[2:5]
	s_barrier
	s_setprio 0
	s_add_i32 s52, s52, 2
	s_add_u32 s28, s28, 0x100
	s_addc_u32 s29, s29, 0
	s_add_u32 s46, s46, 0x100
	s_addc_u32 s47, s47, 0
	s_cmp_gt_u32 s52, 13
	s_cbranch_scc0 .LBB0_451

.Lpk495_peel:
	ds_read_b128 v[152:155], v149
	ds_read_b128 v[156:159], v149 offset:1024
	ds_read_b128 v[160:163], v149 offset:2048
	ds_read_b128 v[164:167], v149 offset:3072
	ds_read_b128 v[168:171], v150
	ds_read_b128 v[172:175], v150 offset:1024
	ds_read_b128 v[178:181], v150 offset:2048
	ds_read_b128 v[182:185], v150 offset:3072
	s_add_u32 s2, s18, 0x4000
	s_addc_u32 s3, s19, 0
	s_cmp_eq_u32 s50, 40
	s_cselect_b32 s2, s45, s2
	s_cselect_b32 s3, s44, s3
	s_cselect_b32 s23, s46, s49
	s_cselect_b32 s22, s47, s48
	s_add_u32 s20, s2, 0x8000
	s_addc_u32 s21, s3, 0
	v_lshl_add_u64 v[144:145], s[18:19], 0, v[138:139]
	s_add_i32 m0, s29, 0xc000
	ds_read_b128 v[186:189], v151
	ds_read_b128 v[190:193], v151 offset:1024
	ds_read_b128 v[194:197], v151 offset:2048
	ds_read_b128 v[198:201], v151 offset:3072
	ds_read_b128 v[202:205], v151 offset:4096
	ds_read_b128 v[206:209], v151 offset:5120
	ds_read_b128 v[210:213], v151 offset:6144
	ds_read_b128 v[214:217], v151 offset:7168
	global_load_lds_dwordx4 v[144:145], off
	v_lshl_add_u64 v[144:145], s[18:19], 0, v[140:141]
	s_add_i32 m0, s29, 0xe000
	s_nop 0
	global_load_lds_dwordx4 v[144:145], off
	s_waitcnt vmcnt(8)
	s_waitcnt lgkmcnt(0)
	s_setprio 2
	s_barrier
	v_mfma_f32_16x16x32_bf16 v[126:129], v[152:155], v[186:189], 0
	v_mfma_f32_16x16x32_bf16 v[122:125], v[160:163], v[186:189], 0
	v_mfma_f32_16x16x32_bf16 v[114:117], v[152:155], v[194:197], 0
	v_mfma_f32_16x16x32_bf16 v[106:109], v[160:163], v[194:197], 0
	v_mfma_f32_16x16x32_bf16 v[98:101], v[152:155], v[202:205], 0
	v_mfma_f32_16x16x32_bf16 v[90:93], v[160:163], v[202:205], 0
	v_mfma_f32_16x16x32_bf16 v[82:85], v[152:155], v[210:213], 0
	v_mfma_f32_16x16x32_bf16 v[74:77], v[160:163], v[210:213], 0
	v_mfma_f32_16x16x32_bf16 v[126:129], v[156:159], v[190:193], v[126:129]
	v_mfma_f32_16x16x32_bf16 v[122:125], v[164:167], v[190:193], v[122:125]
	v_mfma_f32_16x16x32_bf16 v[114:117], v[156:159], v[198:201], v[114:117]
	v_mfma_f32_16x16x32_bf16 v[106:109], v[164:167], v[198:201], v[106:109]
	v_mfma_f32_16x16x32_bf16 v[98:101], v[156:159], v[206:209], v[98:101]
	v_mfma_f32_16x16x32_bf16 v[90:93], v[164:167], v[206:209], v[90:93]
	v_mfma_f32_16x16x32_bf16 v[82:85], v[156:159], v[214:217], v[82:85]
	v_mfma_f32_16x16x32_bf16 v[74:77], v[164:167], v[214:217], v[74:77]
	v_mfma_f32_16x16x32_bf16 v[118:121], v[168:171], v[186:189], 0
	v_mfma_f32_16x16x32_bf16 v[110:113], v[178:181], v[186:189], 0
	v_mfma_f32_16x16x32_bf16 v[102:105], v[168:171], v[194:197], 0
	v_mfma_f32_16x16x32_bf16 v[94:97], v[178:181], v[194:197], 0
	v_mfma_f32_16x16x32_bf16 v[86:89], v[168:171], v[202:205], 0
	v_mfma_f32_16x16x32_bf16 v[78:81], v[178:181], v[202:205], 0
	v_mfma_f32_16x16x32_bf16 v[70:73], v[168:171], v[210:213], 0
	v_mfma_f32_16x16x32_bf16 v[66:69], v[178:181], v[210:213], 0
	v_mfma_f32_16x16x32_bf16 v[118:121], v[172:175], v[190:193], v[118:121]
	v_mfma_f32_16x16x32_bf16 v[110:113], v[182:185], v[190:193], v[110:113]
	v_mfma_f32_16x16x32_bf16 v[102:105], v[172:175], v[198:201], v[102:105]
	v_mfma_f32_16x16x32_bf16 v[94:97], v[182:185], v[198:201], v[94:97]
	v_mfma_f32_16x16x32_bf16 v[86:89], v[172:175], v[206:209], v[86:89]
	v_mfma_f32_16x16x32_bf16 v[78:81], v[182:185], v[206:209], v[78:81]
	v_mfma_f32_16x16x32_bf16 v[70:73], v[172:175], v[214:217], v[70:73]
	v_mfma_f32_16x16x32_bf16 v[66:69], v[182:185], v[214:217], v[66:69]
	s_barrier
	s_setprio 0
	s_add_i32 s51, s38, s28
	v_lshl_add_u64 v[144:145], s[22:23], 0, v[132:133]
	s_mov_b32 m0, s51
	ds_read_b128 v[186:189], v151 offset:16384
	ds_read_b128 v[190:193], v151 offset:17408
	ds_read_b128 v[194:197], v151 offset:18432
	ds_read_b128 v[198:201], v151 offset:19456
	ds_read_b128 v[202:205], v151 offset:20480
	ds_read_b128 v[206:209], v151 offset:21504
	ds_read_b128 v[210:213], v151 offset:22528
	ds_read_b128 v[214:217], v151 offset:23552
	global_load_lds_dwordx4 v[144:145], off
	s_add_i32 m0, s51, 0x2000
	s_add_u32 s52, s22, 0x4000
	v_lshl_add_u64 v[144:145], s[22:23], 0, v[136:137]
	s_addc_u32 s53, s23, 0
	s_add_i32 s51, s39, s28
	global_load_lds_dwordx4 v[144:145], off
	v_lshl_add_u64 v[144:145], s[52:53], 0, v[132:133]
	s_mov_b32 m0, s51
	s_nop 0
	global_load_lds_dwordx4 v[144:145], off
	v_lshl_add_u64 v[144:145], s[52:53], 0, v[136:137]
	s_add_i32 m0, s51, 0x2000
	s_nop 0
	global_load_lds_dwordx4 v[144:145], off
	v_lshl_add_u64 v[144:145], s[2:3], 0, v[130:131]
	s_mov_b32 m0, s29
	s_nop 0
	global_load_lds_dwordx4 v[144:145], off
	v_lshl_add_u64 v[144:145], s[2:3], 0, v[134:135]
	s_mov_b32 m0, s30
	s_nop 0
	global_load_lds_dwordx4 v[144:145], off
	s_waitcnt vmcnt(8)
	s_waitcnt lgkmcnt(0)
	s_setprio 2
	s_barrier
	v_mfma_f32_16x16x32_bf16 v[62:65], v[152:155], v[186:189], 0
	v_mfma_f32_16x16x32_bf16 v[58:61], v[160:163], v[186:189], 0
	v_mfma_f32_16x16x32_bf16 v[50:53], v[152:155], v[194:197], 0
	v_mfma_f32_16x16x32_bf16 v[42:45], v[160:163], v[194:197], 0
	v_mfma_f32_16x16x32_bf16 v[34:37], v[152:155], v[202:205], 0
	v_mfma_f32_16x16x32_bf16 v[26:29], v[160:163], v[202:205], 0
	v_mfma_f32_16x16x32_bf16 v[18:21], v[152:155], v[210:213], 0
	v_mfma_f32_16x16x32_bf16 v[10:13], v[160:163], v[210:213], 0
	v_mfma_f32_16x16x32_bf16 v[62:65], v[156:159], v[190:193], v[62:65]
	v_mfma_f32_16x16x32_bf16 v[58:61], v[164:167], v[190:193], v[58:61]
	v_mfma_f32_16x16x32_bf16 v[50:53], v[156:159], v[198:201], v[50:53]
	v_mfma_f32_16x16x32_bf16 v[42:45], v[164:167], v[198:201], v[42:45]
	v_mfma_f32_16x16x32_bf16 v[34:37], v[156:159], v[206:209], v[34:37]
	v_mfma_f32_16x16x32_bf16 v[26:29], v[164:167], v[206:209], v[26:29]
	v_mfma_f32_16x16x32_bf16 v[18:21], v[156:159], v[214:217], v[18:21]
	v_mfma_f32_16x16x32_bf16 v[10:13], v[164:167], v[214:217], v[10:13]
	v_mfma_f32_16x16x32_bf16 v[54:57], v[168:171], v[186:189], 0
	v_mfma_f32_16x16x32_bf16 v[46:49], v[178:181], v[186:189], 0
	v_mfma_f32_16x16x32_bf16 v[38:41], v[168:171], v[194:197], 0
	v_mfma_f32_16x16x32_bf16 v[30:33], v[178:181], v[194:197], 0
	v_mfma_f32_16x16x32_bf16 v[22:25], v[168:171], v[202:205], 0
	v_mfma_f32_16x16x32_bf16 v[14:17], v[178:181], v[202:205], 0
	v_mfma_f32_16x16x32_bf16 v[6:9], v[168:171], v[210:213], 0
	v_mfma_f32_16x16x32_bf16 v[2:5], v[178:181], v[210:213], 0
	v_mfma_f32_16x16x32_bf16 v[54:57], v[172:175], v[190:193], v[54:57]
	v_mfma_f32_16x16x32_bf16 v[46:49], v[182:185], v[190:193], v[46:49]
	v_mfma_f32_16x16x32_bf16 v[38:41], v[172:175], v[198:201], v[38:41]
	v_mfma_f32_16x16x32_bf16 v[30:33], v[182:185], v[198:201], v[30:33]
	v_mfma_f32_16x16x32_bf16 v[22:25], v[172:175], v[206:209], v[22:25]
	v_mfma_f32_16x16x32_bf16 v[14:17], v[182:185], v[206:209], v[14:17]
	v_mfma_f32_16x16x32_bf16 v[6:9], v[172:175], v[214:217], v[6:9]
	v_mfma_f32_16x16x32_bf16 v[2:5], v[182:185], v[214:217], v[2:5]
	s_barrier
	s_setprio 0
	s_add_i32 s51, 0, 0x18000
	v_add_u32_e32 v144, s51, v147
	s_add_i32 s52, 0, 0x1c000
	ds_read_b128 v[152:155], v144
	ds_read_b128 v[156:159], v144 offset:1024
	ds_read_b128 v[160:163], v144 offset:2048
	ds_read_b128 v[164:167], v144 offset:3072
	v_add_u32_e32 v144, s52, v147
	ds_read_b128 v[168:171], v144
	ds_read_b128 v[172:175], v144 offset:1024
	ds_read_b128 v[178:181], v144 offset:2048
	ds_read_b128 v[182:185], v144 offset:3072
	s_add_u32 s2, s2, 0x4000
	s_addc_u32 s3, s3, 0
	s_mov_b32 m0, s31
	v_lshl_add_u64 v[144:145], s[2:3], 0, v[130:131]
	ds_read_b128 v[186:189], v151 offset:32768
	ds_read_b128 v[190:193], v151 offset:33792
	ds_read_b128 v[194:197], v151 offset:34816
	ds_read_b128 v[198:201], v151 offset:35840
	ds_read_b128 v[202:205], v151 offset:36864
	ds_read_b128 v[206:209], v151 offset:37888
	ds_read_b128 v[210:213], v151 offset:38912
	ds_read_b128 v[214:217], v151 offset:39936
	global_load_lds_dwordx4 v[144:145], off
	v_lshl_add_u64 v[144:145], s[2:3], 0, v[134:135]
	s_mov_b32 m0, s34
	s_nop 0
	global_load_lds_dwordx4 v[144:145], off
	s_waitcnt vmcnt(8)
	s_waitcnt lgkmcnt(0)
	s_setprio 2
	s_barrier
	v_mfma_f32_16x16x32_bf16 v[126:129], v[152:155], v[186:189], v[126:129]
	v_mfma_f32_16x16x32_bf16 v[122:125], v[160:163], v[186:189], v[122:125]
	v_mfma_f32_16x16x32_bf16 v[114:117], v[152:155], v[194:197], v[114:117]
	v_mfma_f32_16x16x32_bf16 v[106:109], v[160:163], v[194:197], v[106:109]
	v_mfma_f32_16x16x32_bf16 v[98:101], v[152:155], v[202:205], v[98:101]
	v_mfma_f32_16x16x32_bf16 v[90:93], v[160:163], v[202:205], v[90:93]
	v_mfma_f32_16x16x32_bf16 v[82:85], v[152:155], v[210:213], v[82:85]
	v_mfma_f32_16x16x32_bf16 v[74:77], v[160:163], v[210:213], v[74:77]
	v_mfma_f32_16x16x32_bf16 v[126:129], v[156:159], v[190:193], v[126:129]
	v_mfma_f32_16x16x32_bf16 v[122:125], v[164:167], v[190:193], v[122:125]
	v_mfma_f32_16x16x32_bf16 v[114:117], v[156:159], v[198:201], v[114:117]
	v_mfma_f32_16x16x32_bf16 v[106:109], v[164:167], v[198:201], v[106:109]
	v_mfma_f32_16x16x32_bf16 v[98:101], v[156:159], v[206:209], v[98:101]
	v_mfma_f32_16x16x32_bf16 v[90:93], v[164:167], v[206:209], v[90:93]
	v_mfma_f32_16x16x32_bf16 v[82:85], v[156:159], v[214:217], v[82:85]
	v_mfma_f32_16x16x32_bf16 v[74:77], v[164:167], v[214:217], v[74:77]
	v_mfma_f32_16x16x32_bf16 v[118:121], v[168:171], v[186:189], v[118:121]
	v_mfma_f32_16x16x32_bf16 v[110:113], v[178:181], v[186:189], v[110:113]
	v_mfma_f32_16x16x32_bf16 v[102:105], v[168:171], v[194:197], v[102:105]
	v_mfma_f32_16x16x32_bf16 v[94:97], v[178:181], v[194:197], v[94:97]
	v_mfma_f32_16x16x32_bf16 v[86:89], v[168:171], v[202:205], v[86:89]
	v_mfma_f32_16x16x32_bf16 v[78:81], v[178:181], v[202:205], v[78:81]
	v_mfma_f32_16x16x32_bf16 v[70:73], v[168:171], v[210:213], v[70:73]
	v_mfma_f32_16x16x32_bf16 v[66:69], v[178:181], v[210:213], v[66:69]
	v_mfma_f32_16x16x32_bf16 v[118:121], v[172:175], v[190:193], v[118:121]
	v_mfma_f32_16x16x32_bf16 v[110:113], v[182:185], v[190:193], v[110:113]
	v_mfma_f32_16x16x32_bf16 v[102:105], v[172:175], v[198:201], v[102:105]
	v_mfma_f32_16x16x32_bf16 v[94:97], v[182:185], v[198:201], v[94:97]
	v_mfma_f32_16x16x32_bf16 v[86:89], v[172:175], v[206:209], v[86:89]
	v_mfma_f32_16x16x32_bf16 v[78:81], v[182:185], v[206:209], v[78:81]
	v_mfma_f32_16x16x32_bf16 v[70:73], v[172:175], v[214:217], v[70:73]
	v_mfma_f32_16x16x32_bf16 v[66:69], v[182:185], v[214:217], v[66:69]
	s_barrier
	s_setprio 0
	s_add_u32 s2, s22, 0x8000
	s_addc_u32 s3, s23, 0
	s_add_i32 s51, s51, s28
	v_lshl_add_u64 v[144:145], s[2:3], 0, v[132:133]
	s_mov_b32 m0, s51
	ds_read_b128 v[186:189], v151 offset:49152
	ds_read_b128 v[190:193], v151 offset:50176
	ds_read_b128 v[194:197], v151 offset:51200
	ds_read_b128 v[198:201], v151 offset:52224
	ds_read_b128 v[202:205], v151 offset:53248
	ds_read_b128 v[206:209], v151 offset:54272
	ds_read_b128 v[210:213], v151 offset:55296
	ds_read_b128 v[214:217], v151 offset:56320
	global_load_lds_dwordx4 v[144:145], off
	s_add_i32 m0, s51, 0x2000
	v_lshl_add_u64 v[144:145], s[2:3], 0, v[136:137]
	s_add_u32 s2, s22, 0xc000
	s_addc_u32 s3, s23, 0
	s_add_i32 s22, s52, s28
	global_load_lds_dwordx4 v[144:145], off
	v_lshl_add_u64 v[144:145], s[2:3], 0, v[132:133]
	s_mov_b32 m0, s22
	s_nop 0
	global_load_lds_dwordx4 v[144:145], off
	v_lshl_add_u64 v[144:145], s[2:3], 0, v[136:137]
	s_add_i32 m0, s22, 0x2000
	s_nop 0
	global_load_lds_dwordx4 v[144:145], off
	v_lshl_add_u64 v[144:145], s[20:21], 0, v[130:131]
	s_mov_b32 m0, s36
	s_nop 0
	global_load_lds_dwordx4 v[144:145], off
	v_lshl_add_u64 v[144:145], s[20:21], 0, v[134:135]
	s_mov_b32 m0, s37
	s_nop 0
	global_load_lds_dwordx4 v[144:145], off
	s_waitcnt vmcnt(8)
	s_waitcnt lgkmcnt(0)
	s_setprio 2
	s_barrier
	v_mfma_f32_16x16x32_bf16 v[62:65], v[152:155], v[186:189], v[62:65]
	v_mfma_f32_16x16x32_bf16 v[58:61], v[160:163], v[186:189], v[58:61]
	v_mfma_f32_16x16x32_bf16 v[50:53], v[152:155], v[194:197], v[50:53]
	v_mfma_f32_16x16x32_bf16 v[42:45], v[160:163], v[194:197], v[42:45]
	v_mfma_f32_16x16x32_bf16 v[34:37], v[152:155], v[202:205], v[34:37]
	v_mfma_f32_16x16x32_bf16 v[26:29], v[160:163], v[202:205], v[26:29]
	v_mfma_f32_16x16x32_bf16 v[18:21], v[152:155], v[210:213], v[18:21]
	v_mfma_f32_16x16x32_bf16 v[10:13], v[160:163], v[210:213], v[10:13]
	v_mfma_f32_16x16x32_bf16 v[62:65], v[156:159], v[190:193], v[62:65]
	v_mfma_f32_16x16x32_bf16 v[58:61], v[164:167], v[190:193], v[58:61]
	v_mfma_f32_16x16x32_bf16 v[50:53], v[156:159], v[198:201], v[50:53]
	v_mfma_f32_16x16x32_bf16 v[42:45], v[164:167], v[198:201], v[42:45]
	v_mfma_f32_16x16x32_bf16 v[34:37], v[156:159], v[206:209], v[34:37]
	v_mfma_f32_16x16x32_bf16 v[26:29], v[164:167], v[206:209], v[26:29]
	v_mfma_f32_16x16x32_bf16 v[18:21], v[156:159], v[214:217], v[18:21]
	v_mfma_f32_16x16x32_bf16 v[10:13], v[164:167], v[214:217], v[10:13]
	v_mfma_f32_16x16x32_bf16 v[54:57], v[168:171], v[186:189], v[54:57]
	v_mfma_f32_16x16x32_bf16 v[46:49], v[178:181], v[186:189], v[46:49]
	v_mfma_f32_16x16x32_bf16 v[38:41], v[168:171], v[194:197], v[38:41]
	v_mfma_f32_16x16x32_bf16 v[30:33], v[178:181], v[194:197], v[30:33]
	v_mfma_f32_16x16x32_bf16 v[22:25], v[168:171], v[202:205], v[22:25]
	v_mfma_f32_16x16x32_bf16 v[14:17], v[178:181], v[202:205], v[14:17]
	v_mfma_f32_16x16x32_bf16 v[6:9], v[168:171], v[210:213], v[6:9]
	v_mfma_f32_16x16x32_bf16 v[2:5], v[178:181], v[210:213], v[2:5]
	v_mfma_f32_16x16x32_bf16 v[54:57], v[172:175], v[190:193], v[54:57]
	v_mfma_f32_16x16x32_bf16 v[46:49], v[182:185], v[190:193], v[46:49]
	v_mfma_f32_16x16x32_bf16 v[38:41], v[172:175], v[198:201], v[38:41]
	v_mfma_f32_16x16x32_bf16 v[30:33], v[182:185], v[198:201], v[30:33]
	v_mfma_f32_16x16x32_bf16 v[22:25], v[172:175], v[206:209], v[22:25]
	v_mfma_f32_16x16x32_bf16 v[14:17], v[182:185], v[206:209], v[14:17]
	v_mfma_f32_16x16x32_bf16 v[6:9], v[172:175], v[214:217], v[6:9]
	v_mfma_f32_16x16x32_bf16 v[2:5], v[182:185], v[214:217], v[2:5]
	s_barrier
	s_setprio 0
	s_add_i32 s50, s50, 2
	s_add_u32 s18, s18, 0x10000
	s_addc_u32 s19, s19, 0
	s_add_u32 s48, s48, 0x10000
	s_addc_u32 s49, s49, 0
	s_cmp_gt_u32 s50, 41
	s_cbranch_scc0 .LBB0_495
	s_branch .Lpk495_exit
.LBB0_495:
	ds_read_b128 v[152:155], v149
	ds_read_b128 v[156:159], v149 offset:1024
	ds_read_b128 v[160:163], v149 offset:2048
	ds_read_b128 v[164:167], v149 offset:3072
	ds_read_b128 v[168:171], v150
	ds_read_b128 v[172:175], v150 offset:1024
	ds_read_b128 v[178:181], v150 offset:2048
	ds_read_b128 v[182:185], v150 offset:3072
	s_add_u32 s2, s18, 0x4000
	s_addc_u32 s3, s19, 0
	s_cmp_eq_u32 s50, 40
	s_cselect_b32 s2, s45, s2
	s_cselect_b32 s3, s44, s3
	s_cselect_b32 s23, s46, s49
	s_cselect_b32 s22, s47, s48
	s_add_u32 s20, s2, 0x8000
	s_addc_u32 s21, s3, 0
	v_lshl_add_u64 v[144:145], s[18:19], 0, v[138:139]
	s_add_i32 m0, s29, 0xc000
	ds_read_b128 v[186:189], v151
	ds_read_b128 v[190:193], v151 offset:1024
	ds_read_b128 v[194:197], v151 offset:2048
	ds_read_b128 v[198:201], v151 offset:3072
	ds_read_b128 v[202:205], v151 offset:4096
	ds_read_b128 v[206:209], v151 offset:5120
	ds_read_b128 v[210:213], v151 offset:6144
	ds_read_b128 v[214:217], v151 offset:7168
	global_load_lds_dwordx4 v[144:145], off
	v_lshl_add_u64 v[144:145], s[18:19], 0, v[140:141]
	s_add_i32 m0, s29, 0xe000
	s_nop 0
	global_load_lds_dwordx4 v[144:145], off
	s_waitcnt vmcnt(8)
	s_waitcnt lgkmcnt(0)
	s_setprio 2
	s_barrier
	v_mfma_f32_16x16x32_bf16 v[126:129], v[152:155], v[186:189], v[126:129]
	v_mfma_f32_16x16x32_bf16 v[122:125], v[160:163], v[186:189], v[122:125]
	v_mfma_f32_16x16x32_bf16 v[114:117], v[152:155], v[194:197], v[114:117]
	v_mfma_f32_16x16x32_bf16 v[106:109], v[160:163], v[194:197], v[106:109]
	v_mfma_f32_16x16x32_bf16 v[98:101], v[152:155], v[202:205], v[98:101]
	v_mfma_f32_16x16x32_bf16 v[90:93], v[160:163], v[202:205], v[90:93]
	v_mfma_f32_16x16x32_bf16 v[82:85], v[152:155], v[210:213], v[82:85]
	v_mfma_f32_16x16x32_bf16 v[74:77], v[160:163], v[210:213], v[74:77]
	v_mfma_f32_16x16x32_bf16 v[126:129], v[156:159], v[190:193], v[126:129]
	v_mfma_f32_16x16x32_bf16 v[122:125], v[164:167], v[190:193], v[122:125]
	v_mfma_f32_16x16x32_bf16 v[114:117], v[156:159], v[198:201], v[114:117]
	v_mfma_f32_16x16x32_bf16 v[106:109], v[164:167], v[198:201], v[106:109]
	v_mfma_f32_16x16x32_bf16 v[98:101], v[156:159], v[206:209], v[98:101]
	v_mfma_f32_16x16x32_bf16 v[90:93], v[164:167], v[206:209], v[90:93]
	v_mfma_f32_16x16x32_bf16 v[82:85], v[156:159], v[214:217], v[82:85]
	v_mfma_f32_16x16x32_bf16 v[74:77], v[164:167], v[214:217], v[74:77]
	v_mfma_f32_16x16x32_bf16 v[118:121], v[168:171], v[186:189], v[118:121]
	v_mfma_f32_16x16x32_bf16 v[110:113], v[178:181], v[186:189], v[110:113]
	v_mfma_f32_16x16x32_bf16 v[102:105], v[168:171], v[194:197], v[102:105]
	v_mfma_f32_16x16x32_bf16 v[94:97], v[178:181], v[194:197], v[94:97]
	v_mfma_f32_16x16x32_bf16 v[86:89], v[168:171], v[202:205], v[86:89]
	v_mfma_f32_16x16x32_bf16 v[78:81], v[178:181], v[202:205], v[78:81]
	v_mfma_f32_16x16x32_bf16 v[70:73], v[168:171], v[210:213], v[70:73]
	v_mfma_f32_16x16x32_bf16 v[66:69], v[178:181], v[210:213], v[66:69]
	v_mfma_f32_16x16x32_bf16 v[118:121], v[172:175], v[190:193], v[118:121]
	v_mfma_f32_16x16x32_bf16 v[110:113], v[182:185], v[190:193], v[110:113]
	v_mfma_f32_16x16x32_bf16 v[102:105], v[172:175], v[198:201], v[102:105]
	v_mfma_f32_16x16x32_bf16 v[94:97], v[182:185], v[198:201], v[94:97]
	v_mfma_f32_16x16x32_bf16 v[86:89], v[172:175], v[206:209], v[86:89]
	v_mfma_f32_16x16x32_bf16 v[78:81], v[182:185], v[206:209], v[78:81]
	v_mfma_f32_16x16x32_bf16 v[70:73], v[172:175], v[214:217], v[70:73]
	v_mfma_f32_16x16x32_bf16 v[66:69], v[182:185], v[214:217], v[66:69]
	s_barrier
	s_setprio 0
	s_add_i32 s51, s38, s28
	v_lshl_add_u64 v[144:145], s[22:23], 0, v[132:133]
	s_mov_b32 m0, s51
	ds_read_b128 v[186:189], v151 offset:16384
	ds_read_b128 v[190:193], v151 offset:17408
	ds_read_b128 v[194:197], v151 offset:18432
	ds_read_b128 v[198:201], v151 offset:19456
	ds_read_b128 v[202:205], v151 offset:20480
	ds_read_b128 v[206:209], v151 offset:21504
	ds_read_b128 v[210:213], v151 offset:22528
	ds_read_b128 v[214:217], v151 offset:23552
	global_load_lds_dwordx4 v[144:145], off
	s_add_i32 m0, s51, 0x2000
	s_add_u32 s52, s22, 0x4000
	v_lshl_add_u64 v[144:145], s[22:23], 0, v[136:137]
	s_addc_u32 s53, s23, 0
	s_add_i32 s51, s39, s28
	global_load_lds_dwordx4 v[144:145], off
	v_lshl_add_u64 v[144:145], s[52:53], 0, v[132:133]
	s_mov_b32 m0, s51
	s_nop 0
	global_load_lds_dwordx4 v[144:145], off
	v_lshl_add_u64 v[144:145], s[52:53], 0, v[136:137]
	s_add_i32 m0, s51, 0x2000
	s_nop 0
	global_load_lds_dwordx4 v[144:145], off
	v_lshl_add_u64 v[144:145], s[2:3], 0, v[130:131]
	s_mov_b32 m0, s29
	s_nop 0
	global_load_lds_dwordx4 v[144:145], off
	v_lshl_add_u64 v[144:145], s[2:3], 0, v[134:135]
	s_mov_b32 m0, s30
	s_nop 0
	global_load_lds_dwordx4 v[144:145], off
	s_waitcnt vmcnt(8)
	s_waitcnt lgkmcnt(0)
	s_setprio 2
	s_barrier
	v_mfma_f32_16x16x32_bf16 v[62:65], v[152:155], v[186:189], v[62:65]
	v_mfma_f32_16x16x32_bf16 v[58:61], v[160:163], v[186:189], v[58:61]
	v_mfma_f32_16x16x32_bf16 v[50:53], v[152:155], v[194:197], v[50:53]
	v_mfma_f32_16x16x32_bf16 v[42:45], v[160:163], v[194:197], v[42:45]
	v_mfma_f32_16x16x32_bf16 v[34:37], v[152:155], v[202:205], v[34:37]
	v_mfma_f32_16x16x32_bf16 v[26:29], v[160:163], v[202:205], v[26:29]
	v_mfma_f32_16x16x32_bf16 v[18:21], v[152:155], v[210:213], v[18:21]
	v_mfma_f32_16x16x32_bf16 v[10:13], v[160:163], v[210:213], v[10:13]
	v_mfma_f32_16x16x32_bf16 v[62:65], v[156:159], v[190:193], v[62:65]
	v_mfma_f32_16x16x32_bf16 v[58:61], v[164:167], v[190:193], v[58:61]
	v_mfma_f32_16x16x32_bf16 v[50:53], v[156:159], v[198:201], v[50:53]
	v_mfma_f32_16x16x32_bf16 v[42:45], v[164:167], v[198:201], v[42:45]
	v_mfma_f32_16x16x32_bf16 v[34:37], v[156:159], v[206:209], v[34:37]
	v_mfma_f32_16x16x32_bf16 v[26:29], v[164:167], v[206:209], v[26:29]
	v_mfma_f32_16x16x32_bf16 v[18:21], v[156:159], v[214:217], v[18:21]
	v_mfma_f32_16x16x32_bf16 v[10:13], v[164:167], v[214:217], v[10:13]
	v_mfma_f32_16x16x32_bf16 v[54:57], v[168:171], v[186:189], v[54:57]
	v_mfma_f32_16x16x32_bf16 v[46:49], v[178:181], v[186:189], v[46:49]
	v_mfma_f32_16x16x32_bf16 v[38:41], v[168:171], v[194:197], v[38:41]
	v_mfma_f32_16x16x32_bf16 v[30:33], v[178:181], v[194:197], v[30:33]
	v_mfma_f32_16x16x32_bf16 v[22:25], v[168:171], v[202:205], v[22:25]
	v_mfma_f32_16x16x32_bf16 v[14:17], v[178:181], v[202:205], v[14:17]
	v_mfma_f32_16x16x32_bf16 v[6:9], v[168:171], v[210:213], v[6:9]
	v_mfma_f32_16x16x32_bf16 v[2:5], v[178:181], v[210:213], v[2:5]
	v_mfma_f32_16x16x32_bf16 v[54:57], v[172:175], v[190:193], v[54:57]
	v_mfma_f32_16x16x32_bf16 v[46:49], v[182:185], v[190:193], v[46:49]
	v_mfma_f32_16x16x32_bf16 v[38:41], v[172:175], v[198:201], v[38:41]
	v_mfma_f32_16x16x32_bf16 v[30:33], v[182:185], v[198:201], v[30:33]
	v_mfma_f32_16x16x32_bf16 v[22:25], v[172:175], v[206:209], v[22:25]
	v_mfma_f32_16x16x32_bf16 v[14:17], v[182:185], v[206:209], v[14:17]
	v_mfma_f32_16x16x32_bf16 v[6:9], v[172:175], v[214:217], v[6:9]
	v_mfma_f32_16x16x32_bf16 v[2:5], v[182:185], v[214:217], v[2:5]
	s_barrier
	s_setprio 0
	s_add_i32 s51, 0, 0x18000
	v_add_u32_e32 v144, s51, v147
	s_add_i32 s52, 0, 0x1c000
	ds_read_b128 v[152:155], v144
	ds_read_b128 v[156:159], v144 offset:1024
	ds_read_b128 v[160:163], v144 offset:2048
	ds_read_b128 v[164:167], v144 offset:3072
	v_add_u32_e32 v144, s52, v147
	ds_read_b128 v[168:171], v144
	ds_read_b128 v[172:175], v144 offset:1024
	ds_read_b128 v[178:181], v144 offset:2048
	ds_read_b128 v[182:185], v144 offset:3072
	s_add_u32 s2, s2, 0x4000
	s_addc_u32 s3, s3, 0
	s_mov_b32 m0, s31
	v_lshl_add_u64 v[144:145], s[2:3], 0, v[130:131]
	ds_read_b128 v[186:189], v151 offset:32768
	ds_read_b128 v[190:193], v151 offset:33792
	ds_read_b128 v[194:197], v151 offset:34816
	ds_read_b128 v[198:201], v151 offset:35840
	ds_read_b128 v[202:205], v151 offset:36864
	ds_read_b128 v[206:209], v151 offset:37888
	ds_read_b128 v[210:213], v151 offset:38912
	ds_read_b128 v[214:217], v151 offset:39936
	global_load_lds_dwordx4 v[144:145], off
	v_lshl_add_u64 v[144:145], s[2:3], 0, v[134:135]
	s_mov_b32 m0, s34
	s_nop 0
	global_load_lds_dwordx4 v[144:145], off
	s_waitcnt vmcnt(8)
	s_waitcnt lgkmcnt(0)
	s_setprio 2
	s_barrier
	v_mfma_f32_16x16x32_bf16 v[126:129], v[152:155], v[186:189], v[126:129]
	v_mfma_f32_16x16x32_bf16 v[122:125], v[160:163], v[186:189], v[122:125]
	v_mfma_f32_16x16x32_bf16 v[114:117], v[152:155], v[194:197], v[114:117]
	v_mfma_f32_16x16x32_bf16 v[106:109], v[160:163], v[194:197], v[106:109]
	v_mfma_f32_16x16x32_bf16 v[98:101], v[152:155], v[202:205], v[98:101]
	v_mfma_f32_16x16x32_bf16 v[90:93], v[160:163], v[202:205], v[90:93]
	v_mfma_f32_16x16x32_bf16 v[82:85], v[152:155], v[210:213], v[82:85]
	v_mfma_f32_16x16x32_bf16 v[74:77], v[160:163], v[210:213], v[74:77]
	v_mfma_f32_16x16x32_bf16 v[126:129], v[156:159], v[190:193], v[126:129]
	v_mfma_f32_16x16x32_bf16 v[122:125], v[164:167], v[190:193], v[122:125]
	v_mfma_f32_16x16x32_bf16 v[114:117], v[156:159], v[198:201], v[114:117]
	v_mfma_f32_16x16x32_bf16 v[106:109], v[164:167], v[198:201], v[106:109]
	v_mfma_f32_16x16x32_bf16 v[98:101], v[156:159], v[206:209], v[98:101]
	v_mfma_f32_16x16x32_bf16 v[90:93], v[164:167], v[206:209], v[90:93]
	v_mfma_f32_16x16x32_bf16 v[82:85], v[156:159], v[214:217], v[82:85]
	v_mfma_f32_16x16x32_bf16 v[74:77], v[164:167], v[214:217], v[74:77]
	v_mfma_f32_16x16x32_bf16 v[118:121], v[168:171], v[186:189], v[118:121]
	v_mfma_f32_16x16x32_bf16 v[110:113], v[178:181], v[186:189], v[110:113]
	v_mfma_f32_16x16x32_bf16 v[102:105], v[168:171], v[194:197], v[102:105]
	v_mfma_f32_16x16x32_bf16 v[94:97], v[178:181], v[194:197], v[94:97]
	v_mfma_f32_16x16x32_bf16 v[86:89], v[168:171], v[202:205], v[86:89]
	v_mfma_f32_16x16x32_bf16 v[78:81], v[178:181], v[202:205], v[78:81]
	v_mfma_f32_16x16x32_bf16 v[70:73], v[168:171], v[210:213], v[70:73]
	v_mfma_f32_16x16x32_bf16 v[66:69], v[178:181], v[210:213], v[66:69]
	v_mfma_f32_16x16x32_bf16 v[118:121], v[172:175], v[190:193], v[118:121]
	v_mfma_f32_16x16x32_bf16 v[110:113], v[182:185], v[190:193], v[110:113]
	v_mfma_f32_16x16x32_bf16 v[102:105], v[172:175], v[198:201], v[102:105]
	v_mfma_f32_16x16x32_bf16 v[94:97], v[182:185], v[198:201], v[94:97]
	v_mfma_f32_16x16x32_bf16 v[86:89], v[172:175], v[206:209], v[86:89]
	v_mfma_f32_16x16x32_bf16 v[78:81], v[182:185], v[206:209], v[78:81]
	v_mfma_f32_16x16x32_bf16 v[70:73], v[172:175], v[214:217], v[70:73]
	v_mfma_f32_16x16x32_bf16 v[66:69], v[182:185], v[214:217], v[66:69]
	s_barrier
	s_setprio 0
	s_add_u32 s2, s22, 0x8000
	s_addc_u32 s3, s23, 0
	s_add_i32 s51, s51, s28
	v_lshl_add_u64 v[144:145], s[2:3], 0, v[132:133]
	s_mov_b32 m0, s51
	ds_read_b128 v[186:189], v151 offset:49152
	ds_read_b128 v[190:193], v151 offset:50176
	ds_read_b128 v[194:197], v151 offset:51200
	ds_read_b128 v[198:201], v151 offset:52224
	ds_read_b128 v[202:205], v151 offset:53248
	ds_read_b128 v[206:209], v151 offset:54272
	ds_read_b128 v[210:213], v151 offset:55296
	ds_read_b128 v[214:217], v151 offset:56320
	global_load_lds_dwordx4 v[144:145], off
	s_add_i32 m0, s51, 0x2000
	v_lshl_add_u64 v[144:145], s[2:3], 0, v[136:137]
	s_add_u32 s2, s22, 0xc000
	s_addc_u32 s3, s23, 0
	s_add_i32 s22, s52, s28
	global_load_lds_dwordx4 v[144:145], off
	v_lshl_add_u64 v[144:145], s[2:3], 0, v[132:133]
	s_mov_b32 m0, s22
	s_nop 0
	global_load_lds_dwordx4 v[144:145], off
	v_lshl_add_u64 v[144:145], s[2:3], 0, v[136:137]
	s_add_i32 m0, s22, 0x2000
	s_nop 0
	global_load_lds_dwordx4 v[144:145], off
	v_lshl_add_u64 v[144:145], s[20:21], 0, v[130:131]
	s_mov_b32 m0, s36
	s_nop 0
	global_load_lds_dwordx4 v[144:145], off
	v_lshl_add_u64 v[144:145], s[20:21], 0, v[134:135]
	s_mov_b32 m0, s37
	s_nop 0
	global_load_lds_dwordx4 v[144:145], off
	s_waitcnt vmcnt(8)
	s_waitcnt lgkmcnt(0)
	s_setprio 2
	s_barrier
	v_mfma_f32_16x16x32_bf16 v[62:65], v[152:155], v[186:189], v[62:65]
	v_mfma_f32_16x16x32_bf16 v[58:61], v[160:163], v[186:189], v[58:61]
	v_mfma_f32_16x16x32_bf16 v[50:53], v[152:155], v[194:197], v[50:53]
	v_mfma_f32_16x16x32_bf16 v[42:45], v[160:163], v[194:197], v[42:45]
	v_mfma_f32_16x16x32_bf16 v[34:37], v[152:155], v[202:205], v[34:37]
	v_mfma_f32_16x16x32_bf16 v[26:29], v[160:163], v[202:205], v[26:29]
	v_mfma_f32_16x16x32_bf16 v[18:21], v[152:155], v[210:213], v[18:21]
	v_mfma_f32_16x16x32_bf16 v[10:13], v[160:163], v[210:213], v[10:13]
	v_mfma_f32_16x16x32_bf16 v[62:65], v[156:159], v[190:193], v[62:65]
	v_mfma_f32_16x16x32_bf16 v[58:61], v[164:167], v[190:193], v[58:61]
	v_mfma_f32_16x16x32_bf16 v[50:53], v[156:159], v[198:201], v[50:53]
	v_mfma_f32_16x16x32_bf16 v[42:45], v[164:167], v[198:201], v[42:45]
	v_mfma_f32_16x16x32_bf16 v[34:37], v[156:159], v[206:209], v[34:37]
	v_mfma_f32_16x16x32_bf16 v[26:29], v[164:167], v[206:209], v[26:29]
	v_mfma_f32_16x16x32_bf16 v[18:21], v[156:159], v[214:217], v[18:21]
	v_mfma_f32_16x16x32_bf16 v[10:13], v[164:167], v[214:217], v[10:13]
	v_mfma_f32_16x16x32_bf16 v[54:57], v[168:171], v[186:189], v[54:57]
	v_mfma_f32_16x16x32_bf16 v[46:49], v[178:181], v[186:189], v[46:49]
	v_mfma_f32_16x16x32_bf16 v[38:41], v[168:171], v[194:197], v[38:41]
	v_mfma_f32_16x16x32_bf16 v[30:33], v[178:181], v[194:197], v[30:33]
	v_mfma_f32_16x16x32_bf16 v[22:25], v[168:171], v[202:205], v[22:25]
	v_mfma_f32_16x16x32_bf16 v[14:17], v[178:181], v[202:205], v[14:17]
	v_mfma_f32_16x16x32_bf16 v[6:9], v[168:171], v[210:213], v[6:9]
	v_mfma_f32_16x16x32_bf16 v[2:5], v[178:181], v[210:213], v[2:5]
	v_mfma_f32_16x16x32_bf16 v[54:57], v[172:175], v[190:193], v[54:57]
	v_mfma_f32_16x16x32_bf16 v[46:49], v[182:185], v[190:193], v[46:49]
	v_mfma_f32_16x16x32_bf16 v[38:41], v[172:175], v[198:201], v[38:41]
	v_mfma_f32_16x16x32_bf16 v[30:33], v[182:185], v[198:201], v[30:33]
	v_mfma_f32_16x16x32_bf16 v[22:25], v[172:175], v[206:209], v[22:25]
	v_mfma_f32_16x16x32_bf16 v[14:17], v[182:185], v[206:209], v[14:17]
	v_mfma_f32_16x16x32_bf16 v[6:9], v[172:175], v[214:217], v[6:9]
	v_mfma_f32_16x16x32_bf16 v[2:5], v[182:185], v[214:217], v[2:5]
	s_barrier
	s_setprio 0
	s_add_i32 s50, s50, 2
	s_add_u32 s18, s18, 0x10000
	s_addc_u32 s19, s19, 0
	s_add_u32 s48, s48, 0x10000
	s_addc_u32 s49, s49, 0
	s_cmp_gt_u32 s50, 41
	s_cbranch_scc0 .LBB0_495

.Lpk555_peel:
	ds_read_b128 v[154:157], v151
	ds_read_b128 v[158:161], v151 offset:1024
	ds_read_b128 v[162:165], v151 offset:2048
	ds_read_b128 v[166:169], v151 offset:3072
	ds_read_b128 v[170:173], v152
	ds_read_b128 v[178:181], v152 offset:1024
	ds_read_b128 v[182:185], v152 offset:2048
	ds_read_b128 v[186:189], v152 offset:3072
	s_add_u32 s2, s26, 0xfffc0080
	s_addc_u32 s3, s27, -1
	s_cmp_eq_u32 s52, 12
	s_cselect_b32 s3, s11, s3
	s_cselect_b32 s2, s13, s2
	s_cselect_b32 s29, s48, s51
	s_cselect_b32 s28, s49, s50
	v_lshl_add_u64 v[144:145], s[26:27], 0, v[138:139]
	s_add_i32 m0, s37, 0xc000
	ds_read_b128 v[190:193], v153
	ds_read_b128 v[194:197], v153 offset:1024
	ds_read_b128 v[198:201], v153 offset:2048
	ds_read_b128 v[202:205], v153 offset:3072
	ds_read_b128 v[206:209], v153 offset:4096
	ds_read_b128 v[210:213], v153 offset:5120
	ds_read_b128 v[214:217], v153 offset:6144
	ds_read_b128 v[218:221], v153 offset:7168
	global_load_lds_dwordx4 v[144:145], off
	v_lshl_add_u64 v[144:145], s[26:27], 0, v[140:141]
	s_add_i32 m0, s37, 0xe000
	s_nop 0
	global_load_lds_dwordx4 v[144:145], off
	s_waitcnt vmcnt(8)
	s_waitcnt lgkmcnt(0)
	s_setprio 2
	s_barrier
	v_mfma_f32_16x16x32_bf16 v[126:129], v[154:157], v[190:193], 0
	v_mfma_f32_16x16x32_bf16 v[122:125], v[162:165], v[190:193], 0
	v_mfma_f32_16x16x32_bf16 v[114:117], v[154:157], v[198:201], 0
	v_mfma_f32_16x16x32_bf16 v[106:109], v[162:165], v[198:201], 0
	v_mfma_f32_16x16x32_bf16 v[98:101], v[154:157], v[206:209], 0
	v_mfma_f32_16x16x32_bf16 v[90:93], v[162:165], v[206:209], 0
	v_mfma_f32_16x16x32_bf16 v[82:85], v[154:157], v[214:217], 0
	v_mfma_f32_16x16x32_bf16 v[74:77], v[162:165], v[214:217], 0
	v_mfma_f32_16x16x32_bf16 v[126:129], v[158:161], v[194:197], v[126:129]
	v_mfma_f32_16x16x32_bf16 v[122:125], v[166:169], v[194:197], v[122:125]
	v_mfma_f32_16x16x32_bf16 v[114:117], v[158:161], v[202:205], v[114:117]
	v_mfma_f32_16x16x32_bf16 v[106:109], v[166:169], v[202:205], v[106:109]
	v_mfma_f32_16x16x32_bf16 v[98:101], v[158:161], v[210:213], v[98:101]
	v_mfma_f32_16x16x32_bf16 v[90:93], v[166:169], v[210:213], v[90:93]
	v_mfma_f32_16x16x32_bf16 v[82:85], v[158:161], v[218:221], v[82:85]
	v_mfma_f32_16x16x32_bf16 v[74:77], v[166:169], v[218:221], v[74:77]
	v_mfma_f32_16x16x32_bf16 v[118:121], v[170:173], v[190:193], 0
	v_mfma_f32_16x16x32_bf16 v[110:113], v[182:185], v[190:193], 0
	v_mfma_f32_16x16x32_bf16 v[102:105], v[170:173], v[198:201], 0
	v_mfma_f32_16x16x32_bf16 v[94:97], v[182:185], v[198:201], 0
	v_mfma_f32_16x16x32_bf16 v[86:89], v[170:173], v[206:209], 0
	v_mfma_f32_16x16x32_bf16 v[78:81], v[182:185], v[206:209], 0
	v_mfma_f32_16x16x32_bf16 v[70:73], v[170:173], v[214:217], 0
	v_mfma_f32_16x16x32_bf16 v[66:69], v[182:185], v[214:217], 0
	v_mfma_f32_16x16x32_bf16 v[118:121], v[178:181], v[194:197], v[118:121]
	v_mfma_f32_16x16x32_bf16 v[110:113], v[186:189], v[194:197], v[110:113]
	v_mfma_f32_16x16x32_bf16 v[102:105], v[178:181], v[202:205], v[102:105]
	v_mfma_f32_16x16x32_bf16 v[94:97], v[186:189], v[202:205], v[94:97]
	v_mfma_f32_16x16x32_bf16 v[86:89], v[178:181], v[210:213], v[86:89]
	v_mfma_f32_16x16x32_bf16 v[78:81], v[186:189], v[210:213], v[78:81]
	v_mfma_f32_16x16x32_bf16 v[70:73], v[178:181], v[218:221], v[70:73]
	v_mfma_f32_16x16x32_bf16 v[66:69], v[186:189], v[218:221], v[66:69]
	s_barrier
	s_setprio 0
	s_add_i32 s53, s44, s34
	v_lshl_add_u64 v[144:145], s[28:29], 0, v[134:135]
	s_mov_b32 m0, s53
	ds_read_b128 v[190:193], v153 offset:16384
	ds_read_b128 v[194:197], v153 offset:17408
	ds_read_b128 v[198:201], v153 offset:18432
	ds_read_b128 v[202:205], v153 offset:19456
	ds_read_b128 v[206:209], v153 offset:20480
	ds_read_b128 v[210:213], v153 offset:21504
	ds_read_b128 v[214:217], v153 offset:22528
	ds_read_b128 v[218:221], v153 offset:23552
	global_load_lds_dwordx4 v[144:145], off
	s_add_i32 m0, s53, 0x2000
	s_add_u32 s54, s28, 0x40000
	v_lshl_add_u64 v[174:175], s[28:29], 0, v[130:131]
	s_addc_u32 s55, s29, 0
	s_add_i32 s53, s45, s34
	global_load_lds_dwordx4 v[174:175], off
	v_lshl_add_u64 v[222:223], s[54:55], 0, v[134:135]
	s_mov_b32 m0, s53
	v_lshl_add_u64 v[224:225], s[2:3], 0, v[132:133]
	global_load_lds_dwordx4 v[222:223], off
	v_lshl_add_u64 v[222:223], s[54:55], 0, v[130:131]
	s_add_i32 m0, s53, 0x2000
	s_nop 0
	global_load_lds_dwordx4 v[222:223], off
	v_lshl_add_u64 v[222:223], s[2:3], 0, v[136:137]
	s_mov_b32 m0, s37
	s_nop 0
	global_load_lds_dwordx4 v[222:223], off
	s_mov_b32 m0, s25
	s_nop 0
	global_load_lds_dwordx4 v[224:225], off
	s_waitcnt vmcnt(8)
	s_waitcnt lgkmcnt(0)
	s_setprio 2
	s_barrier
	v_mfma_f32_16x16x32_bf16 v[62:65], v[154:157], v[190:193], 0
	v_mfma_f32_16x16x32_bf16 v[58:61], v[162:165], v[190:193], 0
	v_mfma_f32_16x16x32_bf16 v[50:53], v[154:157], v[198:201], 0
	v_mfma_f32_16x16x32_bf16 v[42:45], v[162:165], v[198:201], 0
	v_mfma_f32_16x16x32_bf16 v[34:37], v[154:157], v[206:209], 0
	v_mfma_f32_16x16x32_bf16 v[26:29], v[162:165], v[206:209], 0
	v_mfma_f32_16x16x32_bf16 v[18:21], v[154:157], v[214:217], 0
	v_mfma_f32_16x16x32_bf16 v[10:13], v[162:165], v[214:217], 0
	v_mfma_f32_16x16x32_bf16 v[62:65], v[158:161], v[194:197], v[62:65]
	v_mfma_f32_16x16x32_bf16 v[58:61], v[166:169], v[194:197], v[58:61]
	v_mfma_f32_16x16x32_bf16 v[50:53], v[158:161], v[202:205], v[50:53]
	v_mfma_f32_16x16x32_bf16 v[42:45], v[166:169], v[202:205], v[42:45]
	v_mfma_f32_16x16x32_bf16 v[34:37], v[158:161], v[210:213], v[34:37]
	v_mfma_f32_16x16x32_bf16 v[26:29], v[166:169], v[210:213], v[26:29]
	v_mfma_f32_16x16x32_bf16 v[18:21], v[158:161], v[218:221], v[18:21]
	v_mfma_f32_16x16x32_bf16 v[10:13], v[166:169], v[218:221], v[10:13]
	v_mfma_f32_16x16x32_bf16 v[54:57], v[170:173], v[190:193], 0
	v_mfma_f32_16x16x32_bf16 v[46:49], v[182:185], v[190:193], 0
	v_mfma_f32_16x16x32_bf16 v[38:41], v[170:173], v[198:201], 0
	v_mfma_f32_16x16x32_bf16 v[30:33], v[182:185], v[198:201], 0
	v_mfma_f32_16x16x32_bf16 v[22:25], v[170:173], v[206:209], 0
	v_mfma_f32_16x16x32_bf16 v[14:17], v[182:185], v[206:209], 0
	v_mfma_f32_16x16x32_bf16 v[6:9], v[170:173], v[214:217], 0
	v_mfma_f32_16x16x32_bf16 v[2:5], v[182:185], v[214:217], 0
	v_mfma_f32_16x16x32_bf16 v[54:57], v[178:181], v[194:197], v[54:57]
	v_mfma_f32_16x16x32_bf16 v[46:49], v[186:189], v[194:197], v[46:49]
	v_mfma_f32_16x16x32_bf16 v[38:41], v[178:181], v[202:205], v[38:41]
	v_mfma_f32_16x16x32_bf16 v[30:33], v[186:189], v[202:205], v[30:33]
	v_mfma_f32_16x16x32_bf16 v[22:25], v[178:181], v[210:213], v[22:25]
	v_mfma_f32_16x16x32_bf16 v[14:17], v[186:189], v[210:213], v[14:17]
	v_mfma_f32_16x16x32_bf16 v[6:9], v[178:181], v[218:221], v[6:9]
	v_mfma_f32_16x16x32_bf16 v[2:5], v[186:189], v[218:221], v[2:5]
	s_barrier
	s_setprio 0
	s_add_i32 s53, 0, 0x18000
	s_add_i32 s54, 0, 0x1c000
	v_add_u32_e32 v166, s53, v149
	v_add_u32_e32 v176, s54, v149
	ds_read_b128 v[154:157], v166
	ds_read_b128 v[158:161], v166 offset:1024
	ds_read_b128 v[162:165], v166 offset:2048
	ds_read_b128 v[166:169], v166 offset:3072
	ds_read_b128 v[170:173], v176
	ds_read_b128 v[178:181], v176 offset:1024
	ds_read_b128 v[182:185], v176 offset:2048
	ds_read_b128 v[186:189], v176 offset:3072
	s_add_u32 s2, s2, 0x40000
	s_addc_u32 s3, s3, 0
	s_mov_b32 m0, s38
	v_lshl_add_u64 v[226:227], s[2:3], 0, v[136:137]
	ds_read_b128 v[190:193], v153 offset:32768
	ds_read_b128 v[194:197], v153 offset:33792
	ds_read_b128 v[198:201], v153 offset:34816
	ds_read_b128 v[202:205], v153 offset:35840
	ds_read_b128 v[206:209], v153 offset:36864
	ds_read_b128 v[210:213], v153 offset:37888
	ds_read_b128 v[214:217], v153 offset:38912
	ds_read_b128 v[218:221], v153 offset:39936
	global_load_lds_dwordx4 v[226:227], off
	v_lshl_add_u64 v[226:227], s[2:3], 0, v[132:133]
	s_mov_b32 m0, s39
	s_nop 0
	global_load_lds_dwordx4 v[226:227], off
	s_waitcnt vmcnt(8)
	s_waitcnt lgkmcnt(0)
	s_setprio 2
	s_barrier
	v_mfma_f32_16x16x32_bf16 v[126:129], v[154:157], v[190:193], v[126:129]
	v_mfma_f32_16x16x32_bf16 v[122:125], v[162:165], v[190:193], v[122:125]
	v_mfma_f32_16x16x32_bf16 v[114:117], v[154:157], v[198:201], v[114:117]
	v_mfma_f32_16x16x32_bf16 v[106:109], v[162:165], v[198:201], v[106:109]
	v_mfma_f32_16x16x32_bf16 v[98:101], v[154:157], v[206:209], v[98:101]
	v_mfma_f32_16x16x32_bf16 v[90:93], v[162:165], v[206:209], v[90:93]
	v_mfma_f32_16x16x32_bf16 v[82:85], v[154:157], v[214:217], v[82:85]
	v_mfma_f32_16x16x32_bf16 v[74:77], v[162:165], v[214:217], v[74:77]
	v_mfma_f32_16x16x32_bf16 v[126:129], v[158:161], v[194:197], v[126:129]
	v_mfma_f32_16x16x32_bf16 v[122:125], v[166:169], v[194:197], v[122:125]
	v_mfma_f32_16x16x32_bf16 v[114:117], v[158:161], v[202:205], v[114:117]
	v_mfma_f32_16x16x32_bf16 v[106:109], v[166:169], v[202:205], v[106:109]
	v_mfma_f32_16x16x32_bf16 v[98:101], v[158:161], v[210:213], v[98:101]
	v_mfma_f32_16x16x32_bf16 v[90:93], v[166:169], v[210:213], v[90:93]
	v_mfma_f32_16x16x32_bf16 v[82:85], v[158:161], v[218:221], v[82:85]
	v_mfma_f32_16x16x32_bf16 v[74:77], v[166:169], v[218:221], v[74:77]
	v_mfma_f32_16x16x32_bf16 v[118:121], v[170:173], v[190:193], v[118:121]
	v_mfma_f32_16x16x32_bf16 v[110:113], v[182:185], v[190:193], v[110:113]
	v_mfma_f32_16x16x32_bf16 v[102:105], v[170:173], v[198:201], v[102:105]
	v_mfma_f32_16x16x32_bf16 v[94:97], v[182:185], v[198:201], v[94:97]
	v_mfma_f32_16x16x32_bf16 v[86:89], v[170:173], v[206:209], v[86:89]
	v_mfma_f32_16x16x32_bf16 v[78:81], v[182:185], v[206:209], v[78:81]
	v_mfma_f32_16x16x32_bf16 v[70:73], v[170:173], v[214:217], v[70:73]
	v_mfma_f32_16x16x32_bf16 v[66:69], v[182:185], v[214:217], v[66:69]
	v_mfma_f32_16x16x32_bf16 v[118:121], v[178:181], v[194:197], v[118:121]
	v_mfma_f32_16x16x32_bf16 v[110:113], v[186:189], v[194:197], v[110:113]
	v_mfma_f32_16x16x32_bf16 v[102:105], v[178:181], v[202:205], v[102:105]
	v_mfma_f32_16x16x32_bf16 v[94:97], v[186:189], v[202:205], v[94:97]
	v_mfma_f32_16x16x32_bf16 v[86:89], v[178:181], v[210:213], v[86:89]
	v_mfma_f32_16x16x32_bf16 v[78:81], v[186:189], v[210:213], v[78:81]
	v_mfma_f32_16x16x32_bf16 v[70:73], v[178:181], v[218:221], v[70:73]
	v_mfma_f32_16x16x32_bf16 v[66:69], v[186:189], v[218:221], v[66:69]
	s_barrier
	s_setprio 0
	s_add_i32 s2, s53, s34
	v_lshl_add_u64 v[144:145], v[144:145], 0, s[6:7]
	s_mov_b32 m0, s2
	ds_read_b128 v[190:193], v153 offset:49152
	ds_read_b128 v[194:197], v153 offset:50176
	ds_read_b128 v[198:201], v153 offset:51200
	ds_read_b128 v[202:205], v153 offset:52224
	ds_read_b128 v[206:209], v153 offset:53248
	ds_read_b128 v[210:213], v153 offset:54272
	ds_read_b128 v[214:217], v153 offset:55296
	ds_read_b128 v[218:221], v153 offset:56320
	global_load_lds_dwordx4 v[144:145], off
	s_add_i32 m0, s2, 0x2000
	s_add_u32 s2, s28, 0x40080
	v_lshl_add_u64 v[144:145], v[174:175], 0, s[6:7]
	s_addc_u32 s3, s29, 0
	s_add_i32 s28, s54, s34
	global_load_lds_dwordx4 v[144:145], off
	v_lshl_add_u64 v[144:145], s[2:3], 0, v[134:135]
	s_mov_b32 m0, s28
	s_nop 0
	global_load_lds_dwordx4 v[144:145], off
	v_lshl_add_u64 v[144:145], s[2:3], 0, v[130:131]
	s_add_i32 m0, s28, 0x2000
	s_nop 0
	global_load_lds_dwordx4 v[144:145], off
	v_lshl_add_u64 v[144:145], v[222:223], 0, s[6:7]
	s_mov_b32 m0, s41
	s_nop 0
	global_load_lds_dwordx4 v[144:145], off
	v_lshl_add_u64 v[144:145], v[224:225], 0, s[6:7]
	s_mov_b32 m0, s42
	s_nop 0
	global_load_lds_dwordx4 v[144:145], off
	s_waitcnt vmcnt(8)
	s_waitcnt lgkmcnt(0)
	s_setprio 2
	s_barrier
	v_mfma_f32_16x16x32_bf16 v[62:65], v[154:157], v[190:193], v[62:65]
	v_mfma_f32_16x16x32_bf16 v[58:61], v[162:165], v[190:193], v[58:61]
	v_mfma_f32_16x16x32_bf16 v[50:53], v[154:157], v[198:201], v[50:53]
	v_mfma_f32_16x16x32_bf16 v[42:45], v[162:165], v[198:201], v[42:45]
	v_mfma_f32_16x16x32_bf16 v[34:37], v[154:157], v[206:209], v[34:37]
	v_mfma_f32_16x16x32_bf16 v[26:29], v[162:165], v[206:209], v[26:29]
	v_mfma_f32_16x16x32_bf16 v[18:21], v[154:157], v[214:217], v[18:21]
	v_mfma_f32_16x16x32_bf16 v[10:13], v[162:165], v[214:217], v[10:13]
	v_mfma_f32_16x16x32_bf16 v[62:65], v[158:161], v[194:197], v[62:65]
	v_mfma_f32_16x16x32_bf16 v[58:61], v[166:169], v[194:197], v[58:61]
	v_mfma_f32_16x16x32_bf16 v[50:53], v[158:161], v[202:205], v[50:53]
	v_mfma_f32_16x16x32_bf16 v[42:45], v[166:169], v[202:205], v[42:45]
	v_mfma_f32_16x16x32_bf16 v[34:37], v[158:161], v[210:213], v[34:37]
	v_mfma_f32_16x16x32_bf16 v[26:29], v[166:169], v[210:213], v[26:29]
	v_mfma_f32_16x16x32_bf16 v[18:21], v[158:161], v[218:221], v[18:21]
	v_mfma_f32_16x16x32_bf16 v[10:13], v[166:169], v[218:221], v[10:13]
	v_mfma_f32_16x16x32_bf16 v[54:57], v[170:173], v[190:193], v[54:57]
	v_mfma_f32_16x16x32_bf16 v[46:49], v[182:185], v[190:193], v[46:49]
	v_mfma_f32_16x16x32_bf16 v[38:41], v[170:173], v[198:201], v[38:41]
	v_mfma_f32_16x16x32_bf16 v[30:33], v[182:185], v[198:201], v[30:33]
	v_mfma_f32_16x16x32_bf16 v[22:25], v[170:173], v[206:209], v[22:25]
	v_mfma_f32_16x16x32_bf16 v[14:17], v[182:185], v[206:209], v[14:17]
	v_mfma_f32_16x16x32_bf16 v[6:9], v[170:173], v[214:217], v[6:9]
	v_mfma_f32_16x16x32_bf16 v[2:5], v[182:185], v[214:217], v[2:5]
	v_mfma_f32_16x16x32_bf16 v[54:57], v[178:181], v[194:197], v[54:57]
	v_mfma_f32_16x16x32_bf16 v[46:49], v[186:189], v[194:197], v[46:49]
	v_mfma_f32_16x16x32_bf16 v[38:41], v[178:181], v[202:205], v[38:41]
	v_mfma_f32_16x16x32_bf16 v[30:33], v[186:189], v[202:205], v[30:33]
	v_mfma_f32_16x16x32_bf16 v[22:25], v[178:181], v[210:213], v[22:25]
	v_mfma_f32_16x16x32_bf16 v[14:17], v[186:189], v[210:213], v[14:17]
	v_mfma_f32_16x16x32_bf16 v[6:9], v[178:181], v[218:221], v[6:9]
	v_mfma_f32_16x16x32_bf16 v[2:5], v[186:189], v[218:221], v[2:5]
	s_barrier
	s_setprio 0
	s_add_i32 s52, s52, 2
	s_add_u32 s26, s26, 0x100
	s_addc_u32 s27, s27, 0
	s_add_u32 s50, s50, 0x100
	s_addc_u32 s51, s51, 0
	s_cmp_gt_u32 s52, 13
	s_cbranch_scc0 .LBB0_555
	s_branch .Lpk555_exit
.LBB0_555:
	ds_read_b128 v[154:157], v151
	ds_read_b128 v[158:161], v151 offset:1024
	ds_read_b128 v[162:165], v151 offset:2048
	ds_read_b128 v[166:169], v151 offset:3072
	ds_read_b128 v[170:173], v152
	ds_read_b128 v[178:181], v152 offset:1024
	ds_read_b128 v[182:185], v152 offset:2048
	ds_read_b128 v[186:189], v152 offset:3072
	s_add_u32 s2, s26, 0xfffc0080
	s_addc_u32 s3, s27, -1
	s_cmp_eq_u32 s52, 12
	s_cselect_b32 s3, s11, s3
	s_cselect_b32 s2, s13, s2
	s_cselect_b32 s29, s48, s51
	s_cselect_b32 s28, s49, s50
	v_lshl_add_u64 v[144:145], s[26:27], 0, v[138:139]
	s_add_i32 m0, s37, 0xc000
	ds_read_b128 v[190:193], v153
	ds_read_b128 v[194:197], v153 offset:1024
	ds_read_b128 v[198:201], v153 offset:2048
	ds_read_b128 v[202:205], v153 offset:3072
	ds_read_b128 v[206:209], v153 offset:4096
	ds_read_b128 v[210:213], v153 offset:5120
	ds_read_b128 v[214:217], v153 offset:6144
	ds_read_b128 v[218:221], v153 offset:7168
	global_load_lds_dwordx4 v[144:145], off
	v_lshl_add_u64 v[144:145], s[26:27], 0, v[140:141]
	s_add_i32 m0, s37, 0xe000
	s_nop 0
	global_load_lds_dwordx4 v[144:145], off
	s_waitcnt vmcnt(8)
	s_waitcnt lgkmcnt(0)
	s_setprio 2
	s_barrier
	v_mfma_f32_16x16x32_bf16 v[126:129], v[154:157], v[190:193], v[126:129]
	v_mfma_f32_16x16x32_bf16 v[122:125], v[162:165], v[190:193], v[122:125]
	v_mfma_f32_16x16x32_bf16 v[114:117], v[154:157], v[198:201], v[114:117]
	v_mfma_f32_16x16x32_bf16 v[106:109], v[162:165], v[198:201], v[106:109]
	v_mfma_f32_16x16x32_bf16 v[98:101], v[154:157], v[206:209], v[98:101]
	v_mfma_f32_16x16x32_bf16 v[90:93], v[162:165], v[206:209], v[90:93]
	v_mfma_f32_16x16x32_bf16 v[82:85], v[154:157], v[214:217], v[82:85]
	v_mfma_f32_16x16x32_bf16 v[74:77], v[162:165], v[214:217], v[74:77]
	v_mfma_f32_16x16x32_bf16 v[126:129], v[158:161], v[194:197], v[126:129]
	v_mfma_f32_16x16x32_bf16 v[122:125], v[166:169], v[194:197], v[122:125]
	v_mfma_f32_16x16x32_bf16 v[114:117], v[158:161], v[202:205], v[114:117]
	v_mfma_f32_16x16x32_bf16 v[106:109], v[166:169], v[202:205], v[106:109]
	v_mfma_f32_16x16x32_bf16 v[98:101], v[158:161], v[210:213], v[98:101]
	v_mfma_f32_16x16x32_bf16 v[90:93], v[166:169], v[210:213], v[90:93]
	v_mfma_f32_16x16x32_bf16 v[82:85], v[158:161], v[218:221], v[82:85]
	v_mfma_f32_16x16x32_bf16 v[74:77], v[166:169], v[218:221], v[74:77]
	v_mfma_f32_16x16x32_bf16 v[118:121], v[170:173], v[190:193], v[118:121]
	v_mfma_f32_16x16x32_bf16 v[110:113], v[182:185], v[190:193], v[110:113]
	v_mfma_f32_16x16x32_bf16 v[102:105], v[170:173], v[198:201], v[102:105]
	v_mfma_f32_16x16x32_bf16 v[94:97], v[182:185], v[198:201], v[94:97]
	v_mfma_f32_16x16x32_bf16 v[86:89], v[170:173], v[206:209], v[86:89]
	v_mfma_f32_16x16x32_bf16 v[78:81], v[182:185], v[206:209], v[78:81]
	v_mfma_f32_16x16x32_bf16 v[70:73], v[170:173], v[214:217], v[70:73]
	v_mfma_f32_16x16x32_bf16 v[66:69], v[182:185], v[214:217], v[66:69]
	v_mfma_f32_16x16x32_bf16 v[118:121], v[178:181], v[194:197], v[118:121]
	v_mfma_f32_16x16x32_bf16 v[110:113], v[186:189], v[194:197], v[110:113]
	v_mfma_f32_16x16x32_bf16 v[102:105], v[178:181], v[202:205], v[102:105]
	v_mfma_f32_16x16x32_bf16 v[94:97], v[186:189], v[202:205], v[94:97]
	v_mfma_f32_16x16x32_bf16 v[86:89], v[178:181], v[210:213], v[86:89]
	v_mfma_f32_16x16x32_bf16 v[78:81], v[186:189], v[210:213], v[78:81]
	v_mfma_f32_16x16x32_bf16 v[70:73], v[178:181], v[218:221], v[70:73]
	v_mfma_f32_16x16x32_bf16 v[66:69], v[186:189], v[218:221], v[66:69]
	s_barrier
	s_setprio 0
	s_add_i32 s53, s44, s34
	v_lshl_add_u64 v[144:145], s[28:29], 0, v[134:135]
	s_mov_b32 m0, s53
	ds_read_b128 v[190:193], v153 offset:16384
	ds_read_b128 v[194:197], v153 offset:17408
	ds_read_b128 v[198:201], v153 offset:18432
	ds_read_b128 v[202:205], v153 offset:19456
	ds_read_b128 v[206:209], v153 offset:20480
	ds_read_b128 v[210:213], v153 offset:21504
	ds_read_b128 v[214:217], v153 offset:22528
	ds_read_b128 v[218:221], v153 offset:23552
	global_load_lds_dwordx4 v[144:145], off
	s_add_i32 m0, s53, 0x2000
	s_add_u32 s54, s28, 0x40000
	v_lshl_add_u64 v[174:175], s[28:29], 0, v[130:131]
	s_addc_u32 s55, s29, 0
	s_add_i32 s53, s45, s34
	global_load_lds_dwordx4 v[174:175], off
	v_lshl_add_u64 v[222:223], s[54:55], 0, v[134:135]
	s_mov_b32 m0, s53
	v_lshl_add_u64 v[224:225], s[2:3], 0, v[132:133]
	global_load_lds_dwordx4 v[222:223], off
	v_lshl_add_u64 v[222:223], s[54:55], 0, v[130:131]
	s_add_i32 m0, s53, 0x2000
	s_nop 0
	global_load_lds_dwordx4 v[222:223], off
	v_lshl_add_u64 v[222:223], s[2:3], 0, v[136:137]
	s_mov_b32 m0, s37
	s_nop 0
	global_load_lds_dwordx4 v[222:223], off
	s_mov_b32 m0, s25
	s_nop 0
	global_load_lds_dwordx4 v[224:225], off
	s_waitcnt vmcnt(8)
	s_waitcnt lgkmcnt(0)
	s_setprio 2
	s_barrier
	v_mfma_f32_16x16x32_bf16 v[62:65], v[154:157], v[190:193], v[62:65]
	v_mfma_f32_16x16x32_bf16 v[58:61], v[162:165], v[190:193], v[58:61]
	v_mfma_f32_16x16x32_bf16 v[50:53], v[154:157], v[198:201], v[50:53]
	v_mfma_f32_16x16x32_bf16 v[42:45], v[162:165], v[198:201], v[42:45]
	v_mfma_f32_16x16x32_bf16 v[34:37], v[154:157], v[206:209], v[34:37]
	v_mfma_f32_16x16x32_bf16 v[26:29], v[162:165], v[206:209], v[26:29]
	v_mfma_f32_16x16x32_bf16 v[18:21], v[154:157], v[214:217], v[18:21]
	v_mfma_f32_16x16x32_bf16 v[10:13], v[162:165], v[214:217], v[10:13]
	v_mfma_f32_16x16x32_bf16 v[62:65], v[158:161], v[194:197], v[62:65]
	v_mfma_f32_16x16x32_bf16 v[58:61], v[166:169], v[194:197], v[58:61]
	v_mfma_f32_16x16x32_bf16 v[50:53], v[158:161], v[202:205], v[50:53]
	v_mfma_f32_16x16x32_bf16 v[42:45], v[166:169], v[202:205], v[42:45]
	v_mfma_f32_16x16x32_bf16 v[34:37], v[158:161], v[210:213], v[34:37]
	v_mfma_f32_16x16x32_bf16 v[26:29], v[166:169], v[210:213], v[26:29]
	v_mfma_f32_16x16x32_bf16 v[18:21], v[158:161], v[218:221], v[18:21]
	v_mfma_f32_16x16x32_bf16 v[10:13], v[166:169], v[218:221], v[10:13]
	v_mfma_f32_16x16x32_bf16 v[54:57], v[170:173], v[190:193], v[54:57]
	v_mfma_f32_16x16x32_bf16 v[46:49], v[182:185], v[190:193], v[46:49]
	v_mfma_f32_16x16x32_bf16 v[38:41], v[170:173], v[198:201], v[38:41]
	v_mfma_f32_16x16x32_bf16 v[30:33], v[182:185], v[198:201], v[30:33]
	v_mfma_f32_16x16x32_bf16 v[22:25], v[170:173], v[206:209], v[22:25]
	v_mfma_f32_16x16x32_bf16 v[14:17], v[182:185], v[206:209], v[14:17]
	v_mfma_f32_16x16x32_bf16 v[6:9], v[170:173], v[214:217], v[6:9]
	v_mfma_f32_16x16x32_bf16 v[2:5], v[182:185], v[214:217], v[2:5]
	v_mfma_f32_16x16x32_bf16 v[54:57], v[178:181], v[194:197], v[54:57]
	v_mfma_f32_16x16x32_bf16 v[46:49], v[186:189], v[194:197], v[46:49]
	v_mfma_f32_16x16x32_bf16 v[38:41], v[178:181], v[202:205], v[38:41]
	v_mfma_f32_16x16x32_bf16 v[30:33], v[186:189], v[202:205], v[30:33]
	v_mfma_f32_16x16x32_bf16 v[22:25], v[178:181], v[210:213], v[22:25]
	v_mfma_f32_16x16x32_bf16 v[14:17], v[186:189], v[210:213], v[14:17]
	v_mfma_f32_16x16x32_bf16 v[6:9], v[178:181], v[218:221], v[6:9]
	v_mfma_f32_16x16x32_bf16 v[2:5], v[186:189], v[218:221], v[2:5]
	s_barrier
	s_setprio 0
	s_add_i32 s53, 0, 0x18000
	s_add_i32 s54, 0, 0x1c000
	v_add_u32_e32 v166, s53, v149
	v_add_u32_e32 v176, s54, v149
	ds_read_b128 v[154:157], v166
	ds_read_b128 v[158:161], v166 offset:1024
	ds_read_b128 v[162:165], v166 offset:2048
	ds_read_b128 v[166:169], v166 offset:3072
	ds_read_b128 v[170:173], v176
	ds_read_b128 v[178:181], v176 offset:1024
	ds_read_b128 v[182:185], v176 offset:2048
	ds_read_b128 v[186:189], v176 offset:3072
	s_add_u32 s2, s2, 0x40000
	s_addc_u32 s3, s3, 0
	s_mov_b32 m0, s38
	v_lshl_add_u64 v[226:227], s[2:3], 0, v[136:137]
	ds_read_b128 v[190:193], v153 offset:32768
	ds_read_b128 v[194:197], v153 offset:33792
	ds_read_b128 v[198:201], v153 offset:34816
	ds_read_b128 v[202:205], v153 offset:35840
	ds_read_b128 v[206:209], v153 offset:36864
	ds_read_b128 v[210:213], v153 offset:37888
	ds_read_b128 v[214:217], v153 offset:38912
	ds_read_b128 v[218:221], v153 offset:39936
	global_load_lds_dwordx4 v[226:227], off
	v_lshl_add_u64 v[226:227], s[2:3], 0, v[132:133]
	s_mov_b32 m0, s39
	s_nop 0
	global_load_lds_dwordx4 v[226:227], off
	s_waitcnt vmcnt(8)
	s_waitcnt lgkmcnt(0)
	s_setprio 2
	s_barrier
	v_mfma_f32_16x16x32_bf16 v[126:129], v[154:157], v[190:193], v[126:129]
	v_mfma_f32_16x16x32_bf16 v[122:125], v[162:165], v[190:193], v[122:125]
	v_mfma_f32_16x16x32_bf16 v[114:117], v[154:157], v[198:201], v[114:117]
	v_mfma_f32_16x16x32_bf16 v[106:109], v[162:165], v[198:201], v[106:109]
	v_mfma_f32_16x16x32_bf16 v[98:101], v[154:157], v[206:209], v[98:101]
	v_mfma_f32_16x16x32_bf16 v[90:93], v[162:165], v[206:209], v[90:93]
	v_mfma_f32_16x16x32_bf16 v[82:85], v[154:157], v[214:217], v[82:85]
	v_mfma_f32_16x16x32_bf16 v[74:77], v[162:165], v[214:217], v[74:77]
	v_mfma_f32_16x16x32_bf16 v[126:129], v[158:161], v[194:197], v[126:129]
	v_mfma_f32_16x16x32_bf16 v[122:125], v[166:169], v[194:197], v[122:125]
	v_mfma_f32_16x16x32_bf16 v[114:117], v[158:161], v[202:205], v[114:117]
	v_mfma_f32_16x16x32_bf16 v[106:109], v[166:169], v[202:205], v[106:109]
	v_mfma_f32_16x16x32_bf16 v[98:101], v[158:161], v[210:213], v[98:101]
	v_mfma_f32_16x16x32_bf16 v[90:93], v[166:169], v[210:213], v[90:93]
	v_mfma_f32_16x16x32_bf16 v[82:85], v[158:161], v[218:221], v[82:85]
	v_mfma_f32_16x16x32_bf16 v[74:77], v[166:169], v[218:221], v[74:77]
	v_mfma_f32_16x16x32_bf16 v[118:121], v[170:173], v[190:193], v[118:121]
	v_mfma_f32_16x16x32_bf16 v[110:113], v[182:185], v[190:193], v[110:113]
	v_mfma_f32_16x16x32_bf16 v[102:105], v[170:173], v[198:201], v[102:105]
	v_mfma_f32_16x16x32_bf16 v[94:97], v[182:185], v[198:201], v[94:97]
	v_mfma_f32_16x16x32_bf16 v[86:89], v[170:173], v[206:209], v[86:89]
	v_mfma_f32_16x16x32_bf16 v[78:81], v[182:185], v[206:209], v[78:81]
	v_mfma_f32_16x16x32_bf16 v[70:73], v[170:173], v[214:217], v[70:73]
	v_mfma_f32_16x16x32_bf16 v[66:69], v[182:185], v[214:217], v[66:69]
	v_mfma_f32_16x16x32_bf16 v[118:121], v[178:181], v[194:197], v[118:121]
	v_mfma_f32_16x16x32_bf16 v[110:113], v[186:189], v[194:197], v[110:113]
	v_mfma_f32_16x16x32_bf16 v[102:105], v[178:181], v[202:205], v[102:105]
	v_mfma_f32_16x16x32_bf16 v[94:97], v[186:189], v[202:205], v[94:97]
	v_mfma_f32_16x16x32_bf16 v[86:89], v[178:181], v[210:213], v[86:89]
	v_mfma_f32_16x16x32_bf16 v[78:81], v[186:189], v[210:213], v[78:81]
	v_mfma_f32_16x16x32_bf16 v[70:73], v[178:181], v[218:221], v[70:73]
	v_mfma_f32_16x16x32_bf16 v[66:69], v[186:189], v[218:221], v[66:69]
	s_barrier
	s_setprio 0
	s_add_i32 s2, s53, s34
	v_lshl_add_u64 v[144:145], v[144:145], 0, s[6:7]
	s_mov_b32 m0, s2
	ds_read_b128 v[190:193], v153 offset:49152
	ds_read_b128 v[194:197], v153 offset:50176
	ds_read_b128 v[198:201], v153 offset:51200
	ds_read_b128 v[202:205], v153 offset:52224
	ds_read_b128 v[206:209], v153 offset:53248
	ds_read_b128 v[210:213], v153 offset:54272
	ds_read_b128 v[214:217], v153 offset:55296
	ds_read_b128 v[218:221], v153 offset:56320
	global_load_lds_dwordx4 v[144:145], off
	s_add_i32 m0, s2, 0x2000
	s_add_u32 s2, s28, 0x40080
	v_lshl_add_u64 v[144:145], v[174:175], 0, s[6:7]
	s_addc_u32 s3, s29, 0
	s_add_i32 s28, s54, s34
	global_load_lds_dwordx4 v[144:145], off
	v_lshl_add_u64 v[144:145], s[2:3], 0, v[134:135]
	s_mov_b32 m0, s28
	s_nop 0
	global_load_lds_dwordx4 v[144:145], off
	v_lshl_add_u64 v[144:145], s[2:3], 0, v[130:131]
	s_add_i32 m0, s28, 0x2000
	s_nop 0
	global_load_lds_dwordx4 v[144:145], off
	v_lshl_add_u64 v[144:145], v[222:223], 0, s[6:7]
	s_mov_b32 m0, s41
	s_nop 0
	global_load_lds_dwordx4 v[144:145], off
	v_lshl_add_u64 v[144:145], v[224:225], 0, s[6:7]
	s_mov_b32 m0, s42
	s_nop 0
	global_load_lds_dwordx4 v[144:145], off
	s_waitcnt vmcnt(8)
	s_waitcnt lgkmcnt(0)
	s_setprio 2
	s_barrier
	v_mfma_f32_16x16x32_bf16 v[62:65], v[154:157], v[190:193], v[62:65]
	v_mfma_f32_16x16x32_bf16 v[58:61], v[162:165], v[190:193], v[58:61]
	v_mfma_f32_16x16x32_bf16 v[50:53], v[154:157], v[198:201], v[50:53]
	v_mfma_f32_16x16x32_bf16 v[42:45], v[162:165], v[198:201], v[42:45]
	v_mfma_f32_16x16x32_bf16 v[34:37], v[154:157], v[206:209], v[34:37]
	v_mfma_f32_16x16x32_bf16 v[26:29], v[162:165], v[206:209], v[26:29]
	v_mfma_f32_16x16x32_bf16 v[18:21], v[154:157], v[214:217], v[18:21]
	v_mfma_f32_16x16x32_bf16 v[10:13], v[162:165], v[214:217], v[10:13]
	v_mfma_f32_16x16x32_bf16 v[62:65], v[158:161], v[194:197], v[62:65]
	v_mfma_f32_16x16x32_bf16 v[58:61], v[166:169], v[194:197], v[58:61]
	v_mfma_f32_16x16x32_bf16 v[50:53], v[158:161], v[202:205], v[50:53]
	v_mfma_f32_16x16x32_bf16 v[42:45], v[166:169], v[202:205], v[42:45]
	v_mfma_f32_16x16x32_bf16 v[34:37], v[158:161], v[210:213], v[34:37]
	v_mfma_f32_16x16x32_bf16 v[26:29], v[166:169], v[210:213], v[26:29]
	v_mfma_f32_16x16x32_bf16 v[18:21], v[158:161], v[218:221], v[18:21]
	v_mfma_f32_16x16x32_bf16 v[10:13], v[166:169], v[218:221], v[10:13]
	v_mfma_f32_16x16x32_bf16 v[54:57], v[170:173], v[190:193], v[54:57]
	v_mfma_f32_16x16x32_bf16 v[46:49], v[182:185], v[190:193], v[46:49]
	v_mfma_f32_16x16x32_bf16 v[38:41], v[170:173], v[198:201], v[38:41]
	v_mfma_f32_16x16x32_bf16 v[30:33], v[182:185], v[198:201], v[30:33]
	v_mfma_f32_16x16x32_bf16 v[22:25], v[170:173], v[206:209], v[22:25]
	v_mfma_f32_16x16x32_bf16 v[14:17], v[182:185], v[206:209], v[14:17]
	v_mfma_f32_16x16x32_bf16 v[6:9], v[170:173], v[214:217], v[6:9]
	v_mfma_f32_16x16x32_bf16 v[2:5], v[182:185], v[214:217], v[2:5]
	v_mfma_f32_16x16x32_bf16 v[54:57], v[178:181], v[194:197], v[54:57]
	v_mfma_f32_16x16x32_bf16 v[46:49], v[186:189], v[194:197], v[46:49]
	v_mfma_f32_16x16x32_bf16 v[38:41], v[178:181], v[202:205], v[38:41]
	v_mfma_f32_16x16x32_bf16 v[30:33], v[186:189], v[202:205], v[30:33]
	v_mfma_f32_16x16x32_bf16 v[22:25], v[178:181], v[210:213], v[22:25]
	v_mfma_f32_16x16x32_bf16 v[14:17], v[186:189], v[210:213], v[14:17]
	v_mfma_f32_16x16x32_bf16 v[6:9], v[178:181], v[218:221], v[6:9]
	v_mfma_f32_16x16x32_bf16 v[2:5], v[186:189], v[218:221], v[2:5]
	s_barrier
	s_setprio 0
	s_add_i32 s52, s52, 2
	s_add_u32 s26, s26, 0x100
	s_addc_u32 s27, s27, 0
	s_add_u32 s50, s50, 0x100
	s_addc_u32 s51, s51, 0
	s_cmp_gt_u32 s52, 13
	s_cbranch_scc0 .LBB0_555

.LBB0_646:
	ds_read_b128 v[152:155], v146
	ds_read_b128 v[156:159], v146 offset:1024
	ds_read_b128 v[160:163], v146 offset:2048
	ds_read_b128 v[164:167], v146 offset:3072
	ds_read_b128 v[168:171], v147
	ds_read_b128 v[172:175], v147 offset:1024
	ds_read_b128 v[178:181], v147 offset:2048
	ds_read_b128 v[182:185], v147 offset:3072
	s_add_u32 s2, s10, s12
	s_addc_u32 s3, s11, s13
	s_add_u32 s2, s2, 0x3400100
	s_addc_u32 s3, s3, 0
	s_add_u32 s14, s24, s12
	s_addc_u32 s15, s25, s13
	s_cmpk_eq_i32 s12, 0x700
	s_cselect_b32 s3, s7, s3
	s_cselect_b32 s2, s6, s2
	s_cselect_b32 s15, s5, s15
	s_cselect_b32 s14, s4, s14
	s_mov_b32 m0, s27
	v_lshl_add_u64 v[218:219], v[138:139], 0, s[12:13]
	ds_read_b128 v[186:189], v148
	ds_read_b128 v[190:193], v148 offset:1024
	ds_read_b128 v[194:197], v148 offset:2048
	ds_read_b128 v[198:201], v148 offset:3072
	ds_read_b128 v[202:205], v148 offset:4096
	ds_read_b128 v[206:209], v148 offset:5120
	ds_read_b128 v[210:213], v148 offset:6144
	ds_read_b128 v[214:217], v148 offset:7168
	global_load_lds_dwordx4 v[218:219], off
	v_lshl_add_u64 v[218:219], v[140:141], 0, s[12:13]
	s_mov_b32 m0, s28
	s_nop 0
	global_load_lds_dwordx4 v[218:219], off
	s_waitcnt vmcnt(8)
	s_waitcnt lgkmcnt(0)
	s_setprio 2
	s_barrier
	v_mfma_f32_16x16x32_bf16 v[126:129], v[152:155], v[186:189], v[126:129]
	v_mfma_f32_16x16x32_bf16 v[122:125], v[160:163], v[186:189], v[122:125]
	v_mfma_f32_16x16x32_bf16 v[114:117], v[152:155], v[194:197], v[114:117]
	v_mfma_f32_16x16x32_bf16 v[106:109], v[160:163], v[194:197], v[106:109]
	v_mfma_f32_16x16x32_bf16 v[98:101], v[152:155], v[202:205], v[98:101]
	v_mfma_f32_16x16x32_bf16 v[90:93], v[160:163], v[202:205], v[90:93]
	v_mfma_f32_16x16x32_bf16 v[82:85], v[152:155], v[210:213], v[82:85]
	v_mfma_f32_16x16x32_bf16 v[74:77], v[160:163], v[210:213], v[74:77]
	v_mfma_f32_16x16x32_bf16 v[126:129], v[156:159], v[190:193], v[126:129]
	v_mfma_f32_16x16x32_bf16 v[122:125], v[164:167], v[190:193], v[122:125]
	v_mfma_f32_16x16x32_bf16 v[114:117], v[156:159], v[198:201], v[114:117]
	v_mfma_f32_16x16x32_bf16 v[106:109], v[164:167], v[198:201], v[106:109]
	v_mfma_f32_16x16x32_bf16 v[98:101], v[156:159], v[206:209], v[98:101]
	v_mfma_f32_16x16x32_bf16 v[90:93], v[164:167], v[206:209], v[90:93]
	v_mfma_f32_16x16x32_bf16 v[82:85], v[156:159], v[214:217], v[82:85]
	v_mfma_f32_16x16x32_bf16 v[74:77], v[164:167], v[214:217], v[74:77]
	v_mfma_f32_16x16x32_bf16 v[118:121], v[168:171], v[186:189], v[118:121]
	v_mfma_f32_16x16x32_bf16 v[110:113], v[178:181], v[186:189], v[110:113]
	v_mfma_f32_16x16x32_bf16 v[102:105], v[168:171], v[194:197], v[102:105]
	v_mfma_f32_16x16x32_bf16 v[94:97], v[178:181], v[194:197], v[94:97]
	v_mfma_f32_16x16x32_bf16 v[86:89], v[168:171], v[202:205], v[86:89]
	v_mfma_f32_16x16x32_bf16 v[78:81], v[178:181], v[202:205], v[78:81]
	v_mfma_f32_16x16x32_bf16 v[70:73], v[168:171], v[210:213], v[70:73]
	v_mfma_f32_16x16x32_bf16 v[66:69], v[178:181], v[210:213], v[66:69]
	v_mfma_f32_16x16x32_bf16 v[118:121], v[172:175], v[190:193], v[118:121]
	v_mfma_f32_16x16x32_bf16 v[110:113], v[182:185], v[190:193], v[110:113]
	v_mfma_f32_16x16x32_bf16 v[102:105], v[172:175], v[198:201], v[102:105]
	v_mfma_f32_16x16x32_bf16 v[94:97], v[182:185], v[198:201], v[94:97]
	v_mfma_f32_16x16x32_bf16 v[86:89], v[172:175], v[206:209], v[86:89]
	v_mfma_f32_16x16x32_bf16 v[78:81], v[182:185], v[206:209], v[78:81]
	v_mfma_f32_16x16x32_bf16 v[70:73], v[172:175], v[214:217], v[70:73]
	v_mfma_f32_16x16x32_bf16 v[66:69], v[182:185], v[214:217], v[66:69]
	s_barrier
	s_setprio 0
	s_mov_b32 m0, s29
	v_lshl_add_u64 v[218:219], s[14:15], 0, v[134:135]
	s_add_u32 s40, s14, 0x40000
	ds_read_b128 v[186:189], v148 offset:16384
	ds_read_b128 v[190:193], v148 offset:17408
	ds_read_b128 v[194:197], v148 offset:18432
	ds_read_b128 v[198:201], v148 offset:19456
	ds_read_b128 v[202:205], v148 offset:20480
	ds_read_b128 v[206:209], v148 offset:21504
	ds_read_b128 v[210:213], v148 offset:22528
	ds_read_b128 v[214:217], v148 offset:23552
	global_load_lds_dwordx4 v[218:219], off
	v_lshl_add_u64 v[220:221], s[14:15], 0, v[130:131]
	s_mov_b32 m0, s30
	s_addc_u32 s41, s15, 0
	global_load_lds_dwordx4 v[220:221], off
	v_lshl_add_u64 v[222:223], s[40:41], 0, v[134:135]
	s_mov_b32 m0, s31
	v_lshl_add_u64 v[224:225], s[2:3], 0, v[132:133]
	global_load_lds_dwordx4 v[222:223], off
	v_lshl_add_u64 v[222:223], s[40:41], 0, v[130:131]
	s_mov_b32 m0, s34
	s_nop 0
	global_load_lds_dwordx4 v[222:223], off
	v_lshl_add_u64 v[222:223], s[2:3], 0, v[136:137]
	s_mov_b32 m0, s18
	s_nop 0
	global_load_lds_dwordx4 v[222:223], off
	s_mov_b32 m0, s1
	s_nop 0
	global_load_lds_dwordx4 v[224:225], off
	s_waitcnt vmcnt(8)
	s_waitcnt lgkmcnt(0)
	s_setprio 2
	s_barrier
	v_mfma_f32_16x16x32_bf16 v[62:65], v[152:155], v[186:189], v[62:65]
	v_mfma_f32_16x16x32_bf16 v[58:61], v[160:163], v[186:189], v[58:61]
	v_mfma_f32_16x16x32_bf16 v[50:53], v[152:155], v[194:197], v[50:53]
	v_mfma_f32_16x16x32_bf16 v[42:45], v[160:163], v[194:197], v[42:45]
	v_mfma_f32_16x16x32_bf16 v[34:37], v[152:155], v[202:205], v[34:37]
	v_mfma_f32_16x16x32_bf16 v[26:29], v[160:163], v[202:205], v[26:29]
	v_mfma_f32_16x16x32_bf16 v[18:21], v[152:155], v[210:213], v[18:21]
	v_mfma_f32_16x16x32_bf16 v[10:13], v[160:163], v[210:213], v[10:13]
	v_mfma_f32_16x16x32_bf16 v[62:65], v[156:159], v[190:193], v[62:65]
	v_mfma_f32_16x16x32_bf16 v[58:61], v[164:167], v[190:193], v[58:61]
	v_mfma_f32_16x16x32_bf16 v[50:53], v[156:159], v[198:201], v[50:53]
	v_mfma_f32_16x16x32_bf16 v[42:45], v[164:167], v[198:201], v[42:45]
	v_mfma_f32_16x16x32_bf16 v[34:37], v[156:159], v[206:209], v[34:37]
	v_mfma_f32_16x16x32_bf16 v[26:29], v[164:167], v[206:209], v[26:29]
	v_mfma_f32_16x16x32_bf16 v[18:21], v[156:159], v[214:217], v[18:21]
	v_mfma_f32_16x16x32_bf16 v[10:13], v[164:167], v[214:217], v[10:13]
	v_mfma_f32_16x16x32_bf16 v[54:57], v[168:171], v[186:189], v[54:57]
	v_mfma_f32_16x16x32_bf16 v[46:49], v[178:181], v[186:189], v[46:49]
	v_mfma_f32_16x16x32_bf16 v[38:41], v[168:171], v[194:197], v[38:41]
	v_mfma_f32_16x16x32_bf16 v[30:33], v[178:181], v[194:197], v[30:33]
	v_mfma_f32_16x16x32_bf16 v[22:25], v[168:171], v[202:205], v[22:25]
	v_mfma_f32_16x16x32_bf16 v[14:17], v[178:181], v[202:205], v[14:17]
	v_mfma_f32_16x16x32_bf16 v[6:9], v[168:171], v[210:213], v[6:9]
	v_mfma_f32_16x16x32_bf16 v[2:5], v[178:181], v[210:213], v[2:5]
	v_mfma_f32_16x16x32_bf16 v[54:57], v[172:175], v[190:193], v[54:57]
	v_mfma_f32_16x16x32_bf16 v[46:49], v[182:185], v[190:193], v[46:49]
	v_mfma_f32_16x16x32_bf16 v[38:41], v[172:175], v[198:201], v[38:41]
	v_mfma_f32_16x16x32_bf16 v[30:33], v[182:185], v[198:201], v[30:33]
	v_mfma_f32_16x16x32_bf16 v[22:25], v[172:175], v[206:209], v[22:25]
	v_mfma_f32_16x16x32_bf16 v[14:17], v[182:185], v[206:209], v[14:17]
	v_mfma_f32_16x16x32_bf16 v[6:9], v[172:175], v[214:217], v[6:9]
	v_mfma_f32_16x16x32_bf16 v[2:5], v[182:185], v[214:217], v[2:5]
	s_barrier
	s_setprio 0
	ds_read_b128 v[152:155], v149
	ds_read_b128 v[156:159], v149 offset:1024
	ds_read_b128 v[160:163], v149 offset:2048
	ds_read_b128 v[164:167], v149 offset:3072
	ds_read_b128 v[168:171], v150
	ds_read_b128 v[172:175], v150 offset:1024
	ds_read_b128 v[178:181], v150 offset:2048
	ds_read_b128 v[182:185], v150 offset:3072
	s_add_u32 s2, s2, 0x40000
	s_addc_u32 s3, s3, 0
	s_mov_b32 m0, s19
	v_lshl_add_u64 v[226:227], s[2:3], 0, v[136:137]
	ds_read_b128 v[186:189], v148 offset:32768
	ds_read_b128 v[190:193], v148 offset:33792
	ds_read_b128 v[194:197], v148 offset:34816
	ds_read_b128 v[198:201], v148 offset:35840
	ds_read_b128 v[202:205], v148 offset:36864
	ds_read_b128 v[206:209], v148 offset:37888
	ds_read_b128 v[210:213], v148 offset:38912
	ds_read_b128 v[214:217], v148 offset:39936
	global_load_lds_dwordx4 v[226:227], off
	v_lshl_add_u64 v[226:227], s[2:3], 0, v[132:133]
	s_mov_b32 m0, s20
	s_nop 0
	global_load_lds_dwordx4 v[226:227], off
	s_waitcnt vmcnt(8)
	s_waitcnt lgkmcnt(0)
	s_setprio 2
	s_barrier
	v_mfma_f32_16x16x32_bf16 v[126:129], v[152:155], v[186:189], v[126:129]
	v_mfma_f32_16x16x32_bf16 v[122:125], v[160:163], v[186:189], v[122:125]
	v_mfma_f32_16x16x32_bf16 v[114:117], v[152:155], v[194:197], v[114:117]
	v_mfma_f32_16x16x32_bf16 v[106:109], v[160:163], v[194:197], v[106:109]
	v_mfma_f32_16x16x32_bf16 v[98:101], v[152:155], v[202:205], v[98:101]
	v_mfma_f32_16x16x32_bf16 v[90:93], v[160:163], v[202:205], v[90:93]
	v_mfma_f32_16x16x32_bf16 v[82:85], v[152:155], v[210:213], v[82:85]
	v_mfma_f32_16x16x32_bf16 v[74:77], v[160:163], v[210:213], v[74:77]
	v_mfma_f32_16x16x32_bf16 v[126:129], v[156:159], v[190:193], v[126:129]
	v_mfma_f32_16x16x32_bf16 v[122:125], v[164:167], v[190:193], v[122:125]
	v_mfma_f32_16x16x32_bf16 v[114:117], v[156:159], v[198:201], v[114:117]
	v_mfma_f32_16x16x32_bf16 v[106:109], v[164:167], v[198:201], v[106:109]
	v_mfma_f32_16x16x32_bf16 v[98:101], v[156:159], v[206:209], v[98:101]
	v_mfma_f32_16x16x32_bf16 v[90:93], v[164:167], v[206:209], v[90:93]
	v_mfma_f32_16x16x32_bf16 v[82:85], v[156:159], v[214:217], v[82:85]
	v_mfma_f32_16x16x32_bf16 v[74:77], v[164:167], v[214:217], v[74:77]
	v_mfma_f32_16x16x32_bf16 v[118:121], v[168:171], v[186:189], v[118:121]
	v_mfma_f32_16x16x32_bf16 v[110:113], v[178:181], v[186:189], v[110:113]
	v_mfma_f32_16x16x32_bf16 v[102:105], v[168:171], v[194:197], v[102:105]
	v_mfma_f32_16x16x32_bf16 v[94:97], v[178:181], v[194:197], v[94:97]
	v_mfma_f32_16x16x32_bf16 v[86:89], v[168:171], v[202:205], v[86:89]
	v_mfma_f32_16x16x32_bf16 v[78:81], v[178:181], v[202:205], v[78:81]
	v_mfma_f32_16x16x32_bf16 v[70:73], v[168:171], v[210:213], v[70:73]
	v_mfma_f32_16x16x32_bf16 v[66:69], v[178:181], v[210:213], v[66:69]
	v_mfma_f32_16x16x32_bf16 v[118:121], v[172:175], v[190:193], v[118:121]
	v_mfma_f32_16x16x32_bf16 v[110:113], v[182:185], v[190:193], v[110:113]
	v_mfma_f32_16x16x32_bf16 v[102:105], v[172:175], v[198:201], v[102:105]
	v_mfma_f32_16x16x32_bf16 v[94:97], v[182:185], v[198:201], v[94:97]
	v_mfma_f32_16x16x32_bf16 v[86:89], v[172:175], v[206:209], v[86:89]
	v_mfma_f32_16x16x32_bf16 v[78:81], v[182:185], v[206:209], v[78:81]
	v_mfma_f32_16x16x32_bf16 v[70:73], v[172:175], v[214:217], v[70:73]
	v_mfma_f32_16x16x32_bf16 v[66:69], v[182:185], v[214:217], v[66:69]
	s_barrier
	s_setprio 0
	s_mov_b32 m0, s35
	v_lshl_add_u64 v[218:219], v[218:219], 0, s[8:9]
	s_add_u32 s2, s14, 0x40080
	ds_read_b128 v[186:189], v148 offset:49152
	ds_read_b128 v[190:193], v148 offset:50176
	ds_read_b128 v[194:197], v148 offset:51200
	ds_read_b128 v[198:201], v148 offset:52224
	ds_read_b128 v[202:205], v148 offset:53248
	ds_read_b128 v[206:209], v148 offset:54272
	ds_read_b128 v[210:213], v148 offset:55296
	ds_read_b128 v[214:217], v148 offset:56320
	global_load_lds_dwordx4 v[218:219], off
	v_lshl_add_u64 v[218:219], v[220:221], 0, s[8:9]
	s_mov_b32 m0, s36
	s_addc_u32 s3, s15, 0
	global_load_lds_dwordx4 v[218:219], off
	v_lshl_add_u64 v[218:219], s[2:3], 0, v[134:135]
	s_mov_b32 m0, s37
	s_nop 0
	global_load_lds_dwordx4 v[218:219], off
	v_lshl_add_u64 v[218:219], s[2:3], 0, v[130:131]
	s_mov_b32 m0, s38
	s_nop 0
	global_load_lds_dwordx4 v[218:219], off
	v_lshl_add_u64 v[218:219], v[222:223], 0, s[8:9]
	s_mov_b32 m0, s22
	s_nop 0
	global_load_lds_dwordx4 v[218:219], off
	v_lshl_add_u64 v[218:219], v[224:225], 0, s[8:9]
	s_mov_b32 m0, s23
	s_nop 0
	global_load_lds_dwordx4 v[218:219], off
	s_waitcnt vmcnt(8)
	s_waitcnt lgkmcnt(0)
	s_setprio 2
	s_barrier
	v_mfma_f32_16x16x32_bf16 v[62:65], v[152:155], v[186:189], v[62:65]
	v_mfma_f32_16x16x32_bf16 v[58:61], v[160:163], v[186:189], v[58:61]
	v_mfma_f32_16x16x32_bf16 v[50:53], v[152:155], v[194:197], v[50:53]
	v_mfma_f32_16x16x32_bf16 v[42:45], v[160:163], v[194:197], v[42:45]
	v_mfma_f32_16x16x32_bf16 v[34:37], v[152:155], v[202:205], v[34:37]
	v_mfma_f32_16x16x32_bf16 v[26:29], v[160:163], v[202:205], v[26:29]
	v_mfma_f32_16x16x32_bf16 v[18:21], v[152:155], v[210:213], v[18:21]
	v_mfma_f32_16x16x32_bf16 v[10:13], v[160:163], v[210:213], v[10:13]
	v_mfma_f32_16x16x32_bf16 v[62:65], v[156:159], v[190:193], v[62:65]
	v_mfma_f32_16x16x32_bf16 v[58:61], v[164:167], v[190:193], v[58:61]
	v_mfma_f32_16x16x32_bf16 v[50:53], v[156:159], v[198:201], v[50:53]
	v_mfma_f32_16x16x32_bf16 v[42:45], v[164:167], v[198:201], v[42:45]
	v_mfma_f32_16x16x32_bf16 v[34:37], v[156:159], v[206:209], v[34:37]
	v_mfma_f32_16x16x32_bf16 v[26:29], v[164:167], v[206:209], v[26:29]
	v_mfma_f32_16x16x32_bf16 v[18:21], v[156:159], v[214:217], v[18:21]
	v_mfma_f32_16x16x32_bf16 v[10:13], v[164:167], v[214:217], v[10:13]
	v_mfma_f32_16x16x32_bf16 v[54:57], v[168:171], v[186:189], v[54:57]
	v_mfma_f32_16x16x32_bf16 v[46:49], v[178:181], v[186:189], v[46:49]
	v_mfma_f32_16x16x32_bf16 v[38:41], v[168:171], v[194:197], v[38:41]
	v_mfma_f32_16x16x32_bf16 v[30:33], v[178:181], v[194:197], v[30:33]
	v_mfma_f32_16x16x32_bf16 v[22:25], v[168:171], v[202:205], v[22:25]
	v_mfma_f32_16x16x32_bf16 v[14:17], v[178:181], v[202:205], v[14:17]
	v_mfma_f32_16x16x32_bf16 v[6:9], v[168:171], v[210:213], v[6:9]
	v_mfma_f32_16x16x32_bf16 v[2:5], v[178:181], v[210:213], v[2:5]
	v_mfma_f32_16x16x32_bf16 v[54:57], v[172:175], v[190:193], v[54:57]
	v_mfma_f32_16x16x32_bf16 v[46:49], v[182:185], v[190:193], v[46:49]
	v_mfma_f32_16x16x32_bf16 v[38:41], v[172:175], v[198:201], v[38:41]
	v_mfma_f32_16x16x32_bf16 v[30:33], v[182:185], v[198:201], v[30:33]
	v_mfma_f32_16x16x32_bf16 v[22:25], v[172:175], v[206:209], v[22:25]
	v_mfma_f32_16x16x32_bf16 v[14:17], v[182:185], v[206:209], v[14:17]
	v_mfma_f32_16x16x32_bf16 v[6:9], v[172:175], v[214:217], v[6:9]
	v_mfma_f32_16x16x32_bf16 v[2:5], v[182:185], v[214:217], v[2:5]
	s_barrier
	s_setprio 0
	s_add_i32 s26, s26, 2
	s_add_u32 s12, s12, 0x100
	s_addc_u32 s13, s13, 0
	s_cmp_gt_u32 s26, 13
	s_cbranch_scc0 .LBB0_646
	s_cmpk_lt_u32 s16, 0x100
	s_mov_b32 s28, s33
	v_readlane_b32 s30, v253, 58
	s_cbranch_scc0 .LBB0_649
	s_barrier

.Lpk1098_peel:
	ds_read_b128 v[152:155], v148
	ds_read_b128 v[156:159], v148 offset:1024
	ds_read_b128 v[160:163], v148 offset:2048
	ds_read_b128 v[164:167], v148 offset:3072
	ds_read_b128 v[168:171], v149
	ds_read_b128 v[172:175], v149 offset:1024
	ds_read_b128 v[178:181], v149 offset:2048
	ds_read_b128 v[182:185], v149 offset:3072
	s_add_u32 s2, s30, 0xfffc0080
	s_addc_u32 s3, s31, -1
	s_cmp_eq_u32 s56, 12
	s_cselect_b32 s3, s15, s3
	s_cselect_b32 s2, s17, s2
	s_cselect_b32 s35, s52, s55
	s_cselect_b32 s34, s53, s54
	v_lshl_add_u64 v[144:145], s[30:31], 0, v[138:139]
	s_add_i32 m0, s40, 0xc000
	ds_read_b128 v[186:189], v150
	ds_read_b128 v[190:193], v150 offset:1024
	ds_read_b128 v[194:197], v150 offset:2048
	ds_read_b128 v[198:201], v150 offset:3072
	ds_read_b128 v[202:205], v150 offset:4096
	ds_read_b128 v[206:209], v150 offset:5120
	ds_read_b128 v[210:213], v150 offset:6144
	ds_read_b128 v[214:217], v150 offset:7168
	global_load_lds_dwordx4 v[144:145], off
	v_lshl_add_u64 v[144:145], s[30:31], 0, v[140:141]
	s_add_i32 m0, s40, 0xe000
	s_nop 0
	global_load_lds_dwordx4 v[144:145], off
	s_waitcnt vmcnt(8)
	s_waitcnt lgkmcnt(0)
	s_setprio 2
	s_barrier
	v_mfma_f32_16x16x32_bf16 v[126:129], v[152:155], v[186:189], 0
	v_mfma_f32_16x16x32_bf16 v[122:125], v[160:163], v[186:189], 0
	v_mfma_f32_16x16x32_bf16 v[114:117], v[152:155], v[194:197], 0
	v_mfma_f32_16x16x32_bf16 v[106:109], v[160:163], v[194:197], 0
	v_mfma_f32_16x16x32_bf16 v[98:101], v[152:155], v[202:205], 0
	v_mfma_f32_16x16x32_bf16 v[90:93], v[160:163], v[202:205], 0
	v_mfma_f32_16x16x32_bf16 v[82:85], v[152:155], v[210:213], 0
	v_mfma_f32_16x16x32_bf16 v[74:77], v[160:163], v[210:213], 0
	v_mfma_f32_16x16x32_bf16 v[126:129], v[156:159], v[190:193], v[126:129]
	v_mfma_f32_16x16x32_bf16 v[122:125], v[164:167], v[190:193], v[122:125]
	v_mfma_f32_16x16x32_bf16 v[114:117], v[156:159], v[198:201], v[114:117]
	v_mfma_f32_16x16x32_bf16 v[106:109], v[164:167], v[198:201], v[106:109]
	v_mfma_f32_16x16x32_bf16 v[98:101], v[156:159], v[206:209], v[98:101]
	v_mfma_f32_16x16x32_bf16 v[90:93], v[164:167], v[206:209], v[90:93]
	v_mfma_f32_16x16x32_bf16 v[82:85], v[156:159], v[214:217], v[82:85]
	v_mfma_f32_16x16x32_bf16 v[74:77], v[164:167], v[214:217], v[74:77]
	v_mfma_f32_16x16x32_bf16 v[118:121], v[168:171], v[186:189], 0
	v_mfma_f32_16x16x32_bf16 v[110:113], v[178:181], v[186:189], 0
	v_mfma_f32_16x16x32_bf16 v[102:105], v[168:171], v[194:197], 0
	v_mfma_f32_16x16x32_bf16 v[94:97], v[178:181], v[194:197], 0
	v_mfma_f32_16x16x32_bf16 v[86:89], v[168:171], v[202:205], 0
	v_mfma_f32_16x16x32_bf16 v[78:81], v[178:181], v[202:205], 0
	v_mfma_f32_16x16x32_bf16 v[70:73], v[168:171], v[210:213], 0
	v_mfma_f32_16x16x32_bf16 v[66:69], v[178:181], v[210:213], 0
	v_mfma_f32_16x16x32_bf16 v[118:121], v[172:175], v[190:193], v[118:121]
	v_mfma_f32_16x16x32_bf16 v[110:113], v[182:185], v[190:193], v[110:113]
	v_mfma_f32_16x16x32_bf16 v[102:105], v[172:175], v[198:201], v[102:105]
	v_mfma_f32_16x16x32_bf16 v[94:97], v[182:185], v[198:201], v[94:97]
	v_mfma_f32_16x16x32_bf16 v[86:89], v[172:175], v[206:209], v[86:89]
	v_mfma_f32_16x16x32_bf16 v[78:81], v[182:185], v[206:209], v[78:81]
	v_mfma_f32_16x16x32_bf16 v[70:73], v[172:175], v[214:217], v[70:73]
	v_mfma_f32_16x16x32_bf16 v[66:69], v[182:185], v[214:217], v[66:69]
	s_barrier
	s_setprio 0
	s_add_i32 s57, s47, s39
	v_lshl_add_u64 v[144:145], s[34:35], 0, v[132:133]
	s_mov_b32 m0, s57
	ds_read_b128 v[186:189], v150 offset:16384
	ds_read_b128 v[190:193], v150 offset:17408
	ds_read_b128 v[194:197], v150 offset:18432
	ds_read_b128 v[198:201], v150 offset:19456
	ds_read_b128 v[202:205], v150 offset:20480
	ds_read_b128 v[206:209], v150 offset:21504
	ds_read_b128 v[210:213], v150 offset:22528
	ds_read_b128 v[214:217], v150 offset:23552
	global_load_lds_dwordx4 v[144:145], off
	s_add_i32 m0, s57, 0x2000
	s_add_u32 s58, s34, 0x40000
	v_lshl_add_u64 v[218:219], s[34:35], 0, v[136:137]
	s_addc_u32 s59, s35, 0
	s_add_i32 s57, s48, s39
	global_load_lds_dwordx4 v[218:219], off
	v_lshl_add_u64 v[220:221], s[58:59], 0, v[132:133]
	s_mov_b32 m0, s57
	v_lshl_add_u64 v[222:223], s[2:3], 0, v[134:135]
	global_load_lds_dwordx4 v[220:221], off
	v_lshl_add_u64 v[220:221], s[58:59], 0, v[136:137]
	s_add_i32 m0, s57, 0x2000
	s_nop 0
	global_load_lds_dwordx4 v[220:221], off
	v_lshl_add_u64 v[220:221], s[2:3], 0, v[130:131]
	s_mov_b32 m0, s40
	s_nop 0
	global_load_lds_dwordx4 v[220:221], off
	s_mov_b32 m0, s29
	s_nop 0
	global_load_lds_dwordx4 v[222:223], off
	s_waitcnt vmcnt(8)
	s_waitcnt lgkmcnt(0)
	s_setprio 2
	s_barrier
	v_mfma_f32_16x16x32_bf16 v[62:65], v[152:155], v[186:189], 0
	v_mfma_f32_16x16x32_bf16 v[58:61], v[160:163], v[186:189], 0
	v_mfma_f32_16x16x32_bf16 v[50:53], v[152:155], v[194:197], 0
	v_mfma_f32_16x16x32_bf16 v[42:45], v[160:163], v[194:197], 0
	v_mfma_f32_16x16x32_bf16 v[34:37], v[152:155], v[202:205], 0
	v_mfma_f32_16x16x32_bf16 v[26:29], v[160:163], v[202:205], 0
	v_mfma_f32_16x16x32_bf16 v[18:21], v[152:155], v[210:213], 0
	v_mfma_f32_16x16x32_bf16 v[10:13], v[160:163], v[210:213], 0
	v_mfma_f32_16x16x32_bf16 v[62:65], v[156:159], v[190:193], v[62:65]
	v_mfma_f32_16x16x32_bf16 v[58:61], v[164:167], v[190:193], v[58:61]
	v_mfma_f32_16x16x32_bf16 v[50:53], v[156:159], v[198:201], v[50:53]
	v_mfma_f32_16x16x32_bf16 v[42:45], v[164:167], v[198:201], v[42:45]
	v_mfma_f32_16x16x32_bf16 v[34:37], v[156:159], v[206:209], v[34:37]
	v_mfma_f32_16x16x32_bf16 v[26:29], v[164:167], v[206:209], v[26:29]
	v_mfma_f32_16x16x32_bf16 v[18:21], v[156:159], v[214:217], v[18:21]
	v_mfma_f32_16x16x32_bf16 v[10:13], v[164:167], v[214:217], v[10:13]
	v_mfma_f32_16x16x32_bf16 v[54:57], v[168:171], v[186:189], 0
	v_mfma_f32_16x16x32_bf16 v[46:49], v[178:181], v[186:189], 0
	v_mfma_f32_16x16x32_bf16 v[38:41], v[168:171], v[194:197], 0
	v_mfma_f32_16x16x32_bf16 v[30:33], v[178:181], v[194:197], 0
	v_mfma_f32_16x16x32_bf16 v[22:25], v[168:171], v[202:205], 0
	v_mfma_f32_16x16x32_bf16 v[14:17], v[178:181], v[202:205], 0
	v_mfma_f32_16x16x32_bf16 v[6:9], v[168:171], v[210:213], 0
	v_mfma_f32_16x16x32_bf16 v[2:5], v[178:181], v[210:213], 0
	v_mfma_f32_16x16x32_bf16 v[54:57], v[172:175], v[190:193], v[54:57]
	v_mfma_f32_16x16x32_bf16 v[46:49], v[182:185], v[190:193], v[46:49]
	v_mfma_f32_16x16x32_bf16 v[38:41], v[172:175], v[198:201], v[38:41]
	v_mfma_f32_16x16x32_bf16 v[30:33], v[182:185], v[198:201], v[30:33]
	v_mfma_f32_16x16x32_bf16 v[22:25], v[172:175], v[206:209], v[22:25]
	v_mfma_f32_16x16x32_bf16 v[14:17], v[182:185], v[206:209], v[14:17]
	v_mfma_f32_16x16x32_bf16 v[6:9], v[172:175], v[214:217], v[6:9]
	v_mfma_f32_16x16x32_bf16 v[2:5], v[182:185], v[214:217], v[2:5]
	s_barrier
	s_setprio 0
	s_add_i32 s57, 0, 0x18000
	v_add_u32_e32 v151, s57, v146
	s_add_i32 s58, 0, 0x1c000
	ds_read_b128 v[152:155], v151
	ds_read_b128 v[156:159], v151 offset:1024
	ds_read_b128 v[160:163], v151 offset:2048
	ds_read_b128 v[164:167], v151 offset:3072
	v_add_u32_e32 v151, s58, v146
	ds_read_b128 v[168:171], v151
	ds_read_b128 v[172:175], v151 offset:1024
	ds_read_b128 v[178:181], v151 offset:2048
	ds_read_b128 v[182:185], v151 offset:3072
	s_add_u32 s2, s2, 0x40000
	s_addc_u32 s3, s3, 0
	s_mov_b32 m0, s41
	v_lshl_add_u64 v[224:225], s[2:3], 0, v[130:131]
	ds_read_b128 v[186:189], v150 offset:32768
	ds_read_b128 v[190:193], v150 offset:33792
	ds_read_b128 v[194:197], v150 offset:34816
	ds_read_b128 v[198:201], v150 offset:35840
	ds_read_b128 v[202:205], v150 offset:36864
	ds_read_b128 v[206:209], v150 offset:37888
	ds_read_b128 v[210:213], v150 offset:38912
	ds_read_b128 v[214:217], v150 offset:39936
	global_load_lds_dwordx4 v[224:225], off
	v_lshl_add_u64 v[224:225], s[2:3], 0, v[134:135]
	s_mov_b32 m0, s42
	s_nop 0
	global_load_lds_dwordx4 v[224:225], off
	s_waitcnt vmcnt(8)
	s_waitcnt lgkmcnt(0)
	s_setprio 2
	s_barrier
	v_mfma_f32_16x16x32_bf16 v[126:129], v[152:155], v[186:189], v[126:129]
	v_mfma_f32_16x16x32_bf16 v[122:125], v[160:163], v[186:189], v[122:125]
	v_mfma_f32_16x16x32_bf16 v[114:117], v[152:155], v[194:197], v[114:117]
	v_mfma_f32_16x16x32_bf16 v[106:109], v[160:163], v[194:197], v[106:109]
	v_mfma_f32_16x16x32_bf16 v[98:101], v[152:155], v[202:205], v[98:101]
	v_mfma_f32_16x16x32_bf16 v[90:93], v[160:163], v[202:205], v[90:93]
	v_mfma_f32_16x16x32_bf16 v[82:85], v[152:155], v[210:213], v[82:85]
	v_mfma_f32_16x16x32_bf16 v[74:77], v[160:163], v[210:213], v[74:77]
	v_mfma_f32_16x16x32_bf16 v[126:129], v[156:159], v[190:193], v[126:129]
	v_mfma_f32_16x16x32_bf16 v[122:125], v[164:167], v[190:193], v[122:125]
	v_mfma_f32_16x16x32_bf16 v[114:117], v[156:159], v[198:201], v[114:117]
	v_mfma_f32_16x16x32_bf16 v[106:109], v[164:167], v[198:201], v[106:109]
	v_mfma_f32_16x16x32_bf16 v[98:101], v[156:159], v[206:209], v[98:101]
	v_mfma_f32_16x16x32_bf16 v[90:93], v[164:167], v[206:209], v[90:93]
	v_mfma_f32_16x16x32_bf16 v[82:85], v[156:159], v[214:217], v[82:85]
	v_mfma_f32_16x16x32_bf16 v[74:77], v[164:167], v[214:217], v[74:77]
	v_mfma_f32_16x16x32_bf16 v[118:121], v[168:171], v[186:189], v[118:121]
	v_mfma_f32_16x16x32_bf16 v[110:113], v[178:181], v[186:189], v[110:113]
	v_mfma_f32_16x16x32_bf16 v[102:105], v[168:171], v[194:197], v[102:105]
	v_mfma_f32_16x16x32_bf16 v[94:97], v[178:181], v[194:197], v[94:97]
	v_mfma_f32_16x16x32_bf16 v[86:89], v[168:171], v[202:205], v[86:89]
	v_mfma_f32_16x16x32_bf16 v[78:81], v[178:181], v[202:205], v[78:81]
	v_mfma_f32_16x16x32_bf16 v[70:73], v[168:171], v[210:213], v[70:73]
	v_mfma_f32_16x16x32_bf16 v[66:69], v[178:181], v[210:213], v[66:69]
	v_mfma_f32_16x16x32_bf16 v[118:121], v[172:175], v[190:193], v[118:121]
	v_mfma_f32_16x16x32_bf16 v[110:113], v[182:185], v[190:193], v[110:113]
	v_mfma_f32_16x16x32_bf16 v[102:105], v[172:175], v[198:201], v[102:105]
	v_mfma_f32_16x16x32_bf16 v[94:97], v[182:185], v[198:201], v[94:97]
	v_mfma_f32_16x16x32_bf16 v[86:89], v[172:175], v[206:209], v[86:89]
	v_mfma_f32_16x16x32_bf16 v[78:81], v[182:185], v[206:209], v[78:81]
	v_mfma_f32_16x16x32_bf16 v[70:73], v[172:175], v[214:217], v[70:73]
	v_mfma_f32_16x16x32_bf16 v[66:69], v[182:185], v[214:217], v[66:69]
	s_barrier
	s_setprio 0
	s_add_i32 s2, s57, s39
	v_lshl_add_u64 v[144:145], v[144:145], 0, s[6:7]
	s_mov_b32 m0, s2
	ds_read_b128 v[186:189], v150 offset:49152
	ds_read_b128 v[190:193], v150 offset:50176
	ds_read_b128 v[194:197], v150 offset:51200
	ds_read_b128 v[198:201], v150 offset:52224
	ds_read_b128 v[202:205], v150 offset:53248
	ds_read_b128 v[206:209], v150 offset:54272
	ds_read_b128 v[210:213], v150 offset:55296
	ds_read_b128 v[214:217], v150 offset:56320
	global_load_lds_dwordx4 v[144:145], off
	s_add_i32 m0, s2, 0x2000
	s_add_u32 s2, s34, 0x40080
	v_lshl_add_u64 v[144:145], v[218:219], 0, s[6:7]
	s_addc_u32 s3, s35, 0
	s_add_i32 s34, s58, s39
	global_load_lds_dwordx4 v[144:145], off
	v_lshl_add_u64 v[144:145], s[2:3], 0, v[132:133]
	s_mov_b32 m0, s34
	s_nop 0
	global_load_lds_dwordx4 v[144:145], off
	v_lshl_add_u64 v[144:145], s[2:3], 0, v[136:137]
	s_add_i32 m0, s34, 0x2000
	s_nop 0
	global_load_lds_dwordx4 v[144:145], off
	v_lshl_add_u64 v[144:145], v[220:221], 0, s[6:7]
	s_mov_b32 m0, s44
	s_nop 0
	global_load_lds_dwordx4 v[144:145], off
	v_lshl_add_u64 v[144:145], v[222:223], 0, s[6:7]
	s_mov_b32 m0, s45
	s_nop 0
	global_load_lds_dwordx4 v[144:145], off
	s_waitcnt vmcnt(8)
	s_waitcnt lgkmcnt(0)
	s_setprio 2
	s_barrier
	v_mfma_f32_16x16x32_bf16 v[62:65], v[152:155], v[186:189], v[62:65]
	v_mfma_f32_16x16x32_bf16 v[58:61], v[160:163], v[186:189], v[58:61]
	v_mfma_f32_16x16x32_bf16 v[50:53], v[152:155], v[194:197], v[50:53]
	v_mfma_f32_16x16x32_bf16 v[42:45], v[160:163], v[194:197], v[42:45]
	v_mfma_f32_16x16x32_bf16 v[34:37], v[152:155], v[202:205], v[34:37]
	v_mfma_f32_16x16x32_bf16 v[26:29], v[160:163], v[202:205], v[26:29]
	v_mfma_f32_16x16x32_bf16 v[18:21], v[152:155], v[210:213], v[18:21]
	v_mfma_f32_16x16x32_bf16 v[10:13], v[160:163], v[210:213], v[10:13]
	v_mfma_f32_16x16x32_bf16 v[62:65], v[156:159], v[190:193], v[62:65]
	v_mfma_f32_16x16x32_bf16 v[58:61], v[164:167], v[190:193], v[58:61]
	v_mfma_f32_16x16x32_bf16 v[50:53], v[156:159], v[198:201], v[50:53]
	v_mfma_f32_16x16x32_bf16 v[42:45], v[164:167], v[198:201], v[42:45]
	v_mfma_f32_16x16x32_bf16 v[34:37], v[156:159], v[206:209], v[34:37]
	v_mfma_f32_16x16x32_bf16 v[26:29], v[164:167], v[206:209], v[26:29]
	v_mfma_f32_16x16x32_bf16 v[18:21], v[156:159], v[214:217], v[18:21]
	v_mfma_f32_16x16x32_bf16 v[10:13], v[164:167], v[214:217], v[10:13]
	v_mfma_f32_16x16x32_bf16 v[54:57], v[168:171], v[186:189], v[54:57]
	v_mfma_f32_16x16x32_bf16 v[46:49], v[178:181], v[186:189], v[46:49]
	v_mfma_f32_16x16x32_bf16 v[38:41], v[168:171], v[194:197], v[38:41]
	v_mfma_f32_16x16x32_bf16 v[30:33], v[178:181], v[194:197], v[30:33]
	v_mfma_f32_16x16x32_bf16 v[22:25], v[168:171], v[202:205], v[22:25]
	v_mfma_f32_16x16x32_bf16 v[14:17], v[178:181], v[202:205], v[14:17]
	v_mfma_f32_16x16x32_bf16 v[6:9], v[168:171], v[210:213], v[6:9]
	v_mfma_f32_16x16x32_bf16 v[2:5], v[178:181], v[210:213], v[2:5]
	v_mfma_f32_16x16x32_bf16 v[54:57], v[172:175], v[190:193], v[54:57]
	v_mfma_f32_16x16x32_bf16 v[46:49], v[182:185], v[190:193], v[46:49]
	v_mfma_f32_16x16x32_bf16 v[38:41], v[172:175], v[198:201], v[38:41]
	v_mfma_f32_16x16x32_bf16 v[30:33], v[182:185], v[198:201], v[30:33]
	v_mfma_f32_16x16x32_bf16 v[22:25], v[172:175], v[206:209], v[22:25]
	v_mfma_f32_16x16x32_bf16 v[14:17], v[182:185], v[206:209], v[14:17]
	v_mfma_f32_16x16x32_bf16 v[6:9], v[172:175], v[214:217], v[6:9]
	v_mfma_f32_16x16x32_bf16 v[2:5], v[182:185], v[214:217], v[2:5]
	s_barrier
	s_setprio 0
	s_add_i32 s56, s56, 2
	s_add_u32 s30, s30, 0x100
	s_addc_u32 s31, s31, 0
	s_add_u32 s54, s54, 0x100
	s_addc_u32 s55, s55, 0
	s_cmp_gt_u32 s56, 13
	s_cbranch_scc0 .LBB0_1098
	s_branch .Lpk1098_exit
.LBB0_1098:
	ds_read_b128 v[152:155], v148
	ds_read_b128 v[156:159], v148 offset:1024
	ds_read_b128 v[160:163], v148 offset:2048
	ds_read_b128 v[164:167], v148 offset:3072
	ds_read_b128 v[168:171], v149
	ds_read_b128 v[172:175], v149 offset:1024
	ds_read_b128 v[178:181], v149 offset:2048
	ds_read_b128 v[182:185], v149 offset:3072
	s_add_u32 s2, s30, 0xfffc0080
	s_addc_u32 s3, s31, -1
	s_cmp_eq_u32 s56, 12
	s_cselect_b32 s3, s15, s3
	s_cselect_b32 s2, s17, s2
	s_cselect_b32 s35, s52, s55
	s_cselect_b32 s34, s53, s54
	v_lshl_add_u64 v[144:145], s[30:31], 0, v[138:139]
	s_add_i32 m0, s40, 0xc000
	ds_read_b128 v[186:189], v150
	ds_read_b128 v[190:193], v150 offset:1024
	ds_read_b128 v[194:197], v150 offset:2048
	ds_read_b128 v[198:201], v150 offset:3072
	ds_read_b128 v[202:205], v150 offset:4096
	ds_read_b128 v[206:209], v150 offset:5120
	ds_read_b128 v[210:213], v150 offset:6144
	ds_read_b128 v[214:217], v150 offset:7168
	global_load_lds_dwordx4 v[144:145], off
	v_lshl_add_u64 v[144:145], s[30:31], 0, v[140:141]
	s_add_i32 m0, s40, 0xe000
	s_nop 0
	global_load_lds_dwordx4 v[144:145], off
	s_waitcnt vmcnt(8)
	s_waitcnt lgkmcnt(0)
	s_setprio 2
	s_barrier
	v_mfma_f32_16x16x32_bf16 v[126:129], v[152:155], v[186:189], v[126:129]
	v_mfma_f32_16x16x32_bf16 v[122:125], v[160:163], v[186:189], v[122:125]
	v_mfma_f32_16x16x32_bf16 v[114:117], v[152:155], v[194:197], v[114:117]
	v_mfma_f32_16x16x32_bf16 v[106:109], v[160:163], v[194:197], v[106:109]
	v_mfma_f32_16x16x32_bf16 v[98:101], v[152:155], v[202:205], v[98:101]
	v_mfma_f32_16x16x32_bf16 v[90:93], v[160:163], v[202:205], v[90:93]
	v_mfma_f32_16x16x32_bf16 v[82:85], v[152:155], v[210:213], v[82:85]
	v_mfma_f32_16x16x32_bf16 v[74:77], v[160:163], v[210:213], v[74:77]
	v_mfma_f32_16x16x32_bf16 v[126:129], v[156:159], v[190:193], v[126:129]
	v_mfma_f32_16x16x32_bf16 v[122:125], v[164:167], v[190:193], v[122:125]
	v_mfma_f32_16x16x32_bf16 v[114:117], v[156:159], v[198:201], v[114:117]
	v_mfma_f32_16x16x32_bf16 v[106:109], v[164:167], v[198:201], v[106:109]
	v_mfma_f32_16x16x32_bf16 v[98:101], v[156:159], v[206:209], v[98:101]
	v_mfma_f32_16x16x32_bf16 v[90:93], v[164:167], v[206:209], v[90:93]
	v_mfma_f32_16x16x32_bf16 v[82:85], v[156:159], v[214:217], v[82:85]
	v_mfma_f32_16x16x32_bf16 v[74:77], v[164:167], v[214:217], v[74:77]
	v_mfma_f32_16x16x32_bf16 v[118:121], v[168:171], v[186:189], v[118:121]
	v_mfma_f32_16x16x32_bf16 v[110:113], v[178:181], v[186:189], v[110:113]
	v_mfma_f32_16x16x32_bf16 v[102:105], v[168:171], v[194:197], v[102:105]
	v_mfma_f32_16x16x32_bf16 v[94:97], v[178:181], v[194:197], v[94:97]
	v_mfma_f32_16x16x32_bf16 v[86:89], v[168:171], v[202:205], v[86:89]
	v_mfma_f32_16x16x32_bf16 v[78:81], v[178:181], v[202:205], v[78:81]
	v_mfma_f32_16x16x32_bf16 v[70:73], v[168:171], v[210:213], v[70:73]
	v_mfma_f32_16x16x32_bf16 v[66:69], v[178:181], v[210:213], v[66:69]
	v_mfma_f32_16x16x32_bf16 v[118:121], v[172:175], v[190:193], v[118:121]
	v_mfma_f32_16x16x32_bf16 v[110:113], v[182:185], v[190:193], v[110:113]
	v_mfma_f32_16x16x32_bf16 v[102:105], v[172:175], v[198:201], v[102:105]
	v_mfma_f32_16x16x32_bf16 v[94:97], v[182:185], v[198:201], v[94:97]
	v_mfma_f32_16x16x32_bf16 v[86:89], v[172:175], v[206:209], v[86:89]
	v_mfma_f32_16x16x32_bf16 v[78:81], v[182:185], v[206:209], v[78:81]
	v_mfma_f32_16x16x32_bf16 v[70:73], v[172:175], v[214:217], v[70:73]
	v_mfma_f32_16x16x32_bf16 v[66:69], v[182:185], v[214:217], v[66:69]
	s_barrier
	s_setprio 0
	s_add_i32 s57, s47, s39
	v_lshl_add_u64 v[144:145], s[34:35], 0, v[132:133]
	s_mov_b32 m0, s57
	ds_read_b128 v[186:189], v150 offset:16384
	ds_read_b128 v[190:193], v150 offset:17408
	ds_read_b128 v[194:197], v150 offset:18432
	ds_read_b128 v[198:201], v150 offset:19456
	ds_read_b128 v[202:205], v150 offset:20480
	ds_read_b128 v[206:209], v150 offset:21504
	ds_read_b128 v[210:213], v150 offset:22528
	ds_read_b128 v[214:217], v150 offset:23552
	global_load_lds_dwordx4 v[144:145], off
	s_add_i32 m0, s57, 0x2000
	s_add_u32 s58, s34, 0x40000
	v_lshl_add_u64 v[218:219], s[34:35], 0, v[136:137]
	s_addc_u32 s59, s35, 0
	s_add_i32 s57, s48, s39
	global_load_lds_dwordx4 v[218:219], off
	v_lshl_add_u64 v[220:221], s[58:59], 0, v[132:133]
	s_mov_b32 m0, s57
	v_lshl_add_u64 v[222:223], s[2:3], 0, v[134:135]
	global_load_lds_dwordx4 v[220:221], off
	v_lshl_add_u64 v[220:221], s[58:59], 0, v[136:137]
	s_add_i32 m0, s57, 0x2000
	s_nop 0
	global_load_lds_dwordx4 v[220:221], off
	v_lshl_add_u64 v[220:221], s[2:3], 0, v[130:131]
	s_mov_b32 m0, s40
	s_nop 0
	global_load_lds_dwordx4 v[220:221], off
	s_mov_b32 m0, s29
	s_nop 0
	global_load_lds_dwordx4 v[222:223], off
	s_waitcnt vmcnt(8)
	s_waitcnt lgkmcnt(0)
	s_setprio 2
	s_barrier
	v_mfma_f32_16x16x32_bf16 v[62:65], v[152:155], v[186:189], v[62:65]
	v_mfma_f32_16x16x32_bf16 v[58:61], v[160:163], v[186:189], v[58:61]
	v_mfma_f32_16x16x32_bf16 v[50:53], v[152:155], v[194:197], v[50:53]
	v_mfma_f32_16x16x32_bf16 v[42:45], v[160:163], v[194:197], v[42:45]
	v_mfma_f32_16x16x32_bf16 v[34:37], v[152:155], v[202:205], v[34:37]
	v_mfma_f32_16x16x32_bf16 v[26:29], v[160:163], v[202:205], v[26:29]
	v_mfma_f32_16x16x32_bf16 v[18:21], v[152:155], v[210:213], v[18:21]
	v_mfma_f32_16x16x32_bf16 v[10:13], v[160:163], v[210:213], v[10:13]
	v_mfma_f32_16x16x32_bf16 v[62:65], v[156:159], v[190:193], v[62:65]
	v_mfma_f32_16x16x32_bf16 v[58:61], v[164:167], v[190:193], v[58:61]
	v_mfma_f32_16x16x32_bf16 v[50:53], v[156:159], v[198:201], v[50:53]
	v_mfma_f32_16x16x32_bf16 v[42:45], v[164:167], v[198:201], v[42:45]
	v_mfma_f32_16x16x32_bf16 v[34:37], v[156:159], v[206:209], v[34:37]
	v_mfma_f32_16x16x32_bf16 v[26:29], v[164:167], v[206:209], v[26:29]
	v_mfma_f32_16x16x32_bf16 v[18:21], v[156:159], v[214:217], v[18:21]
	v_mfma_f32_16x16x32_bf16 v[10:13], v[164:167], v[214:217], v[10:13]
	v_mfma_f32_16x16x32_bf16 v[54:57], v[168:171], v[186:189], v[54:57]
	v_mfma_f32_16x16x32_bf16 v[46:49], v[178:181], v[186:189], v[46:49]
	v_mfma_f32_16x16x32_bf16 v[38:41], v[168:171], v[194:197], v[38:41]
	v_mfma_f32_16x16x32_bf16 v[30:33], v[178:181], v[194:197], v[30:33]
	v_mfma_f32_16x16x32_bf16 v[22:25], v[168:171], v[202:205], v[22:25]
	v_mfma_f32_16x16x32_bf16 v[14:17], v[178:181], v[202:205], v[14:17]
	v_mfma_f32_16x16x32_bf16 v[6:9], v[168:171], v[210:213], v[6:9]
	v_mfma_f32_16x16x32_bf16 v[2:5], v[178:181], v[210:213], v[2:5]
	v_mfma_f32_16x16x32_bf16 v[54:57], v[172:175], v[190:193], v[54:57]
	v_mfma_f32_16x16x32_bf16 v[46:49], v[182:185], v[190:193], v[46:49]
	v_mfma_f32_16x16x32_bf16 v[38:41], v[172:175], v[198:201], v[38:41]
	v_mfma_f32_16x16x32_bf16 v[30:33], v[182:185], v[198:201], v[30:33]
	v_mfma_f32_16x16x32_bf16 v[22:25], v[172:175], v[206:209], v[22:25]
	v_mfma_f32_16x16x32_bf16 v[14:17], v[182:185], v[206:209], v[14:17]
	v_mfma_f32_16x16x32_bf16 v[6:9], v[172:175], v[214:217], v[6:9]
	v_mfma_f32_16x16x32_bf16 v[2:5], v[182:185], v[214:217], v[2:5]
	s_barrier
	s_setprio 0
	s_add_i32 s57, 0, 0x18000
	v_add_u32_e32 v151, s57, v146
	s_add_i32 s58, 0, 0x1c000
	ds_read_b128 v[152:155], v151
	ds_read_b128 v[156:159], v151 offset:1024
	ds_read_b128 v[160:163], v151 offset:2048
	ds_read_b128 v[164:167], v151 offset:3072
	v_add_u32_e32 v151, s58, v146
	ds_read_b128 v[168:171], v151
	ds_read_b128 v[172:175], v151 offset:1024
	ds_read_b128 v[178:181], v151 offset:2048
	ds_read_b128 v[182:185], v151 offset:3072
	s_add_u32 s2, s2, 0x40000
	s_addc_u32 s3, s3, 0
	s_mov_b32 m0, s41
	v_lshl_add_u64 v[224:225], s[2:3], 0, v[130:131]
	ds_read_b128 v[186:189], v150 offset:32768
	ds_read_b128 v[190:193], v150 offset:33792
	ds_read_b128 v[194:197], v150 offset:34816
	ds_read_b128 v[198:201], v150 offset:35840
	ds_read_b128 v[202:205], v150 offset:36864
	ds_read_b128 v[206:209], v150 offset:37888
	ds_read_b128 v[210:213], v150 offset:38912
	ds_read_b128 v[214:217], v150 offset:39936
	global_load_lds_dwordx4 v[224:225], off
	v_lshl_add_u64 v[224:225], s[2:3], 0, v[134:135]
	s_mov_b32 m0, s42
	s_nop 0
	global_load_lds_dwordx4 v[224:225], off
	s_waitcnt vmcnt(8)
	s_waitcnt lgkmcnt(0)
	s_setprio 2
	s_barrier
	v_mfma_f32_16x16x32_bf16 v[126:129], v[152:155], v[186:189], v[126:129]
	v_mfma_f32_16x16x32_bf16 v[122:125], v[160:163], v[186:189], v[122:125]
	v_mfma_f32_16x16x32_bf16 v[114:117], v[152:155], v[194:197], v[114:117]
	v_mfma_f32_16x16x32_bf16 v[106:109], v[160:163], v[194:197], v[106:109]
	v_mfma_f32_16x16x32_bf16 v[98:101], v[152:155], v[202:205], v[98:101]
	v_mfma_f32_16x16x32_bf16 v[90:93], v[160:163], v[202:205], v[90:93]
	v_mfma_f32_16x16x32_bf16 v[82:85], v[152:155], v[210:213], v[82:85]
	v_mfma_f32_16x16x32_bf16 v[74:77], v[160:163], v[210:213], v[74:77]
	v_mfma_f32_16x16x32_bf16 v[126:129], v[156:159], v[190:193], v[126:129]
	v_mfma_f32_16x16x32_bf16 v[122:125], v[164:167], v[190:193], v[122:125]
	v_mfma_f32_16x16x32_bf16 v[114:117], v[156:159], v[198:201], v[114:117]
	v_mfma_f32_16x16x32_bf16 v[106:109], v[164:167], v[198:201], v[106:109]
	v_mfma_f32_16x16x32_bf16 v[98:101], v[156:159], v[206:209], v[98:101]
	v_mfma_f32_16x16x32_bf16 v[90:93], v[164:167], v[206:209], v[90:93]
	v_mfma_f32_16x16x32_bf16 v[82:85], v[156:159], v[214:217], v[82:85]
	v_mfma_f32_16x16x32_bf16 v[74:77], v[164:167], v[214:217], v[74:77]
	v_mfma_f32_16x16x32_bf16 v[118:121], v[168:171], v[186:189], v[118:121]
	v_mfma_f32_16x16x32_bf16 v[110:113], v[178:181], v[186:189], v[110:113]
	v_mfma_f32_16x16x32_bf16 v[102:105], v[168:171], v[194:197], v[102:105]
	v_mfma_f32_16x16x32_bf16 v[94:97], v[178:181], v[194:197], v[94:97]
	v_mfma_f32_16x16x32_bf16 v[86:89], v[168:171], v[202:205], v[86:89]
	v_mfma_f32_16x16x32_bf16 v[78:81], v[178:181], v[202:205], v[78:81]
	v_mfma_f32_16x16x32_bf16 v[70:73], v[168:171], v[210:213], v[70:73]
	v_mfma_f32_16x16x32_bf16 v[66:69], v[178:181], v[210:213], v[66:69]
	v_mfma_f32_16x16x32_bf16 v[118:121], v[172:175], v[190:193], v[118:121]
	v_mfma_f32_16x16x32_bf16 v[110:113], v[182:185], v[190:193], v[110:113]
	v_mfma_f32_16x16x32_bf16 v[102:105], v[172:175], v[198:201], v[102:105]
	v_mfma_f32_16x16x32_bf16 v[94:97], v[182:185], v[198:201], v[94:97]
	v_mfma_f32_16x16x32_bf16 v[86:89], v[172:175], v[206:209], v[86:89]
	v_mfma_f32_16x16x32_bf16 v[78:81], v[182:185], v[206:209], v[78:81]
	v_mfma_f32_16x16x32_bf16 v[70:73], v[172:175], v[214:217], v[70:73]
	v_mfma_f32_16x16x32_bf16 v[66:69], v[182:185], v[214:217], v[66:69]
	s_barrier
	s_setprio 0
	s_add_i32 s2, s57, s39
	v_lshl_add_u64 v[144:145], v[144:145], 0, s[6:7]
	s_mov_b32 m0, s2
	ds_read_b128 v[186:189], v150 offset:49152
	ds_read_b128 v[190:193], v150 offset:50176
	ds_read_b128 v[194:197], v150 offset:51200
	ds_read_b128 v[198:201], v150 offset:52224
	ds_read_b128 v[202:205], v150 offset:53248
	ds_read_b128 v[206:209], v150 offset:54272
	ds_read_b128 v[210:213], v150 offset:55296
	ds_read_b128 v[214:217], v150 offset:56320
	global_load_lds_dwordx4 v[144:145], off
	s_add_i32 m0, s2, 0x2000
	s_add_u32 s2, s34, 0x40080
	v_lshl_add_u64 v[144:145], v[218:219], 0, s[6:7]
	s_addc_u32 s3, s35, 0
	s_add_i32 s34, s58, s39
	global_load_lds_dwordx4 v[144:145], off
	v_lshl_add_u64 v[144:145], s[2:3], 0, v[132:133]
	s_mov_b32 m0, s34
	s_nop 0
	global_load_lds_dwordx4 v[144:145], off
	v_lshl_add_u64 v[144:145], s[2:3], 0, v[136:137]
	s_add_i32 m0, s34, 0x2000
	s_nop 0
	global_load_lds_dwordx4 v[144:145], off
	v_lshl_add_u64 v[144:145], v[220:221], 0, s[6:7]
	s_mov_b32 m0, s44
	s_nop 0
	global_load_lds_dwordx4 v[144:145], off
	v_lshl_add_u64 v[144:145], v[222:223], 0, s[6:7]
	s_mov_b32 m0, s45
	s_nop 0
	global_load_lds_dwordx4 v[144:145], off
	s_waitcnt vmcnt(8)
	s_waitcnt lgkmcnt(0)
	s_setprio 2
	s_barrier
	v_mfma_f32_16x16x32_bf16 v[62:65], v[152:155], v[186:189], v[62:65]
	v_mfma_f32_16x16x32_bf16 v[58:61], v[160:163], v[186:189], v[58:61]
	v_mfma_f32_16x16x32_bf16 v[50:53], v[152:155], v[194:197], v[50:53]
	v_mfma_f32_16x16x32_bf16 v[42:45], v[160:163], v[194:197], v[42:45]
	v_mfma_f32_16x16x32_bf16 v[34:37], v[152:155], v[202:205], v[34:37]
	v_mfma_f32_16x16x32_bf16 v[26:29], v[160:163], v[202:205], v[26:29]
	v_mfma_f32_16x16x32_bf16 v[18:21], v[152:155], v[210:213], v[18:21]
	v_mfma_f32_16x16x32_bf16 v[10:13], v[160:163], v[210:213], v[10:13]
	v_mfma_f32_16x16x32_bf16 v[62:65], v[156:159], v[190:193], v[62:65]
	v_mfma_f32_16x16x32_bf16 v[58:61], v[164:167], v[190:193], v[58:61]
	v_mfma_f32_16x16x32_bf16 v[50:53], v[156:159], v[198:201], v[50:53]
	v_mfma_f32_16x16x32_bf16 v[42:45], v[164:167], v[198:201], v[42:45]
	v_mfma_f32_16x16x32_bf16 v[34:37], v[156:159], v[206:209], v[34:37]
	v_mfma_f32_16x16x32_bf16 v[26:29], v[164:167], v[206:209], v[26:29]
	v_mfma_f32_16x16x32_bf16 v[18:21], v[156:159], v[214:217], v[18:21]
	v_mfma_f32_16x16x32_bf16 v[10:13], v[164:167], v[214:217], v[10:13]
	v_mfma_f32_16x16x32_bf16 v[54:57], v[168:171], v[186:189], v[54:57]
	v_mfma_f32_16x16x32_bf16 v[46:49], v[178:181], v[186:189], v[46:49]
	v_mfma_f32_16x16x32_bf16 v[38:41], v[168:171], v[194:197], v[38:41]
	v_mfma_f32_16x16x32_bf16 v[30:33], v[178:181], v[194:197], v[30:33]
	v_mfma_f32_16x16x32_bf16 v[22:25], v[168:171], v[202:205], v[22:25]
	v_mfma_f32_16x16x32_bf16 v[14:17], v[178:181], v[202:205], v[14:17]
	v_mfma_f32_16x16x32_bf16 v[6:9], v[168:171], v[210:213], v[6:9]
	v_mfma_f32_16x16x32_bf16 v[2:5], v[178:181], v[210:213], v[2:5]
	v_mfma_f32_16x16x32_bf16 v[54:57], v[172:175], v[190:193], v[54:57]
	v_mfma_f32_16x16x32_bf16 v[46:49], v[182:185], v[190:193], v[46:49]
	v_mfma_f32_16x16x32_bf16 v[38:41], v[172:175], v[198:201], v[38:41]
	v_mfma_f32_16x16x32_bf16 v[30:33], v[182:185], v[198:201], v[30:33]
	v_mfma_f32_16x16x32_bf16 v[22:25], v[172:175], v[206:209], v[22:25]
	v_mfma_f32_16x16x32_bf16 v[14:17], v[182:185], v[206:209], v[14:17]
	v_mfma_f32_16x16x32_bf16 v[6:9], v[172:175], v[214:217], v[6:9]
	v_mfma_f32_16x16x32_bf16 v[2:5], v[182:185], v[214:217], v[2:5]
	s_barrier
	s_setprio 0
	s_add_i32 s56, s56, 2
	s_add_u32 s30, s30, 0x100
	s_addc_u32 s31, s31, 0
	s_add_u32 s54, s54, 0x100
	s_addc_u32 s55, s55, 0
	s_cmp_gt_u32 s56, 13
	s_cbranch_scc0 .LBB0_1098

.LBB0_1137:
	s_add_i32 s26, 0, 0x18000
	s_add_i32 s3, s26, s18
	s_mov_b64 s[24:25], 0x80
	v_lshl_add_u64 v[4:5], v[26:27], 0, s[24:25]
	s_mov_b32 m0, s3
	s_add_i32 s5, s3, 0x2000
	s_waitcnt vmcnt(2)
	s_barrier
	global_load_lds_dwordx4 v[4:5], off
	v_lshl_add_u64 v[6:7], v[28:29], 0, s[24:25]
	s_mov_b32 m0, s5
	s_add_i32 s4, s15, 0x8000
	global_load_lds_dwordx4 v[6:7], off
	v_lshl_add_u64 v[2:3], v[20:21], 0, s[24:25]
	s_mov_b32 m0, s4
	s_add_i32 s9, s15, 0xa000
	s_add_i32 s27, 0, 0x1c000
	global_load_lds_dwordx4 v[2:3], off
	v_lshl_add_u64 v[8:9], v[22:23], 0, s[24:25]
	s_mov_b32 m0, s9
	s_add_i32 s13, s27, s18
	global_load_lds_dwordx4 v[8:9], off
	v_lshl_add_u64 v[10:11], v[24:25], 0, s[24:25]
	s_mov_b32 m0, s13
	s_add_i32 s14, s13, 0x2000
	global_load_lds_dwordx4 v[10:11], off
	v_lshl_add_u64 v[12:13], v[18:19], 0, s[24:25]
	s_mov_b32 m0, s14
	v_and_b32_e32 v30, 15, v0
	global_load_lds_dwordx4 v[12:13], off
	v_lshlrev_b32_e32 v31, 1, v1
	v_lshlrev_b32_e32 v32, 2, v0
	v_lshl_or_b32 v130, s17, 6, v30
	v_lshl_or_b32 v30, v30, 6, v31
	s_lshl_b32 s2, s17, 13
	v_and_b32_e32 v32, 32, v32
	v_bitop3_b32 v62, v30, s2, v32 bitop3:0xde
	s_lshl_b32 s2, s19, 5
	s_and_b32 s2, s2, 0x60
	v_lshlrev_b32_e32 v30, 6, v0
	s_movk_i32 s17, 0x3c0
	v_and_or_b32 v30, v30, s17, v31
	s_lshl_b32 s17, s2, 7
	v_bitop3_b32 v63, s17, v30, v32 bitop3:0xf6
	s_add_i32 s29, 0, 0x10000
	s_add_i32 s28, 0, 0x14000
	v_add_u32_e32 v176, s29, v63
	s_waitcnt vmcnt(6)
	s_barrier
	v_add_u32_e32 v131, s28, v63
	ds_read_b128 v[30:33], v176
	ds_read_b128 v[34:37], v176 offset:1024
	ds_read_b128 v[38:41], v176 offset:2048
	ds_read_b128 v[42:45], v176 offset:3072
	ds_read_b128 v[46:49], v131
	ds_read_b128 v[50:53], v131 offset:1024
	ds_read_b128 v[54:57], v131 offset:2048
	ds_read_b128 v[58:61], v131 offset:3072
	s_add_i32 s20, s29, s18
	s_add_i32 s18, s28, s18
	s_add_i32 s22, s15, 0xc000
	s_add_i32 s21, s15, 0xe000
	s_add_i32 s19, s20, 0x2000
	s_add_i32 s17, s18, 0x2000
	s_cmpk_gt_u32 s23, 0xff
	v_add_u32_e32 v242, 0, v62
	v_add_u32_e32 v238, s27, v63
	v_add_u32_e32 v239, s26, v63
	s_mov_b32 m0, s22
	v_lshl_add_u64 v[94:95], v[14:15], 0, s[24:25]
	ds_read_b128 v[62:65], v242
	ds_read_b128 v[66:69], v242 offset:1024
	ds_read_b128 v[70:73], v242 offset:2048
	ds_read_b128 v[74:77], v242 offset:3072
	ds_read_b128 v[78:81], v242 offset:4096
	ds_read_b128 v[82:85], v242 offset:5120
	ds_read_b128 v[86:89], v242 offset:6144
	ds_read_b128 v[90:93], v242 offset:7168
	global_load_lds_dwordx4 v[94:95], off
	v_lshl_add_u64 v[94:95], v[16:17], 0, s[24:25]
	s_mov_b32 m0, s21
	s_nop 0
	global_load_lds_dwordx4 v[94:95], off
	s_waitcnt vmcnt(8)
	s_waitcnt lgkmcnt(0)
	s_setprio 2
	s_barrier
	v_mfma_f32_16x16x32_bf16 v[94:97], v[30:33], v[62:65], 0
	v_mfma_f32_16x16x32_bf16 v[98:101], v[38:41], v[62:65], 0
	v_mfma_f32_16x16x32_bf16 v[102:105], v[30:33], v[70:73], 0
	v_mfma_f32_16x16x32_bf16 v[106:109], v[38:41], v[70:73], 0
	v_mfma_f32_16x16x32_bf16 v[110:113], v[30:33], v[78:81], 0
	v_mfma_f32_16x16x32_bf16 v[114:117], v[38:41], v[78:81], 0
	v_mfma_f32_16x16x32_bf16 v[118:121], v[30:33], v[86:89], 0
	v_mfma_f32_16x16x32_bf16 v[122:125], v[38:41], v[86:89], 0
	v_mfma_f32_16x16x32_bf16 v[94:97], v[34:37], v[66:69], v[94:97]
	v_mfma_f32_16x16x32_bf16 v[98:101], v[42:45], v[66:69], v[98:101]
	v_mfma_f32_16x16x32_bf16 v[102:105], v[34:37], v[74:77], v[102:105]
	v_mfma_f32_16x16x32_bf16 v[106:109], v[42:45], v[74:77], v[106:109]
	v_mfma_f32_16x16x32_bf16 v[110:113], v[34:37], v[82:85], v[110:113]
	v_mfma_f32_16x16x32_bf16 v[114:117], v[42:45], v[82:85], v[114:117]
	v_mfma_f32_16x16x32_bf16 v[118:121], v[34:37], v[90:93], v[118:121]
	v_mfma_f32_16x16x32_bf16 v[122:125], v[42:45], v[90:93], v[122:125]
	v_mfma_f32_16x16x32_bf16 v[126:129], v[46:49], v[62:65], 0
	v_mfma_f32_16x16x32_bf16 v[62:65], v[54:57], v[62:65], 0
	v_mfma_f32_16x16x32_bf16 v[126:129], v[50:53], v[66:69], v[126:129]
	v_mfma_f32_16x16x32_bf16 v[62:65], v[58:61], v[66:69], v[62:65]
	v_mfma_f32_16x16x32_bf16 v[66:69], v[46:49], v[70:73], 0
	v_mfma_f32_16x16x32_bf16 v[70:73], v[54:57], v[70:73], 0
	v_mfma_f32_16x16x32_bf16 v[66:69], v[50:53], v[74:77], v[66:69]
	v_mfma_f32_16x16x32_bf16 v[70:73], v[58:61], v[74:77], v[70:73]
	v_mfma_f32_16x16x32_bf16 v[74:77], v[46:49], v[78:81], 0
	v_mfma_f32_16x16x32_bf16 v[78:81], v[54:57], v[78:81], 0
	v_mfma_f32_16x16x32_bf16 v[74:77], v[50:53], v[82:85], v[74:77]
	v_mfma_f32_16x16x32_bf16 v[78:81], v[58:61], v[82:85], v[78:81]
	v_mfma_f32_16x16x32_bf16 v[82:85], v[46:49], v[86:89], 0
	v_mfma_f32_16x16x32_bf16 v[86:89], v[54:57], v[86:89], 0
	v_mfma_f32_16x16x32_bf16 v[82:85], v[50:53], v[90:93], v[82:85]
	v_mfma_f32_16x16x32_bf16 v[86:89], v[58:61], v[90:93], v[86:89]
	s_barrier
	s_setprio 0
	s_mov_b64 s[24:25], 0x100
	s_mov_b32 m0, s20
	v_lshl_add_u64 v[160:161], v[26:27], 0, s[24:25]
	ds_read_b128 v[90:93], v242 offset:16384
	ds_read_b128 v[132:135], v242 offset:17408
	ds_read_b128 v[136:139], v242 offset:18432
	ds_read_b128 v[140:143], v242 offset:19456
	ds_read_b128 v[144:147], v242 offset:20480
	ds_read_b128 v[148:151], v242 offset:21504
	ds_read_b128 v[152:155], v242 offset:22528
	ds_read_b128 v[156:159], v242 offset:23552
	global_load_lds_dwordx4 v[160:161], off
	v_lshl_add_u64 v[160:161], v[28:29], 0, s[24:25]
	s_mov_b32 m0, s19
	s_nop 0
	global_load_lds_dwordx4 v[160:161], off
	v_lshl_add_u64 v[160:161], v[24:25], 0, s[24:25]
	s_mov_b32 m0, s18
	s_nop 0
	global_load_lds_dwordx4 v[160:161], off
	v_lshl_add_u64 v[160:161], v[18:19], 0, s[24:25]
	s_mov_b32 m0, s17
	s_nop 0
	global_load_lds_dwordx4 v[160:161], off
	v_lshl_add_u64 v[160:161], v[20:21], 0, s[24:25]
	s_mov_b32 m0, s15
	s_nop 0
	global_load_lds_dwordx4 v[160:161], off
	v_lshl_add_u64 v[160:161], v[22:23], 0, s[24:25]
	s_mov_b32 m0, s16
	s_nop 0
	global_load_lds_dwordx4 v[160:161], off
	s_waitcnt vmcnt(8)
	s_waitcnt lgkmcnt(0)
	s_setprio 2
	s_barrier
	v_mfma_f32_16x16x32_bf16 v[160:163], v[30:33], v[90:93], 0
	v_mfma_f32_16x16x32_bf16 v[168:171], v[30:33], v[136:139], 0
	v_mfma_f32_16x16x32_bf16 v[178:181], v[30:33], v[144:147], 0
	v_mfma_f32_16x16x32_bf16 v[30:33], v[30:33], v[152:155], 0
	v_mfma_f32_16x16x32_bf16 v[160:163], v[34:37], v[132:135], v[160:163]
	v_mfma_f32_16x16x32_bf16 v[168:171], v[34:37], v[140:143], v[168:171]
	v_mfma_f32_16x16x32_bf16 v[178:181], v[34:37], v[148:151], v[178:181]
	v_mfma_f32_16x16x32_bf16 v[30:33], v[34:37], v[156:159], v[30:33]
	v_mfma_f32_16x16x32_bf16 v[34:37], v[38:41], v[152:155], 0
	v_mfma_f32_16x16x32_bf16 v[164:167], v[38:41], v[90:93], 0
	v_mfma_f32_16x16x32_bf16 v[172:175], v[38:41], v[136:139], 0
	v_mfma_f32_16x16x32_bf16 v[182:185], v[38:41], v[144:147], 0
	v_mfma_f32_16x16x32_bf16 v[34:37], v[42:45], v[156:159], v[34:37]
	v_mfma_f32_16x16x32_bf16 v[164:167], v[42:45], v[132:135], v[164:167]
	v_mfma_f32_16x16x32_bf16 v[172:175], v[42:45], v[140:143], v[172:175]
	v_mfma_f32_16x16x32_bf16 v[182:185], v[42:45], v[148:151], v[182:185]
	v_mfma_f32_16x16x32_bf16 v[38:41], v[46:49], v[90:93], 0
	v_mfma_f32_16x16x32_bf16 v[42:45], v[54:57], v[90:93], 0
	v_mfma_f32_16x16x32_bf16 v[38:41], v[50:53], v[132:135], v[38:41]
	v_mfma_f32_16x16x32_bf16 v[42:45], v[58:61], v[132:135], v[42:45]
	v_mfma_f32_16x16x32_bf16 v[90:93], v[46:49], v[136:139], 0
	v_mfma_f32_16x16x32_bf16 v[132:135], v[54:57], v[136:139], 0
	v_mfma_f32_16x16x32_bf16 v[136:139], v[46:49], v[144:147], 0
	v_mfma_f32_16x16x32_bf16 v[46:49], v[46:49], v[152:155], 0
	v_mfma_f32_16x16x32_bf16 v[90:93], v[50:53], v[140:143], v[90:93]
	v_mfma_f32_16x16x32_bf16 v[136:139], v[50:53], v[148:151], v[136:139]
	v_mfma_f32_16x16x32_bf16 v[46:49], v[50:53], v[156:159], v[46:49]
	v_mfma_f32_16x16x32_bf16 v[50:53], v[54:57], v[152:155], 0
	v_mfma_f32_16x16x32_bf16 v[132:135], v[58:61], v[140:143], v[132:135]
	v_mfma_f32_16x16x32_bf16 v[140:143], v[54:57], v[144:147], 0
	v_mfma_f32_16x16x32_bf16 v[50:53], v[58:61], v[156:159], v[50:53]
	v_mfma_f32_16x16x32_bf16 v[140:143], v[58:61], v[148:151], v[140:143]
	s_barrier
	s_setprio 0
	ds_read_b128 v[54:57], v239
	ds_read_b128 v[58:61], v239 offset:1024
	ds_read_b128 v[144:147], v239 offset:2048
	ds_read_b128 v[148:151], v239 offset:3072
	ds_read_b128 v[152:155], v238
	ds_read_b128 v[156:159], v238 offset:1024
	ds_read_b128 v[186:189], v238 offset:2048
	ds_read_b128 v[190:193], v238 offset:3072
	s_mov_b32 m0, s11
	v_lshl_add_u64 v[226:227], v[14:15], 0, s[24:25]
	ds_read_b128 v[194:197], v242 offset:32768
	ds_read_b128 v[198:201], v242 offset:33792
	ds_read_b128 v[202:205], v242 offset:34816
	ds_read_b128 v[206:209], v242 offset:35840
	ds_read_b128 v[210:213], v242 offset:36864
	ds_read_b128 v[214:217], v242 offset:37888
	ds_read_b128 v[218:221], v242 offset:38912
	ds_read_b128 v[222:225], v242 offset:39936
	global_load_lds_dwordx4 v[226:227], off
	v_lshl_add_u64 v[226:227], v[16:17], 0, s[24:25]
	s_mov_b32 m0, s12
	s_nop 0
	global_load_lds_dwordx4 v[226:227], off
	s_waitcnt vmcnt(8)
	s_waitcnt lgkmcnt(0)
	s_setprio 2
	s_barrier
	v_mfma_f32_16x16x32_bf16 v[94:97], v[54:57], v[194:197], v[94:97]
	v_mfma_f32_16x16x32_bf16 v[98:101], v[144:147], v[194:197], v[98:101]
	v_mfma_f32_16x16x32_bf16 v[102:105], v[54:57], v[202:205], v[102:105]
	v_mfma_f32_16x16x32_bf16 v[106:109], v[144:147], v[202:205], v[106:109]
	v_mfma_f32_16x16x32_bf16 v[110:113], v[54:57], v[210:213], v[110:113]
	v_mfma_f32_16x16x32_bf16 v[114:117], v[144:147], v[210:213], v[114:117]
	v_mfma_f32_16x16x32_bf16 v[118:121], v[54:57], v[218:221], v[118:121]
	v_mfma_f32_16x16x32_bf16 v[122:125], v[144:147], v[218:221], v[122:125]
	v_mfma_f32_16x16x32_bf16 v[94:97], v[58:61], v[198:201], v[94:97]
	v_mfma_f32_16x16x32_bf16 v[98:101], v[148:151], v[198:201], v[98:101]
	v_mfma_f32_16x16x32_bf16 v[102:105], v[58:61], v[206:209], v[102:105]
	v_mfma_f32_16x16x32_bf16 v[106:109], v[148:151], v[206:209], v[106:109]
	v_mfma_f32_16x16x32_bf16 v[110:113], v[58:61], v[214:217], v[110:113]
	v_mfma_f32_16x16x32_bf16 v[114:117], v[148:151], v[214:217], v[114:117]
	v_mfma_f32_16x16x32_bf16 v[118:121], v[58:61], v[222:225], v[118:121]
	v_mfma_f32_16x16x32_bf16 v[122:125], v[148:151], v[222:225], v[122:125]
	v_mfma_f32_16x16x32_bf16 v[126:129], v[152:155], v[194:197], v[126:129]
	v_mfma_f32_16x16x32_bf16 v[62:65], v[186:189], v[194:197], v[62:65]
	v_mfma_f32_16x16x32_bf16 v[66:69], v[152:155], v[202:205], v[66:69]
	v_mfma_f32_16x16x32_bf16 v[70:73], v[186:189], v[202:205], v[70:73]
	v_mfma_f32_16x16x32_bf16 v[74:77], v[152:155], v[210:213], v[74:77]
	v_mfma_f32_16x16x32_bf16 v[78:81], v[186:189], v[210:213], v[78:81]
	v_mfma_f32_16x16x32_bf16 v[82:85], v[152:155], v[218:221], v[82:85]
	v_mfma_f32_16x16x32_bf16 v[86:89], v[186:189], v[218:221], v[86:89]
	v_mfma_f32_16x16x32_bf16 v[126:129], v[156:159], v[198:201], v[126:129]
	v_mfma_f32_16x16x32_bf16 v[62:65], v[190:193], v[198:201], v[62:65]
	v_mfma_f32_16x16x32_bf16 v[66:69], v[156:159], v[206:209], v[66:69]
	v_mfma_f32_16x16x32_bf16 v[70:73], v[190:193], v[206:209], v[70:73]
	v_mfma_f32_16x16x32_bf16 v[74:77], v[156:159], v[214:217], v[74:77]
	v_mfma_f32_16x16x32_bf16 v[78:81], v[190:193], v[214:217], v[78:81]
	v_mfma_f32_16x16x32_bf16 v[82:85], v[156:159], v[222:225], v[82:85]
	v_mfma_f32_16x16x32_bf16 v[86:89], v[190:193], v[222:225], v[86:89]
	s_barrier
	s_setprio 0
	s_mov_b64 s[24:25], 0x180
	s_mov_b32 m0, s3
	v_lshl_add_u64 v[226:227], v[26:27], 0, s[24:25]
	ds_read_b128 v[194:197], v242 offset:49152
	ds_read_b128 v[198:201], v242 offset:50176
	ds_read_b128 v[202:205], v242 offset:51200
	ds_read_b128 v[206:209], v242 offset:52224
	ds_read_b128 v[210:213], v242 offset:53248
	ds_read_b128 v[214:217], v242 offset:54272
	ds_read_b128 v[218:221], v242 offset:55296
	ds_read_b128 v[222:225], v242 offset:56320
	global_load_lds_dwordx4 v[226:227], off
	v_lshl_add_u64 v[226:227], v[28:29], 0, s[24:25]
	s_mov_b32 m0, s5
	s_nop 0
	global_load_lds_dwordx4 v[226:227], off
	v_lshl_add_u64 v[226:227], v[24:25], 0, s[24:25]
	s_mov_b32 m0, s13
	s_nop 0
	global_load_lds_dwordx4 v[226:227], off
	v_lshl_add_u64 v[226:227], v[18:19], 0, s[24:25]
	s_mov_b32 m0, s14
	s_nop 0
	global_load_lds_dwordx4 v[226:227], off
	v_lshl_add_u64 v[226:227], v[20:21], 0, s[24:25]
	s_mov_b32 m0, s4
	s_nop 0
	global_load_lds_dwordx4 v[226:227], off
	v_lshl_add_u64 v[226:227], v[22:23], 0, s[24:25]
	s_mov_b32 m0, s9
	s_nop 0
	global_load_lds_dwordx4 v[226:227], off
	s_waitcnt vmcnt(8)
	s_waitcnt lgkmcnt(0)
	s_setprio 2
	s_barrier
	v_mfma_f32_16x16x32_bf16 v[30:33], v[54:57], v[218:221], v[30:33]
	v_mfma_f32_16x16x32_bf16 v[34:37], v[144:147], v[218:221], v[34:37]
	v_mfma_f32_16x16x32_bf16 v[160:163], v[54:57], v[194:197], v[160:163]
	v_mfma_f32_16x16x32_bf16 v[164:167], v[144:147], v[194:197], v[164:167]
	v_mfma_f32_16x16x32_bf16 v[168:171], v[54:57], v[202:205], v[168:171]
	v_mfma_f32_16x16x32_bf16 v[172:175], v[144:147], v[202:205], v[172:175]
	v_mfma_f32_16x16x32_bf16 v[178:181], v[54:57], v[210:213], v[178:181]
	v_mfma_f32_16x16x32_bf16 v[182:185], v[144:147], v[210:213], v[182:185]
	v_mfma_f32_16x16x32_bf16 v[30:33], v[58:61], v[222:225], v[30:33]
	v_mfma_f32_16x16x32_bf16 v[34:37], v[148:151], v[222:225], v[34:37]
	v_mfma_f32_16x16x32_bf16 v[160:163], v[58:61], v[198:201], v[160:163]
	v_mfma_f32_16x16x32_bf16 v[164:167], v[148:151], v[198:201], v[164:167]
	v_mfma_f32_16x16x32_bf16 v[168:171], v[58:61], v[206:209], v[168:171]
	v_mfma_f32_16x16x32_bf16 v[172:175], v[148:151], v[206:209], v[172:175]
	v_mfma_f32_16x16x32_bf16 v[178:181], v[58:61], v[214:217], v[178:181]
	v_mfma_f32_16x16x32_bf16 v[182:185], v[148:151], v[214:217], v[182:185]
	v_mfma_f32_16x16x32_bf16 v[38:41], v[152:155], v[194:197], v[38:41]
	v_mfma_f32_16x16x32_bf16 v[42:45], v[186:189], v[194:197], v[42:45]
	v_mfma_f32_16x16x32_bf16 v[54:57], v[152:155], v[202:205], v[90:93]
	v_mfma_f32_16x16x32_bf16 v[58:61], v[186:189], v[202:205], v[132:135]
	v_mfma_f32_16x16x32_bf16 v[90:93], v[152:155], v[210:213], v[136:139]
	v_mfma_f32_16x16x32_bf16 v[46:49], v[152:155], v[218:221], v[46:49]
	v_mfma_f32_16x16x32_bf16 v[50:53], v[186:189], v[218:221], v[50:53]
	v_mfma_f32_16x16x32_bf16 v[38:41], v[156:159], v[198:201], v[38:41]
	v_mfma_f32_16x16x32_bf16 v[42:45], v[190:193], v[198:201], v[42:45]
	v_mfma_f32_16x16x32_bf16 v[54:57], v[156:159], v[206:209], v[54:57]
	v_mfma_f32_16x16x32_bf16 v[58:61], v[190:193], v[206:209], v[58:61]
	v_mfma_f32_16x16x32_bf16 v[90:93], v[156:159], v[214:217], v[90:93]
	v_mfma_f32_16x16x32_bf16 v[132:135], v[186:189], v[210:213], v[140:143]
	v_mfma_f32_16x16x32_bf16 v[46:49], v[156:159], v[222:225], v[46:49]
	v_mfma_f32_16x16x32_bf16 v[50:53], v[190:193], v[222:225], v[50:53]
	v_mfma_f32_16x16x32_bf16 v[132:135], v[190:193], v[214:217], v[132:135]
	s_barrier
	s_setprio 0
	ds_read_b128 v[136:139], v176
	ds_read_b128 v[140:143], v176 offset:1024
	ds_read_b128 v[144:147], v176 offset:2048
	ds_read_b128 v[148:151], v176 offset:3072
	ds_read_b128 v[152:155], v131
	ds_read_b128 v[156:159], v131 offset:1024
	ds_read_b128 v[186:189], v131 offset:2048
	ds_read_b128 v[190:193], v131 offset:3072
	s_mov_b32 m0, s22
	v_lshl_add_u64 v[226:227], v[14:15], 0, s[24:25]
	ds_read_b128 v[194:197], v242
	ds_read_b128 v[198:201], v242 offset:1024
	ds_read_b128 v[202:205], v242 offset:2048
	ds_read_b128 v[206:209], v242 offset:3072
	ds_read_b128 v[210:213], v242 offset:4096
	ds_read_b128 v[214:217], v242 offset:5120
	ds_read_b128 v[218:221], v242 offset:6144
	ds_read_b128 v[222:225], v242 offset:7168
	global_load_lds_dwordx4 v[226:227], off
	v_lshl_add_u64 v[226:227], v[16:17], 0, s[24:25]
	s_mov_b32 m0, s21
	s_nop 0
	global_load_lds_dwordx4 v[226:227], off
	s_waitcnt vmcnt(8)
	s_waitcnt lgkmcnt(0)
	s_setprio 2
	s_barrier
	v_mfma_f32_16x16x32_bf16 v[110:113], v[136:139], v[210:213], v[110:113]
	v_mfma_f32_16x16x32_bf16 v[226:229], v[140:143], v[214:217], v[110:113]
	v_mfma_f32_16x16x32_bf16 v[110:113], v[144:147], v[210:213], v[114:117]
	v_mfma_f32_16x16x32_bf16 v[94:97], v[136:139], v[194:197], v[94:97]
	v_mfma_f32_16x16x32_bf16 v[98:101], v[144:147], v[194:197], v[98:101]
	v_mfma_f32_16x16x32_bf16 v[102:105], v[136:139], v[202:205], v[102:105]
	v_mfma_f32_16x16x32_bf16 v[106:109], v[144:147], v[202:205], v[106:109]
	v_mfma_f32_16x16x32_bf16 v[114:117], v[148:151], v[214:217], v[110:113]
	v_mfma_f32_16x16x32_bf16 v[110:113], v[136:139], v[218:221], v[118:121]
	v_mfma_f32_16x16x32_bf16 v[94:97], v[140:143], v[198:201], v[94:97]
	v_mfma_f32_16x16x32_bf16 v[98:101], v[148:151], v[198:201], v[98:101]
	v_mfma_f32_16x16x32_bf16 v[102:105], v[140:143], v[206:209], v[102:105]
	v_mfma_f32_16x16x32_bf16 v[106:109], v[148:151], v[206:209], v[106:109]
	v_mfma_f32_16x16x32_bf16 v[118:121], v[140:143], v[222:225], v[110:113]
	v_mfma_f32_16x16x32_bf16 v[110:113], v[144:147], v[218:221], v[122:125]
	v_mfma_f32_16x16x32_bf16 v[230:233], v[148:151], v[222:225], v[110:113]
	v_mfma_f32_16x16x32_bf16 v[74:77], v[152:155], v[210:213], v[74:77]
	v_mfma_f32_16x16x32_bf16 v[110:113], v[152:155], v[194:197], v[126:129]
	v_mfma_f32_16x16x32_bf16 v[62:65], v[186:189], v[194:197], v[62:65]
	v_mfma_f32_16x16x32_bf16 v[194:197], v[156:159], v[214:217], v[74:77]
	v_mfma_f32_16x16x32_bf16 v[74:77], v[186:189], v[210:213], v[78:81]
	v_mfma_f32_16x16x32_bf16 v[234:237], v[156:159], v[198:201], v[110:113]
	v_mfma_f32_16x16x32_bf16 v[62:65], v[190:193], v[198:201], v[62:65]
	v_mfma_f32_16x16x32_bf16 v[66:69], v[152:155], v[202:205], v[66:69]
	v_mfma_f32_16x16x32_bf16 v[70:73], v[186:189], v[202:205], v[70:73]
	v_mfma_f32_16x16x32_bf16 v[198:201], v[190:193], v[214:217], v[74:77]
	v_mfma_f32_16x16x32_bf16 v[74:77], v[152:155], v[218:221], v[82:85]
	v_mfma_f32_16x16x32_bf16 v[66:69], v[156:159], v[206:209], v[66:69]
	v_mfma_f32_16x16x32_bf16 v[70:73], v[190:193], v[206:209], v[70:73]
	v_mfma_f32_16x16x32_bf16 v[202:205], v[156:159], v[222:225], v[74:77]
	v_mfma_f32_16x16x32_bf16 v[74:77], v[186:189], v[218:221], v[86:89]
	v_mfma_f32_16x16x32_bf16 v[206:209], v[190:193], v[222:225], v[74:77]
	s_barrier
	s_setprio 0
	s_mov_b32 m0, s20
	s_nop 3
	ds_read_b128 v[74:77], v242 offset:16384
	ds_read_b128 v[78:81], v242 offset:17408
	ds_read_b128 v[82:85], v242 offset:18432
	ds_read_b128 v[86:89], v242 offset:19456
	ds_read_b128 v[110:113], v242 offset:20480
	ds_read_b128 v[122:125], v242 offset:21504
	ds_read_b128 v[126:129], v242 offset:22528
	ds_read_b128 v[210:213], v242 offset:23552
	global_load_lds_dwordx4 v[26:27], off
	s_mov_b32 m0, s19
	s_nop 0
	global_load_lds_dwordx4 v[28:29], off
	s_mov_b32 m0, s18
	s_nop 0
	global_load_lds_dwordx4 v[24:25], off
	s_mov_b32 m0, s17
	s_nop 0
	global_load_lds_dwordx4 v[18:19], off
	s_mov_b32 m0, s15
	s_nop 0
	global_load_lds_dwordx4 v[20:21], off
	s_mov_b32 m0, s16
	s_nop 0
	global_load_lds_dwordx4 v[22:23], off
	s_waitcnt vmcnt(8)
	s_waitcnt lgkmcnt(0)
	s_setprio 2
	s_barrier
	v_mfma_f32_16x16x32_bf16 v[30:33], v[136:139], v[126:129], v[30:33]
	v_mfma_f32_16x16x32_bf16 v[18:21], v[136:139], v[74:77], v[160:163]
	v_mfma_f32_16x16x32_bf16 v[22:25], v[144:147], v[74:77], v[164:167]
	v_mfma_f32_16x16x32_bf16 v[26:29], v[136:139], v[82:85], v[168:171]
	v_mfma_f32_16x16x32_bf16 v[164:167], v[136:139], v[110:113], v[178:181]
	v_mfma_f32_16x16x32_bf16 v[136:139], v[140:143], v[210:213], v[30:33]
	v_mfma_f32_16x16x32_bf16 v[30:33], v[144:147], v[126:129], v[34:37]
	v_mfma_f32_16x16x32_bf16 v[18:21], v[140:143], v[78:81], v[18:21]
	v_mfma_f32_16x16x32_bf16 v[22:25], v[148:151], v[78:81], v[22:25]
	v_mfma_f32_16x16x32_bf16 v[26:29], v[140:143], v[86:89], v[26:29]
	v_mfma_f32_16x16x32_bf16 v[160:163], v[144:147], v[82:85], v[172:175]
	v_mfma_f32_16x16x32_bf16 v[168:171], v[144:147], v[110:113], v[182:185]
	v_mfma_f32_16x16x32_bf16 v[34:37], v[148:151], v[210:213], v[30:33]
	v_mfma_f32_16x16x32_bf16 v[160:163], v[148:151], v[86:89], v[160:163]
	v_mfma_f32_16x16x32_bf16 v[164:167], v[140:143], v[122:125], v[164:167]
	v_mfma_f32_16x16x32_bf16 v[168:171], v[148:151], v[122:125], v[168:171]
	v_mfma_f32_16x16x32_bf16 v[30:33], v[152:155], v[74:77], v[38:41]
	v_mfma_f32_16x16x32_bf16 v[38:41], v[156:159], v[78:81], v[30:33]
	v_mfma_f32_16x16x32_bf16 v[30:33], v[186:189], v[74:77], v[42:45]
	v_mfma_f32_16x16x32_bf16 v[140:143], v[190:193], v[78:81], v[30:33]
	v_mfma_f32_16x16x32_bf16 v[30:33], v[152:155], v[82:85], v[54:57]
	v_mfma_f32_16x16x32_bf16 v[144:147], v[156:159], v[86:89], v[30:33]
	v_mfma_f32_16x16x32_bf16 v[30:33], v[186:189], v[82:85], v[58:61]
	v_mfma_f32_16x16x32_bf16 v[148:151], v[190:193], v[86:89], v[30:33]
	v_mfma_f32_16x16x32_bf16 v[30:33], v[152:155], v[110:113], v[90:93]
	v_mfma_f32_16x16x32_bf16 v[172:175], v[156:159], v[122:125], v[30:33]
	v_mfma_f32_16x16x32_bf16 v[30:33], v[186:189], v[110:113], v[132:135]
	v_mfma_f32_16x16x32_bf16 v[132:135], v[190:193], v[122:125], v[30:33]
	v_mfma_f32_16x16x32_bf16 v[30:33], v[152:155], v[126:129], v[46:49]
	v_mfma_f32_16x16x32_bf16 v[152:155], v[156:159], v[210:213], v[30:33]
	v_mfma_f32_16x16x32_bf16 v[30:33], v[186:189], v[126:129], v[50:53]
	v_mfma_f32_16x16x32_bf16 v[156:159], v[190:193], v[210:213], v[30:33]
	s_barrier
	s_setprio 0
	ds_read_b128 v[50:53], v239
	ds_read_b128 v[54:57], v239 offset:1024
	ds_read_b128 v[178:181], v239 offset:2048
	ds_read_b128 v[182:185], v239 offset:3072
	ds_read_b128 v[186:189], v238
	ds_read_b128 v[190:193], v238 offset:1024
	ds_read_b128 v[210:213], v238 offset:2048
	ds_read_b128 v[214:217], v238 offset:3072
	s_mov_b32 m0, s11
	ds_read_b128 v[30:33], v242 offset:32768
	ds_read_b128 v[42:45], v242 offset:33792
	ds_read_b128 v[46:49], v242 offset:34816
	ds_read_b128 v[58:61], v242 offset:35840
	ds_read_b128 v[82:85], v242 offset:36864
	ds_read_b128 v[218:221], v242 offset:37888
	ds_read_b128 v[222:225], v242 offset:38912
	ds_read_b128 v[238:241], v242 offset:39936
	global_load_lds_dwordx4 v[14:15], off
	s_mov_b32 m0, s12
	s_nop 0
	global_load_lds_dwordx4 v[16:17], off
	s_waitcnt vmcnt(8)
	s_waitcnt lgkmcnt(0)
	s_setprio 2
	s_barrier
	v_mfma_f32_16x16x32_bf16 v[14:17], v[50:53], v[30:33], v[94:97]
	v_mfma_f32_16x16x32_bf16 v[126:129], v[54:57], v[42:45], v[14:17]
	v_mfma_f32_16x16x32_bf16 v[14:17], v[178:181], v[30:33], v[98:101]
	v_mfma_f32_16x16x32_bf16 v[122:125], v[182:185], v[42:45], v[14:17]
	v_mfma_f32_16x16x32_bf16 v[14:17], v[50:53], v[46:49], v[102:105]
	v_mfma_f32_16x16x32_bf16 v[110:113], v[54:57], v[58:61], v[14:17]
	v_mfma_f32_16x16x32_bf16 v[14:17], v[178:181], v[46:49], v[106:109]
	v_mfma_f32_16x16x32_bf16 v[106:109], v[182:185], v[58:61], v[14:17]
	v_mfma_f32_16x16x32_bf16 v[14:17], v[50:53], v[82:85], v[226:229]
	v_mfma_f32_16x16x32_bf16 v[94:97], v[54:57], v[218:221], v[14:17]
	v_mfma_f32_16x16x32_bf16 v[14:17], v[178:181], v[82:85], v[114:117]
	v_mfma_f32_16x16x32_bf16 v[90:93], v[182:185], v[218:221], v[14:17]
	v_mfma_f32_16x16x32_bf16 v[14:17], v[50:53], v[222:225], v[118:121]
	v_mfma_f32_16x16x32_bf16 v[78:81], v[54:57], v[238:241], v[14:17]
	v_mfma_f32_16x16x32_bf16 v[14:17], v[178:181], v[222:225], v[230:233]
	v_mfma_f32_16x16x32_bf16 v[74:77], v[182:185], v[238:241], v[14:17]
	v_mfma_f32_16x16x32_bf16 v[14:17], v[186:189], v[30:33], v[234:237]
	v_mfma_f32_16x16x32_bf16 v[118:121], v[190:193], v[42:45], v[14:17]
	v_mfma_f32_16x16x32_bf16 v[14:17], v[210:213], v[30:33], v[62:65]
	v_mfma_f32_16x16x32_bf16 v[114:117], v[214:217], v[42:45], v[14:17]
	v_mfma_f32_16x16x32_bf16 v[14:17], v[186:189], v[46:49], v[66:69]
	v_mfma_f32_16x16x32_bf16 v[102:105], v[190:193], v[58:61], v[14:17]
	v_mfma_f32_16x16x32_bf16 v[14:17], v[210:213], v[46:49], v[70:73]
	v_mfma_f32_16x16x32_bf16 v[98:101], v[214:217], v[58:61], v[14:17]
	v_mfma_f32_16x16x32_bf16 v[14:17], v[186:189], v[82:85], v[194:197]
	v_mfma_f32_16x16x32_bf16 v[86:89], v[190:193], v[218:221], v[14:17]
	v_mfma_f32_16x16x32_bf16 v[14:17], v[210:213], v[82:85], v[198:201]
	v_mfma_f32_16x16x32_bf16 v[82:85], v[214:217], v[218:221], v[14:17]
	v_mfma_f32_16x16x32_bf16 v[14:17], v[186:189], v[222:225], v[202:205]
	v_mfma_f32_16x16x32_bf16 v[66:69], v[190:193], v[238:241], v[14:17]
	v_mfma_f32_16x16x32_bf16 v[14:17], v[210:213], v[222:225], v[206:209]
	v_mfma_f32_16x16x32_bf16 v[58:61], v[214:217], v[238:241], v[14:17]
	s_barrier
	s_setprio 0
	s_mov_b32 m0, s3
	ds_read_b128 v[194:197], v242 offset:49152
	ds_read_b128 v[198:201], v242 offset:50176
	ds_read_b128 v[202:205], v242 offset:51200
	ds_read_b128 v[206:209], v242 offset:52224
	ds_read_b128 v[218:221], v242 offset:53248
	ds_read_b128 v[222:225], v242 offset:54272
	ds_read_b128 v[226:229], v242 offset:55296
	ds_read_b128 v[230:233], v242 offset:56320
	global_load_lds_dwordx4 v[4:5], off
	s_mov_b32 m0, s5
	s_nop 0
	global_load_lds_dwordx4 v[6:7], off
	s_mov_b32 m0, s13
	s_nop 0
	global_load_lds_dwordx4 v[10:11], off
	s_mov_b32 m0, s14
	s_nop 0
	global_load_lds_dwordx4 v[12:13], off
	s_mov_b32 m0, s4
	s_nop 0
	global_load_lds_dwordx4 v[2:3], off
	s_mov_b32 m0, s9
	s_nop 0
	global_load_lds_dwordx4 v[8:9], off
	s_waitcnt vmcnt(8)
	s_waitcnt lgkmcnt(0)
	s_setprio 2
	s_barrier
	v_mfma_f32_16x16x32_bf16 v[2:5], v[50:53], v[194:197], v[18:21]
	v_mfma_f32_16x16x32_bf16 v[70:73], v[54:57], v[198:201], v[2:5]
	v_mfma_f32_16x16x32_bf16 v[2:5], v[178:181], v[194:197], v[22:25]
	v_mfma_f32_16x16x32_bf16 v[62:65], v[182:185], v[198:201], v[2:5]
	v_mfma_f32_16x16x32_bf16 v[2:5], v[50:53], v[202:205], v[26:29]
	v_mfma_f32_16x16x32_bf16 v[46:49], v[54:57], v[206:209], v[2:5]
	v_mfma_f32_16x16x32_bf16 v[2:5], v[178:181], v[202:205], v[160:163]
	v_mfma_f32_16x16x32_bf16 v[42:45], v[182:185], v[206:209], v[2:5]
	v_mfma_f32_16x16x32_bf16 v[2:5], v[50:53], v[218:221], v[164:167]
	v_mfma_f32_16x16x32_bf16 v[30:33], v[54:57], v[222:225], v[2:5]
	v_mfma_f32_16x16x32_bf16 v[2:5], v[178:181], v[218:221], v[168:171]
	v_mfma_f32_16x16x32_bf16 v[26:29], v[182:185], v[222:225], v[2:5]
	v_mfma_f32_16x16x32_bf16 v[2:5], v[50:53], v[226:229], v[136:139]
	v_mfma_f32_16x16x32_bf16 v[14:17], v[54:57], v[230:233], v[2:5]
	v_mfma_f32_16x16x32_bf16 v[2:5], v[178:181], v[226:229], v[34:37]
	v_mfma_f32_16x16x32_bf16 v[10:13], v[182:185], v[230:233], v[2:5]
	v_mfma_f32_16x16x32_bf16 v[2:5], v[186:189], v[194:197], v[38:41]
	v_mfma_f32_16x16x32_bf16 v[54:57], v[190:193], v[198:201], v[2:5]
	v_mfma_f32_16x16x32_bf16 v[2:5], v[210:213], v[194:197], v[140:143]
	v_mfma_f32_16x16x32_bf16 v[50:53], v[214:217], v[198:201], v[2:5]
	v_mfma_f32_16x16x32_bf16 v[2:5], v[186:189], v[202:205], v[144:147]
	v_mfma_f32_16x16x32_bf16 v[38:41], v[190:193], v[206:209], v[2:5]
	v_mfma_f32_16x16x32_bf16 v[2:5], v[210:213], v[202:205], v[148:151]
	v_mfma_f32_16x16x32_bf16 v[34:37], v[214:217], v[206:209], v[2:5]
	v_mfma_f32_16x16x32_bf16 v[2:5], v[186:189], v[218:221], v[172:175]
	v_mfma_f32_16x16x32_bf16 v[22:25], v[190:193], v[222:225], v[2:5]
	v_mfma_f32_16x16x32_bf16 v[2:5], v[210:213], v[218:221], v[132:135]
	v_mfma_f32_16x16x32_bf16 v[18:21], v[214:217], v[222:225], v[2:5]
	v_mfma_f32_16x16x32_bf16 v[2:5], v[186:189], v[226:229], v[152:155]
	v_mfma_f32_16x16x32_bf16 v[6:9], v[190:193], v[230:233], v[2:5]
	v_mfma_f32_16x16x32_bf16 v[2:5], v[210:213], v[226:229], v[156:159]
	v_mfma_f32_16x16x32_bf16 v[2:5], v[214:217], v[230:233], v[2:5]
	s_barrier
	s_setprio 0
	s_cbranch_scc1 .LBB0_1139
	s_barrier

.Lpk1179_peel:
	ds_read_b128 v[144:147], v158
	ds_read_b128 v[164:167], v158 offset:1024
	ds_read_b128 v[168:171], v158 offset:2048
	ds_read_b128 v[172:175], v158 offset:3072
	ds_read_b128 v[178:181], v159
	ds_read_b128 v[182:185], v159 offset:1024
	ds_read_b128 v[186:189], v159 offset:2048
	ds_read_b128 v[190:193], v159 offset:3072
	s_add_u32 s2, s36, 0xfffc0080
	s_addc_u32 s3, s37, -1
	s_cmp_eq_u32 s61, 12
	s_cselect_b32 s3, s19, s3
	s_cselect_b32 s2, s21, s2
	s_cselect_b32 s39, s57, s60
	s_cselect_b32 s38, s58, s59
	v_lshl_add_u64 v[226:227], s[36:37], 0, v[138:139]
	s_add_i32 m0, s42, 0xc000
	ds_read_b128 v[194:197], v160
	ds_read_b128 v[198:201], v160 offset:1024
	ds_read_b128 v[202:205], v160 offset:2048
	ds_read_b128 v[206:209], v160 offset:3072
	ds_read_b128 v[210:213], v160 offset:4096
	ds_read_b128 v[214:217], v160 offset:5120
	ds_read_b128 v[218:221], v160 offset:6144
	ds_read_b128 v[222:225], v160 offset:7168
	global_load_lds_dwordx4 v[226:227], off
	v_lshl_add_u64 v[226:227], s[36:37], 0, v[140:141]
	s_add_i32 m0, s42, 0xe000
	s_nop 0
	global_load_lds_dwordx4 v[226:227], off
	s_waitcnt vmcnt(8)
	s_waitcnt lgkmcnt(0)
	s_setprio 2
	s_barrier
	v_mfma_f32_16x16x32_bf16 v[126:129], v[144:147], v[194:197], 0
	v_mfma_f32_16x16x32_bf16 v[122:125], v[168:171], v[194:197], 0
	v_mfma_f32_16x16x32_bf16 v[114:117], v[144:147], v[202:205], 0
	v_mfma_f32_16x16x32_bf16 v[106:109], v[168:171], v[202:205], 0
	v_mfma_f32_16x16x32_bf16 v[98:101], v[144:147], v[210:213], 0
	v_mfma_f32_16x16x32_bf16 v[90:93], v[168:171], v[210:213], 0
	v_mfma_f32_16x16x32_bf16 v[82:85], v[144:147], v[218:221], 0
	v_mfma_f32_16x16x32_bf16 v[74:77], v[168:171], v[218:221], 0
	v_mfma_f32_16x16x32_bf16 v[126:129], v[164:167], v[198:201], v[126:129]
	v_mfma_f32_16x16x32_bf16 v[122:125], v[172:175], v[198:201], v[122:125]
	v_mfma_f32_16x16x32_bf16 v[114:117], v[164:167], v[206:209], v[114:117]
	v_mfma_f32_16x16x32_bf16 v[106:109], v[172:175], v[206:209], v[106:109]
	v_mfma_f32_16x16x32_bf16 v[98:101], v[164:167], v[214:217], v[98:101]
	v_mfma_f32_16x16x32_bf16 v[90:93], v[172:175], v[214:217], v[90:93]
	v_mfma_f32_16x16x32_bf16 v[82:85], v[164:167], v[222:225], v[82:85]
	v_mfma_f32_16x16x32_bf16 v[74:77], v[172:175], v[222:225], v[74:77]
	v_mfma_f32_16x16x32_bf16 v[118:121], v[178:181], v[194:197], 0
	v_mfma_f32_16x16x32_bf16 v[110:113], v[186:189], v[194:197], 0
	v_mfma_f32_16x16x32_bf16 v[102:105], v[178:181], v[202:205], 0
	v_mfma_f32_16x16x32_bf16 v[94:97], v[186:189], v[202:205], 0
	v_mfma_f32_16x16x32_bf16 v[86:89], v[178:181], v[210:213], 0
	v_mfma_f32_16x16x32_bf16 v[78:81], v[186:189], v[210:213], 0
	v_mfma_f32_16x16x32_bf16 v[70:73], v[178:181], v[218:221], 0
	v_mfma_f32_16x16x32_bf16 v[66:69], v[186:189], v[218:221], 0
	v_mfma_f32_16x16x32_bf16 v[118:121], v[182:185], v[198:201], v[118:121]
	v_mfma_f32_16x16x32_bf16 v[110:113], v[190:193], v[198:201], v[110:113]
	v_mfma_f32_16x16x32_bf16 v[102:105], v[182:185], v[206:209], v[102:105]
	v_mfma_f32_16x16x32_bf16 v[94:97], v[190:193], v[206:209], v[94:97]
	v_mfma_f32_16x16x32_bf16 v[86:89], v[182:185], v[214:217], v[86:89]
	v_mfma_f32_16x16x32_bf16 v[78:81], v[190:193], v[214:217], v[78:81]
	v_mfma_f32_16x16x32_bf16 v[70:73], v[182:185], v[222:225], v[70:73]
	v_mfma_f32_16x16x32_bf16 v[66:69], v[190:193], v[222:225], v[66:69]
	s_barrier
	s_setprio 0
	s_add_i32 s62, s51, s41
	v_lshl_add_u64 v[226:227], s[38:39], 0, v[132:133]
	s_mov_b32 m0, s62
	ds_read_b128 v[194:197], v160 offset:16384
	ds_read_b128 v[198:201], v160 offset:17408
	ds_read_b128 v[202:205], v160 offset:18432
	ds_read_b128 v[206:209], v160 offset:19456
	ds_read_b128 v[210:213], v160 offset:20480
	ds_read_b128 v[214:217], v160 offset:21504
	ds_read_b128 v[218:221], v160 offset:22528
	ds_read_b128 v[222:225], v160 offset:23552
	global_load_lds_dwordx4 v[226:227], off
	s_add_i32 m0, s62, 0x2000
	s_add_u32 s62, s38, 0x40000
	v_lshl_add_u64 v[228:229], s[38:39], 0, v[136:137]
	s_addc_u32 s63, s39, 0
	s_add_i32 s64, s52, s41
	global_load_lds_dwordx4 v[228:229], off
	v_lshl_add_u64 v[230:231], s[62:63], 0, v[132:133]
	s_mov_b32 m0, s64
	v_lshl_add_u64 v[232:233], s[2:3], 0, v[134:135]
	global_load_lds_dwordx4 v[230:231], off
	v_lshl_add_u64 v[230:231], s[62:63], 0, v[136:137]
	s_add_i32 m0, s64, 0x2000
	s_nop 0
	global_load_lds_dwordx4 v[230:231], off
	v_lshl_add_u64 v[230:231], s[2:3], 0, v[130:131]
	s_mov_b32 m0, s42
	s_nop 0
	global_load_lds_dwordx4 v[230:231], off
	s_mov_b32 m0, s43
	s_nop 0
	global_load_lds_dwordx4 v[232:233], off
	s_waitcnt vmcnt(8)
	s_waitcnt lgkmcnt(0)
	s_setprio 2
	s_barrier
	v_mfma_f32_16x16x32_bf16 v[62:65], v[144:147], v[194:197], 0
	v_mfma_f32_16x16x32_bf16 v[58:61], v[168:171], v[194:197], 0
	v_mfma_f32_16x16x32_bf16 v[50:53], v[144:147], v[202:205], 0
	v_mfma_f32_16x16x32_bf16 v[42:45], v[168:171], v[202:205], 0
	v_mfma_f32_16x16x32_bf16 v[34:37], v[144:147], v[210:213], 0
	v_mfma_f32_16x16x32_bf16 v[26:29], v[168:171], v[210:213], 0
	v_mfma_f32_16x16x32_bf16 v[18:21], v[144:147], v[218:221], 0
	v_mfma_f32_16x16x32_bf16 v[10:13], v[168:171], v[218:221], 0
	v_mfma_f32_16x16x32_bf16 v[62:65], v[164:167], v[198:201], v[62:65]
	v_mfma_f32_16x16x32_bf16 v[58:61], v[172:175], v[198:201], v[58:61]
	v_mfma_f32_16x16x32_bf16 v[50:53], v[164:167], v[206:209], v[50:53]
	v_mfma_f32_16x16x32_bf16 v[42:45], v[172:175], v[206:209], v[42:45]
	v_mfma_f32_16x16x32_bf16 v[34:37], v[164:167], v[214:217], v[34:37]
	v_mfma_f32_16x16x32_bf16 v[26:29], v[172:175], v[214:217], v[26:29]
	v_mfma_f32_16x16x32_bf16 v[18:21], v[164:167], v[222:225], v[18:21]
	v_mfma_f32_16x16x32_bf16 v[10:13], v[172:175], v[222:225], v[10:13]
	v_mfma_f32_16x16x32_bf16 v[54:57], v[178:181], v[194:197], 0
	v_mfma_f32_16x16x32_bf16 v[46:49], v[186:189], v[194:197], 0
	v_mfma_f32_16x16x32_bf16 v[38:41], v[178:181], v[202:205], 0
	v_mfma_f32_16x16x32_bf16 v[30:33], v[186:189], v[202:205], 0
	v_mfma_f32_16x16x32_bf16 v[22:25], v[178:181], v[210:213], 0
	v_mfma_f32_16x16x32_bf16 v[14:17], v[186:189], v[210:213], 0
	v_mfma_f32_16x16x32_bf16 v[6:9], v[178:181], v[218:221], 0
	v_mfma_f32_16x16x32_bf16 v[2:5], v[186:189], v[218:221], 0
	v_mfma_f32_16x16x32_bf16 v[54:57], v[182:185], v[198:201], v[54:57]
	v_mfma_f32_16x16x32_bf16 v[46:49], v[190:193], v[198:201], v[46:49]
	v_mfma_f32_16x16x32_bf16 v[38:41], v[182:185], v[206:209], v[38:41]
	v_mfma_f32_16x16x32_bf16 v[30:33], v[190:193], v[206:209], v[30:33]
	v_mfma_f32_16x16x32_bf16 v[22:25], v[182:185], v[214:217], v[22:25]
	v_mfma_f32_16x16x32_bf16 v[14:17], v[190:193], v[214:217], v[14:17]
	v_mfma_f32_16x16x32_bf16 v[6:9], v[182:185], v[222:225], v[6:9]
	v_mfma_f32_16x16x32_bf16 v[2:5], v[190:193], v[222:225], v[2:5]
	s_barrier
	s_setprio 0
	s_add_i32 s62, 0, 0x18000
	v_add_u32_e32 v163, s62, v148
	s_add_i32 s63, 0, 0x1c000
	ds_read_b128 v[144:147], v163
	ds_read_b128 v[164:167], v163 offset:1024
	ds_read_b128 v[168:171], v163 offset:2048
	ds_read_b128 v[172:175], v163 offset:3072
	v_add_u32_e32 v163, s63, v148
	ds_read_b128 v[178:181], v163
	ds_read_b128 v[182:185], v163 offset:1024
	ds_read_b128 v[186:189], v163 offset:2048
	ds_read_b128 v[190:193], v163 offset:3072
	s_add_u32 s2, s2, 0x40000
	s_addc_u32 s3, s3, 0
	s_mov_b32 m0, s44
	v_lshl_add_u64 v[234:235], s[2:3], 0, v[130:131]
	ds_read_b128 v[194:197], v160 offset:32768
	ds_read_b128 v[198:201], v160 offset:33792
	ds_read_b128 v[202:205], v160 offset:34816
	ds_read_b128 v[206:209], v160 offset:35840
	ds_read_b128 v[210:213], v160 offset:36864
	ds_read_b128 v[214:217], v160 offset:37888
	ds_read_b128 v[218:221], v160 offset:38912
	ds_read_b128 v[222:225], v160 offset:39936
	global_load_lds_dwordx4 v[234:235], off
	v_lshl_add_u64 v[234:235], s[2:3], 0, v[134:135]
	s_mov_b32 m0, s45
	s_nop 0
	global_load_lds_dwordx4 v[234:235], off
	s_waitcnt vmcnt(8)
	s_waitcnt lgkmcnt(0)
	s_setprio 2
	s_barrier
	v_mfma_f32_16x16x32_bf16 v[126:129], v[144:147], v[194:197], v[126:129]
	v_mfma_f32_16x16x32_bf16 v[122:125], v[168:171], v[194:197], v[122:125]
	v_mfma_f32_16x16x32_bf16 v[114:117], v[144:147], v[202:205], v[114:117]
	v_mfma_f32_16x16x32_bf16 v[106:109], v[168:171], v[202:205], v[106:109]
	v_mfma_f32_16x16x32_bf16 v[98:101], v[144:147], v[210:213], v[98:101]
	v_mfma_f32_16x16x32_bf16 v[90:93], v[168:171], v[210:213], v[90:93]
	v_mfma_f32_16x16x32_bf16 v[82:85], v[144:147], v[218:221], v[82:85]
	v_mfma_f32_16x16x32_bf16 v[74:77], v[168:171], v[218:221], v[74:77]
	v_mfma_f32_16x16x32_bf16 v[126:129], v[164:167], v[198:201], v[126:129]
	v_mfma_f32_16x16x32_bf16 v[122:125], v[172:175], v[198:201], v[122:125]
	v_mfma_f32_16x16x32_bf16 v[114:117], v[164:167], v[206:209], v[114:117]
	v_mfma_f32_16x16x32_bf16 v[106:109], v[172:175], v[206:209], v[106:109]
	v_mfma_f32_16x16x32_bf16 v[98:101], v[164:167], v[214:217], v[98:101]
	v_mfma_f32_16x16x32_bf16 v[90:93], v[172:175], v[214:217], v[90:93]
	v_mfma_f32_16x16x32_bf16 v[82:85], v[164:167], v[222:225], v[82:85]
	v_mfma_f32_16x16x32_bf16 v[74:77], v[172:175], v[222:225], v[74:77]
	v_mfma_f32_16x16x32_bf16 v[118:121], v[178:181], v[194:197], v[118:121]
	v_mfma_f32_16x16x32_bf16 v[110:113], v[186:189], v[194:197], v[110:113]
	v_mfma_f32_16x16x32_bf16 v[102:105], v[178:181], v[202:205], v[102:105]
	v_mfma_f32_16x16x32_bf16 v[94:97], v[186:189], v[202:205], v[94:97]
	v_mfma_f32_16x16x32_bf16 v[86:89], v[178:181], v[210:213], v[86:89]
	v_mfma_f32_16x16x32_bf16 v[78:81], v[186:189], v[210:213], v[78:81]
	v_mfma_f32_16x16x32_bf16 v[70:73], v[178:181], v[218:221], v[70:73]
	v_mfma_f32_16x16x32_bf16 v[66:69], v[186:189], v[218:221], v[66:69]
	v_mfma_f32_16x16x32_bf16 v[118:121], v[182:185], v[198:201], v[118:121]
	v_mfma_f32_16x16x32_bf16 v[110:113], v[190:193], v[198:201], v[110:113]
	v_mfma_f32_16x16x32_bf16 v[102:105], v[182:185], v[206:209], v[102:105]
	v_mfma_f32_16x16x32_bf16 v[94:97], v[190:193], v[206:209], v[94:97]
	v_mfma_f32_16x16x32_bf16 v[86:89], v[182:185], v[214:217], v[86:89]
	v_mfma_f32_16x16x32_bf16 v[78:81], v[190:193], v[214:217], v[78:81]
	v_mfma_f32_16x16x32_bf16 v[70:73], v[182:185], v[222:225], v[70:73]
	v_mfma_f32_16x16x32_bf16 v[66:69], v[190:193], v[222:225], v[66:69]
	s_barrier
	s_setprio 0
	s_add_i32 s2, s62, s41
	v_lshl_add_u64 v[226:227], v[226:227], 0, s[10:11]
	s_mov_b32 m0, s2
	ds_read_b128 v[194:197], v160 offset:49152
	ds_read_b128 v[198:201], v160 offset:50176
	ds_read_b128 v[202:205], v160 offset:51200
	ds_read_b128 v[206:209], v160 offset:52224
	ds_read_b128 v[210:213], v160 offset:53248
	ds_read_b128 v[214:217], v160 offset:54272
	ds_read_b128 v[218:221], v160 offset:55296
	ds_read_b128 v[222:225], v160 offset:56320
	global_load_lds_dwordx4 v[226:227], off
	s_add_i32 m0, s2, 0x2000
	s_add_u32 s2, s38, 0x40080
	v_lshl_add_u64 v[226:227], v[228:229], 0, s[10:11]
	s_addc_u32 s3, s39, 0
	s_add_i32 s38, s63, s41
	global_load_lds_dwordx4 v[226:227], off
	v_lshl_add_u64 v[226:227], s[2:3], 0, v[132:133]
	s_mov_b32 m0, s38
	s_nop 0
	global_load_lds_dwordx4 v[226:227], off
	v_lshl_add_u64 v[226:227], s[2:3], 0, v[136:137]
	s_add_i32 m0, s38, 0x2000
	s_nop 0
	global_load_lds_dwordx4 v[226:227], off
	v_lshl_add_u64 v[226:227], v[230:231], 0, s[10:11]
	s_mov_b32 m0, s47
	s_nop 0
	global_load_lds_dwordx4 v[226:227], off
	v_lshl_add_u64 v[226:227], v[232:233], 0, s[10:11]
	s_mov_b32 m0, s48
	s_nop 0
	global_load_lds_dwordx4 v[226:227], off
	s_waitcnt vmcnt(8)
	s_waitcnt lgkmcnt(0)
	s_setprio 2
	s_barrier
	v_mfma_f32_16x16x32_bf16 v[62:65], v[144:147], v[194:197], v[62:65]
	v_mfma_f32_16x16x32_bf16 v[58:61], v[168:171], v[194:197], v[58:61]
	v_mfma_f32_16x16x32_bf16 v[50:53], v[144:147], v[202:205], v[50:53]
	v_mfma_f32_16x16x32_bf16 v[42:45], v[168:171], v[202:205], v[42:45]
	v_mfma_f32_16x16x32_bf16 v[34:37], v[144:147], v[210:213], v[34:37]
	v_mfma_f32_16x16x32_bf16 v[26:29], v[168:171], v[210:213], v[26:29]
	v_mfma_f32_16x16x32_bf16 v[18:21], v[144:147], v[218:221], v[18:21]
	v_mfma_f32_16x16x32_bf16 v[10:13], v[168:171], v[218:221], v[10:13]
	v_mfma_f32_16x16x32_bf16 v[62:65], v[164:167], v[198:201], v[62:65]
	v_mfma_f32_16x16x32_bf16 v[58:61], v[172:175], v[198:201], v[58:61]
	v_mfma_f32_16x16x32_bf16 v[50:53], v[164:167], v[206:209], v[50:53]
	v_mfma_f32_16x16x32_bf16 v[42:45], v[172:175], v[206:209], v[42:45]
	v_mfma_f32_16x16x32_bf16 v[34:37], v[164:167], v[214:217], v[34:37]
	v_mfma_f32_16x16x32_bf16 v[26:29], v[172:175], v[214:217], v[26:29]
	v_mfma_f32_16x16x32_bf16 v[18:21], v[164:167], v[222:225], v[18:21]
	v_mfma_f32_16x16x32_bf16 v[10:13], v[172:175], v[222:225], v[10:13]
	v_mfma_f32_16x16x32_bf16 v[54:57], v[178:181], v[194:197], v[54:57]
	v_mfma_f32_16x16x32_bf16 v[46:49], v[186:189], v[194:197], v[46:49]
	v_mfma_f32_16x16x32_bf16 v[38:41], v[178:181], v[202:205], v[38:41]
	v_mfma_f32_16x16x32_bf16 v[30:33], v[186:189], v[202:205], v[30:33]
	v_mfma_f32_16x16x32_bf16 v[22:25], v[178:181], v[210:213], v[22:25]
	v_mfma_f32_16x16x32_bf16 v[14:17], v[186:189], v[210:213], v[14:17]
	v_mfma_f32_16x16x32_bf16 v[6:9], v[178:181], v[218:221], v[6:9]
	v_mfma_f32_16x16x32_bf16 v[2:5], v[186:189], v[218:221], v[2:5]
	v_mfma_f32_16x16x32_bf16 v[54:57], v[182:185], v[198:201], v[54:57]
	v_mfma_f32_16x16x32_bf16 v[46:49], v[190:193], v[198:201], v[46:49]
	v_mfma_f32_16x16x32_bf16 v[38:41], v[182:185], v[206:209], v[38:41]
	v_mfma_f32_16x16x32_bf16 v[30:33], v[190:193], v[206:209], v[30:33]
	v_mfma_f32_16x16x32_bf16 v[22:25], v[182:185], v[214:217], v[22:25]
	v_mfma_f32_16x16x32_bf16 v[14:17], v[190:193], v[214:217], v[14:17]
	v_mfma_f32_16x16x32_bf16 v[6:9], v[182:185], v[222:225], v[6:9]
	v_mfma_f32_16x16x32_bf16 v[2:5], v[190:193], v[222:225], v[2:5]
	s_barrier
	s_setprio 0
	s_add_i32 s61, s61, 2
	s_add_u32 s36, s36, 0x100
	s_addc_u32 s37, s37, 0
	s_add_u32 s59, s59, 0x100
	s_addc_u32 s60, s60, 0
	s_cmp_gt_u32 s61, 13
	s_cbranch_scc0 .LBB0_1179
	s_branch .Lpk1179_exit
.LBB0_1179:
	ds_read_b128 v[144:147], v158
	ds_read_b128 v[164:167], v158 offset:1024
	ds_read_b128 v[168:171], v158 offset:2048
	ds_read_b128 v[172:175], v158 offset:3072
	ds_read_b128 v[178:181], v159
	ds_read_b128 v[182:185], v159 offset:1024
	ds_read_b128 v[186:189], v159 offset:2048
	ds_read_b128 v[190:193], v159 offset:3072
	s_add_u32 s2, s36, 0xfffc0080
	s_addc_u32 s3, s37, -1
	s_cmp_eq_u32 s61, 12
	s_cselect_b32 s3, s19, s3
	s_cselect_b32 s2, s21, s2
	s_cselect_b32 s39, s57, s60
	s_cselect_b32 s38, s58, s59
	v_lshl_add_u64 v[226:227], s[36:37], 0, v[138:139]
	s_add_i32 m0, s42, 0xc000
	ds_read_b128 v[194:197], v160
	ds_read_b128 v[198:201], v160 offset:1024
	ds_read_b128 v[202:205], v160 offset:2048
	ds_read_b128 v[206:209], v160 offset:3072
	ds_read_b128 v[210:213], v160 offset:4096
	ds_read_b128 v[214:217], v160 offset:5120
	ds_read_b128 v[218:221], v160 offset:6144
	ds_read_b128 v[222:225], v160 offset:7168
	global_load_lds_dwordx4 v[226:227], off
	v_lshl_add_u64 v[226:227], s[36:37], 0, v[140:141]
	s_add_i32 m0, s42, 0xe000
	s_nop 0
	global_load_lds_dwordx4 v[226:227], off
	s_waitcnt vmcnt(8)
	s_waitcnt lgkmcnt(0)
	s_setprio 2
	s_barrier
	v_mfma_f32_16x16x32_bf16 v[126:129], v[144:147], v[194:197], v[126:129]
	v_mfma_f32_16x16x32_bf16 v[122:125], v[168:171], v[194:197], v[122:125]
	v_mfma_f32_16x16x32_bf16 v[114:117], v[144:147], v[202:205], v[114:117]
	v_mfma_f32_16x16x32_bf16 v[106:109], v[168:171], v[202:205], v[106:109]
	v_mfma_f32_16x16x32_bf16 v[98:101], v[144:147], v[210:213], v[98:101]
	v_mfma_f32_16x16x32_bf16 v[90:93], v[168:171], v[210:213], v[90:93]
	v_mfma_f32_16x16x32_bf16 v[82:85], v[144:147], v[218:221], v[82:85]
	v_mfma_f32_16x16x32_bf16 v[74:77], v[168:171], v[218:221], v[74:77]
	v_mfma_f32_16x16x32_bf16 v[126:129], v[164:167], v[198:201], v[126:129]
	v_mfma_f32_16x16x32_bf16 v[122:125], v[172:175], v[198:201], v[122:125]
	v_mfma_f32_16x16x32_bf16 v[114:117], v[164:167], v[206:209], v[114:117]
	v_mfma_f32_16x16x32_bf16 v[106:109], v[172:175], v[206:209], v[106:109]
	v_mfma_f32_16x16x32_bf16 v[98:101], v[164:167], v[214:217], v[98:101]
	v_mfma_f32_16x16x32_bf16 v[90:93], v[172:175], v[214:217], v[90:93]
	v_mfma_f32_16x16x32_bf16 v[82:85], v[164:167], v[222:225], v[82:85]
	v_mfma_f32_16x16x32_bf16 v[74:77], v[172:175], v[222:225], v[74:77]
	v_mfma_f32_16x16x32_bf16 v[118:121], v[178:181], v[194:197], v[118:121]
	v_mfma_f32_16x16x32_bf16 v[110:113], v[186:189], v[194:197], v[110:113]
	v_mfma_f32_16x16x32_bf16 v[102:105], v[178:181], v[202:205], v[102:105]
	v_mfma_f32_16x16x32_bf16 v[94:97], v[186:189], v[202:205], v[94:97]
	v_mfma_f32_16x16x32_bf16 v[86:89], v[178:181], v[210:213], v[86:89]
	v_mfma_f32_16x16x32_bf16 v[78:81], v[186:189], v[210:213], v[78:81]
	v_mfma_f32_16x16x32_bf16 v[70:73], v[178:181], v[218:221], v[70:73]
	v_mfma_f32_16x16x32_bf16 v[66:69], v[186:189], v[218:221], v[66:69]
	v_mfma_f32_16x16x32_bf16 v[118:121], v[182:185], v[198:201], v[118:121]
	v_mfma_f32_16x16x32_bf16 v[110:113], v[190:193], v[198:201], v[110:113]
	v_mfma_f32_16x16x32_bf16 v[102:105], v[182:185], v[206:209], v[102:105]
	v_mfma_f32_16x16x32_bf16 v[94:97], v[190:193], v[206:209], v[94:97]
	v_mfma_f32_16x16x32_bf16 v[86:89], v[182:185], v[214:217], v[86:89]
	v_mfma_f32_16x16x32_bf16 v[78:81], v[190:193], v[214:217], v[78:81]
	v_mfma_f32_16x16x32_bf16 v[70:73], v[182:185], v[222:225], v[70:73]
	v_mfma_f32_16x16x32_bf16 v[66:69], v[190:193], v[222:225], v[66:69]
	s_barrier
	s_setprio 0
	s_add_i32 s62, s51, s41
	v_lshl_add_u64 v[226:227], s[38:39], 0, v[132:133]
	s_mov_b32 m0, s62
	ds_read_b128 v[194:197], v160 offset:16384
	ds_read_b128 v[198:201], v160 offset:17408
	ds_read_b128 v[202:205], v160 offset:18432
	ds_read_b128 v[206:209], v160 offset:19456
	ds_read_b128 v[210:213], v160 offset:20480
	ds_read_b128 v[214:217], v160 offset:21504
	ds_read_b128 v[218:221], v160 offset:22528
	ds_read_b128 v[222:225], v160 offset:23552
	global_load_lds_dwordx4 v[226:227], off
	s_add_i32 m0, s62, 0x2000
	s_add_u32 s62, s38, 0x40000
	v_lshl_add_u64 v[228:229], s[38:39], 0, v[136:137]
	s_addc_u32 s63, s39, 0
	s_add_i32 s64, s52, s41
	global_load_lds_dwordx4 v[228:229], off
	v_lshl_add_u64 v[230:231], s[62:63], 0, v[132:133]
	s_mov_b32 m0, s64
	v_lshl_add_u64 v[232:233], s[2:3], 0, v[134:135]
	global_load_lds_dwordx4 v[230:231], off
	v_lshl_add_u64 v[230:231], s[62:63], 0, v[136:137]
	s_add_i32 m0, s64, 0x2000
	s_nop 0
	global_load_lds_dwordx4 v[230:231], off
	v_lshl_add_u64 v[230:231], s[2:3], 0, v[130:131]
	s_mov_b32 m0, s42
	s_nop 0
	global_load_lds_dwordx4 v[230:231], off
	s_mov_b32 m0, s43
	s_nop 0
	global_load_lds_dwordx4 v[232:233], off
	s_waitcnt vmcnt(8)
	s_waitcnt lgkmcnt(0)
	s_setprio 2
	s_barrier
	v_mfma_f32_16x16x32_bf16 v[62:65], v[144:147], v[194:197], v[62:65]
	v_mfma_f32_16x16x32_bf16 v[58:61], v[168:171], v[194:197], v[58:61]
	v_mfma_f32_16x16x32_bf16 v[50:53], v[144:147], v[202:205], v[50:53]
	v_mfma_f32_16x16x32_bf16 v[42:45], v[168:171], v[202:205], v[42:45]
	v_mfma_f32_16x16x32_bf16 v[34:37], v[144:147], v[210:213], v[34:37]
	v_mfma_f32_16x16x32_bf16 v[26:29], v[168:171], v[210:213], v[26:29]
	v_mfma_f32_16x16x32_bf16 v[18:21], v[144:147], v[218:221], v[18:21]
	v_mfma_f32_16x16x32_bf16 v[10:13], v[168:171], v[218:221], v[10:13]
	v_mfma_f32_16x16x32_bf16 v[62:65], v[164:167], v[198:201], v[62:65]
	v_mfma_f32_16x16x32_bf16 v[58:61], v[172:175], v[198:201], v[58:61]
	v_mfma_f32_16x16x32_bf16 v[50:53], v[164:167], v[206:209], v[50:53]
	v_mfma_f32_16x16x32_bf16 v[42:45], v[172:175], v[206:209], v[42:45]
	v_mfma_f32_16x16x32_bf16 v[34:37], v[164:167], v[214:217], v[34:37]
	v_mfma_f32_16x16x32_bf16 v[26:29], v[172:175], v[214:217], v[26:29]
	v_mfma_f32_16x16x32_bf16 v[18:21], v[164:167], v[222:225], v[18:21]
	v_mfma_f32_16x16x32_bf16 v[10:13], v[172:175], v[222:225], v[10:13]
	v_mfma_f32_16x16x32_bf16 v[54:57], v[178:181], v[194:197], v[54:57]
	v_mfma_f32_16x16x32_bf16 v[46:49], v[186:189], v[194:197], v[46:49]
	v_mfma_f32_16x16x32_bf16 v[38:41], v[178:181], v[202:205], v[38:41]
	v_mfma_f32_16x16x32_bf16 v[30:33], v[186:189], v[202:205], v[30:33]
	v_mfma_f32_16x16x32_bf16 v[22:25], v[178:181], v[210:213], v[22:25]
	v_mfma_f32_16x16x32_bf16 v[14:17], v[186:189], v[210:213], v[14:17]
	v_mfma_f32_16x16x32_bf16 v[6:9], v[178:181], v[218:221], v[6:9]
	v_mfma_f32_16x16x32_bf16 v[2:5], v[186:189], v[218:221], v[2:5]
	v_mfma_f32_16x16x32_bf16 v[54:57], v[182:185], v[198:201], v[54:57]
	v_mfma_f32_16x16x32_bf16 v[46:49], v[190:193], v[198:201], v[46:49]
	v_mfma_f32_16x16x32_bf16 v[38:41], v[182:185], v[206:209], v[38:41]
	v_mfma_f32_16x16x32_bf16 v[30:33], v[190:193], v[206:209], v[30:33]
	v_mfma_f32_16x16x32_bf16 v[22:25], v[182:185], v[214:217], v[22:25]
	v_mfma_f32_16x16x32_bf16 v[14:17], v[190:193], v[214:217], v[14:17]
	v_mfma_f32_16x16x32_bf16 v[6:9], v[182:185], v[222:225], v[6:9]
	v_mfma_f32_16x16x32_bf16 v[2:5], v[190:193], v[222:225], v[2:5]
	s_barrier
	s_setprio 0
	s_add_i32 s62, 0, 0x18000
	v_add_u32_e32 v163, s62, v148
	s_add_i32 s63, 0, 0x1c000
	ds_read_b128 v[144:147], v163
	ds_read_b128 v[164:167], v163 offset:1024
	ds_read_b128 v[168:171], v163 offset:2048
	ds_read_b128 v[172:175], v163 offset:3072
	v_add_u32_e32 v163, s63, v148
	ds_read_b128 v[178:181], v163
	ds_read_b128 v[182:185], v163 offset:1024
	ds_read_b128 v[186:189], v163 offset:2048
	ds_read_b128 v[190:193], v163 offset:3072
	s_add_u32 s2, s2, 0x40000
	s_addc_u32 s3, s3, 0
	s_mov_b32 m0, s44
	v_lshl_add_u64 v[234:235], s[2:3], 0, v[130:131]
	ds_read_b128 v[194:197], v160 offset:32768
	ds_read_b128 v[198:201], v160 offset:33792
	ds_read_b128 v[202:205], v160 offset:34816
	ds_read_b128 v[206:209], v160 offset:35840
	ds_read_b128 v[210:213], v160 offset:36864
	ds_read_b128 v[214:217], v160 offset:37888
	ds_read_b128 v[218:221], v160 offset:38912
	ds_read_b128 v[222:225], v160 offset:39936
	global_load_lds_dwordx4 v[234:235], off
	v_lshl_add_u64 v[234:235], s[2:3], 0, v[134:135]
	s_mov_b32 m0, s45
	s_nop 0
	global_load_lds_dwordx4 v[234:235], off
	s_waitcnt vmcnt(8)
	s_waitcnt lgkmcnt(0)
	s_setprio 2
	s_barrier
	v_mfma_f32_16x16x32_bf16 v[126:129], v[144:147], v[194:197], v[126:129]
	v_mfma_f32_16x16x32_bf16 v[122:125], v[168:171], v[194:197], v[122:125]
	v_mfma_f32_16x16x32_bf16 v[114:117], v[144:147], v[202:205], v[114:117]
	v_mfma_f32_16x16x32_bf16 v[106:109], v[168:171], v[202:205], v[106:109]
	v_mfma_f32_16x16x32_bf16 v[98:101], v[144:147], v[210:213], v[98:101]
	v_mfma_f32_16x16x32_bf16 v[90:93], v[168:171], v[210:213], v[90:93]
	v_mfma_f32_16x16x32_bf16 v[82:85], v[144:147], v[218:221], v[82:85]
	v_mfma_f32_16x16x32_bf16 v[74:77], v[168:171], v[218:221], v[74:77]
	v_mfma_f32_16x16x32_bf16 v[126:129], v[164:167], v[198:201], v[126:129]
	v_mfma_f32_16x16x32_bf16 v[122:125], v[172:175], v[198:201], v[122:125]
	v_mfma_f32_16x16x32_bf16 v[114:117], v[164:167], v[206:209], v[114:117]
	v_mfma_f32_16x16x32_bf16 v[106:109], v[172:175], v[206:209], v[106:109]
	v_mfma_f32_16x16x32_bf16 v[98:101], v[164:167], v[214:217], v[98:101]
	v_mfma_f32_16x16x32_bf16 v[90:93], v[172:175], v[214:217], v[90:93]
	v_mfma_f32_16x16x32_bf16 v[82:85], v[164:167], v[222:225], v[82:85]
	v_mfma_f32_16x16x32_bf16 v[74:77], v[172:175], v[222:225], v[74:77]
	v_mfma_f32_16x16x32_bf16 v[118:121], v[178:181], v[194:197], v[118:121]
	v_mfma_f32_16x16x32_bf16 v[110:113], v[186:189], v[194:197], v[110:113]
	v_mfma_f32_16x16x32_bf16 v[102:105], v[178:181], v[202:205], v[102:105]
	v_mfma_f32_16x16x32_bf16 v[94:97], v[186:189], v[202:205], v[94:97]
	v_mfma_f32_16x16x32_bf16 v[86:89], v[178:181], v[210:213], v[86:89]
	v_mfma_f32_16x16x32_bf16 v[78:81], v[186:189], v[210:213], v[78:81]
	v_mfma_f32_16x16x32_bf16 v[70:73], v[178:181], v[218:221], v[70:73]
	v_mfma_f32_16x16x32_bf16 v[66:69], v[186:189], v[218:221], v[66:69]
	v_mfma_f32_16x16x32_bf16 v[118:121], v[182:185], v[198:201], v[118:121]
	v_mfma_f32_16x16x32_bf16 v[110:113], v[190:193], v[198:201], v[110:113]
	v_mfma_f32_16x16x32_bf16 v[102:105], v[182:185], v[206:209], v[102:105]
	v_mfma_f32_16x16x32_bf16 v[94:97], v[190:193], v[206:209], v[94:97]
	v_mfma_f32_16x16x32_bf16 v[86:89], v[182:185], v[214:217], v[86:89]
	v_mfma_f32_16x16x32_bf16 v[78:81], v[190:193], v[214:217], v[78:81]
	v_mfma_f32_16x16x32_bf16 v[70:73], v[182:185], v[222:225], v[70:73]
	v_mfma_f32_16x16x32_bf16 v[66:69], v[190:193], v[222:225], v[66:69]
	s_barrier
	s_setprio 0
	s_add_i32 s2, s62, s41
	v_lshl_add_u64 v[226:227], v[226:227], 0, s[10:11]
	s_mov_b32 m0, s2
	ds_read_b128 v[194:197], v160 offset:49152
	ds_read_b128 v[198:201], v160 offset:50176
	ds_read_b128 v[202:205], v160 offset:51200
	ds_read_b128 v[206:209], v160 offset:52224
	ds_read_b128 v[210:213], v160 offset:53248
	ds_read_b128 v[214:217], v160 offset:54272
	ds_read_b128 v[218:221], v160 offset:55296
	ds_read_b128 v[222:225], v160 offset:56320
	global_load_lds_dwordx4 v[226:227], off
	s_add_i32 m0, s2, 0x2000
	s_add_u32 s2, s38, 0x40080
	v_lshl_add_u64 v[226:227], v[228:229], 0, s[10:11]
	s_addc_u32 s3, s39, 0
	s_add_i32 s38, s63, s41
	global_load_lds_dwordx4 v[226:227], off
	v_lshl_add_u64 v[226:227], s[2:3], 0, v[132:133]
	s_mov_b32 m0, s38
	s_nop 0
	global_load_lds_dwordx4 v[226:227], off
	v_lshl_add_u64 v[226:227], s[2:3], 0, v[136:137]
	s_add_i32 m0, s38, 0x2000
	s_nop 0
	global_load_lds_dwordx4 v[226:227], off
	v_lshl_add_u64 v[226:227], v[230:231], 0, s[10:11]
	s_mov_b32 m0, s47
	s_nop 0
	global_load_lds_dwordx4 v[226:227], off
	v_lshl_add_u64 v[226:227], v[232:233], 0, s[10:11]
	s_mov_b32 m0, s48
	s_nop 0
	global_load_lds_dwordx4 v[226:227], off
	s_waitcnt vmcnt(8)
	s_waitcnt lgkmcnt(0)
	s_setprio 2
	s_barrier
	v_mfma_f32_16x16x32_bf16 v[62:65], v[144:147], v[194:197], v[62:65]
	v_mfma_f32_16x16x32_bf16 v[58:61], v[168:171], v[194:197], v[58:61]
	v_mfma_f32_16x16x32_bf16 v[50:53], v[144:147], v[202:205], v[50:53]
	v_mfma_f32_16x16x32_bf16 v[42:45], v[168:171], v[202:205], v[42:45]
	v_mfma_f32_16x16x32_bf16 v[34:37], v[144:147], v[210:213], v[34:37]
	v_mfma_f32_16x16x32_bf16 v[26:29], v[168:171], v[210:213], v[26:29]
	v_mfma_f32_16x16x32_bf16 v[18:21], v[144:147], v[218:221], v[18:21]
	v_mfma_f32_16x16x32_bf16 v[10:13], v[168:171], v[218:221], v[10:13]
	v_mfma_f32_16x16x32_bf16 v[62:65], v[164:167], v[198:201], v[62:65]
	v_mfma_f32_16x16x32_bf16 v[58:61], v[172:175], v[198:201], v[58:61]
	v_mfma_f32_16x16x32_bf16 v[50:53], v[164:167], v[206:209], v[50:53]
	v_mfma_f32_16x16x32_bf16 v[42:45], v[172:175], v[206:209], v[42:45]
	v_mfma_f32_16x16x32_bf16 v[34:37], v[164:167], v[214:217], v[34:37]
	v_mfma_f32_16x16x32_bf16 v[26:29], v[172:175], v[214:217], v[26:29]
	v_mfma_f32_16x16x32_bf16 v[18:21], v[164:167], v[222:225], v[18:21]
	v_mfma_f32_16x16x32_bf16 v[10:13], v[172:175], v[222:225], v[10:13]
	v_mfma_f32_16x16x32_bf16 v[54:57], v[178:181], v[194:197], v[54:57]
	v_mfma_f32_16x16x32_bf16 v[46:49], v[186:189], v[194:197], v[46:49]
	v_mfma_f32_16x16x32_bf16 v[38:41], v[178:181], v[202:205], v[38:41]
	v_mfma_f32_16x16x32_bf16 v[30:33], v[186:189], v[202:205], v[30:33]
	v_mfma_f32_16x16x32_bf16 v[22:25], v[178:181], v[210:213], v[22:25]
	v_mfma_f32_16x16x32_bf16 v[14:17], v[186:189], v[210:213], v[14:17]
	v_mfma_f32_16x16x32_bf16 v[6:9], v[178:181], v[218:221], v[6:9]
	v_mfma_f32_16x16x32_bf16 v[2:5], v[186:189], v[218:221], v[2:5]
	v_mfma_f32_16x16x32_bf16 v[54:57], v[182:185], v[198:201], v[54:57]
	v_mfma_f32_16x16x32_bf16 v[46:49], v[190:193], v[198:201], v[46:49]
	v_mfma_f32_16x16x32_bf16 v[38:41], v[182:185], v[206:209], v[38:41]
	v_mfma_f32_16x16x32_bf16 v[30:33], v[190:193], v[206:209], v[30:33]
	v_mfma_f32_16x16x32_bf16 v[22:25], v[182:185], v[214:217], v[22:25]
	v_mfma_f32_16x16x32_bf16 v[14:17], v[190:193], v[214:217], v[14:17]
	v_mfma_f32_16x16x32_bf16 v[6:9], v[182:185], v[222:225], v[6:9]
	v_mfma_f32_16x16x32_bf16 v[2:5], v[190:193], v[222:225], v[2:5]
	s_barrier
	s_setprio 0
	s_add_i32 s61, s61, 2
	s_add_u32 s36, s36, 0x100
	s_addc_u32 s37, s37, 0
	s_add_u32 s59, s59, 0x100
	s_addc_u32 s60, s60, 0
	s_cmp_gt_u32 s61, 13
	s_cbranch_scc0 .LBB0_1179

.Lpk1239_peel:
	ds_read_b128 v[152:155], v148
	ds_read_b128 v[156:159], v148 offset:1024
	ds_read_b128 v[160:163], v148 offset:2048
	ds_read_b128 v[164:167], v148 offset:3072
	ds_read_b128 v[168:171], v149
	ds_read_b128 v[172:175], v149 offset:1024
	ds_read_b128 v[178:181], v149 offset:2048
	ds_read_b128 v[182:185], v149 offset:3072
	s_add_u32 s2, s36, 0xfffc0080
	s_addc_u32 s3, s37, -1
	s_cmp_eq_u32 s62, 12
	s_cselect_b32 s3, s19, s3
	s_cselect_b32 s2, s21, s2
	s_cselect_b32 s39, s58, s61
	s_cselect_b32 s38, s59, s60
	v_lshl_add_u64 v[144:145], s[36:37], 0, v[138:139]
	s_add_i32 m0, s44, 0xc000
	ds_read_b128 v[186:189], v150
	ds_read_b128 v[190:193], v150 offset:1024
	ds_read_b128 v[194:197], v150 offset:2048
	ds_read_b128 v[198:201], v150 offset:3072
	ds_read_b128 v[202:205], v150 offset:4096
	ds_read_b128 v[206:209], v150 offset:5120
	ds_read_b128 v[210:213], v150 offset:6144
	ds_read_b128 v[214:217], v150 offset:7168
	global_load_lds_dwordx4 v[144:145], off
	v_lshl_add_u64 v[144:145], s[36:37], 0, v[140:141]
	s_add_i32 m0, s44, 0xe000
	s_nop 0
	global_load_lds_dwordx4 v[144:145], off
	s_waitcnt vmcnt(8)
	s_waitcnt lgkmcnt(0)
	s_setprio 2
	s_barrier
	v_mfma_f32_16x16x32_bf16 v[126:129], v[152:155], v[186:189], 0
	v_mfma_f32_16x16x32_bf16 v[122:125], v[160:163], v[186:189], 0
	v_mfma_f32_16x16x32_bf16 v[114:117], v[152:155], v[194:197], 0
	v_mfma_f32_16x16x32_bf16 v[106:109], v[160:163], v[194:197], 0
	v_mfma_f32_16x16x32_bf16 v[98:101], v[152:155], v[202:205], 0
	v_mfma_f32_16x16x32_bf16 v[90:93], v[160:163], v[202:205], 0
	v_mfma_f32_16x16x32_bf16 v[82:85], v[152:155], v[210:213], 0
	v_mfma_f32_16x16x32_bf16 v[74:77], v[160:163], v[210:213], 0
	v_mfma_f32_16x16x32_bf16 v[126:129], v[156:159], v[190:193], v[126:129]
	v_mfma_f32_16x16x32_bf16 v[122:125], v[164:167], v[190:193], v[122:125]
	v_mfma_f32_16x16x32_bf16 v[114:117], v[156:159], v[198:201], v[114:117]
	v_mfma_f32_16x16x32_bf16 v[106:109], v[164:167], v[198:201], v[106:109]
	v_mfma_f32_16x16x32_bf16 v[98:101], v[156:159], v[206:209], v[98:101]
	v_mfma_f32_16x16x32_bf16 v[90:93], v[164:167], v[206:209], v[90:93]
	v_mfma_f32_16x16x32_bf16 v[82:85], v[156:159], v[214:217], v[82:85]
	v_mfma_f32_16x16x32_bf16 v[74:77], v[164:167], v[214:217], v[74:77]
	v_mfma_f32_16x16x32_bf16 v[118:121], v[168:171], v[186:189], 0
	v_mfma_f32_16x16x32_bf16 v[110:113], v[178:181], v[186:189], 0
	v_mfma_f32_16x16x32_bf16 v[102:105], v[168:171], v[194:197], 0
	v_mfma_f32_16x16x32_bf16 v[94:97], v[178:181], v[194:197], 0
	v_mfma_f32_16x16x32_bf16 v[86:89], v[168:171], v[202:205], 0
	v_mfma_f32_16x16x32_bf16 v[78:81], v[178:181], v[202:205], 0
	v_mfma_f32_16x16x32_bf16 v[70:73], v[168:171], v[210:213], 0
	v_mfma_f32_16x16x32_bf16 v[66:69], v[178:181], v[210:213], 0
	v_mfma_f32_16x16x32_bf16 v[118:121], v[172:175], v[190:193], v[118:121]
	v_mfma_f32_16x16x32_bf16 v[110:113], v[182:185], v[190:193], v[110:113]
	v_mfma_f32_16x16x32_bf16 v[102:105], v[172:175], v[198:201], v[102:105]
	v_mfma_f32_16x16x32_bf16 v[94:97], v[182:185], v[198:201], v[94:97]
	v_mfma_f32_16x16x32_bf16 v[86:89], v[172:175], v[206:209], v[86:89]
	v_mfma_f32_16x16x32_bf16 v[78:81], v[182:185], v[206:209], v[78:81]
	v_mfma_f32_16x16x32_bf16 v[70:73], v[172:175], v[214:217], v[70:73]
	v_mfma_f32_16x16x32_bf16 v[66:69], v[182:185], v[214:217], v[66:69]
	s_barrier
	s_setprio 0
	s_add_i32 s63, s51, s43
	v_lshl_add_u64 v[144:145], s[38:39], 0, v[132:133]
	s_mov_b32 m0, s63
	ds_read_b128 v[186:189], v150 offset:16384
	ds_read_b128 v[190:193], v150 offset:17408
	ds_read_b128 v[194:197], v150 offset:18432
	ds_read_b128 v[198:201], v150 offset:19456
	ds_read_b128 v[202:205], v150 offset:20480
	ds_read_b128 v[206:209], v150 offset:21504
	ds_read_b128 v[210:213], v150 offset:22528
	ds_read_b128 v[214:217], v150 offset:23552
	global_load_lds_dwordx4 v[144:145], off
	s_add_i32 m0, s63, 0x2000
	s_add_u32 s64, s38, 0x40000
	v_lshl_add_u64 v[218:219], s[38:39], 0, v[136:137]
	s_addc_u32 s65, s39, 0
	s_add_i32 s63, s52, s43
	global_load_lds_dwordx4 v[218:219], off
	v_lshl_add_u64 v[220:221], s[64:65], 0, v[132:133]
	s_mov_b32 m0, s63
	v_lshl_add_u64 v[222:223], s[2:3], 0, v[134:135]
	global_load_lds_dwordx4 v[220:221], off
	v_lshl_add_u64 v[220:221], s[64:65], 0, v[136:137]
	s_add_i32 m0, s63, 0x2000
	s_nop 0
	global_load_lds_dwordx4 v[220:221], off
	v_lshl_add_u64 v[220:221], s[2:3], 0, v[130:131]
	s_mov_b32 m0, s44
	s_nop 0
	global_load_lds_dwordx4 v[220:221], off
	s_mov_b32 m0, s35
	s_nop 0
	global_load_lds_dwordx4 v[222:223], off
	s_waitcnt vmcnt(8)
	s_waitcnt lgkmcnt(0)
	s_setprio 2
	s_barrier
	v_mfma_f32_16x16x32_bf16 v[62:65], v[152:155], v[186:189], 0
	v_mfma_f32_16x16x32_bf16 v[58:61], v[160:163], v[186:189], 0
	v_mfma_f32_16x16x32_bf16 v[50:53], v[152:155], v[194:197], 0
	v_mfma_f32_16x16x32_bf16 v[42:45], v[160:163], v[194:197], 0
	v_mfma_f32_16x16x32_bf16 v[34:37], v[152:155], v[202:205], 0
	v_mfma_f32_16x16x32_bf16 v[26:29], v[160:163], v[202:205], 0
	v_mfma_f32_16x16x32_bf16 v[18:21], v[152:155], v[210:213], 0
	v_mfma_f32_16x16x32_bf16 v[10:13], v[160:163], v[210:213], 0
	v_mfma_f32_16x16x32_bf16 v[62:65], v[156:159], v[190:193], v[62:65]
	v_mfma_f32_16x16x32_bf16 v[58:61], v[164:167], v[190:193], v[58:61]
	v_mfma_f32_16x16x32_bf16 v[50:53], v[156:159], v[198:201], v[50:53]
	v_mfma_f32_16x16x32_bf16 v[42:45], v[164:167], v[198:201], v[42:45]
	v_mfma_f32_16x16x32_bf16 v[34:37], v[156:159], v[206:209], v[34:37]
	v_mfma_f32_16x16x32_bf16 v[26:29], v[164:167], v[206:209], v[26:29]
	v_mfma_f32_16x16x32_bf16 v[18:21], v[156:159], v[214:217], v[18:21]
	v_mfma_f32_16x16x32_bf16 v[10:13], v[164:167], v[214:217], v[10:13]
	v_mfma_f32_16x16x32_bf16 v[54:57], v[168:171], v[186:189], 0
	v_mfma_f32_16x16x32_bf16 v[46:49], v[178:181], v[186:189], 0
	v_mfma_f32_16x16x32_bf16 v[38:41], v[168:171], v[194:197], 0
	v_mfma_f32_16x16x32_bf16 v[30:33], v[178:181], v[194:197], 0
	v_mfma_f32_16x16x32_bf16 v[22:25], v[168:171], v[202:205], 0
	v_mfma_f32_16x16x32_bf16 v[14:17], v[178:181], v[202:205], 0
	v_mfma_f32_16x16x32_bf16 v[6:9], v[168:171], v[210:213], 0
	v_mfma_f32_16x16x32_bf16 v[2:5], v[178:181], v[210:213], 0
	v_mfma_f32_16x16x32_bf16 v[54:57], v[172:175], v[190:193], v[54:57]
	v_mfma_f32_16x16x32_bf16 v[46:49], v[182:185], v[190:193], v[46:49]
	v_mfma_f32_16x16x32_bf16 v[38:41], v[172:175], v[198:201], v[38:41]
	v_mfma_f32_16x16x32_bf16 v[30:33], v[182:185], v[198:201], v[30:33]
	v_mfma_f32_16x16x32_bf16 v[22:25], v[172:175], v[206:209], v[22:25]
	v_mfma_f32_16x16x32_bf16 v[14:17], v[182:185], v[206:209], v[14:17]
	v_mfma_f32_16x16x32_bf16 v[6:9], v[172:175], v[214:217], v[6:9]
	v_mfma_f32_16x16x32_bf16 v[2:5], v[182:185], v[214:217], v[2:5]
	s_barrier
	s_setprio 0
	s_add_i32 s63, 0, 0x18000
	v_add_u32_e32 v151, s63, v146
	s_add_i32 s64, 0, 0x1c000
	ds_read_b128 v[152:155], v151
	ds_read_b128 v[156:159], v151 offset:1024
	ds_read_b128 v[160:163], v151 offset:2048
	ds_read_b128 v[164:167], v151 offset:3072
	v_add_u32_e32 v151, s64, v146
	ds_read_b128 v[168:171], v151
	ds_read_b128 v[172:175], v151 offset:1024
	ds_read_b128 v[178:181], v151 offset:2048
	ds_read_b128 v[182:185], v151 offset:3072
	s_add_u32 s2, s2, 0x40000
	s_addc_u32 s3, s3, 0
	s_mov_b32 m0, s45
	v_lshl_add_u64 v[224:225], s[2:3], 0, v[130:131]
	ds_read_b128 v[186:189], v150 offset:32768
	ds_read_b128 v[190:193], v150 offset:33792
	ds_read_b128 v[194:197], v150 offset:34816
	ds_read_b128 v[198:201], v150 offset:35840
	ds_read_b128 v[202:205], v150 offset:36864
	ds_read_b128 v[206:209], v150 offset:37888
	ds_read_b128 v[210:213], v150 offset:38912
	ds_read_b128 v[214:217], v150 offset:39936
	global_load_lds_dwordx4 v[224:225], off
	v_lshl_add_u64 v[224:225], s[2:3], 0, v[134:135]
	s_mov_b32 m0, s46
	s_nop 0
	global_load_lds_dwordx4 v[224:225], off
	s_waitcnt vmcnt(8)
	s_waitcnt lgkmcnt(0)
	s_setprio 2
	s_barrier
	v_mfma_f32_16x16x32_bf16 v[126:129], v[152:155], v[186:189], v[126:129]
	v_mfma_f32_16x16x32_bf16 v[122:125], v[160:163], v[186:189], v[122:125]
	v_mfma_f32_16x16x32_bf16 v[114:117], v[152:155], v[194:197], v[114:117]
	v_mfma_f32_16x16x32_bf16 v[106:109], v[160:163], v[194:197], v[106:109]
	v_mfma_f32_16x16x32_bf16 v[98:101], v[152:155], v[202:205], v[98:101]
	v_mfma_f32_16x16x32_bf16 v[90:93], v[160:163], v[202:205], v[90:93]
	v_mfma_f32_16x16x32_bf16 v[82:85], v[152:155], v[210:213], v[82:85]
	v_mfma_f32_16x16x32_bf16 v[74:77], v[160:163], v[210:213], v[74:77]
	v_mfma_f32_16x16x32_bf16 v[126:129], v[156:159], v[190:193], v[126:129]
	v_mfma_f32_16x16x32_bf16 v[122:125], v[164:167], v[190:193], v[122:125]
	v_mfma_f32_16x16x32_bf16 v[114:117], v[156:159], v[198:201], v[114:117]
	v_mfma_f32_16x16x32_bf16 v[106:109], v[164:167], v[198:201], v[106:109]
	v_mfma_f32_16x16x32_bf16 v[98:101], v[156:159], v[206:209], v[98:101]
	v_mfma_f32_16x16x32_bf16 v[90:93], v[164:167], v[206:209], v[90:93]
	v_mfma_f32_16x16x32_bf16 v[82:85], v[156:159], v[214:217], v[82:85]
	v_mfma_f32_16x16x32_bf16 v[74:77], v[164:167], v[214:217], v[74:77]
	v_mfma_f32_16x16x32_bf16 v[118:121], v[168:171], v[186:189], v[118:121]
	v_mfma_f32_16x16x32_bf16 v[110:113], v[178:181], v[186:189], v[110:113]
	v_mfma_f32_16x16x32_bf16 v[102:105], v[168:171], v[194:197], v[102:105]
	v_mfma_f32_16x16x32_bf16 v[94:97], v[178:181], v[194:197], v[94:97]
	v_mfma_f32_16x16x32_bf16 v[86:89], v[168:171], v[202:205], v[86:89]
	v_mfma_f32_16x16x32_bf16 v[78:81], v[178:181], v[202:205], v[78:81]
	v_mfma_f32_16x16x32_bf16 v[70:73], v[168:171], v[210:213], v[70:73]
	v_mfma_f32_16x16x32_bf16 v[66:69], v[178:181], v[210:213], v[66:69]
	v_mfma_f32_16x16x32_bf16 v[118:121], v[172:175], v[190:193], v[118:121]
	v_mfma_f32_16x16x32_bf16 v[110:113], v[182:185], v[190:193], v[110:113]
	v_mfma_f32_16x16x32_bf16 v[102:105], v[172:175], v[198:201], v[102:105]
	v_mfma_f32_16x16x32_bf16 v[94:97], v[182:185], v[198:201], v[94:97]
	v_mfma_f32_16x16x32_bf16 v[86:89], v[172:175], v[206:209], v[86:89]
	v_mfma_f32_16x16x32_bf16 v[78:81], v[182:185], v[206:209], v[78:81]
	v_mfma_f32_16x16x32_bf16 v[70:73], v[172:175], v[214:217], v[70:73]
	v_mfma_f32_16x16x32_bf16 v[66:69], v[182:185], v[214:217], v[66:69]
	s_barrier
	s_setprio 0
	s_add_i32 s2, s63, s43
	v_lshl_add_u64 v[144:145], v[144:145], 0, s[8:9]
	s_mov_b32 m0, s2
	ds_read_b128 v[186:189], v150 offset:49152
	ds_read_b128 v[190:193], v150 offset:50176
	ds_read_b128 v[194:197], v150 offset:51200
	ds_read_b128 v[198:201], v150 offset:52224
	ds_read_b128 v[202:205], v150 offset:53248
	ds_read_b128 v[206:209], v150 offset:54272
	ds_read_b128 v[210:213], v150 offset:55296
	ds_read_b128 v[214:217], v150 offset:56320
	global_load_lds_dwordx4 v[144:145], off
	s_add_i32 m0, s2, 0x2000
	s_add_u32 s2, s38, 0x40080
	v_lshl_add_u64 v[144:145], v[218:219], 0, s[8:9]
	s_addc_u32 s3, s39, 0
	s_add_i32 s38, s64, s43
	global_load_lds_dwordx4 v[144:145], off
	v_lshl_add_u64 v[144:145], s[2:3], 0, v[132:133]
	s_mov_b32 m0, s38
	s_nop 0
	global_load_lds_dwordx4 v[144:145], off
	v_lshl_add_u64 v[144:145], s[2:3], 0, v[136:137]
	s_add_i32 m0, s38, 0x2000
	s_nop 0
	global_load_lds_dwordx4 v[144:145], off
	v_lshl_add_u64 v[144:145], v[220:221], 0, s[8:9]
	s_mov_b32 m0, s48
	s_nop 0
	global_load_lds_dwordx4 v[144:145], off
	v_lshl_add_u64 v[144:145], v[222:223], 0, s[8:9]
	s_mov_b32 m0, s49
	s_nop 0
	global_load_lds_dwordx4 v[144:145], off
	s_waitcnt vmcnt(8)
	s_waitcnt lgkmcnt(0)
	s_setprio 2
	s_barrier
	v_mfma_f32_16x16x32_bf16 v[62:65], v[152:155], v[186:189], v[62:65]
	v_mfma_f32_16x16x32_bf16 v[58:61], v[160:163], v[186:189], v[58:61]
	v_mfma_f32_16x16x32_bf16 v[50:53], v[152:155], v[194:197], v[50:53]
	v_mfma_f32_16x16x32_bf16 v[42:45], v[160:163], v[194:197], v[42:45]
	v_mfma_f32_16x16x32_bf16 v[34:37], v[152:155], v[202:205], v[34:37]
	v_mfma_f32_16x16x32_bf16 v[26:29], v[160:163], v[202:205], v[26:29]
	v_mfma_f32_16x16x32_bf16 v[18:21], v[152:155], v[210:213], v[18:21]
	v_mfma_f32_16x16x32_bf16 v[10:13], v[160:163], v[210:213], v[10:13]
	v_mfma_f32_16x16x32_bf16 v[62:65], v[156:159], v[190:193], v[62:65]
	v_mfma_f32_16x16x32_bf16 v[58:61], v[164:167], v[190:193], v[58:61]
	v_mfma_f32_16x16x32_bf16 v[50:53], v[156:159], v[198:201], v[50:53]
	v_mfma_f32_16x16x32_bf16 v[42:45], v[164:167], v[198:201], v[42:45]
	v_mfma_f32_16x16x32_bf16 v[34:37], v[156:159], v[206:209], v[34:37]
	v_mfma_f32_16x16x32_bf16 v[26:29], v[164:167], v[206:209], v[26:29]
	v_mfma_f32_16x16x32_bf16 v[18:21], v[156:159], v[214:217], v[18:21]
	v_mfma_f32_16x16x32_bf16 v[10:13], v[164:167], v[214:217], v[10:13]
	v_mfma_f32_16x16x32_bf16 v[54:57], v[168:171], v[186:189], v[54:57]
	v_mfma_f32_16x16x32_bf16 v[46:49], v[178:181], v[186:189], v[46:49]
	v_mfma_f32_16x16x32_bf16 v[38:41], v[168:171], v[194:197], v[38:41]
	v_mfma_f32_16x16x32_bf16 v[30:33], v[178:181], v[194:197], v[30:33]
	v_mfma_f32_16x16x32_bf16 v[22:25], v[168:171], v[202:205], v[22:25]
	v_mfma_f32_16x16x32_bf16 v[14:17], v[178:181], v[202:205], v[14:17]
	v_mfma_f32_16x16x32_bf16 v[6:9], v[168:171], v[210:213], v[6:9]
	v_mfma_f32_16x16x32_bf16 v[2:5], v[178:181], v[210:213], v[2:5]
	v_mfma_f32_16x16x32_bf16 v[54:57], v[172:175], v[190:193], v[54:57]
	v_mfma_f32_16x16x32_bf16 v[46:49], v[182:185], v[190:193], v[46:49]
	v_mfma_f32_16x16x32_bf16 v[38:41], v[172:175], v[198:201], v[38:41]
	v_mfma_f32_16x16x32_bf16 v[30:33], v[182:185], v[198:201], v[30:33]
	v_mfma_f32_16x16x32_bf16 v[22:25], v[172:175], v[206:209], v[22:25]
	v_mfma_f32_16x16x32_bf16 v[14:17], v[182:185], v[206:209], v[14:17]
	v_mfma_f32_16x16x32_bf16 v[6:9], v[172:175], v[214:217], v[6:9]
	v_mfma_f32_16x16x32_bf16 v[2:5], v[182:185], v[214:217], v[2:5]
	s_barrier
	s_setprio 0
	s_add_i32 s62, s62, 2
	s_add_u32 s36, s36, 0x100
	s_addc_u32 s37, s37, 0
	s_add_u32 s60, s60, 0x100
	s_addc_u32 s61, s61, 0
	s_cmp_gt_u32 s62, 13
	s_cbranch_scc0 .LBB0_1239
	s_branch .Lpk1239_exit
.LBB0_1239:
	ds_read_b128 v[152:155], v148
	ds_read_b128 v[156:159], v148 offset:1024
	ds_read_b128 v[160:163], v148 offset:2048
	ds_read_b128 v[164:167], v148 offset:3072
	ds_read_b128 v[168:171], v149
	ds_read_b128 v[172:175], v149 offset:1024
	ds_read_b128 v[178:181], v149 offset:2048
	ds_read_b128 v[182:185], v149 offset:3072
	s_add_u32 s2, s36, 0xfffc0080
	s_addc_u32 s3, s37, -1
	s_cmp_eq_u32 s62, 12
	s_cselect_b32 s3, s19, s3
	s_cselect_b32 s2, s21, s2
	s_cselect_b32 s39, s58, s61
	s_cselect_b32 s38, s59, s60
	v_lshl_add_u64 v[144:145], s[36:37], 0, v[138:139]
	s_add_i32 m0, s44, 0xc000
	ds_read_b128 v[186:189], v150
	ds_read_b128 v[190:193], v150 offset:1024
	ds_read_b128 v[194:197], v150 offset:2048
	ds_read_b128 v[198:201], v150 offset:3072
	ds_read_b128 v[202:205], v150 offset:4096
	ds_read_b128 v[206:209], v150 offset:5120
	ds_read_b128 v[210:213], v150 offset:6144
	ds_read_b128 v[214:217], v150 offset:7168
	global_load_lds_dwordx4 v[144:145], off
	v_lshl_add_u64 v[144:145], s[36:37], 0, v[140:141]
	s_add_i32 m0, s44, 0xe000
	s_nop 0
	global_load_lds_dwordx4 v[144:145], off
	s_waitcnt vmcnt(8)
	s_waitcnt lgkmcnt(0)
	s_setprio 2
	s_barrier
	v_mfma_f32_16x16x32_bf16 v[126:129], v[152:155], v[186:189], v[126:129]
	v_mfma_f32_16x16x32_bf16 v[122:125], v[160:163], v[186:189], v[122:125]
	v_mfma_f32_16x16x32_bf16 v[114:117], v[152:155], v[194:197], v[114:117]
	v_mfma_f32_16x16x32_bf16 v[106:109], v[160:163], v[194:197], v[106:109]
	v_mfma_f32_16x16x32_bf16 v[98:101], v[152:155], v[202:205], v[98:101]
	v_mfma_f32_16x16x32_bf16 v[90:93], v[160:163], v[202:205], v[90:93]
	v_mfma_f32_16x16x32_bf16 v[82:85], v[152:155], v[210:213], v[82:85]
	v_mfma_f32_16x16x32_bf16 v[74:77], v[160:163], v[210:213], v[74:77]
	v_mfma_f32_16x16x32_bf16 v[126:129], v[156:159], v[190:193], v[126:129]
	v_mfma_f32_16x16x32_bf16 v[122:125], v[164:167], v[190:193], v[122:125]
	v_mfma_f32_16x16x32_bf16 v[114:117], v[156:159], v[198:201], v[114:117]
	v_mfma_f32_16x16x32_bf16 v[106:109], v[164:167], v[198:201], v[106:109]
	v_mfma_f32_16x16x32_bf16 v[98:101], v[156:159], v[206:209], v[98:101]
	v_mfma_f32_16x16x32_bf16 v[90:93], v[164:167], v[206:209], v[90:93]
	v_mfma_f32_16x16x32_bf16 v[82:85], v[156:159], v[214:217], v[82:85]
	v_mfma_f32_16x16x32_bf16 v[74:77], v[164:167], v[214:217], v[74:77]
	v_mfma_f32_16x16x32_bf16 v[118:121], v[168:171], v[186:189], v[118:121]
	v_mfma_f32_16x16x32_bf16 v[110:113], v[178:181], v[186:189], v[110:113]
	v_mfma_f32_16x16x32_bf16 v[102:105], v[168:171], v[194:197], v[102:105]
	v_mfma_f32_16x16x32_bf16 v[94:97], v[178:181], v[194:197], v[94:97]
	v_mfma_f32_16x16x32_bf16 v[86:89], v[168:171], v[202:205], v[86:89]
	v_mfma_f32_16x16x32_bf16 v[78:81], v[178:181], v[202:205], v[78:81]
	v_mfma_f32_16x16x32_bf16 v[70:73], v[168:171], v[210:213], v[70:73]
	v_mfma_f32_16x16x32_bf16 v[66:69], v[178:181], v[210:213], v[66:69]
	v_mfma_f32_16x16x32_bf16 v[118:121], v[172:175], v[190:193], v[118:121]
	v_mfma_f32_16x16x32_bf16 v[110:113], v[182:185], v[190:193], v[110:113]
	v_mfma_f32_16x16x32_bf16 v[102:105], v[172:175], v[198:201], v[102:105]
	v_mfma_f32_16x16x32_bf16 v[94:97], v[182:185], v[198:201], v[94:97]
	v_mfma_f32_16x16x32_bf16 v[86:89], v[172:175], v[206:209], v[86:89]
	v_mfma_f32_16x16x32_bf16 v[78:81], v[182:185], v[206:209], v[78:81]
	v_mfma_f32_16x16x32_bf16 v[70:73], v[172:175], v[214:217], v[70:73]
	v_mfma_f32_16x16x32_bf16 v[66:69], v[182:185], v[214:217], v[66:69]
	s_barrier
	s_setprio 0
	s_add_i32 s63, s51, s43
	v_lshl_add_u64 v[144:145], s[38:39], 0, v[132:133]
	s_mov_b32 m0, s63
	ds_read_b128 v[186:189], v150 offset:16384
	ds_read_b128 v[190:193], v150 offset:17408
	ds_read_b128 v[194:197], v150 offset:18432
	ds_read_b128 v[198:201], v150 offset:19456
	ds_read_b128 v[202:205], v150 offset:20480
	ds_read_b128 v[206:209], v150 offset:21504
	ds_read_b128 v[210:213], v150 offset:22528
	ds_read_b128 v[214:217], v150 offset:23552
	global_load_lds_dwordx4 v[144:145], off
	s_add_i32 m0, s63, 0x2000
	s_add_u32 s64, s38, 0x40000
	v_lshl_add_u64 v[218:219], s[38:39], 0, v[136:137]
	s_addc_u32 s65, s39, 0
	s_add_i32 s63, s52, s43
	global_load_lds_dwordx4 v[218:219], off
	v_lshl_add_u64 v[220:221], s[64:65], 0, v[132:133]
	s_mov_b32 m0, s63
	v_lshl_add_u64 v[222:223], s[2:3], 0, v[134:135]
	global_load_lds_dwordx4 v[220:221], off
	v_lshl_add_u64 v[220:221], s[64:65], 0, v[136:137]
	s_add_i32 m0, s63, 0x2000
	s_nop 0
	global_load_lds_dwordx4 v[220:221], off
	v_lshl_add_u64 v[220:221], s[2:3], 0, v[130:131]
	s_mov_b32 m0, s44
	s_nop 0
	global_load_lds_dwordx4 v[220:221], off
	s_mov_b32 m0, s35
	s_nop 0
	global_load_lds_dwordx4 v[222:223], off
	s_waitcnt vmcnt(8)
	s_waitcnt lgkmcnt(0)
	s_setprio 2
	s_barrier
	v_mfma_f32_16x16x32_bf16 v[62:65], v[152:155], v[186:189], v[62:65]
	v_mfma_f32_16x16x32_bf16 v[58:61], v[160:163], v[186:189], v[58:61]
	v_mfma_f32_16x16x32_bf16 v[50:53], v[152:155], v[194:197], v[50:53]
	v_mfma_f32_16x16x32_bf16 v[42:45], v[160:163], v[194:197], v[42:45]
	v_mfma_f32_16x16x32_bf16 v[34:37], v[152:155], v[202:205], v[34:37]
	v_mfma_f32_16x16x32_bf16 v[26:29], v[160:163], v[202:205], v[26:29]
	v_mfma_f32_16x16x32_bf16 v[18:21], v[152:155], v[210:213], v[18:21]
	v_mfma_f32_16x16x32_bf16 v[10:13], v[160:163], v[210:213], v[10:13]
	v_mfma_f32_16x16x32_bf16 v[62:65], v[156:159], v[190:193], v[62:65]
	v_mfma_f32_16x16x32_bf16 v[58:61], v[164:167], v[190:193], v[58:61]
	v_mfma_f32_16x16x32_bf16 v[50:53], v[156:159], v[198:201], v[50:53]
	v_mfma_f32_16x16x32_bf16 v[42:45], v[164:167], v[198:201], v[42:45]
	v_mfma_f32_16x16x32_bf16 v[34:37], v[156:159], v[206:209], v[34:37]
	v_mfma_f32_16x16x32_bf16 v[26:29], v[164:167], v[206:209], v[26:29]
	v_mfma_f32_16x16x32_bf16 v[18:21], v[156:159], v[214:217], v[18:21]
	v_mfma_f32_16x16x32_bf16 v[10:13], v[164:167], v[214:217], v[10:13]
	v_mfma_f32_16x16x32_bf16 v[54:57], v[168:171], v[186:189], v[54:57]
	v_mfma_f32_16x16x32_bf16 v[46:49], v[178:181], v[186:189], v[46:49]
	v_mfma_f32_16x16x32_bf16 v[38:41], v[168:171], v[194:197], v[38:41]
	v_mfma_f32_16x16x32_bf16 v[30:33], v[178:181], v[194:197], v[30:33]
	v_mfma_f32_16x16x32_bf16 v[22:25], v[168:171], v[202:205], v[22:25]
	v_mfma_f32_16x16x32_bf16 v[14:17], v[178:181], v[202:205], v[14:17]
	v_mfma_f32_16x16x32_bf16 v[6:9], v[168:171], v[210:213], v[6:9]
	v_mfma_f32_16x16x32_bf16 v[2:5], v[178:181], v[210:213], v[2:5]
	v_mfma_f32_16x16x32_bf16 v[54:57], v[172:175], v[190:193], v[54:57]
	v_mfma_f32_16x16x32_bf16 v[46:49], v[182:185], v[190:193], v[46:49]
	v_mfma_f32_16x16x32_bf16 v[38:41], v[172:175], v[198:201], v[38:41]
	v_mfma_f32_16x16x32_bf16 v[30:33], v[182:185], v[198:201], v[30:33]
	v_mfma_f32_16x16x32_bf16 v[22:25], v[172:175], v[206:209], v[22:25]
	v_mfma_f32_16x16x32_bf16 v[14:17], v[182:185], v[206:209], v[14:17]
	v_mfma_f32_16x16x32_bf16 v[6:9], v[172:175], v[214:217], v[6:9]
	v_mfma_f32_16x16x32_bf16 v[2:5], v[182:185], v[214:217], v[2:5]
	s_barrier
	s_setprio 0
	s_add_i32 s63, 0, 0x18000
	v_add_u32_e32 v151, s63, v146
	s_add_i32 s64, 0, 0x1c000
	ds_read_b128 v[152:155], v151
	ds_read_b128 v[156:159], v151 offset:1024
	ds_read_b128 v[160:163], v151 offset:2048
	ds_read_b128 v[164:167], v151 offset:3072
	v_add_u32_e32 v151, s64, v146
	ds_read_b128 v[168:171], v151
	ds_read_b128 v[172:175], v151 offset:1024
	ds_read_b128 v[178:181], v151 offset:2048
	ds_read_b128 v[182:185], v151 offset:3072
	s_add_u32 s2, s2, 0x40000
	s_addc_u32 s3, s3, 0
	s_mov_b32 m0, s45
	v_lshl_add_u64 v[224:225], s[2:3], 0, v[130:131]
	ds_read_b128 v[186:189], v150 offset:32768
	ds_read_b128 v[190:193], v150 offset:33792
	ds_read_b128 v[194:197], v150 offset:34816
	ds_read_b128 v[198:201], v150 offset:35840
	ds_read_b128 v[202:205], v150 offset:36864
	ds_read_b128 v[206:209], v150 offset:37888
	ds_read_b128 v[210:213], v150 offset:38912
	ds_read_b128 v[214:217], v150 offset:39936
	global_load_lds_dwordx4 v[224:225], off
	v_lshl_add_u64 v[224:225], s[2:3], 0, v[134:135]
	s_mov_b32 m0, s46
	s_nop 0
	global_load_lds_dwordx4 v[224:225], off
	s_waitcnt vmcnt(8)
	s_waitcnt lgkmcnt(0)
	s_setprio 2
	s_barrier
	v_mfma_f32_16x16x32_bf16 v[126:129], v[152:155], v[186:189], v[126:129]
	v_mfma_f32_16x16x32_bf16 v[122:125], v[160:163], v[186:189], v[122:125]
	v_mfma_f32_16x16x32_bf16 v[114:117], v[152:155], v[194:197], v[114:117]
	v_mfma_f32_16x16x32_bf16 v[106:109], v[160:163], v[194:197], v[106:109]
	v_mfma_f32_16x16x32_bf16 v[98:101], v[152:155], v[202:205], v[98:101]
	v_mfma_f32_16x16x32_bf16 v[90:93], v[160:163], v[202:205], v[90:93]
	v_mfma_f32_16x16x32_bf16 v[82:85], v[152:155], v[210:213], v[82:85]
	v_mfma_f32_16x16x32_bf16 v[74:77], v[160:163], v[210:213], v[74:77]
	v_mfma_f32_16x16x32_bf16 v[126:129], v[156:159], v[190:193], v[126:129]
	v_mfma_f32_16x16x32_bf16 v[122:125], v[164:167], v[190:193], v[122:125]
	v_mfma_f32_16x16x32_bf16 v[114:117], v[156:159], v[198:201], v[114:117]
	v_mfma_f32_16x16x32_bf16 v[106:109], v[164:167], v[198:201], v[106:109]
	v_mfma_f32_16x16x32_bf16 v[98:101], v[156:159], v[206:209], v[98:101]
	v_mfma_f32_16x16x32_bf16 v[90:93], v[164:167], v[206:209], v[90:93]
	v_mfma_f32_16x16x32_bf16 v[82:85], v[156:159], v[214:217], v[82:85]
	v_mfma_f32_16x16x32_bf16 v[74:77], v[164:167], v[214:217], v[74:77]
	v_mfma_f32_16x16x32_bf16 v[118:121], v[168:171], v[186:189], v[118:121]
	v_mfma_f32_16x16x32_bf16 v[110:113], v[178:181], v[186:189], v[110:113]
	v_mfma_f32_16x16x32_bf16 v[102:105], v[168:171], v[194:197], v[102:105]
	v_mfma_f32_16x16x32_bf16 v[94:97], v[178:181], v[194:197], v[94:97]
	v_mfma_f32_16x16x32_bf16 v[86:89], v[168:171], v[202:205], v[86:89]
	v_mfma_f32_16x16x32_bf16 v[78:81], v[178:181], v[202:205], v[78:81]
	v_mfma_f32_16x16x32_bf16 v[70:73], v[168:171], v[210:213], v[70:73]
	v_mfma_f32_16x16x32_bf16 v[66:69], v[178:181], v[210:213], v[66:69]
	v_mfma_f32_16x16x32_bf16 v[118:121], v[172:175], v[190:193], v[118:121]
	v_mfma_f32_16x16x32_bf16 v[110:113], v[182:185], v[190:193], v[110:113]
	v_mfma_f32_16x16x32_bf16 v[102:105], v[172:175], v[198:201], v[102:105]
	v_mfma_f32_16x16x32_bf16 v[94:97], v[182:185], v[198:201], v[94:97]
	v_mfma_f32_16x16x32_bf16 v[86:89], v[172:175], v[206:209], v[86:89]
	v_mfma_f32_16x16x32_bf16 v[78:81], v[182:185], v[206:209], v[78:81]
	v_mfma_f32_16x16x32_bf16 v[70:73], v[172:175], v[214:217], v[70:73]
	v_mfma_f32_16x16x32_bf16 v[66:69], v[182:185], v[214:217], v[66:69]
	s_barrier
	s_setprio 0
	s_add_i32 s2, s63, s43
	v_lshl_add_u64 v[144:145], v[144:145], 0, s[8:9]
	s_mov_b32 m0, s2
	ds_read_b128 v[186:189], v150 offset:49152
	ds_read_b128 v[190:193], v150 offset:50176
	ds_read_b128 v[194:197], v150 offset:51200
	ds_read_b128 v[198:201], v150 offset:52224
	ds_read_b128 v[202:205], v150 offset:53248
	ds_read_b128 v[206:209], v150 offset:54272
	ds_read_b128 v[210:213], v150 offset:55296
	ds_read_b128 v[214:217], v150 offset:56320
	global_load_lds_dwordx4 v[144:145], off
	s_add_i32 m0, s2, 0x2000
	s_add_u32 s2, s38, 0x40080
	v_lshl_add_u64 v[144:145], v[218:219], 0, s[8:9]
	s_addc_u32 s3, s39, 0
	s_add_i32 s38, s64, s43
	global_load_lds_dwordx4 v[144:145], off
	v_lshl_add_u64 v[144:145], s[2:3], 0, v[132:133]
	s_mov_b32 m0, s38
	s_nop 0
	global_load_lds_dwordx4 v[144:145], off
	v_lshl_add_u64 v[144:145], s[2:3], 0, v[136:137]
	s_add_i32 m0, s38, 0x2000
	s_nop 0
	global_load_lds_dwordx4 v[144:145], off
	v_lshl_add_u64 v[144:145], v[220:221], 0, s[8:9]
	s_mov_b32 m0, s48
	s_nop 0
	global_load_lds_dwordx4 v[144:145], off
	v_lshl_add_u64 v[144:145], v[222:223], 0, s[8:9]
	s_mov_b32 m0, s49
	s_nop 0
	global_load_lds_dwordx4 v[144:145], off
	s_waitcnt vmcnt(8)
	s_waitcnt lgkmcnt(0)
	s_setprio 2
	s_barrier
	v_mfma_f32_16x16x32_bf16 v[62:65], v[152:155], v[186:189], v[62:65]
	v_mfma_f32_16x16x32_bf16 v[58:61], v[160:163], v[186:189], v[58:61]
	v_mfma_f32_16x16x32_bf16 v[50:53], v[152:155], v[194:197], v[50:53]
	v_mfma_f32_16x16x32_bf16 v[42:45], v[160:163], v[194:197], v[42:45]
	v_mfma_f32_16x16x32_bf16 v[34:37], v[152:155], v[202:205], v[34:37]
	v_mfma_f32_16x16x32_bf16 v[26:29], v[160:163], v[202:205], v[26:29]
	v_mfma_f32_16x16x32_bf16 v[18:21], v[152:155], v[210:213], v[18:21]
	v_mfma_f32_16x16x32_bf16 v[10:13], v[160:163], v[210:213], v[10:13]
	v_mfma_f32_16x16x32_bf16 v[62:65], v[156:159], v[190:193], v[62:65]
	v_mfma_f32_16x16x32_bf16 v[58:61], v[164:167], v[190:193], v[58:61]
	v_mfma_f32_16x16x32_bf16 v[50:53], v[156:159], v[198:201], v[50:53]
	v_mfma_f32_16x16x32_bf16 v[42:45], v[164:167], v[198:201], v[42:45]
	v_mfma_f32_16x16x32_bf16 v[34:37], v[156:159], v[206:209], v[34:37]
	v_mfma_f32_16x16x32_bf16 v[26:29], v[164:167], v[206:209], v[26:29]
	v_mfma_f32_16x16x32_bf16 v[18:21], v[156:159], v[214:217], v[18:21]
	v_mfma_f32_16x16x32_bf16 v[10:13], v[164:167], v[214:217], v[10:13]
	v_mfma_f32_16x16x32_bf16 v[54:57], v[168:171], v[186:189], v[54:57]
	v_mfma_f32_16x16x32_bf16 v[46:49], v[178:181], v[186:189], v[46:49]
	v_mfma_f32_16x16x32_bf16 v[38:41], v[168:171], v[194:197], v[38:41]
	v_mfma_f32_16x16x32_bf16 v[30:33], v[178:181], v[194:197], v[30:33]
	v_mfma_f32_16x16x32_bf16 v[22:25], v[168:171], v[202:205], v[22:25]
	v_mfma_f32_16x16x32_bf16 v[14:17], v[178:181], v[202:205], v[14:17]
	v_mfma_f32_16x16x32_bf16 v[6:9], v[168:171], v[210:213], v[6:9]
	v_mfma_f32_16x16x32_bf16 v[2:5], v[178:181], v[210:213], v[2:5]
	v_mfma_f32_16x16x32_bf16 v[54:57], v[172:175], v[190:193], v[54:57]
	v_mfma_f32_16x16x32_bf16 v[46:49], v[182:185], v[190:193], v[46:49]
	v_mfma_f32_16x16x32_bf16 v[38:41], v[172:175], v[198:201], v[38:41]
	v_mfma_f32_16x16x32_bf16 v[30:33], v[182:185], v[198:201], v[30:33]
	v_mfma_f32_16x16x32_bf16 v[22:25], v[172:175], v[206:209], v[22:25]
	v_mfma_f32_16x16x32_bf16 v[14:17], v[182:185], v[206:209], v[14:17]
	v_mfma_f32_16x16x32_bf16 v[6:9], v[172:175], v[214:217], v[6:9]
	v_mfma_f32_16x16x32_bf16 v[2:5], v[182:185], v[214:217], v[2:5]
	s_barrier
	s_setprio 0
	s_add_i32 s62, s62, 2
	s_add_u32 s36, s36, 0x100
	s_addc_u32 s37, s37, 0
	s_add_u32 s60, s60, 0x100
	s_addc_u32 s61, s61, 0
	s_cmp_gt_u32 s62, 13
	s_cbranch_scc0 .LBB0_1239

.Lpk1303_peel:
	ds_read_b128 v[166:169], v139
	ds_read_b128 v[170:173], v139 offset:1024
	ds_read_b128 v[178:181], v139 offset:2048
	ds_read_b128 v[182:185], v139 offset:3072
	ds_read_b128 v[186:189], v163
	ds_read_b128 v[190:193], v163 offset:1024
	ds_read_b128 v[194:197], v163 offset:2048
	ds_read_b128 v[198:201], v163 offset:3072
	s_add_u32 s2, s26, 0xfffc0080
	s_addc_u32 s3, s27, -1
	s_cmp_eq_u32 s55, 12
	s_cselect_b32 s3, s11, s3
	s_cselect_b32 s2, s13, s2
	s_cselect_b32 s29, s47, s54
	s_cselect_b32 s28, s52, s53
	v_lshl_add_u64 v[148:149], s[26:27], 0, v[142:143]
	s_add_i32 m0, s34, 0xc000
	ds_read_b128 v[202:205], v164
	ds_read_b128 v[206:209], v164 offset:1024
	ds_read_b128 v[210:213], v164 offset:2048
	ds_read_b128 v[214:217], v164 offset:3072
	ds_read_b128 v[218:221], v164 offset:4096
	ds_read_b128 v[222:225], v164 offset:5120
	ds_read_b128 v[226:229], v164 offset:6144
	ds_read_b128 v[230:233], v164 offset:7168
	global_load_lds_dwordx4 v[148:149], off
	v_lshl_add_u64 v[148:149], s[26:27], 0, v[144:145]
	s_add_i32 m0, s34, 0xe000
	s_nop 0
	global_load_lds_dwordx4 v[148:149], off
	s_waitcnt vmcnt(8)
	s_waitcnt lgkmcnt(0)
	s_setprio 2
	s_barrier
	v_mfma_f32_16x16x32_bf16 v[126:129], v[166:169], v[202:205], 0
	v_mfma_f32_16x16x32_bf16 v[122:125], v[178:181], v[202:205], 0
	v_mfma_f32_16x16x32_bf16 v[110:113], v[166:169], v[210:213], 0
	v_mfma_f32_16x16x32_bf16 v[106:109], v[178:181], v[210:213], 0
	v_mfma_f32_16x16x32_bf16 v[94:97], v[166:169], v[218:221], 0
	v_mfma_f32_16x16x32_bf16 v[90:93], v[178:181], v[218:221], 0
	v_mfma_f32_16x16x32_bf16 v[78:81], v[166:169], v[226:229], 0
	v_mfma_f32_16x16x32_bf16 v[74:77], v[178:181], v[226:229], 0
	v_mfma_f32_16x16x32_bf16 v[126:129], v[170:173], v[206:209], v[126:129]
	v_mfma_f32_16x16x32_bf16 v[122:125], v[182:185], v[206:209], v[122:125]
	v_mfma_f32_16x16x32_bf16 v[110:113], v[170:173], v[214:217], v[110:113]
	v_mfma_f32_16x16x32_bf16 v[106:109], v[182:185], v[214:217], v[106:109]
	v_mfma_f32_16x16x32_bf16 v[94:97], v[170:173], v[222:225], v[94:97]
	v_mfma_f32_16x16x32_bf16 v[90:93], v[182:185], v[222:225], v[90:93]
	v_mfma_f32_16x16x32_bf16 v[78:81], v[170:173], v[230:233], v[78:81]
	v_mfma_f32_16x16x32_bf16 v[74:77], v[182:185], v[230:233], v[74:77]
	v_mfma_f32_16x16x32_bf16 v[118:121], v[186:189], v[202:205], 0
	v_mfma_f32_16x16x32_bf16 v[114:117], v[194:197], v[202:205], 0
	v_mfma_f32_16x16x32_bf16 v[102:105], v[186:189], v[210:213], 0
	v_mfma_f32_16x16x32_bf16 v[98:101], v[194:197], v[210:213], 0
	v_mfma_f32_16x16x32_bf16 v[86:89], v[186:189], v[218:221], 0
	v_mfma_f32_16x16x32_bf16 v[82:85], v[194:197], v[218:221], 0
	v_mfma_f32_16x16x32_bf16 v[70:73], v[186:189], v[226:229], 0
	v_mfma_f32_16x16x32_bf16 v[66:69], v[194:197], v[226:229], 0
	v_mfma_f32_16x16x32_bf16 v[118:121], v[190:193], v[206:209], v[118:121]
	v_mfma_f32_16x16x32_bf16 v[114:117], v[198:201], v[206:209], v[114:117]
	v_mfma_f32_16x16x32_bf16 v[102:105], v[190:193], v[214:217], v[102:105]
	v_mfma_f32_16x16x32_bf16 v[98:101], v[198:201], v[214:217], v[98:101]
	v_mfma_f32_16x16x32_bf16 v[86:89], v[190:193], v[222:225], v[86:89]
	v_mfma_f32_16x16x32_bf16 v[82:85], v[198:201], v[222:225], v[82:85]
	v_mfma_f32_16x16x32_bf16 v[70:73], v[190:193], v[230:233], v[70:73]
	v_mfma_f32_16x16x32_bf16 v[66:69], v[198:201], v[230:233], v[66:69]
	s_barrier
	s_setprio 0
	s_add_i32 s56, s42, s30
	v_lshl_add_u64 v[148:149], s[28:29], 0, v[132:133]
	s_mov_b32 m0, s56
	ds_read_b128 v[202:205], v164 offset:16384
	ds_read_b128 v[206:209], v164 offset:17408
	ds_read_b128 v[210:213], v164 offset:18432
	ds_read_b128 v[214:217], v164 offset:19456
	ds_read_b128 v[218:221], v164 offset:20480
	ds_read_b128 v[222:225], v164 offset:21504
	ds_read_b128 v[226:229], v164 offset:22528
	ds_read_b128 v[230:233], v164 offset:23552
	global_load_lds_dwordx4 v[148:149], off
	s_add_i32 m0, s56, 0x2000
	s_add_u32 s56, s28, 0x40000
	v_lshl_add_u64 v[174:175], s[28:29], 0, v[136:137]
	s_addc_u32 s57, s29, 0
	s_add_i32 s58, s43, s30
	global_load_lds_dwordx4 v[174:175], off
	v_lshl_add_u64 v[234:235], s[56:57], 0, v[132:133]
	s_mov_b32 m0, s58
	v_lshl_add_u64 v[236:237], s[2:3], 0, v[134:135]
	global_load_lds_dwordx4 v[234:235], off
	v_lshl_add_u64 v[234:235], s[56:57], 0, v[136:137]
	s_add_i32 m0, s58, 0x2000
	s_nop 0
	global_load_lds_dwordx4 v[234:235], off
	v_lshl_add_u64 v[234:235], s[2:3], 0, v[130:131]
	s_mov_b32 m0, s34
	s_nop 0
	global_load_lds_dwordx4 v[234:235], off
	s_mov_b32 m0, s25
	s_nop 0
	global_load_lds_dwordx4 v[236:237], off
	s_waitcnt vmcnt(8)
	s_waitcnt lgkmcnt(0)
	s_setprio 2
	s_barrier
	v_mfma_f32_16x16x32_bf16 v[62:65], v[166:169], v[202:205], 0
	v_mfma_f32_16x16x32_bf16 v[58:61], v[178:181], v[202:205], 0
	v_mfma_f32_16x16x32_bf16 v[46:49], v[166:169], v[210:213], 0
	v_mfma_f32_16x16x32_bf16 v[42:45], v[178:181], v[210:213], 0
	v_mfma_f32_16x16x32_bf16 v[30:33], v[166:169], v[218:221], 0
	v_mfma_f32_16x16x32_bf16 v[26:29], v[178:181], v[218:221], 0
	v_mfma_f32_16x16x32_bf16 v[14:17], v[166:169], v[226:229], 0
	v_mfma_f32_16x16x32_bf16 v[10:13], v[178:181], v[226:229], 0
	v_mfma_f32_16x16x32_bf16 v[62:65], v[170:173], v[206:209], v[62:65]
	v_mfma_f32_16x16x32_bf16 v[58:61], v[182:185], v[206:209], v[58:61]
	v_mfma_f32_16x16x32_bf16 v[46:49], v[170:173], v[214:217], v[46:49]
	v_mfma_f32_16x16x32_bf16 v[42:45], v[182:185], v[214:217], v[42:45]
	v_mfma_f32_16x16x32_bf16 v[30:33], v[170:173], v[222:225], v[30:33]
	v_mfma_f32_16x16x32_bf16 v[26:29], v[182:185], v[222:225], v[26:29]
	v_mfma_f32_16x16x32_bf16 v[14:17], v[170:173], v[230:233], v[14:17]
	v_mfma_f32_16x16x32_bf16 v[10:13], v[182:185], v[230:233], v[10:13]
	v_mfma_f32_16x16x32_bf16 v[54:57], v[186:189], v[202:205], 0
	v_mfma_f32_16x16x32_bf16 v[50:53], v[194:197], v[202:205], 0
	v_mfma_f32_16x16x32_bf16 v[38:41], v[186:189], v[210:213], 0
	v_mfma_f32_16x16x32_bf16 v[34:37], v[194:197], v[210:213], 0
	v_mfma_f32_16x16x32_bf16 v[22:25], v[186:189], v[218:221], 0
	v_mfma_f32_16x16x32_bf16 v[18:21], v[194:197], v[218:221], 0
	v_mfma_f32_16x16x32_bf16 v[6:9], v[186:189], v[226:229], 0
	v_mfma_f32_16x16x32_bf16 v[2:5], v[194:197], v[226:229], 0
	v_mfma_f32_16x16x32_bf16 v[54:57], v[190:193], v[206:209], v[54:57]
	v_mfma_f32_16x16x32_bf16 v[50:53], v[198:201], v[206:209], v[50:53]
	v_mfma_f32_16x16x32_bf16 v[38:41], v[190:193], v[214:217], v[38:41]
	v_mfma_f32_16x16x32_bf16 v[34:37], v[198:201], v[214:217], v[34:37]
	v_mfma_f32_16x16x32_bf16 v[22:25], v[190:193], v[222:225], v[22:25]
	v_mfma_f32_16x16x32_bf16 v[18:21], v[198:201], v[222:225], v[18:21]
	v_mfma_f32_16x16x32_bf16 v[6:9], v[190:193], v[230:233], v[6:9]
	v_mfma_f32_16x16x32_bf16 v[2:5], v[198:201], v[230:233], v[2:5]
	s_barrier
	s_setprio 0
	s_add_i32 s56, 0, 0x18000
	v_add_u32_e32 v165, s56, v162
	s_add_i32 s57, 0, 0x1c000
	ds_read_b128 v[166:169], v165
	ds_read_b128 v[170:173], v165 offset:1024
	ds_read_b128 v[178:181], v165 offset:2048
	ds_read_b128 v[182:185], v165 offset:3072
	v_add_u32_e32 v165, s57, v162
	ds_read_b128 v[186:189], v165
	ds_read_b128 v[190:193], v165 offset:1024
	ds_read_b128 v[194:197], v165 offset:2048
	ds_read_b128 v[198:201], v165 offset:3072
	s_add_u32 s2, s2, 0x40000
	s_addc_u32 s3, s3, 0
	s_mov_b32 m0, s35
	v_lshl_add_u64 v[238:239], s[2:3], 0, v[130:131]
	ds_read_b128 v[202:205], v164 offset:32768
	ds_read_b128 v[206:209], v164 offset:33792
	ds_read_b128 v[210:213], v164 offset:34816
	ds_read_b128 v[214:217], v164 offset:35840
	ds_read_b128 v[218:221], v164 offset:36864
	ds_read_b128 v[222:225], v164 offset:37888
	ds_read_b128 v[226:229], v164 offset:38912
	ds_read_b128 v[230:233], v164 offset:39936
	global_load_lds_dwordx4 v[238:239], off
	v_lshl_add_u64 v[238:239], s[2:3], 0, v[134:135]
	s_mov_b32 m0, s36
	s_nop 0
	global_load_lds_dwordx4 v[238:239], off
	s_waitcnt vmcnt(8)
	s_waitcnt lgkmcnt(0)
	s_setprio 2
	s_barrier
	v_mfma_f32_16x16x32_bf16 v[126:129], v[166:169], v[202:205], v[126:129]
	v_mfma_f32_16x16x32_bf16 v[122:125], v[178:181], v[202:205], v[122:125]
	v_mfma_f32_16x16x32_bf16 v[110:113], v[166:169], v[210:213], v[110:113]
	v_mfma_f32_16x16x32_bf16 v[106:109], v[178:181], v[210:213], v[106:109]
	v_mfma_f32_16x16x32_bf16 v[94:97], v[166:169], v[218:221], v[94:97]
	v_mfma_f32_16x16x32_bf16 v[90:93], v[178:181], v[218:221], v[90:93]
	v_mfma_f32_16x16x32_bf16 v[78:81], v[166:169], v[226:229], v[78:81]
	v_mfma_f32_16x16x32_bf16 v[74:77], v[178:181], v[226:229], v[74:77]
	v_mfma_f32_16x16x32_bf16 v[126:129], v[170:173], v[206:209], v[126:129]
	v_mfma_f32_16x16x32_bf16 v[122:125], v[182:185], v[206:209], v[122:125]
	v_mfma_f32_16x16x32_bf16 v[110:113], v[170:173], v[214:217], v[110:113]
	v_mfma_f32_16x16x32_bf16 v[106:109], v[182:185], v[214:217], v[106:109]
	v_mfma_f32_16x16x32_bf16 v[94:97], v[170:173], v[222:225], v[94:97]
	v_mfma_f32_16x16x32_bf16 v[90:93], v[182:185], v[222:225], v[90:93]
	v_mfma_f32_16x16x32_bf16 v[78:81], v[170:173], v[230:233], v[78:81]
	v_mfma_f32_16x16x32_bf16 v[74:77], v[182:185], v[230:233], v[74:77]
	v_mfma_f32_16x16x32_bf16 v[118:121], v[186:189], v[202:205], v[118:121]
	v_mfma_f32_16x16x32_bf16 v[114:117], v[194:197], v[202:205], v[114:117]
	v_mfma_f32_16x16x32_bf16 v[102:105], v[186:189], v[210:213], v[102:105]
	v_mfma_f32_16x16x32_bf16 v[98:101], v[194:197], v[210:213], v[98:101]
	v_mfma_f32_16x16x32_bf16 v[86:89], v[186:189], v[218:221], v[86:89]
	v_mfma_f32_16x16x32_bf16 v[82:85], v[194:197], v[218:221], v[82:85]
	v_mfma_f32_16x16x32_bf16 v[70:73], v[186:189], v[226:229], v[70:73]
	v_mfma_f32_16x16x32_bf16 v[66:69], v[194:197], v[226:229], v[66:69]
	v_mfma_f32_16x16x32_bf16 v[118:121], v[190:193], v[206:209], v[118:121]
	v_mfma_f32_16x16x32_bf16 v[114:117], v[198:201], v[206:209], v[114:117]
	v_mfma_f32_16x16x32_bf16 v[102:105], v[190:193], v[214:217], v[102:105]
	v_mfma_f32_16x16x32_bf16 v[98:101], v[198:201], v[214:217], v[98:101]
	v_mfma_f32_16x16x32_bf16 v[86:89], v[190:193], v[222:225], v[86:89]
	v_mfma_f32_16x16x32_bf16 v[82:85], v[198:201], v[222:225], v[82:85]
	v_mfma_f32_16x16x32_bf16 v[70:73], v[190:193], v[230:233], v[70:73]
	v_mfma_f32_16x16x32_bf16 v[66:69], v[198:201], v[230:233], v[66:69]
	s_barrier
	s_setprio 0
	s_add_i32 s2, s56, s30
	v_lshl_add_u64 v[148:149], v[148:149], 0, s[6:7]
	s_mov_b32 m0, s2
	ds_read_b128 v[202:205], v164 offset:49152
	ds_read_b128 v[206:209], v164 offset:50176
	ds_read_b128 v[210:213], v164 offset:51200
	ds_read_b128 v[214:217], v164 offset:52224
	ds_read_b128 v[218:221], v164 offset:53248
	ds_read_b128 v[222:225], v164 offset:54272
	ds_read_b128 v[226:229], v164 offset:55296
	ds_read_b128 v[230:233], v164 offset:56320
	global_load_lds_dwordx4 v[148:149], off
	s_add_i32 m0, s2, 0x2000
	s_add_u32 s2, s28, 0x40080
	v_lshl_add_u64 v[148:149], v[174:175], 0, s[6:7]
	s_addc_u32 s3, s29, 0
	s_add_i32 s28, s57, s30
	global_load_lds_dwordx4 v[148:149], off
	v_lshl_add_u64 v[148:149], s[2:3], 0, v[132:133]
	s_mov_b32 m0, s28
	s_nop 0
	global_load_lds_dwordx4 v[148:149], off
	v_lshl_add_u64 v[148:149], s[2:3], 0, v[136:137]
	s_add_i32 m0, s28, 0x2000
	s_nop 0
	global_load_lds_dwordx4 v[148:149], off
	v_lshl_add_u64 v[148:149], v[234:235], 0, s[6:7]
	s_mov_b32 m0, s39
	s_nop 0
	global_load_lds_dwordx4 v[148:149], off
	v_lshl_add_u64 v[148:149], v[236:237], 0, s[6:7]
	s_mov_b32 m0, s40
	s_nop 0
	global_load_lds_dwordx4 v[148:149], off
	s_waitcnt vmcnt(8)
	s_waitcnt lgkmcnt(0)
	s_setprio 2
	s_barrier
	v_mfma_f32_16x16x32_bf16 v[62:65], v[166:169], v[202:205], v[62:65]
	v_mfma_f32_16x16x32_bf16 v[58:61], v[178:181], v[202:205], v[58:61]
	v_mfma_f32_16x16x32_bf16 v[46:49], v[166:169], v[210:213], v[46:49]
	v_mfma_f32_16x16x32_bf16 v[42:45], v[178:181], v[210:213], v[42:45]
	v_mfma_f32_16x16x32_bf16 v[30:33], v[166:169], v[218:221], v[30:33]
	v_mfma_f32_16x16x32_bf16 v[26:29], v[178:181], v[218:221], v[26:29]
	v_mfma_f32_16x16x32_bf16 v[14:17], v[166:169], v[226:229], v[14:17]
	v_mfma_f32_16x16x32_bf16 v[10:13], v[178:181], v[226:229], v[10:13]
	v_mfma_f32_16x16x32_bf16 v[62:65], v[170:173], v[206:209], v[62:65]
	v_mfma_f32_16x16x32_bf16 v[58:61], v[182:185], v[206:209], v[58:61]
	v_mfma_f32_16x16x32_bf16 v[46:49], v[170:173], v[214:217], v[46:49]
	v_mfma_f32_16x16x32_bf16 v[42:45], v[182:185], v[214:217], v[42:45]
	v_mfma_f32_16x16x32_bf16 v[30:33], v[170:173], v[222:225], v[30:33]
	v_mfma_f32_16x16x32_bf16 v[26:29], v[182:185], v[222:225], v[26:29]
	v_mfma_f32_16x16x32_bf16 v[14:17], v[170:173], v[230:233], v[14:17]
	v_mfma_f32_16x16x32_bf16 v[10:13], v[182:185], v[230:233], v[10:13]
	v_mfma_f32_16x16x32_bf16 v[54:57], v[186:189], v[202:205], v[54:57]
	v_mfma_f32_16x16x32_bf16 v[50:53], v[194:197], v[202:205], v[50:53]
	v_mfma_f32_16x16x32_bf16 v[38:41], v[186:189], v[210:213], v[38:41]
	v_mfma_f32_16x16x32_bf16 v[34:37], v[194:197], v[210:213], v[34:37]
	v_mfma_f32_16x16x32_bf16 v[22:25], v[186:189], v[218:221], v[22:25]
	v_mfma_f32_16x16x32_bf16 v[18:21], v[194:197], v[218:221], v[18:21]
	v_mfma_f32_16x16x32_bf16 v[6:9], v[186:189], v[226:229], v[6:9]
	v_mfma_f32_16x16x32_bf16 v[2:5], v[194:197], v[226:229], v[2:5]
	v_mfma_f32_16x16x32_bf16 v[54:57], v[190:193], v[206:209], v[54:57]
	v_mfma_f32_16x16x32_bf16 v[50:53], v[198:201], v[206:209], v[50:53]
	v_mfma_f32_16x16x32_bf16 v[38:41], v[190:193], v[214:217], v[38:41]
	v_mfma_f32_16x16x32_bf16 v[34:37], v[198:201], v[214:217], v[34:37]
	v_mfma_f32_16x16x32_bf16 v[22:25], v[190:193], v[222:225], v[22:25]
	v_mfma_f32_16x16x32_bf16 v[18:21], v[198:201], v[222:225], v[18:21]
	v_mfma_f32_16x16x32_bf16 v[6:9], v[190:193], v[230:233], v[6:9]
	v_mfma_f32_16x16x32_bf16 v[2:5], v[198:201], v[230:233], v[2:5]
	s_barrier
	s_setprio 0
	s_add_i32 s55, s55, 2
	s_add_u32 s26, s26, 0x100
	s_addc_u32 s27, s27, 0
	s_add_u32 s53, s53, 0x100
	s_addc_u32 s54, s54, 0
	s_cmp_gt_u32 s55, 13
	s_cbranch_scc0 .LBB0_1303
	s_branch .Lpk1303_exit
.LBB0_1303:
	ds_read_b128 v[166:169], v139
	ds_read_b128 v[170:173], v139 offset:1024
	ds_read_b128 v[178:181], v139 offset:2048
	ds_read_b128 v[182:185], v139 offset:3072
	ds_read_b128 v[186:189], v163
	ds_read_b128 v[190:193], v163 offset:1024
	ds_read_b128 v[194:197], v163 offset:2048
	ds_read_b128 v[198:201], v163 offset:3072
	s_add_u32 s2, s26, 0xfffc0080
	s_addc_u32 s3, s27, -1
	s_cmp_eq_u32 s55, 12
	s_cselect_b32 s3, s11, s3
	s_cselect_b32 s2, s13, s2
	s_cselect_b32 s29, s47, s54
	s_cselect_b32 s28, s52, s53
	v_lshl_add_u64 v[148:149], s[26:27], 0, v[142:143]
	s_add_i32 m0, s34, 0xc000
	ds_read_b128 v[202:205], v164
	ds_read_b128 v[206:209], v164 offset:1024
	ds_read_b128 v[210:213], v164 offset:2048
	ds_read_b128 v[214:217], v164 offset:3072
	ds_read_b128 v[218:221], v164 offset:4096
	ds_read_b128 v[222:225], v164 offset:5120
	ds_read_b128 v[226:229], v164 offset:6144
	ds_read_b128 v[230:233], v164 offset:7168
	global_load_lds_dwordx4 v[148:149], off
	v_lshl_add_u64 v[148:149], s[26:27], 0, v[144:145]
	s_add_i32 m0, s34, 0xe000
	s_nop 0
	global_load_lds_dwordx4 v[148:149], off
	s_waitcnt vmcnt(8)
	s_waitcnt lgkmcnt(0)
	s_setprio 2
	s_barrier
	v_mfma_f32_16x16x32_bf16 v[126:129], v[166:169], v[202:205], v[126:129]
	v_mfma_f32_16x16x32_bf16 v[122:125], v[178:181], v[202:205], v[122:125]
	v_mfma_f32_16x16x32_bf16 v[110:113], v[166:169], v[210:213], v[110:113]
	v_mfma_f32_16x16x32_bf16 v[106:109], v[178:181], v[210:213], v[106:109]
	v_mfma_f32_16x16x32_bf16 v[94:97], v[166:169], v[218:221], v[94:97]
	v_mfma_f32_16x16x32_bf16 v[90:93], v[178:181], v[218:221], v[90:93]
	v_mfma_f32_16x16x32_bf16 v[78:81], v[166:169], v[226:229], v[78:81]
	v_mfma_f32_16x16x32_bf16 v[74:77], v[178:181], v[226:229], v[74:77]
	v_mfma_f32_16x16x32_bf16 v[126:129], v[170:173], v[206:209], v[126:129]
	v_mfma_f32_16x16x32_bf16 v[122:125], v[182:185], v[206:209], v[122:125]
	v_mfma_f32_16x16x32_bf16 v[110:113], v[170:173], v[214:217], v[110:113]
	v_mfma_f32_16x16x32_bf16 v[106:109], v[182:185], v[214:217], v[106:109]
	v_mfma_f32_16x16x32_bf16 v[94:97], v[170:173], v[222:225], v[94:97]
	v_mfma_f32_16x16x32_bf16 v[90:93], v[182:185], v[222:225], v[90:93]
	v_mfma_f32_16x16x32_bf16 v[78:81], v[170:173], v[230:233], v[78:81]
	v_mfma_f32_16x16x32_bf16 v[74:77], v[182:185], v[230:233], v[74:77]
	v_mfma_f32_16x16x32_bf16 v[118:121], v[186:189], v[202:205], v[118:121]
	v_mfma_f32_16x16x32_bf16 v[114:117], v[194:197], v[202:205], v[114:117]
	v_mfma_f32_16x16x32_bf16 v[102:105], v[186:189], v[210:213], v[102:105]
	v_mfma_f32_16x16x32_bf16 v[98:101], v[194:197], v[210:213], v[98:101]
	v_mfma_f32_16x16x32_bf16 v[86:89], v[186:189], v[218:221], v[86:89]
	v_mfma_f32_16x16x32_bf16 v[82:85], v[194:197], v[218:221], v[82:85]
	v_mfma_f32_16x16x32_bf16 v[70:73], v[186:189], v[226:229], v[70:73]
	v_mfma_f32_16x16x32_bf16 v[66:69], v[194:197], v[226:229], v[66:69]
	v_mfma_f32_16x16x32_bf16 v[118:121], v[190:193], v[206:209], v[118:121]
	v_mfma_f32_16x16x32_bf16 v[114:117], v[198:201], v[206:209], v[114:117]
	v_mfma_f32_16x16x32_bf16 v[102:105], v[190:193], v[214:217], v[102:105]
	v_mfma_f32_16x16x32_bf16 v[98:101], v[198:201], v[214:217], v[98:101]
	v_mfma_f32_16x16x32_bf16 v[86:89], v[190:193], v[222:225], v[86:89]
	v_mfma_f32_16x16x32_bf16 v[82:85], v[198:201], v[222:225], v[82:85]
	v_mfma_f32_16x16x32_bf16 v[70:73], v[190:193], v[230:233], v[70:73]
	v_mfma_f32_16x16x32_bf16 v[66:69], v[198:201], v[230:233], v[66:69]
	s_barrier
	s_setprio 0
	s_add_i32 s56, s42, s30
	v_lshl_add_u64 v[148:149], s[28:29], 0, v[132:133]
	s_mov_b32 m0, s56
	ds_read_b128 v[202:205], v164 offset:16384
	ds_read_b128 v[206:209], v164 offset:17408
	ds_read_b128 v[210:213], v164 offset:18432
	ds_read_b128 v[214:217], v164 offset:19456
	ds_read_b128 v[218:221], v164 offset:20480
	ds_read_b128 v[222:225], v164 offset:21504
	ds_read_b128 v[226:229], v164 offset:22528
	ds_read_b128 v[230:233], v164 offset:23552
	global_load_lds_dwordx4 v[148:149], off
	s_add_i32 m0, s56, 0x2000
	s_add_u32 s56, s28, 0x40000
	v_lshl_add_u64 v[174:175], s[28:29], 0, v[136:137]
	s_addc_u32 s57, s29, 0
	s_add_i32 s58, s43, s30
	global_load_lds_dwordx4 v[174:175], off
	v_lshl_add_u64 v[234:235], s[56:57], 0, v[132:133]
	s_mov_b32 m0, s58
	v_lshl_add_u64 v[236:237], s[2:3], 0, v[134:135]
	global_load_lds_dwordx4 v[234:235], off
	v_lshl_add_u64 v[234:235], s[56:57], 0, v[136:137]
	s_add_i32 m0, s58, 0x2000
	s_nop 0
	global_load_lds_dwordx4 v[234:235], off
	v_lshl_add_u64 v[234:235], s[2:3], 0, v[130:131]
	s_mov_b32 m0, s34
	s_nop 0
	global_load_lds_dwordx4 v[234:235], off
	s_mov_b32 m0, s25
	s_nop 0
	global_load_lds_dwordx4 v[236:237], off
	s_waitcnt vmcnt(8)
	s_waitcnt lgkmcnt(0)
	s_setprio 2
	s_barrier
	v_mfma_f32_16x16x32_bf16 v[62:65], v[166:169], v[202:205], v[62:65]
	v_mfma_f32_16x16x32_bf16 v[58:61], v[178:181], v[202:205], v[58:61]
	v_mfma_f32_16x16x32_bf16 v[46:49], v[166:169], v[210:213], v[46:49]
	v_mfma_f32_16x16x32_bf16 v[42:45], v[178:181], v[210:213], v[42:45]
	v_mfma_f32_16x16x32_bf16 v[30:33], v[166:169], v[218:221], v[30:33]
	v_mfma_f32_16x16x32_bf16 v[26:29], v[178:181], v[218:221], v[26:29]
	v_mfma_f32_16x16x32_bf16 v[14:17], v[166:169], v[226:229], v[14:17]
	v_mfma_f32_16x16x32_bf16 v[10:13], v[178:181], v[226:229], v[10:13]
	v_mfma_f32_16x16x32_bf16 v[62:65], v[170:173], v[206:209], v[62:65]
	v_mfma_f32_16x16x32_bf16 v[58:61], v[182:185], v[206:209], v[58:61]
	v_mfma_f32_16x16x32_bf16 v[46:49], v[170:173], v[214:217], v[46:49]
	v_mfma_f32_16x16x32_bf16 v[42:45], v[182:185], v[214:217], v[42:45]
	v_mfma_f32_16x16x32_bf16 v[30:33], v[170:173], v[222:225], v[30:33]
	v_mfma_f32_16x16x32_bf16 v[26:29], v[182:185], v[222:225], v[26:29]
	v_mfma_f32_16x16x32_bf16 v[14:17], v[170:173], v[230:233], v[14:17]
	v_mfma_f32_16x16x32_bf16 v[10:13], v[182:185], v[230:233], v[10:13]
	v_mfma_f32_16x16x32_bf16 v[54:57], v[186:189], v[202:205], v[54:57]
	v_mfma_f32_16x16x32_bf16 v[50:53], v[194:197], v[202:205], v[50:53]
	v_mfma_f32_16x16x32_bf16 v[38:41], v[186:189], v[210:213], v[38:41]
	v_mfma_f32_16x16x32_bf16 v[34:37], v[194:197], v[210:213], v[34:37]
	v_mfma_f32_16x16x32_bf16 v[22:25], v[186:189], v[218:221], v[22:25]
	v_mfma_f32_16x16x32_bf16 v[18:21], v[194:197], v[218:221], v[18:21]
	v_mfma_f32_16x16x32_bf16 v[6:9], v[186:189], v[226:229], v[6:9]
	v_mfma_f32_16x16x32_bf16 v[2:5], v[194:197], v[226:229], v[2:5]
	v_mfma_f32_16x16x32_bf16 v[54:57], v[190:193], v[206:209], v[54:57]
	v_mfma_f32_16x16x32_bf16 v[50:53], v[198:201], v[206:209], v[50:53]
	v_mfma_f32_16x16x32_bf16 v[38:41], v[190:193], v[214:217], v[38:41]
	v_mfma_f32_16x16x32_bf16 v[34:37], v[198:201], v[214:217], v[34:37]
	v_mfma_f32_16x16x32_bf16 v[22:25], v[190:193], v[222:225], v[22:25]
	v_mfma_f32_16x16x32_bf16 v[18:21], v[198:201], v[222:225], v[18:21]
	v_mfma_f32_16x16x32_bf16 v[6:9], v[190:193], v[230:233], v[6:9]
	v_mfma_f32_16x16x32_bf16 v[2:5], v[198:201], v[230:233], v[2:5]
	s_barrier
	s_setprio 0
	s_add_i32 s56, 0, 0x18000
	v_add_u32_e32 v165, s56, v162
	s_add_i32 s57, 0, 0x1c000
	ds_read_b128 v[166:169], v165
	ds_read_b128 v[170:173], v165 offset:1024
	ds_read_b128 v[178:181], v165 offset:2048
	ds_read_b128 v[182:185], v165 offset:3072
	v_add_u32_e32 v165, s57, v162
	ds_read_b128 v[186:189], v165
	ds_read_b128 v[190:193], v165 offset:1024
	ds_read_b128 v[194:197], v165 offset:2048
	ds_read_b128 v[198:201], v165 offset:3072
	s_add_u32 s2, s2, 0x40000
	s_addc_u32 s3, s3, 0
	s_mov_b32 m0, s35
	v_lshl_add_u64 v[238:239], s[2:3], 0, v[130:131]
	ds_read_b128 v[202:205], v164 offset:32768
	ds_read_b128 v[206:209], v164 offset:33792
	ds_read_b128 v[210:213], v164 offset:34816
	ds_read_b128 v[214:217], v164 offset:35840
	ds_read_b128 v[218:221], v164 offset:36864
	ds_read_b128 v[222:225], v164 offset:37888
	ds_read_b128 v[226:229], v164 offset:38912
	ds_read_b128 v[230:233], v164 offset:39936
	global_load_lds_dwordx4 v[238:239], off
	v_lshl_add_u64 v[238:239], s[2:3], 0, v[134:135]
	s_mov_b32 m0, s36
	s_nop 0
	global_load_lds_dwordx4 v[238:239], off
	s_waitcnt vmcnt(8)
	s_waitcnt lgkmcnt(0)
	s_setprio 2
	s_barrier
	v_mfma_f32_16x16x32_bf16 v[126:129], v[166:169], v[202:205], v[126:129]
	v_mfma_f32_16x16x32_bf16 v[122:125], v[178:181], v[202:205], v[122:125]
	v_mfma_f32_16x16x32_bf16 v[110:113], v[166:169], v[210:213], v[110:113]
	v_mfma_f32_16x16x32_bf16 v[106:109], v[178:181], v[210:213], v[106:109]
	v_mfma_f32_16x16x32_bf16 v[94:97], v[166:169], v[218:221], v[94:97]
	v_mfma_f32_16x16x32_bf16 v[90:93], v[178:181], v[218:221], v[90:93]
	v_mfma_f32_16x16x32_bf16 v[78:81], v[166:169], v[226:229], v[78:81]
	v_mfma_f32_16x16x32_bf16 v[74:77], v[178:181], v[226:229], v[74:77]
	v_mfma_f32_16x16x32_bf16 v[126:129], v[170:173], v[206:209], v[126:129]
	v_mfma_f32_16x16x32_bf16 v[122:125], v[182:185], v[206:209], v[122:125]
	v_mfma_f32_16x16x32_bf16 v[110:113], v[170:173], v[214:217], v[110:113]
	v_mfma_f32_16x16x32_bf16 v[106:109], v[182:185], v[214:217], v[106:109]
	v_mfma_f32_16x16x32_bf16 v[94:97], v[170:173], v[222:225], v[94:97]
	v_mfma_f32_16x16x32_bf16 v[90:93], v[182:185], v[222:225], v[90:93]
	v_mfma_f32_16x16x32_bf16 v[78:81], v[170:173], v[230:233], v[78:81]
	v_mfma_f32_16x16x32_bf16 v[74:77], v[182:185], v[230:233], v[74:77]
	v_mfma_f32_16x16x32_bf16 v[118:121], v[186:189], v[202:205], v[118:121]
	v_mfma_f32_16x16x32_bf16 v[114:117], v[194:197], v[202:205], v[114:117]
	v_mfma_f32_16x16x32_bf16 v[102:105], v[186:189], v[210:213], v[102:105]
	v_mfma_f32_16x16x32_bf16 v[98:101], v[194:197], v[210:213], v[98:101]
	v_mfma_f32_16x16x32_bf16 v[86:89], v[186:189], v[218:221], v[86:89]
	v_mfma_f32_16x16x32_bf16 v[82:85], v[194:197], v[218:221], v[82:85]
	v_mfma_f32_16x16x32_bf16 v[70:73], v[186:189], v[226:229], v[70:73]
	v_mfma_f32_16x16x32_bf16 v[66:69], v[194:197], v[226:229], v[66:69]
	v_mfma_f32_16x16x32_bf16 v[118:121], v[190:193], v[206:209], v[118:121]
	v_mfma_f32_16x16x32_bf16 v[114:117], v[198:201], v[206:209], v[114:117]
	v_mfma_f32_16x16x32_bf16 v[102:105], v[190:193], v[214:217], v[102:105]
	v_mfma_f32_16x16x32_bf16 v[98:101], v[198:201], v[214:217], v[98:101]
	v_mfma_f32_16x16x32_bf16 v[86:89], v[190:193], v[222:225], v[86:89]
	v_mfma_f32_16x16x32_bf16 v[82:85], v[198:201], v[222:225], v[82:85]
	v_mfma_f32_16x16x32_bf16 v[70:73], v[190:193], v[230:233], v[70:73]
	v_mfma_f32_16x16x32_bf16 v[66:69], v[198:201], v[230:233], v[66:69]
	s_barrier
	s_setprio 0
	s_add_i32 s2, s56, s30
	v_lshl_add_u64 v[148:149], v[148:149], 0, s[6:7]
	s_mov_b32 m0, s2
	ds_read_b128 v[202:205], v164 offset:49152
	ds_read_b128 v[206:209], v164 offset:50176
	ds_read_b128 v[210:213], v164 offset:51200
	ds_read_b128 v[214:217], v164 offset:52224
	ds_read_b128 v[218:221], v164 offset:53248
	ds_read_b128 v[222:225], v164 offset:54272
	ds_read_b128 v[226:229], v164 offset:55296
	ds_read_b128 v[230:233], v164 offset:56320
	global_load_lds_dwordx4 v[148:149], off
	s_add_i32 m0, s2, 0x2000
	s_add_u32 s2, s28, 0x40080
	v_lshl_add_u64 v[148:149], v[174:175], 0, s[6:7]
	s_addc_u32 s3, s29, 0
	s_add_i32 s28, s57, s30
	global_load_lds_dwordx4 v[148:149], off
	v_lshl_add_u64 v[148:149], s[2:3], 0, v[132:133]
	s_mov_b32 m0, s28
	s_nop 0
	global_load_lds_dwordx4 v[148:149], off
	v_lshl_add_u64 v[148:149], s[2:3], 0, v[136:137]
	s_add_i32 m0, s28, 0x2000
	s_nop 0
	global_load_lds_dwordx4 v[148:149], off
	v_lshl_add_u64 v[148:149], v[234:235], 0, s[6:7]
	s_mov_b32 m0, s39
	s_nop 0
	global_load_lds_dwordx4 v[148:149], off
	v_lshl_add_u64 v[148:149], v[236:237], 0, s[6:7]
	s_mov_b32 m0, s40
	s_nop 0
	global_load_lds_dwordx4 v[148:149], off
	s_waitcnt vmcnt(8)
	s_waitcnt lgkmcnt(0)
	s_setprio 2
	s_barrier
	v_mfma_f32_16x16x32_bf16 v[62:65], v[166:169], v[202:205], v[62:65]
	v_mfma_f32_16x16x32_bf16 v[58:61], v[178:181], v[202:205], v[58:61]
	v_mfma_f32_16x16x32_bf16 v[46:49], v[166:169], v[210:213], v[46:49]
	v_mfma_f32_16x16x32_bf16 v[42:45], v[178:181], v[210:213], v[42:45]
	v_mfma_f32_16x16x32_bf16 v[30:33], v[166:169], v[218:221], v[30:33]
	v_mfma_f32_16x16x32_bf16 v[26:29], v[178:181], v[218:221], v[26:29]
	v_mfma_f32_16x16x32_bf16 v[14:17], v[166:169], v[226:229], v[14:17]
	v_mfma_f32_16x16x32_bf16 v[10:13], v[178:181], v[226:229], v[10:13]
	v_mfma_f32_16x16x32_bf16 v[62:65], v[170:173], v[206:209], v[62:65]
	v_mfma_f32_16x16x32_bf16 v[58:61], v[182:185], v[206:209], v[58:61]
	v_mfma_f32_16x16x32_bf16 v[46:49], v[170:173], v[214:217], v[46:49]
	v_mfma_f32_16x16x32_bf16 v[42:45], v[182:185], v[214:217], v[42:45]
	v_mfma_f32_16x16x32_bf16 v[30:33], v[170:173], v[222:225], v[30:33]
	v_mfma_f32_16x16x32_bf16 v[26:29], v[182:185], v[222:225], v[26:29]
	v_mfma_f32_16x16x32_bf16 v[14:17], v[170:173], v[230:233], v[14:17]
	v_mfma_f32_16x16x32_bf16 v[10:13], v[182:185], v[230:233], v[10:13]
	v_mfma_f32_16x16x32_bf16 v[54:57], v[186:189], v[202:205], v[54:57]
	v_mfma_f32_16x16x32_bf16 v[50:53], v[194:197], v[202:205], v[50:53]
	v_mfma_f32_16x16x32_bf16 v[38:41], v[186:189], v[210:213], v[38:41]
	v_mfma_f32_16x16x32_bf16 v[34:37], v[194:197], v[210:213], v[34:37]
	v_mfma_f32_16x16x32_bf16 v[22:25], v[186:189], v[218:221], v[22:25]
	v_mfma_f32_16x16x32_bf16 v[18:21], v[194:197], v[218:221], v[18:21]
	v_mfma_f32_16x16x32_bf16 v[6:9], v[186:189], v[226:229], v[6:9]
	v_mfma_f32_16x16x32_bf16 v[2:5], v[194:197], v[226:229], v[2:5]
	v_mfma_f32_16x16x32_bf16 v[54:57], v[190:193], v[206:209], v[54:57]
	v_mfma_f32_16x16x32_bf16 v[50:53], v[198:201], v[206:209], v[50:53]
	v_mfma_f32_16x16x32_bf16 v[38:41], v[190:193], v[214:217], v[38:41]
	v_mfma_f32_16x16x32_bf16 v[34:37], v[198:201], v[214:217], v[34:37]
	v_mfma_f32_16x16x32_bf16 v[22:25], v[190:193], v[222:225], v[22:25]
	v_mfma_f32_16x16x32_bf16 v[18:21], v[198:201], v[222:225], v[18:21]
	v_mfma_f32_16x16x32_bf16 v[6:9], v[190:193], v[230:233], v[6:9]
	v_mfma_f32_16x16x32_bf16 v[2:5], v[198:201], v[230:233], v[2:5]
	s_barrier
	s_setprio 0
	s_add_i32 s55, s55, 2
	s_add_u32 s26, s26, 0x100
	s_addc_u32 s27, s27, 0
	s_add_u32 s53, s53, 0x100
	s_addc_u32 s54, s54, 0
	s_cmp_gt_u32 s55, 13
	s_cbranch_scc0 .LBB0_1303

.LBB0_1386:
	ds_read_b128 v[160:163], v133
	ds_read_b128 v[164:167], v133 offset:1024
	ds_read_b128 v[168:171], v133 offset:2048
	ds_read_b128 v[172:175], v133 offset:3072
	ds_read_b128 v[178:181], v135
	ds_read_b128 v[182:185], v135 offset:1024
	ds_read_b128 v[186:189], v135 offset:2048
	ds_read_b128 v[190:193], v135 offset:3072
	s_cmp_lg_u32 s8, 0x160000
	s_cselect_b32 s13, s8, 0
	s_cselect_b32 s12, s9, 0
	s_add_u32 s2, s6, s13
	s_addc_u32 s3, s7, s12
	s_add_u32 s14, s0, s13
	s_addc_u32 s15, s1, s12
	s_add_u32 s12, s2, 0x8000
	s_addc_u32 s13, s3, 0
	v_lshl_add_u64 v[226:227], v[148:149], 0, s[8:9]
	s_mov_b32 m0, s27
	v_lshl_add_u64 v[226:227], v[226:227], 0, s[10:11]
	ds_read_b128 v[194:197], v137
	ds_read_b128 v[198:201], v137 offset:1024
	ds_read_b128 v[202:205], v137 offset:2048
	ds_read_b128 v[206:209], v137 offset:3072
	ds_read_b128 v[210:213], v137 offset:4096
	ds_read_b128 v[214:217], v137 offset:5120
	ds_read_b128 v[218:221], v137 offset:6144
	ds_read_b128 v[222:225], v137 offset:7168
	global_load_lds_dwordx4 v[226:227], off
	v_lshl_add_u64 v[226:227], v[150:151], 0, s[8:9]
	v_lshl_add_u64 v[226:227], v[226:227], 0, s[10:11]
	s_mov_b32 m0, s28
	s_nop 0
	global_load_lds_dwordx4 v[226:227], off
	s_waitcnt vmcnt(8)
	s_waitcnt lgkmcnt(0)
	s_setprio 2
	s_barrier
	v_mfma_f32_16x16x32_bf16 v[126:129], v[160:163], v[194:197], v[126:129]
	v_mfma_f32_16x16x32_bf16 v[122:125], v[168:171], v[194:197], v[122:125]
	v_mfma_f32_16x16x32_bf16 v[114:117], v[160:163], v[202:205], v[114:117]
	v_mfma_f32_16x16x32_bf16 v[106:109], v[168:171], v[202:205], v[106:109]
	v_mfma_f32_16x16x32_bf16 v[98:101], v[160:163], v[210:213], v[98:101]
	v_mfma_f32_16x16x32_bf16 v[90:93], v[168:171], v[210:213], v[90:93]
	v_mfma_f32_16x16x32_bf16 v[82:85], v[160:163], v[218:221], v[82:85]
	v_mfma_f32_16x16x32_bf16 v[74:77], v[168:171], v[218:221], v[74:77]
	v_mfma_f32_16x16x32_bf16 v[126:129], v[164:167], v[198:201], v[126:129]
	v_mfma_f32_16x16x32_bf16 v[122:125], v[172:175], v[198:201], v[122:125]
	v_mfma_f32_16x16x32_bf16 v[114:117], v[164:167], v[206:209], v[114:117]
	v_mfma_f32_16x16x32_bf16 v[106:109], v[172:175], v[206:209], v[106:109]
	v_mfma_f32_16x16x32_bf16 v[98:101], v[164:167], v[214:217], v[98:101]
	v_mfma_f32_16x16x32_bf16 v[90:93], v[172:175], v[214:217], v[90:93]
	v_mfma_f32_16x16x32_bf16 v[82:85], v[164:167], v[222:225], v[82:85]
	v_mfma_f32_16x16x32_bf16 v[74:77], v[172:175], v[222:225], v[74:77]
	v_mfma_f32_16x16x32_bf16 v[118:121], v[178:181], v[194:197], v[118:121]
	v_mfma_f32_16x16x32_bf16 v[110:113], v[186:189], v[194:197], v[110:113]
	v_mfma_f32_16x16x32_bf16 v[102:105], v[178:181], v[202:205], v[102:105]
	v_mfma_f32_16x16x32_bf16 v[94:97], v[186:189], v[202:205], v[94:97]
	v_mfma_f32_16x16x32_bf16 v[86:89], v[178:181], v[210:213], v[86:89]
	v_mfma_f32_16x16x32_bf16 v[78:81], v[186:189], v[210:213], v[78:81]
	v_mfma_f32_16x16x32_bf16 v[70:73], v[178:181], v[218:221], v[70:73]
	v_mfma_f32_16x16x32_bf16 v[66:69], v[186:189], v[218:221], v[66:69]
	v_mfma_f32_16x16x32_bf16 v[118:121], v[182:185], v[198:201], v[118:121]
	v_mfma_f32_16x16x32_bf16 v[110:113], v[190:193], v[198:201], v[110:113]
	v_mfma_f32_16x16x32_bf16 v[102:105], v[182:185], v[206:209], v[102:105]
	v_mfma_f32_16x16x32_bf16 v[94:97], v[190:193], v[206:209], v[94:97]
	v_mfma_f32_16x16x32_bf16 v[86:89], v[182:185], v[214:217], v[86:89]
	v_mfma_f32_16x16x32_bf16 v[78:81], v[190:193], v[214:217], v[78:81]
	v_mfma_f32_16x16x32_bf16 v[70:73], v[182:185], v[222:225], v[70:73]
	v_mfma_f32_16x16x32_bf16 v[66:69], v[190:193], v[222:225], v[66:69]
	s_barrier
	s_setprio 0
	s_mov_b32 m0, s29
	v_lshl_add_u64 v[226:227], s[14:15], 0, v[142:143]
	s_add_u32 s40, s14, 0x4000
	ds_read_b128 v[194:197], v137 offset:16384
	ds_read_b128 v[198:201], v137 offset:17408
	ds_read_b128 v[202:205], v137 offset:18432
	ds_read_b128 v[206:209], v137 offset:19456
	ds_read_b128 v[210:213], v137 offset:20480
	ds_read_b128 v[214:217], v137 offset:21504
	ds_read_b128 v[218:221], v137 offset:22528
	ds_read_b128 v[222:225], v137 offset:23552
	global_load_lds_dwordx4 v[226:227], off
	v_lshl_add_u64 v[226:227], s[14:15], 0, v[146:147]
	s_mov_b32 m0, s30
	s_addc_u32 s41, s15, 0
	global_load_lds_dwordx4 v[226:227], off
	v_lshl_add_u64 v[226:227], s[40:41], 0, v[142:143]
	s_mov_b32 m0, s31
	s_nop 0
	global_load_lds_dwordx4 v[226:227], off
	v_lshl_add_u64 v[226:227], s[40:41], 0, v[146:147]
	s_mov_b32 m0, s34
	s_nop 0
	global_load_lds_dwordx4 v[226:227], off
	v_lshl_add_u64 v[226:227], s[2:3], 0, v[140:141]
	s_mov_b32 m0, s19
	s_nop 0
	global_load_lds_dwordx4 v[226:227], off
	v_lshl_add_u64 v[226:227], s[2:3], 0, v[144:145]
	s_mov_b32 m0, s20
	s_nop 0
	global_load_lds_dwordx4 v[226:227], off
	s_waitcnt vmcnt(8)
	s_waitcnt lgkmcnt(0)
	s_setprio 2
	s_barrier
	v_mfma_f32_16x16x32_bf16 v[62:65], v[160:163], v[194:197], v[62:65]
	v_mfma_f32_16x16x32_bf16 v[58:61], v[168:171], v[194:197], v[58:61]
	v_mfma_f32_16x16x32_bf16 v[50:53], v[160:163], v[202:205], v[50:53]
	v_mfma_f32_16x16x32_bf16 v[42:45], v[168:171], v[202:205], v[42:45]
	v_mfma_f32_16x16x32_bf16 v[34:37], v[160:163], v[210:213], v[34:37]
	v_mfma_f32_16x16x32_bf16 v[26:29], v[168:171], v[210:213], v[26:29]
	v_mfma_f32_16x16x32_bf16 v[18:21], v[160:163], v[218:221], v[18:21]
	v_mfma_f32_16x16x32_bf16 v[10:13], v[168:171], v[218:221], v[10:13]
	v_mfma_f32_16x16x32_bf16 v[62:65], v[164:167], v[198:201], v[62:65]
	v_mfma_f32_16x16x32_bf16 v[58:61], v[172:175], v[198:201], v[58:61]
	v_mfma_f32_16x16x32_bf16 v[50:53], v[164:167], v[206:209], v[50:53]
	v_mfma_f32_16x16x32_bf16 v[42:45], v[172:175], v[206:209], v[42:45]
	v_mfma_f32_16x16x32_bf16 v[34:37], v[164:167], v[214:217], v[34:37]
	v_mfma_f32_16x16x32_bf16 v[26:29], v[172:175], v[214:217], v[26:29]
	v_mfma_f32_16x16x32_bf16 v[18:21], v[164:167], v[222:225], v[18:21]
	v_mfma_f32_16x16x32_bf16 v[10:13], v[172:175], v[222:225], v[10:13]
	v_mfma_f32_16x16x32_bf16 v[54:57], v[178:181], v[194:197], v[54:57]
	v_mfma_f32_16x16x32_bf16 v[46:49], v[186:189], v[194:197], v[46:49]
	v_mfma_f32_16x16x32_bf16 v[38:41], v[178:181], v[202:205], v[38:41]
	v_mfma_f32_16x16x32_bf16 v[30:33], v[186:189], v[202:205], v[30:33]
	v_mfma_f32_16x16x32_bf16 v[22:25], v[178:181], v[210:213], v[22:25]
	v_mfma_f32_16x16x32_bf16 v[14:17], v[186:189], v[210:213], v[14:17]
	v_mfma_f32_16x16x32_bf16 v[6:9], v[178:181], v[218:221], v[6:9]
	v_mfma_f32_16x16x32_bf16 v[2:5], v[186:189], v[218:221], v[2:5]
	v_mfma_f32_16x16x32_bf16 v[54:57], v[182:185], v[198:201], v[54:57]
	v_mfma_f32_16x16x32_bf16 v[46:49], v[190:193], v[198:201], v[46:49]
	v_mfma_f32_16x16x32_bf16 v[38:41], v[182:185], v[206:209], v[38:41]
	v_mfma_f32_16x16x32_bf16 v[30:33], v[190:193], v[206:209], v[30:33]
	v_mfma_f32_16x16x32_bf16 v[22:25], v[182:185], v[214:217], v[22:25]
	v_mfma_f32_16x16x32_bf16 v[14:17], v[190:193], v[214:217], v[14:17]
	v_mfma_f32_16x16x32_bf16 v[6:9], v[182:185], v[222:225], v[6:9]
	v_mfma_f32_16x16x32_bf16 v[2:5], v[190:193], v[222:225], v[2:5]
	s_barrier
	s_setprio 0
	ds_read_b128 v[160:163], v139
	ds_read_b128 v[164:167], v139 offset:1024
	ds_read_b128 v[168:171], v139 offset:2048
	ds_read_b128 v[172:175], v139 offset:3072
	ds_read_b128 v[178:181], v158
	ds_read_b128 v[182:185], v158 offset:1024
	ds_read_b128 v[186:189], v158 offset:2048
	ds_read_b128 v[190:193], v158 offset:3072
	s_add_u32 s2, s2, 0x4000
	s_addc_u32 s3, s3, 0
	s_mov_b32 m0, s21
	v_lshl_add_u64 v[226:227], s[2:3], 0, v[140:141]
	ds_read_b128 v[194:197], v137 offset:32768
	ds_read_b128 v[198:201], v137 offset:33792
	ds_read_b128 v[202:205], v137 offset:34816
	ds_read_b128 v[206:209], v137 offset:35840
	ds_read_b128 v[210:213], v137 offset:36864
	ds_read_b128 v[214:217], v137 offset:37888
	ds_read_b128 v[218:221], v137 offset:38912
	ds_read_b128 v[222:225], v137 offset:39936
	global_load_lds_dwordx4 v[226:227], off
	v_lshl_add_u64 v[226:227], s[2:3], 0, v[144:145]
	s_mov_b32 m0, s22
	s_nop 0
	global_load_lds_dwordx4 v[226:227], off
	s_waitcnt vmcnt(8)
	s_waitcnt lgkmcnt(0)
	s_setprio 2
	s_barrier
	v_mfma_f32_16x16x32_bf16 v[126:129], v[160:163], v[194:197], v[126:129]
	v_mfma_f32_16x16x32_bf16 v[122:125], v[168:171], v[194:197], v[122:125]
	v_mfma_f32_16x16x32_bf16 v[114:117], v[160:163], v[202:205], v[114:117]
	v_mfma_f32_16x16x32_bf16 v[106:109], v[168:171], v[202:205], v[106:109]
	v_mfma_f32_16x16x32_bf16 v[98:101], v[160:163], v[210:213], v[98:101]
	v_mfma_f32_16x16x32_bf16 v[90:93], v[168:171], v[210:213], v[90:93]
	v_mfma_f32_16x16x32_bf16 v[82:85], v[160:163], v[218:221], v[82:85]
	v_mfma_f32_16x16x32_bf16 v[74:77], v[168:171], v[218:221], v[74:77]
	v_mfma_f32_16x16x32_bf16 v[126:129], v[164:167], v[198:201], v[126:129]
	v_mfma_f32_16x16x32_bf16 v[122:125], v[172:175], v[198:201], v[122:125]
	v_mfma_f32_16x16x32_bf16 v[114:117], v[164:167], v[206:209], v[114:117]
	v_mfma_f32_16x16x32_bf16 v[106:109], v[172:175], v[206:209], v[106:109]
	v_mfma_f32_16x16x32_bf16 v[98:101], v[164:167], v[214:217], v[98:101]
	v_mfma_f32_16x16x32_bf16 v[90:93], v[172:175], v[214:217], v[90:93]
	v_mfma_f32_16x16x32_bf16 v[82:85], v[164:167], v[222:225], v[82:85]
	v_mfma_f32_16x16x32_bf16 v[74:77], v[172:175], v[222:225], v[74:77]
	v_mfma_f32_16x16x32_bf16 v[118:121], v[178:181], v[194:197], v[118:121]
	v_mfma_f32_16x16x32_bf16 v[110:113], v[186:189], v[194:197], v[110:113]
	v_mfma_f32_16x16x32_bf16 v[102:105], v[178:181], v[202:205], v[102:105]
	v_mfma_f32_16x16x32_bf16 v[94:97], v[186:189], v[202:205], v[94:97]
	v_mfma_f32_16x16x32_bf16 v[86:89], v[178:181], v[210:213], v[86:89]
	v_mfma_f32_16x16x32_bf16 v[78:81], v[186:189], v[210:213], v[78:81]
	v_mfma_f32_16x16x32_bf16 v[70:73], v[178:181], v[218:221], v[70:73]
	v_mfma_f32_16x16x32_bf16 v[66:69], v[186:189], v[218:221], v[66:69]
	v_mfma_f32_16x16x32_bf16 v[118:121], v[182:185], v[198:201], v[118:121]
	v_mfma_f32_16x16x32_bf16 v[110:113], v[190:193], v[198:201], v[110:113]
	v_mfma_f32_16x16x32_bf16 v[102:105], v[182:185], v[206:209], v[102:105]
	v_mfma_f32_16x16x32_bf16 v[94:97], v[190:193], v[206:209], v[94:97]
	v_mfma_f32_16x16x32_bf16 v[86:89], v[182:185], v[214:217], v[86:89]
	v_mfma_f32_16x16x32_bf16 v[78:81], v[190:193], v[214:217], v[78:81]
	v_mfma_f32_16x16x32_bf16 v[70:73], v[182:185], v[222:225], v[70:73]
	v_mfma_f32_16x16x32_bf16 v[66:69], v[190:193], v[222:225], v[66:69]
	s_barrier
	s_setprio 0
	s_add_u32 s2, s14, 0x8000
	s_addc_u32 s3, s15, 0
	s_mov_b32 m0, s35
	v_lshl_add_u64 v[226:227], s[2:3], 0, v[142:143]
	ds_read_b128 v[194:197], v137 offset:49152
	ds_read_b128 v[198:201], v137 offset:50176
	ds_read_b128 v[202:205], v137 offset:51200
	ds_read_b128 v[206:209], v137 offset:52224
	ds_read_b128 v[210:213], v137 offset:53248
	ds_read_b128 v[214:217], v137 offset:54272
	ds_read_b128 v[218:221], v137 offset:55296
	ds_read_b128 v[222:225], v137 offset:56320
	global_load_lds_dwordx4 v[226:227], off
	v_lshl_add_u64 v[226:227], s[2:3], 0, v[146:147]
	s_add_u32 s2, s14, 0xc000
	s_mov_b32 m0, s36
	s_addc_u32 s3, s15, 0
	global_load_lds_dwordx4 v[226:227], off
	v_lshl_add_u64 v[226:227], s[2:3], 0, v[142:143]
	s_mov_b32 m0, s37
	s_nop 0
	global_load_lds_dwordx4 v[226:227], off
	v_lshl_add_u64 v[226:227], s[2:3], 0, v[146:147]
	s_mov_b32 m0, s38
	s_nop 0
	global_load_lds_dwordx4 v[226:227], off
	v_lshl_add_u64 v[226:227], s[12:13], 0, v[140:141]
	s_mov_b32 m0, s24
	s_nop 0
	global_load_lds_dwordx4 v[226:227], off
	v_lshl_add_u64 v[226:227], s[12:13], 0, v[144:145]
	s_mov_b32 m0, s25
	s_nop 0
	global_load_lds_dwordx4 v[226:227], off
	s_waitcnt vmcnt(8)
	s_waitcnt lgkmcnt(0)
	s_setprio 2
	s_barrier
	v_mfma_f32_16x16x32_bf16 v[62:65], v[160:163], v[194:197], v[62:65]
	v_mfma_f32_16x16x32_bf16 v[58:61], v[168:171], v[194:197], v[58:61]
	v_mfma_f32_16x16x32_bf16 v[50:53], v[160:163], v[202:205], v[50:53]
	v_mfma_f32_16x16x32_bf16 v[42:45], v[168:171], v[202:205], v[42:45]
	v_mfma_f32_16x16x32_bf16 v[34:37], v[160:163], v[210:213], v[34:37]
	v_mfma_f32_16x16x32_bf16 v[26:29], v[168:171], v[210:213], v[26:29]
	v_mfma_f32_16x16x32_bf16 v[18:21], v[160:163], v[218:221], v[18:21]
	v_mfma_f32_16x16x32_bf16 v[10:13], v[168:171], v[218:221], v[10:13]
	v_mfma_f32_16x16x32_bf16 v[62:65], v[164:167], v[198:201], v[62:65]
	v_mfma_f32_16x16x32_bf16 v[58:61], v[172:175], v[198:201], v[58:61]
	v_mfma_f32_16x16x32_bf16 v[50:53], v[164:167], v[206:209], v[50:53]
	v_mfma_f32_16x16x32_bf16 v[42:45], v[172:175], v[206:209], v[42:45]
	v_mfma_f32_16x16x32_bf16 v[34:37], v[164:167], v[214:217], v[34:37]
	v_mfma_f32_16x16x32_bf16 v[26:29], v[172:175], v[214:217], v[26:29]
	v_mfma_f32_16x16x32_bf16 v[18:21], v[164:167], v[222:225], v[18:21]
	v_mfma_f32_16x16x32_bf16 v[10:13], v[172:175], v[222:225], v[10:13]
	v_mfma_f32_16x16x32_bf16 v[54:57], v[178:181], v[194:197], v[54:57]
	v_mfma_f32_16x16x32_bf16 v[46:49], v[186:189], v[194:197], v[46:49]
	v_mfma_f32_16x16x32_bf16 v[38:41], v[178:181], v[202:205], v[38:41]
	v_mfma_f32_16x16x32_bf16 v[30:33], v[186:189], v[202:205], v[30:33]
	v_mfma_f32_16x16x32_bf16 v[22:25], v[178:181], v[210:213], v[22:25]
	v_mfma_f32_16x16x32_bf16 v[14:17], v[186:189], v[210:213], v[14:17]
	v_mfma_f32_16x16x32_bf16 v[6:9], v[178:181], v[218:221], v[6:9]
	v_mfma_f32_16x16x32_bf16 v[2:5], v[186:189], v[218:221], v[2:5]
	v_mfma_f32_16x16x32_bf16 v[54:57], v[182:185], v[198:201], v[54:57]
	v_mfma_f32_16x16x32_bf16 v[46:49], v[190:193], v[198:201], v[46:49]
	v_mfma_f32_16x16x32_bf16 v[38:41], v[182:185], v[206:209], v[38:41]
	v_mfma_f32_16x16x32_bf16 v[30:33], v[190:193], v[206:209], v[30:33]
	v_mfma_f32_16x16x32_bf16 v[22:25], v[182:185], v[214:217], v[22:25]
	v_mfma_f32_16x16x32_bf16 v[14:17], v[190:193], v[214:217], v[14:17]
	v_mfma_f32_16x16x32_bf16 v[6:9], v[182:185], v[222:225], v[6:9]
	v_mfma_f32_16x16x32_bf16 v[2:5], v[190:193], v[222:225], v[2:5]
	s_barrier
	s_setprio 0
	s_add_i32 s26, s26, 2
	s_add_u32 s8, s8, 0x10000
	s_addc_u32 s9, s9, 0
	s_cmp_gt_u32 s26, 41
	s_cbranch_scc0 .LBB0_1386
	s_cmpk_lt_u32 s16, 0x100
	s_cbranch_scc0 .LBB0_1389
	s_barrier

.Lpk1400_peel:
	ds_read_b128 v[152:155], v1
	ds_read_b128 v[156:159], v1 offset:1024
	ds_read_b128 v[160:163], v1 offset:2048
	ds_read_b128 v[164:167], v1 offset:3072
	ds_read_b128 v[168:171], v149
	ds_read_b128 v[172:175], v149 offset:1024
	ds_read_b128 v[178:181], v149 offset:2048
	ds_read_b128 v[182:185], v149 offset:3072
	s_add_u32 s2, s28, 0xfffc0080
	s_addc_u32 s3, s29, -1
	s_cmp_eq_u32 s55, 12
	s_cselect_b32 s3, s11, s3
	s_cselect_b32 s2, s13, s2
	s_cselect_b32 s31, s47, s54
	s_cselect_b32 s30, s52, s53
	v_lshl_add_u64 v[146:147], s[28:29], 0, v[140:141]
	s_add_i32 m0, s25, 0xc000
	ds_read_b128 v[186:189], v150
	ds_read_b128 v[190:193], v150 offset:1024
	ds_read_b128 v[194:197], v150 offset:2048
	ds_read_b128 v[198:201], v150 offset:3072
	ds_read_b128 v[202:205], v150 offset:4096
	ds_read_b128 v[206:209], v150 offset:5120
	ds_read_b128 v[210:213], v150 offset:6144
	ds_read_b128 v[214:217], v150 offset:7168
	global_load_lds_dwordx4 v[146:147], off
	v_lshl_add_u64 v[146:147], s[28:29], 0, v[142:143]
	s_add_i32 m0, s25, 0xe000
	s_nop 0
	global_load_lds_dwordx4 v[146:147], off
	s_waitcnt vmcnt(8)
	s_waitcnt lgkmcnt(0)
	s_setprio 2
	s_barrier
	v_mfma_f32_16x16x32_bf16 v[126:129], v[152:155], v[186:189], 0
	v_mfma_f32_16x16x32_bf16 v[122:125], v[160:163], v[186:189], 0
	v_mfma_f32_16x16x32_bf16 v[110:113], v[152:155], v[194:197], 0
	v_mfma_f32_16x16x32_bf16 v[106:109], v[160:163], v[194:197], 0
	v_mfma_f32_16x16x32_bf16 v[94:97], v[152:155], v[202:205], 0
	v_mfma_f32_16x16x32_bf16 v[90:93], v[160:163], v[202:205], 0
	v_mfma_f32_16x16x32_bf16 v[78:81], v[152:155], v[210:213], 0
	v_mfma_f32_16x16x32_bf16 v[74:77], v[160:163], v[210:213], 0
	v_mfma_f32_16x16x32_bf16 v[126:129], v[156:159], v[190:193], v[126:129]
	v_mfma_f32_16x16x32_bf16 v[122:125], v[164:167], v[190:193], v[122:125]
	v_mfma_f32_16x16x32_bf16 v[110:113], v[156:159], v[198:201], v[110:113]
	v_mfma_f32_16x16x32_bf16 v[106:109], v[164:167], v[198:201], v[106:109]
	v_mfma_f32_16x16x32_bf16 v[94:97], v[156:159], v[206:209], v[94:97]
	v_mfma_f32_16x16x32_bf16 v[90:93], v[164:167], v[206:209], v[90:93]
	v_mfma_f32_16x16x32_bf16 v[78:81], v[156:159], v[214:217], v[78:81]
	v_mfma_f32_16x16x32_bf16 v[74:77], v[164:167], v[214:217], v[74:77]
	v_mfma_f32_16x16x32_bf16 v[118:121], v[168:171], v[186:189], 0
	v_mfma_f32_16x16x32_bf16 v[114:117], v[178:181], v[186:189], 0
	v_mfma_f32_16x16x32_bf16 v[102:105], v[168:171], v[194:197], 0
	v_mfma_f32_16x16x32_bf16 v[98:101], v[178:181], v[194:197], 0
	v_mfma_f32_16x16x32_bf16 v[86:89], v[168:171], v[202:205], 0
	v_mfma_f32_16x16x32_bf16 v[82:85], v[178:181], v[202:205], 0
	v_mfma_f32_16x16x32_bf16 v[70:73], v[168:171], v[210:213], 0
	v_mfma_f32_16x16x32_bf16 v[66:69], v[178:181], v[210:213], 0
	v_mfma_f32_16x16x32_bf16 v[118:121], v[172:175], v[190:193], v[118:121]
	v_mfma_f32_16x16x32_bf16 v[114:117], v[182:185], v[190:193], v[114:117]
	v_mfma_f32_16x16x32_bf16 v[102:105], v[172:175], v[198:201], v[102:105]
	v_mfma_f32_16x16x32_bf16 v[98:101], v[182:185], v[198:201], v[98:101]
	v_mfma_f32_16x16x32_bf16 v[86:89], v[172:175], v[206:209], v[86:89]
	v_mfma_f32_16x16x32_bf16 v[82:85], v[182:185], v[206:209], v[82:85]
	v_mfma_f32_16x16x32_bf16 v[70:73], v[172:175], v[214:217], v[70:73]
	v_mfma_f32_16x16x32_bf16 v[66:69], v[182:185], v[214:217], v[66:69]
	s_barrier
	s_setprio 0
	s_add_i32 s56, s43, s34
	v_lshl_add_u64 v[146:147], s[30:31], 0, v[132:133]
	s_mov_b32 m0, s56
	ds_read_b128 v[186:189], v150 offset:16384
	ds_read_b128 v[190:193], v150 offset:17408
	ds_read_b128 v[194:197], v150 offset:18432
	ds_read_b128 v[198:201], v150 offset:19456
	ds_read_b128 v[202:205], v150 offset:20480
	ds_read_b128 v[206:209], v150 offset:21504
	ds_read_b128 v[210:213], v150 offset:22528
	ds_read_b128 v[214:217], v150 offset:23552
	global_load_lds_dwordx4 v[146:147], off
	s_add_i32 m0, s56, 0x2000
	s_add_u32 s56, s30, 0x40000
	v_lshl_add_u64 v[218:219], s[30:31], 0, v[136:137]
	s_addc_u32 s57, s31, 0
	s_add_i32 s58, s44, s34
	global_load_lds_dwordx4 v[218:219], off
	v_lshl_add_u64 v[220:221], s[56:57], 0, v[132:133]
	s_mov_b32 m0, s58
	v_lshl_add_u64 v[222:223], s[2:3], 0, v[134:135]
	global_load_lds_dwordx4 v[220:221], off
	v_lshl_add_u64 v[220:221], s[56:57], 0, v[136:137]
	s_add_i32 m0, s58, 0x2000
	s_nop 0
	global_load_lds_dwordx4 v[220:221], off
	v_lshl_add_u64 v[220:221], s[2:3], 0, v[130:131]
	s_mov_b32 m0, s25
	s_nop 0
	global_load_lds_dwordx4 v[220:221], off
	s_mov_b32 m0, s27
	s_nop 0
	global_load_lds_dwordx4 v[222:223], off
	s_waitcnt vmcnt(8)
	s_waitcnt lgkmcnt(0)
	s_setprio 2
	s_barrier
	v_mfma_f32_16x16x32_bf16 v[62:65], v[152:155], v[186:189], 0
	v_mfma_f32_16x16x32_bf16 v[58:61], v[160:163], v[186:189], 0
	v_mfma_f32_16x16x32_bf16 v[46:49], v[152:155], v[194:197], 0
	v_mfma_f32_16x16x32_bf16 v[42:45], v[160:163], v[194:197], 0
	v_mfma_f32_16x16x32_bf16 v[30:33], v[152:155], v[202:205], 0
	v_mfma_f32_16x16x32_bf16 v[26:29], v[160:163], v[202:205], 0
	v_mfma_f32_16x16x32_bf16 v[14:17], v[152:155], v[210:213], 0
	v_mfma_f32_16x16x32_bf16 v[10:13], v[160:163], v[210:213], 0
	v_mfma_f32_16x16x32_bf16 v[62:65], v[156:159], v[190:193], v[62:65]
	v_mfma_f32_16x16x32_bf16 v[58:61], v[164:167], v[190:193], v[58:61]
	v_mfma_f32_16x16x32_bf16 v[46:49], v[156:159], v[198:201], v[46:49]
	v_mfma_f32_16x16x32_bf16 v[42:45], v[164:167], v[198:201], v[42:45]
	v_mfma_f32_16x16x32_bf16 v[30:33], v[156:159], v[206:209], v[30:33]
	v_mfma_f32_16x16x32_bf16 v[26:29], v[164:167], v[206:209], v[26:29]
	v_mfma_f32_16x16x32_bf16 v[14:17], v[156:159], v[214:217], v[14:17]
	v_mfma_f32_16x16x32_bf16 v[10:13], v[164:167], v[214:217], v[10:13]
	v_mfma_f32_16x16x32_bf16 v[54:57], v[168:171], v[186:189], 0
	v_mfma_f32_16x16x32_bf16 v[50:53], v[178:181], v[186:189], 0
	v_mfma_f32_16x16x32_bf16 v[38:41], v[168:171], v[194:197], 0
	v_mfma_f32_16x16x32_bf16 v[34:37], v[178:181], v[194:197], 0
	v_mfma_f32_16x16x32_bf16 v[22:25], v[168:171], v[202:205], 0
	v_mfma_f32_16x16x32_bf16 v[18:21], v[178:181], v[202:205], 0
	v_mfma_f32_16x16x32_bf16 v[6:9], v[168:171], v[210:213], 0
	v_mfma_f32_16x16x32_bf16 v[2:5], v[178:181], v[210:213], 0
	v_mfma_f32_16x16x32_bf16 v[54:57], v[172:175], v[190:193], v[54:57]
	v_mfma_f32_16x16x32_bf16 v[50:53], v[182:185], v[190:193], v[50:53]
	v_mfma_f32_16x16x32_bf16 v[38:41], v[172:175], v[198:201], v[38:41]
	v_mfma_f32_16x16x32_bf16 v[34:37], v[182:185], v[198:201], v[34:37]
	v_mfma_f32_16x16x32_bf16 v[22:25], v[172:175], v[206:209], v[22:25]
	v_mfma_f32_16x16x32_bf16 v[18:21], v[182:185], v[206:209], v[18:21]
	v_mfma_f32_16x16x32_bf16 v[6:9], v[172:175], v[214:217], v[6:9]
	v_mfma_f32_16x16x32_bf16 v[2:5], v[182:185], v[214:217], v[2:5]
	s_barrier
	s_setprio 0
	s_add_i32 s56, 0, 0x18000
	v_add_u32_e32 v151, s56, v148
	s_add_i32 s57, 0, 0x1c000
	ds_read_b128 v[152:155], v151
	ds_read_b128 v[156:159], v151 offset:1024
	ds_read_b128 v[160:163], v151 offset:2048
	ds_read_b128 v[164:167], v151 offset:3072
	v_add_u32_e32 v151, s57, v148
	ds_read_b128 v[168:171], v151
	ds_read_b128 v[172:175], v151 offset:1024
	ds_read_b128 v[178:181], v151 offset:2048
	ds_read_b128 v[182:185], v151 offset:3072
	s_add_u32 s2, s2, 0x40000
	s_addc_u32 s3, s3, 0
	s_mov_b32 m0, s36
	v_lshl_add_u64 v[224:225], s[2:3], 0, v[130:131]
	ds_read_b128 v[186:189], v150 offset:32768
	ds_read_b128 v[190:193], v150 offset:33792
	ds_read_b128 v[194:197], v150 offset:34816
	ds_read_b128 v[198:201], v150 offset:35840
	ds_read_b128 v[202:205], v150 offset:36864
	ds_read_b128 v[206:209], v150 offset:37888
	ds_read_b128 v[210:213], v150 offset:38912
	ds_read_b128 v[214:217], v150 offset:39936
	global_load_lds_dwordx4 v[224:225], off
	v_lshl_add_u64 v[224:225], s[2:3], 0, v[134:135]
	s_mov_b32 m0, s37
	s_nop 0
	global_load_lds_dwordx4 v[224:225], off
	s_waitcnt vmcnt(8)
	s_waitcnt lgkmcnt(0)
	s_setprio 2
	s_barrier
	v_mfma_f32_16x16x32_bf16 v[126:129], v[152:155], v[186:189], v[126:129]
	v_mfma_f32_16x16x32_bf16 v[122:125], v[160:163], v[186:189], v[122:125]
	v_mfma_f32_16x16x32_bf16 v[110:113], v[152:155], v[194:197], v[110:113]
	v_mfma_f32_16x16x32_bf16 v[106:109], v[160:163], v[194:197], v[106:109]
	v_mfma_f32_16x16x32_bf16 v[94:97], v[152:155], v[202:205], v[94:97]
	v_mfma_f32_16x16x32_bf16 v[90:93], v[160:163], v[202:205], v[90:93]
	v_mfma_f32_16x16x32_bf16 v[78:81], v[152:155], v[210:213], v[78:81]
	v_mfma_f32_16x16x32_bf16 v[74:77], v[160:163], v[210:213], v[74:77]
	v_mfma_f32_16x16x32_bf16 v[126:129], v[156:159], v[190:193], v[126:129]
	v_mfma_f32_16x16x32_bf16 v[122:125], v[164:167], v[190:193], v[122:125]
	v_mfma_f32_16x16x32_bf16 v[110:113], v[156:159], v[198:201], v[110:113]
	v_mfma_f32_16x16x32_bf16 v[106:109], v[164:167], v[198:201], v[106:109]
	v_mfma_f32_16x16x32_bf16 v[94:97], v[156:159], v[206:209], v[94:97]
	v_mfma_f32_16x16x32_bf16 v[90:93], v[164:167], v[206:209], v[90:93]
	v_mfma_f32_16x16x32_bf16 v[78:81], v[156:159], v[214:217], v[78:81]
	v_mfma_f32_16x16x32_bf16 v[74:77], v[164:167], v[214:217], v[74:77]
	v_mfma_f32_16x16x32_bf16 v[118:121], v[168:171], v[186:189], v[118:121]
	v_mfma_f32_16x16x32_bf16 v[114:117], v[178:181], v[186:189], v[114:117]
	v_mfma_f32_16x16x32_bf16 v[102:105], v[168:171], v[194:197], v[102:105]
	v_mfma_f32_16x16x32_bf16 v[98:101], v[178:181], v[194:197], v[98:101]
	v_mfma_f32_16x16x32_bf16 v[86:89], v[168:171], v[202:205], v[86:89]
	v_mfma_f32_16x16x32_bf16 v[82:85], v[178:181], v[202:205], v[82:85]
	v_mfma_f32_16x16x32_bf16 v[70:73], v[168:171], v[210:213], v[70:73]
	v_mfma_f32_16x16x32_bf16 v[66:69], v[178:181], v[210:213], v[66:69]
	v_mfma_f32_16x16x32_bf16 v[118:121], v[172:175], v[190:193], v[118:121]
	v_mfma_f32_16x16x32_bf16 v[114:117], v[182:185], v[190:193], v[114:117]
	v_mfma_f32_16x16x32_bf16 v[102:105], v[172:175], v[198:201], v[102:105]
	v_mfma_f32_16x16x32_bf16 v[98:101], v[182:185], v[198:201], v[98:101]
	v_mfma_f32_16x16x32_bf16 v[86:89], v[172:175], v[206:209], v[86:89]
	v_mfma_f32_16x16x32_bf16 v[82:85], v[182:185], v[206:209], v[82:85]
	v_mfma_f32_16x16x32_bf16 v[70:73], v[172:175], v[214:217], v[70:73]
	v_mfma_f32_16x16x32_bf16 v[66:69], v[182:185], v[214:217], v[66:69]
	s_barrier
	s_setprio 0
	s_add_i32 s2, s56, s34
	v_lshl_add_u64 v[146:147], v[146:147], 0, s[6:7]
	s_mov_b32 m0, s2
	ds_read_b128 v[186:189], v150 offset:49152
	ds_read_b128 v[190:193], v150 offset:50176
	ds_read_b128 v[194:197], v150 offset:51200
	ds_read_b128 v[198:201], v150 offset:52224
	ds_read_b128 v[202:205], v150 offset:53248
	ds_read_b128 v[206:209], v150 offset:54272
	ds_read_b128 v[210:213], v150 offset:55296
	ds_read_b128 v[214:217], v150 offset:56320
	global_load_lds_dwordx4 v[146:147], off
	s_add_i32 m0, s2, 0x2000
	s_add_u32 s2, s30, 0x40080
	v_lshl_add_u64 v[146:147], v[218:219], 0, s[6:7]
	s_addc_u32 s3, s31, 0
	s_add_i32 s30, s57, s34
	global_load_lds_dwordx4 v[146:147], off
	v_lshl_add_u64 v[146:147], s[2:3], 0, v[132:133]
	s_mov_b32 m0, s30
	s_nop 0
	global_load_lds_dwordx4 v[146:147], off
	v_lshl_add_u64 v[146:147], s[2:3], 0, v[136:137]
	s_add_i32 m0, s30, 0x2000
	s_nop 0
	global_load_lds_dwordx4 v[146:147], off
	v_lshl_add_u64 v[146:147], v[220:221], 0, s[6:7]
	s_mov_b32 m0, s40
	s_nop 0
	global_load_lds_dwordx4 v[146:147], off
	v_lshl_add_u64 v[146:147], v[222:223], 0, s[6:7]
	s_mov_b32 m0, s41
	s_nop 0
	global_load_lds_dwordx4 v[146:147], off
	s_waitcnt vmcnt(8)
	s_waitcnt lgkmcnt(0)
	s_setprio 2
	s_barrier
	v_mfma_f32_16x16x32_bf16 v[62:65], v[152:155], v[186:189], v[62:65]
	v_mfma_f32_16x16x32_bf16 v[58:61], v[160:163], v[186:189], v[58:61]
	v_mfma_f32_16x16x32_bf16 v[46:49], v[152:155], v[194:197], v[46:49]
	v_mfma_f32_16x16x32_bf16 v[42:45], v[160:163], v[194:197], v[42:45]
	v_mfma_f32_16x16x32_bf16 v[30:33], v[152:155], v[202:205], v[30:33]
	v_mfma_f32_16x16x32_bf16 v[26:29], v[160:163], v[202:205], v[26:29]
	v_mfma_f32_16x16x32_bf16 v[14:17], v[152:155], v[210:213], v[14:17]
	v_mfma_f32_16x16x32_bf16 v[10:13], v[160:163], v[210:213], v[10:13]
	v_mfma_f32_16x16x32_bf16 v[62:65], v[156:159], v[190:193], v[62:65]
	v_mfma_f32_16x16x32_bf16 v[58:61], v[164:167], v[190:193], v[58:61]
	v_mfma_f32_16x16x32_bf16 v[46:49], v[156:159], v[198:201], v[46:49]
	v_mfma_f32_16x16x32_bf16 v[42:45], v[164:167], v[198:201], v[42:45]
	v_mfma_f32_16x16x32_bf16 v[30:33], v[156:159], v[206:209], v[30:33]
	v_mfma_f32_16x16x32_bf16 v[26:29], v[164:167], v[206:209], v[26:29]
	v_mfma_f32_16x16x32_bf16 v[14:17], v[156:159], v[214:217], v[14:17]
	v_mfma_f32_16x16x32_bf16 v[10:13], v[164:167], v[214:217], v[10:13]
	v_mfma_f32_16x16x32_bf16 v[54:57], v[168:171], v[186:189], v[54:57]
	v_mfma_f32_16x16x32_bf16 v[50:53], v[178:181], v[186:189], v[50:53]
	v_mfma_f32_16x16x32_bf16 v[38:41], v[168:171], v[194:197], v[38:41]
	v_mfma_f32_16x16x32_bf16 v[34:37], v[178:181], v[194:197], v[34:37]
	v_mfma_f32_16x16x32_bf16 v[22:25], v[168:171], v[202:205], v[22:25]
	v_mfma_f32_16x16x32_bf16 v[18:21], v[178:181], v[202:205], v[18:21]
	v_mfma_f32_16x16x32_bf16 v[6:9], v[168:171], v[210:213], v[6:9]
	v_mfma_f32_16x16x32_bf16 v[2:5], v[178:181], v[210:213], v[2:5]
	v_mfma_f32_16x16x32_bf16 v[54:57], v[172:175], v[190:193], v[54:57]
	v_mfma_f32_16x16x32_bf16 v[50:53], v[182:185], v[190:193], v[50:53]
	v_mfma_f32_16x16x32_bf16 v[38:41], v[172:175], v[198:201], v[38:41]
	v_mfma_f32_16x16x32_bf16 v[34:37], v[182:185], v[198:201], v[34:37]
	v_mfma_f32_16x16x32_bf16 v[22:25], v[172:175], v[206:209], v[22:25]
	v_mfma_f32_16x16x32_bf16 v[18:21], v[182:185], v[206:209], v[18:21]
	v_mfma_f32_16x16x32_bf16 v[6:9], v[172:175], v[214:217], v[6:9]
	v_mfma_f32_16x16x32_bf16 v[2:5], v[182:185], v[214:217], v[2:5]
	s_barrier
	s_setprio 0
	s_add_i32 s55, s55, 2
	s_add_u32 s28, s28, 0x100
	s_addc_u32 s29, s29, 0
	s_add_u32 s53, s53, 0x100
	s_addc_u32 s54, s54, 0
	s_cmp_gt_u32 s55, 13
	s_cbranch_scc0 .LBB0_1400
	s_branch .Lpk1400_exit
.LBB0_1400:
	ds_read_b128 v[152:155], v1
	ds_read_b128 v[156:159], v1 offset:1024
	ds_read_b128 v[160:163], v1 offset:2048
	ds_read_b128 v[164:167], v1 offset:3072
	ds_read_b128 v[168:171], v149
	ds_read_b128 v[172:175], v149 offset:1024
	ds_read_b128 v[178:181], v149 offset:2048
	ds_read_b128 v[182:185], v149 offset:3072
	s_add_u32 s2, s28, 0xfffc0080
	s_addc_u32 s3, s29, -1
	s_cmp_eq_u32 s55, 12
	s_cselect_b32 s3, s11, s3
	s_cselect_b32 s2, s13, s2
	s_cselect_b32 s31, s47, s54
	s_cselect_b32 s30, s52, s53
	v_lshl_add_u64 v[146:147], s[28:29], 0, v[140:141]
	s_add_i32 m0, s25, 0xc000
	ds_read_b128 v[186:189], v150
	ds_read_b128 v[190:193], v150 offset:1024
	ds_read_b128 v[194:197], v150 offset:2048
	ds_read_b128 v[198:201], v150 offset:3072
	ds_read_b128 v[202:205], v150 offset:4096
	ds_read_b128 v[206:209], v150 offset:5120
	ds_read_b128 v[210:213], v150 offset:6144
	ds_read_b128 v[214:217], v150 offset:7168
	global_load_lds_dwordx4 v[146:147], off
	v_lshl_add_u64 v[146:147], s[28:29], 0, v[142:143]
	s_add_i32 m0, s25, 0xe000
	s_nop 0
	global_load_lds_dwordx4 v[146:147], off
	s_waitcnt vmcnt(8)
	s_waitcnt lgkmcnt(0)
	s_setprio 2
	s_barrier
	v_mfma_f32_16x16x32_bf16 v[126:129], v[152:155], v[186:189], v[126:129]
	v_mfma_f32_16x16x32_bf16 v[122:125], v[160:163], v[186:189], v[122:125]
	v_mfma_f32_16x16x32_bf16 v[110:113], v[152:155], v[194:197], v[110:113]
	v_mfma_f32_16x16x32_bf16 v[106:109], v[160:163], v[194:197], v[106:109]
	v_mfma_f32_16x16x32_bf16 v[94:97], v[152:155], v[202:205], v[94:97]
	v_mfma_f32_16x16x32_bf16 v[90:93], v[160:163], v[202:205], v[90:93]
	v_mfma_f32_16x16x32_bf16 v[78:81], v[152:155], v[210:213], v[78:81]
	v_mfma_f32_16x16x32_bf16 v[74:77], v[160:163], v[210:213], v[74:77]
	v_mfma_f32_16x16x32_bf16 v[126:129], v[156:159], v[190:193], v[126:129]
	v_mfma_f32_16x16x32_bf16 v[122:125], v[164:167], v[190:193], v[122:125]
	v_mfma_f32_16x16x32_bf16 v[110:113], v[156:159], v[198:201], v[110:113]
	v_mfma_f32_16x16x32_bf16 v[106:109], v[164:167], v[198:201], v[106:109]
	v_mfma_f32_16x16x32_bf16 v[94:97], v[156:159], v[206:209], v[94:97]
	v_mfma_f32_16x16x32_bf16 v[90:93], v[164:167], v[206:209], v[90:93]
	v_mfma_f32_16x16x32_bf16 v[78:81], v[156:159], v[214:217], v[78:81]
	v_mfma_f32_16x16x32_bf16 v[74:77], v[164:167], v[214:217], v[74:77]
	v_mfma_f32_16x16x32_bf16 v[118:121], v[168:171], v[186:189], v[118:121]
	v_mfma_f32_16x16x32_bf16 v[114:117], v[178:181], v[186:189], v[114:117]
	v_mfma_f32_16x16x32_bf16 v[102:105], v[168:171], v[194:197], v[102:105]
	v_mfma_f32_16x16x32_bf16 v[98:101], v[178:181], v[194:197], v[98:101]
	v_mfma_f32_16x16x32_bf16 v[86:89], v[168:171], v[202:205], v[86:89]
	v_mfma_f32_16x16x32_bf16 v[82:85], v[178:181], v[202:205], v[82:85]
	v_mfma_f32_16x16x32_bf16 v[70:73], v[168:171], v[210:213], v[70:73]
	v_mfma_f32_16x16x32_bf16 v[66:69], v[178:181], v[210:213], v[66:69]
	v_mfma_f32_16x16x32_bf16 v[118:121], v[172:175], v[190:193], v[118:121]
	v_mfma_f32_16x16x32_bf16 v[114:117], v[182:185], v[190:193], v[114:117]
	v_mfma_f32_16x16x32_bf16 v[102:105], v[172:175], v[198:201], v[102:105]
	v_mfma_f32_16x16x32_bf16 v[98:101], v[182:185], v[198:201], v[98:101]
	v_mfma_f32_16x16x32_bf16 v[86:89], v[172:175], v[206:209], v[86:89]
	v_mfma_f32_16x16x32_bf16 v[82:85], v[182:185], v[206:209], v[82:85]
	v_mfma_f32_16x16x32_bf16 v[70:73], v[172:175], v[214:217], v[70:73]
	v_mfma_f32_16x16x32_bf16 v[66:69], v[182:185], v[214:217], v[66:69]
	s_barrier
	s_setprio 0
	s_add_i32 s56, s43, s34
	v_lshl_add_u64 v[146:147], s[30:31], 0, v[132:133]
	s_mov_b32 m0, s56
	ds_read_b128 v[186:189], v150 offset:16384
	ds_read_b128 v[190:193], v150 offset:17408
	ds_read_b128 v[194:197], v150 offset:18432
	ds_read_b128 v[198:201], v150 offset:19456
	ds_read_b128 v[202:205], v150 offset:20480
	ds_read_b128 v[206:209], v150 offset:21504
	ds_read_b128 v[210:213], v150 offset:22528
	ds_read_b128 v[214:217], v150 offset:23552
	global_load_lds_dwordx4 v[146:147], off
	s_add_i32 m0, s56, 0x2000
	s_add_u32 s56, s30, 0x40000
	v_lshl_add_u64 v[218:219], s[30:31], 0, v[136:137]
	s_addc_u32 s57, s31, 0
	s_add_i32 s58, s44, s34
	global_load_lds_dwordx4 v[218:219], off
	v_lshl_add_u64 v[220:221], s[56:57], 0, v[132:133]
	s_mov_b32 m0, s58
	v_lshl_add_u64 v[222:223], s[2:3], 0, v[134:135]
	global_load_lds_dwordx4 v[220:221], off
	v_lshl_add_u64 v[220:221], s[56:57], 0, v[136:137]
	s_add_i32 m0, s58, 0x2000
	s_nop 0
	global_load_lds_dwordx4 v[220:221], off
	v_lshl_add_u64 v[220:221], s[2:3], 0, v[130:131]
	s_mov_b32 m0, s25
	s_nop 0
	global_load_lds_dwordx4 v[220:221], off
	s_mov_b32 m0, s27
	s_nop 0
	global_load_lds_dwordx4 v[222:223], off
	s_waitcnt vmcnt(8)
	s_waitcnt lgkmcnt(0)
	s_setprio 2
	s_barrier
	v_mfma_f32_16x16x32_bf16 v[62:65], v[152:155], v[186:189], v[62:65]
	v_mfma_f32_16x16x32_bf16 v[58:61], v[160:163], v[186:189], v[58:61]
	v_mfma_f32_16x16x32_bf16 v[46:49], v[152:155], v[194:197], v[46:49]
	v_mfma_f32_16x16x32_bf16 v[42:45], v[160:163], v[194:197], v[42:45]
	v_mfma_f32_16x16x32_bf16 v[30:33], v[152:155], v[202:205], v[30:33]
	v_mfma_f32_16x16x32_bf16 v[26:29], v[160:163], v[202:205], v[26:29]
	v_mfma_f32_16x16x32_bf16 v[14:17], v[152:155], v[210:213], v[14:17]
	v_mfma_f32_16x16x32_bf16 v[10:13], v[160:163], v[210:213], v[10:13]
	v_mfma_f32_16x16x32_bf16 v[62:65], v[156:159], v[190:193], v[62:65]
	v_mfma_f32_16x16x32_bf16 v[58:61], v[164:167], v[190:193], v[58:61]
	v_mfma_f32_16x16x32_bf16 v[46:49], v[156:159], v[198:201], v[46:49]
	v_mfma_f32_16x16x32_bf16 v[42:45], v[164:167], v[198:201], v[42:45]
	v_mfma_f32_16x16x32_bf16 v[30:33], v[156:159], v[206:209], v[30:33]
	v_mfma_f32_16x16x32_bf16 v[26:29], v[164:167], v[206:209], v[26:29]
	v_mfma_f32_16x16x32_bf16 v[14:17], v[156:159], v[214:217], v[14:17]
	v_mfma_f32_16x16x32_bf16 v[10:13], v[164:167], v[214:217], v[10:13]
	v_mfma_f32_16x16x32_bf16 v[54:57], v[168:171], v[186:189], v[54:57]
	v_mfma_f32_16x16x32_bf16 v[50:53], v[178:181], v[186:189], v[50:53]
	v_mfma_f32_16x16x32_bf16 v[38:41], v[168:171], v[194:197], v[38:41]
	v_mfma_f32_16x16x32_bf16 v[34:37], v[178:181], v[194:197], v[34:37]
	v_mfma_f32_16x16x32_bf16 v[22:25], v[168:171], v[202:205], v[22:25]
	v_mfma_f32_16x16x32_bf16 v[18:21], v[178:181], v[202:205], v[18:21]
	v_mfma_f32_16x16x32_bf16 v[6:9], v[168:171], v[210:213], v[6:9]
	v_mfma_f32_16x16x32_bf16 v[2:5], v[178:181], v[210:213], v[2:5]
	v_mfma_f32_16x16x32_bf16 v[54:57], v[172:175], v[190:193], v[54:57]
	v_mfma_f32_16x16x32_bf16 v[50:53], v[182:185], v[190:193], v[50:53]
	v_mfma_f32_16x16x32_bf16 v[38:41], v[172:175], v[198:201], v[38:41]
	v_mfma_f32_16x16x32_bf16 v[34:37], v[182:185], v[198:201], v[34:37]
	v_mfma_f32_16x16x32_bf16 v[22:25], v[172:175], v[206:209], v[22:25]
	v_mfma_f32_16x16x32_bf16 v[18:21], v[182:185], v[206:209], v[18:21]
	v_mfma_f32_16x16x32_bf16 v[6:9], v[172:175], v[214:217], v[6:9]
	v_mfma_f32_16x16x32_bf16 v[2:5], v[182:185], v[214:217], v[2:5]
	s_barrier
	s_setprio 0
	s_add_i32 s56, 0, 0x18000
	v_add_u32_e32 v151, s56, v148
	s_add_i32 s57, 0, 0x1c000
	ds_read_b128 v[152:155], v151
	ds_read_b128 v[156:159], v151 offset:1024
	ds_read_b128 v[160:163], v151 offset:2048
	ds_read_b128 v[164:167], v151 offset:3072
	v_add_u32_e32 v151, s57, v148
	ds_read_b128 v[168:171], v151
	ds_read_b128 v[172:175], v151 offset:1024
	ds_read_b128 v[178:181], v151 offset:2048
	ds_read_b128 v[182:185], v151 offset:3072
	s_add_u32 s2, s2, 0x40000
	s_addc_u32 s3, s3, 0
	s_mov_b32 m0, s36
	v_lshl_add_u64 v[224:225], s[2:3], 0, v[130:131]
	ds_read_b128 v[186:189], v150 offset:32768
	ds_read_b128 v[190:193], v150 offset:33792
	ds_read_b128 v[194:197], v150 offset:34816
	ds_read_b128 v[198:201], v150 offset:35840
	ds_read_b128 v[202:205], v150 offset:36864
	ds_read_b128 v[206:209], v150 offset:37888
	ds_read_b128 v[210:213], v150 offset:38912
	ds_read_b128 v[214:217], v150 offset:39936
	global_load_lds_dwordx4 v[224:225], off
	v_lshl_add_u64 v[224:225], s[2:3], 0, v[134:135]
	s_mov_b32 m0, s37
	s_nop 0
	global_load_lds_dwordx4 v[224:225], off
	s_waitcnt vmcnt(8)
	s_waitcnt lgkmcnt(0)
	s_setprio 2
	s_barrier
	v_mfma_f32_16x16x32_bf16 v[126:129], v[152:155], v[186:189], v[126:129]
	v_mfma_f32_16x16x32_bf16 v[122:125], v[160:163], v[186:189], v[122:125]
	v_mfma_f32_16x16x32_bf16 v[110:113], v[152:155], v[194:197], v[110:113]
	v_mfma_f32_16x16x32_bf16 v[106:109], v[160:163], v[194:197], v[106:109]
	v_mfma_f32_16x16x32_bf16 v[94:97], v[152:155], v[202:205], v[94:97]
	v_mfma_f32_16x16x32_bf16 v[90:93], v[160:163], v[202:205], v[90:93]
	v_mfma_f32_16x16x32_bf16 v[78:81], v[152:155], v[210:213], v[78:81]
	v_mfma_f32_16x16x32_bf16 v[74:77], v[160:163], v[210:213], v[74:77]
	v_mfma_f32_16x16x32_bf16 v[126:129], v[156:159], v[190:193], v[126:129]
	v_mfma_f32_16x16x32_bf16 v[122:125], v[164:167], v[190:193], v[122:125]
	v_mfma_f32_16x16x32_bf16 v[110:113], v[156:159], v[198:201], v[110:113]
	v_mfma_f32_16x16x32_bf16 v[106:109], v[164:167], v[198:201], v[106:109]
	v_mfma_f32_16x16x32_bf16 v[94:97], v[156:159], v[206:209], v[94:97]
	v_mfma_f32_16x16x32_bf16 v[90:93], v[164:167], v[206:209], v[90:93]
	v_mfma_f32_16x16x32_bf16 v[78:81], v[156:159], v[214:217], v[78:81]
	v_mfma_f32_16x16x32_bf16 v[74:77], v[164:167], v[214:217], v[74:77]
	v_mfma_f32_16x16x32_bf16 v[118:121], v[168:171], v[186:189], v[118:121]
	v_mfma_f32_16x16x32_bf16 v[114:117], v[178:181], v[186:189], v[114:117]
	v_mfma_f32_16x16x32_bf16 v[102:105], v[168:171], v[194:197], v[102:105]
	v_mfma_f32_16x16x32_bf16 v[98:101], v[178:181], v[194:197], v[98:101]
	v_mfma_f32_16x16x32_bf16 v[86:89], v[168:171], v[202:205], v[86:89]
	v_mfma_f32_16x16x32_bf16 v[82:85], v[178:181], v[202:205], v[82:85]
	v_mfma_f32_16x16x32_bf16 v[70:73], v[168:171], v[210:213], v[70:73]
	v_mfma_f32_16x16x32_bf16 v[66:69], v[178:181], v[210:213], v[66:69]
	v_mfma_f32_16x16x32_bf16 v[118:121], v[172:175], v[190:193], v[118:121]
	v_mfma_f32_16x16x32_bf16 v[114:117], v[182:185], v[190:193], v[114:117]
	v_mfma_f32_16x16x32_bf16 v[102:105], v[172:175], v[198:201], v[102:105]
	v_mfma_f32_16x16x32_bf16 v[98:101], v[182:185], v[198:201], v[98:101]
	v_mfma_f32_16x16x32_bf16 v[86:89], v[172:175], v[206:209], v[86:89]
	v_mfma_f32_16x16x32_bf16 v[82:85], v[182:185], v[206:209], v[82:85]
	v_mfma_f32_16x16x32_bf16 v[70:73], v[172:175], v[214:217], v[70:73]
	v_mfma_f32_16x16x32_bf16 v[66:69], v[182:185], v[214:217], v[66:69]
	s_barrier
	s_setprio 0
	s_add_i32 s2, s56, s34
	v_lshl_add_u64 v[146:147], v[146:147], 0, s[6:7]
	s_mov_b32 m0, s2
	ds_read_b128 v[186:189], v150 offset:49152
	ds_read_b128 v[190:193], v150 offset:50176
	ds_read_b128 v[194:197], v150 offset:51200
	ds_read_b128 v[198:201], v150 offset:52224
	ds_read_b128 v[202:205], v150 offset:53248
	ds_read_b128 v[206:209], v150 offset:54272
	ds_read_b128 v[210:213], v150 offset:55296
	ds_read_b128 v[214:217], v150 offset:56320
	global_load_lds_dwordx4 v[146:147], off
	s_add_i32 m0, s2, 0x2000
	s_add_u32 s2, s30, 0x40080
	v_lshl_add_u64 v[146:147], v[218:219], 0, s[6:7]
	s_addc_u32 s3, s31, 0
	s_add_i32 s30, s57, s34
	global_load_lds_dwordx4 v[146:147], off
	v_lshl_add_u64 v[146:147], s[2:3], 0, v[132:133]
	s_mov_b32 m0, s30
	s_nop 0
	global_load_lds_dwordx4 v[146:147], off
	v_lshl_add_u64 v[146:147], s[2:3], 0, v[136:137]
	s_add_i32 m0, s30, 0x2000
	s_nop 0
	global_load_lds_dwordx4 v[146:147], off
	v_lshl_add_u64 v[146:147], v[220:221], 0, s[6:7]
	s_mov_b32 m0, s40
	s_nop 0
	global_load_lds_dwordx4 v[146:147], off
	v_lshl_add_u64 v[146:147], v[222:223], 0, s[6:7]
	s_mov_b32 m0, s41
	s_nop 0
	global_load_lds_dwordx4 v[146:147], off
	s_waitcnt vmcnt(8)
	s_waitcnt lgkmcnt(0)
	s_setprio 2
	s_barrier
	v_mfma_f32_16x16x32_bf16 v[62:65], v[152:155], v[186:189], v[62:65]
	v_mfma_f32_16x16x32_bf16 v[58:61], v[160:163], v[186:189], v[58:61]
	v_mfma_f32_16x16x32_bf16 v[46:49], v[152:155], v[194:197], v[46:49]
	v_mfma_f32_16x16x32_bf16 v[42:45], v[160:163], v[194:197], v[42:45]
	v_mfma_f32_16x16x32_bf16 v[30:33], v[152:155], v[202:205], v[30:33]
	v_mfma_f32_16x16x32_bf16 v[26:29], v[160:163], v[202:205], v[26:29]
	v_mfma_f32_16x16x32_bf16 v[14:17], v[152:155], v[210:213], v[14:17]
	v_mfma_f32_16x16x32_bf16 v[10:13], v[160:163], v[210:213], v[10:13]
	v_mfma_f32_16x16x32_bf16 v[62:65], v[156:159], v[190:193], v[62:65]
	v_mfma_f32_16x16x32_bf16 v[58:61], v[164:167], v[190:193], v[58:61]
	v_mfma_f32_16x16x32_bf16 v[46:49], v[156:159], v[198:201], v[46:49]
	v_mfma_f32_16x16x32_bf16 v[42:45], v[164:167], v[198:201], v[42:45]
	v_mfma_f32_16x16x32_bf16 v[30:33], v[156:159], v[206:209], v[30:33]
	v_mfma_f32_16x16x32_bf16 v[26:29], v[164:167], v[206:209], v[26:29]
	v_mfma_f32_16x16x32_bf16 v[14:17], v[156:159], v[214:217], v[14:17]
	v_mfma_f32_16x16x32_bf16 v[10:13], v[164:167], v[214:217], v[10:13]
	v_mfma_f32_16x16x32_bf16 v[54:57], v[168:171], v[186:189], v[54:57]
	v_mfma_f32_16x16x32_bf16 v[50:53], v[178:181], v[186:189], v[50:53]
	v_mfma_f32_16x16x32_bf16 v[38:41], v[168:171], v[194:197], v[38:41]
	v_mfma_f32_16x16x32_bf16 v[34:37], v[178:181], v[194:197], v[34:37]
	v_mfma_f32_16x16x32_bf16 v[22:25], v[168:171], v[202:205], v[22:25]
	v_mfma_f32_16x16x32_bf16 v[18:21], v[178:181], v[202:205], v[18:21]
	v_mfma_f32_16x16x32_bf16 v[6:9], v[168:171], v[210:213], v[6:9]
	v_mfma_f32_16x16x32_bf16 v[2:5], v[178:181], v[210:213], v[2:5]
	v_mfma_f32_16x16x32_bf16 v[54:57], v[172:175], v[190:193], v[54:57]
	v_mfma_f32_16x16x32_bf16 v[50:53], v[182:185], v[190:193], v[50:53]
	v_mfma_f32_16x16x32_bf16 v[38:41], v[172:175], v[198:201], v[38:41]
	v_mfma_f32_16x16x32_bf16 v[34:37], v[182:185], v[198:201], v[34:37]
	v_mfma_f32_16x16x32_bf16 v[22:25], v[172:175], v[206:209], v[22:25]
	v_mfma_f32_16x16x32_bf16 v[18:21], v[182:185], v[206:209], v[18:21]
	v_mfma_f32_16x16x32_bf16 v[6:9], v[172:175], v[214:217], v[6:9]
	v_mfma_f32_16x16x32_bf16 v[2:5], v[182:185], v[214:217], v[2:5]
	s_barrier
	s_setprio 0
	s_add_i32 s55, s55, 2
	s_add_u32 s28, s28, 0x100
	s_addc_u32 s29, s29, 0
	s_add_u32 s53, s53, 0x100
	s_addc_u32 s54, s54, 0
	s_cmp_gt_u32 s55, 13
	s_cbranch_scc0 .LBB0_1400

.Lpk1444_peel:
	ds_read_b128 v[152:155], v148
	ds_read_b128 v[156:159], v148 offset:1024
	ds_read_b128 v[160:163], v148 offset:2048
	ds_read_b128 v[164:167], v148 offset:3072
	ds_read_b128 v[168:171], v149
	ds_read_b128 v[172:175], v149 offset:1024
	ds_read_b128 v[178:181], v149 offset:2048
	ds_read_b128 v[182:185], v149 offset:3072
	s_add_u32 s2, s26, 0x4000
	s_addc_u32 s3, s27, 0
	s_cmp_eq_u32 s62, 40
	s_cselect_b32 s2, s57, s2
	s_cselect_b32 s3, s56, s3
	s_cselect_b32 s31, s58, s61
	s_cselect_b32 s30, s59, s60
	s_add_u32 s28, s2, 0x8000
	s_addc_u32 s29, s3, 0
	v_lshl_add_u64 v[144:145], s[26:27], 0, v[138:139]
	s_add_i32 m0, s39, 0xc000
	ds_read_b128 v[186:189], v150
	ds_read_b128 v[190:193], v150 offset:1024
	ds_read_b128 v[194:197], v150 offset:2048
	ds_read_b128 v[198:201], v150 offset:3072
	ds_read_b128 v[202:205], v150 offset:4096
	ds_read_b128 v[206:209], v150 offset:5120
	ds_read_b128 v[210:213], v150 offset:6144
	ds_read_b128 v[214:217], v150 offset:7168
	global_load_lds_dwordx4 v[144:145], off
	v_lshl_add_u64 v[144:145], s[26:27], 0, v[140:141]
	s_add_i32 m0, s39, 0xe000
	s_nop 0
	global_load_lds_dwordx4 v[144:145], off
	s_waitcnt vmcnt(8)
	s_waitcnt lgkmcnt(0)
	s_setprio 2
	s_barrier
	v_mfma_f32_16x16x32_bf16 v[126:129], v[152:155], v[186:189], 0
	v_mfma_f32_16x16x32_bf16 v[122:125], v[160:163], v[186:189], 0
	v_mfma_f32_16x16x32_bf16 v[114:117], v[152:155], v[194:197], 0
	v_mfma_f32_16x16x32_bf16 v[106:109], v[160:163], v[194:197], 0
	v_mfma_f32_16x16x32_bf16 v[98:101], v[152:155], v[202:205], 0
	v_mfma_f32_16x16x32_bf16 v[90:93], v[160:163], v[202:205], 0
	v_mfma_f32_16x16x32_bf16 v[82:85], v[152:155], v[210:213], 0
	v_mfma_f32_16x16x32_bf16 v[74:77], v[160:163], v[210:213], 0
	v_mfma_f32_16x16x32_bf16 v[126:129], v[156:159], v[190:193], v[126:129]
	v_mfma_f32_16x16x32_bf16 v[122:125], v[164:167], v[190:193], v[122:125]
	v_mfma_f32_16x16x32_bf16 v[114:117], v[156:159], v[198:201], v[114:117]
	v_mfma_f32_16x16x32_bf16 v[106:109], v[164:167], v[198:201], v[106:109]
	v_mfma_f32_16x16x32_bf16 v[98:101], v[156:159], v[206:209], v[98:101]
	v_mfma_f32_16x16x32_bf16 v[90:93], v[164:167], v[206:209], v[90:93]
	v_mfma_f32_16x16x32_bf16 v[82:85], v[156:159], v[214:217], v[82:85]
	v_mfma_f32_16x16x32_bf16 v[74:77], v[164:167], v[214:217], v[74:77]
	v_mfma_f32_16x16x32_bf16 v[118:121], v[168:171], v[186:189], 0
	v_mfma_f32_16x16x32_bf16 v[110:113], v[178:181], v[186:189], 0
	v_mfma_f32_16x16x32_bf16 v[102:105], v[168:171], v[194:197], 0
	v_mfma_f32_16x16x32_bf16 v[94:97], v[178:181], v[194:197], 0
	v_mfma_f32_16x16x32_bf16 v[86:89], v[168:171], v[202:205], 0
	v_mfma_f32_16x16x32_bf16 v[78:81], v[178:181], v[202:205], 0
	v_mfma_f32_16x16x32_bf16 v[70:73], v[168:171], v[210:213], 0
	v_mfma_f32_16x16x32_bf16 v[66:69], v[178:181], v[210:213], 0
	v_mfma_f32_16x16x32_bf16 v[118:121], v[172:175], v[190:193], v[118:121]
	v_mfma_f32_16x16x32_bf16 v[110:113], v[182:185], v[190:193], v[110:113]
	v_mfma_f32_16x16x32_bf16 v[102:105], v[172:175], v[198:201], v[102:105]
	v_mfma_f32_16x16x32_bf16 v[94:97], v[182:185], v[198:201], v[94:97]
	v_mfma_f32_16x16x32_bf16 v[86:89], v[172:175], v[206:209], v[86:89]
	v_mfma_f32_16x16x32_bf16 v[78:81], v[182:185], v[206:209], v[78:81]
	v_mfma_f32_16x16x32_bf16 v[70:73], v[172:175], v[214:217], v[70:73]
	v_mfma_f32_16x16x32_bf16 v[66:69], v[182:185], v[214:217], v[66:69]
	s_barrier
	s_setprio 0
	s_add_i32 s63, s46, s38
	v_lshl_add_u64 v[144:145], s[30:31], 0, v[132:133]
	s_mov_b32 m0, s63
	ds_read_b128 v[186:189], v150 offset:16384
	ds_read_b128 v[190:193], v150 offset:17408
	ds_read_b128 v[194:197], v150 offset:18432
	ds_read_b128 v[198:201], v150 offset:19456
	ds_read_b128 v[202:205], v150 offset:20480
	ds_read_b128 v[206:209], v150 offset:21504
	ds_read_b128 v[210:213], v150 offset:22528
	ds_read_b128 v[214:217], v150 offset:23552
	global_load_lds_dwordx4 v[144:145], off
	s_add_i32 m0, s63, 0x2000
	s_add_u32 s64, s30, 0x4000
	v_lshl_add_u64 v[144:145], s[30:31], 0, v[136:137]
	s_addc_u32 s65, s31, 0
	s_add_i32 s63, s47, s38
	global_load_lds_dwordx4 v[144:145], off
	v_lshl_add_u64 v[144:145], s[64:65], 0, v[132:133]
	s_mov_b32 m0, s63
	s_nop 0
	global_load_lds_dwordx4 v[144:145], off
	v_lshl_add_u64 v[144:145], s[64:65], 0, v[136:137]
	s_add_i32 m0, s63, 0x2000
	s_nop 0
	global_load_lds_dwordx4 v[144:145], off
	v_lshl_add_u64 v[144:145], s[2:3], 0, v[130:131]
	s_mov_b32 m0, s39
	s_nop 0
	global_load_lds_dwordx4 v[144:145], off
	v_lshl_add_u64 v[144:145], s[2:3], 0, v[134:135]
	s_mov_b32 m0, s40
	s_nop 0
	global_load_lds_dwordx4 v[144:145], off
	s_waitcnt vmcnt(8)
	s_waitcnt lgkmcnt(0)
	s_setprio 2
	s_barrier
	v_mfma_f32_16x16x32_bf16 v[62:65], v[152:155], v[186:189], 0
	v_mfma_f32_16x16x32_bf16 v[58:61], v[160:163], v[186:189], 0
	v_mfma_f32_16x16x32_bf16 v[50:53], v[152:155], v[194:197], 0
	v_mfma_f32_16x16x32_bf16 v[42:45], v[160:163], v[194:197], 0
	v_mfma_f32_16x16x32_bf16 v[34:37], v[152:155], v[202:205], 0
	v_mfma_f32_16x16x32_bf16 v[26:29], v[160:163], v[202:205], 0
	v_mfma_f32_16x16x32_bf16 v[18:21], v[152:155], v[210:213], 0
	v_mfma_f32_16x16x32_bf16 v[10:13], v[160:163], v[210:213], 0
	v_mfma_f32_16x16x32_bf16 v[62:65], v[156:159], v[190:193], v[62:65]
	v_mfma_f32_16x16x32_bf16 v[58:61], v[164:167], v[190:193], v[58:61]
	v_mfma_f32_16x16x32_bf16 v[50:53], v[156:159], v[198:201], v[50:53]
	v_mfma_f32_16x16x32_bf16 v[42:45], v[164:167], v[198:201], v[42:45]
	v_mfma_f32_16x16x32_bf16 v[34:37], v[156:159], v[206:209], v[34:37]
	v_mfma_f32_16x16x32_bf16 v[26:29], v[164:167], v[206:209], v[26:29]
	v_mfma_f32_16x16x32_bf16 v[18:21], v[156:159], v[214:217], v[18:21]
	v_mfma_f32_16x16x32_bf16 v[10:13], v[164:167], v[214:217], v[10:13]
	v_mfma_f32_16x16x32_bf16 v[54:57], v[168:171], v[186:189], 0
	v_mfma_f32_16x16x32_bf16 v[46:49], v[178:181], v[186:189], 0
	v_mfma_f32_16x16x32_bf16 v[38:41], v[168:171], v[194:197], 0
	v_mfma_f32_16x16x32_bf16 v[30:33], v[178:181], v[194:197], 0
	v_mfma_f32_16x16x32_bf16 v[22:25], v[168:171], v[202:205], 0
	v_mfma_f32_16x16x32_bf16 v[14:17], v[178:181], v[202:205], 0
	v_mfma_f32_16x16x32_bf16 v[6:9], v[168:171], v[210:213], 0
	v_mfma_f32_16x16x32_bf16 v[2:5], v[178:181], v[210:213], 0
	v_mfma_f32_16x16x32_bf16 v[54:57], v[172:175], v[190:193], v[54:57]
	v_mfma_f32_16x16x32_bf16 v[46:49], v[182:185], v[190:193], v[46:49]
	v_mfma_f32_16x16x32_bf16 v[38:41], v[172:175], v[198:201], v[38:41]
	v_mfma_f32_16x16x32_bf16 v[30:33], v[182:185], v[198:201], v[30:33]
	v_mfma_f32_16x16x32_bf16 v[22:25], v[172:175], v[206:209], v[22:25]
	v_mfma_f32_16x16x32_bf16 v[14:17], v[182:185], v[206:209], v[14:17]
	v_mfma_f32_16x16x32_bf16 v[6:9], v[172:175], v[214:217], v[6:9]
	v_mfma_f32_16x16x32_bf16 v[2:5], v[182:185], v[214:217], v[2:5]
	s_barrier
	s_setprio 0
	s_add_i32 s63, 0, 0x18000
	v_add_u32_e32 v144, s63, v146
	s_add_i32 s64, 0, 0x1c000
	ds_read_b128 v[152:155], v144
	ds_read_b128 v[156:159], v144 offset:1024
	ds_read_b128 v[160:163], v144 offset:2048
	ds_read_b128 v[164:167], v144 offset:3072
	v_add_u32_e32 v144, s64, v146
	ds_read_b128 v[168:171], v144
	ds_read_b128 v[172:175], v144 offset:1024
	ds_read_b128 v[178:181], v144 offset:2048
	ds_read_b128 v[182:185], v144 offset:3072
	s_add_u32 s2, s2, 0x4000
	s_addc_u32 s3, s3, 0
	s_mov_b32 m0, s41
	v_lshl_add_u64 v[144:145], s[2:3], 0, v[130:131]
	ds_read_b128 v[186:189], v150 offset:32768
	ds_read_b128 v[190:193], v150 offset:33792
	ds_read_b128 v[194:197], v150 offset:34816
	ds_read_b128 v[198:201], v150 offset:35840
	ds_read_b128 v[202:205], v150 offset:36864
	ds_read_b128 v[206:209], v150 offset:37888
	ds_read_b128 v[210:213], v150 offset:38912
	ds_read_b128 v[214:217], v150 offset:39936
	global_load_lds_dwordx4 v[144:145], off
	v_lshl_add_u64 v[144:145], s[2:3], 0, v[134:135]
	s_mov_b32 m0, s42
	s_nop 0
	global_load_lds_dwordx4 v[144:145], off
	s_waitcnt vmcnt(8)
	s_waitcnt lgkmcnt(0)
	s_setprio 2
	s_barrier
	v_mfma_f32_16x16x32_bf16 v[126:129], v[152:155], v[186:189], v[126:129]
	v_mfma_f32_16x16x32_bf16 v[122:125], v[160:163], v[186:189], v[122:125]
	v_mfma_f32_16x16x32_bf16 v[114:117], v[152:155], v[194:197], v[114:117]
	v_mfma_f32_16x16x32_bf16 v[106:109], v[160:163], v[194:197], v[106:109]
	v_mfma_f32_16x16x32_bf16 v[98:101], v[152:155], v[202:205], v[98:101]
	v_mfma_f32_16x16x32_bf16 v[90:93], v[160:163], v[202:205], v[90:93]
	v_mfma_f32_16x16x32_bf16 v[82:85], v[152:155], v[210:213], v[82:85]
	v_mfma_f32_16x16x32_bf16 v[74:77], v[160:163], v[210:213], v[74:77]
	v_mfma_f32_16x16x32_bf16 v[126:129], v[156:159], v[190:193], v[126:129]
	v_mfma_f32_16x16x32_bf16 v[122:125], v[164:167], v[190:193], v[122:125]
	v_mfma_f32_16x16x32_bf16 v[114:117], v[156:159], v[198:201], v[114:117]
	v_mfma_f32_16x16x32_bf16 v[106:109], v[164:167], v[198:201], v[106:109]
	v_mfma_f32_16x16x32_bf16 v[98:101], v[156:159], v[206:209], v[98:101]
	v_mfma_f32_16x16x32_bf16 v[90:93], v[164:167], v[206:209], v[90:93]
	v_mfma_f32_16x16x32_bf16 v[82:85], v[156:159], v[214:217], v[82:85]
	v_mfma_f32_16x16x32_bf16 v[74:77], v[164:167], v[214:217], v[74:77]
	v_mfma_f32_16x16x32_bf16 v[118:121], v[168:171], v[186:189], v[118:121]
	v_mfma_f32_16x16x32_bf16 v[110:113], v[178:181], v[186:189], v[110:113]
	v_mfma_f32_16x16x32_bf16 v[102:105], v[168:171], v[194:197], v[102:105]
	v_mfma_f32_16x16x32_bf16 v[94:97], v[178:181], v[194:197], v[94:97]
	v_mfma_f32_16x16x32_bf16 v[86:89], v[168:171], v[202:205], v[86:89]
	v_mfma_f32_16x16x32_bf16 v[78:81], v[178:181], v[202:205], v[78:81]
	v_mfma_f32_16x16x32_bf16 v[70:73], v[168:171], v[210:213], v[70:73]
	v_mfma_f32_16x16x32_bf16 v[66:69], v[178:181], v[210:213], v[66:69]
	v_mfma_f32_16x16x32_bf16 v[118:121], v[172:175], v[190:193], v[118:121]
	v_mfma_f32_16x16x32_bf16 v[110:113], v[182:185], v[190:193], v[110:113]
	v_mfma_f32_16x16x32_bf16 v[102:105], v[172:175], v[198:201], v[102:105]
	v_mfma_f32_16x16x32_bf16 v[94:97], v[182:185], v[198:201], v[94:97]
	v_mfma_f32_16x16x32_bf16 v[86:89], v[172:175], v[206:209], v[86:89]
	v_mfma_f32_16x16x32_bf16 v[78:81], v[182:185], v[206:209], v[78:81]
	v_mfma_f32_16x16x32_bf16 v[70:73], v[172:175], v[214:217], v[70:73]
	v_mfma_f32_16x16x32_bf16 v[66:69], v[182:185], v[214:217], v[66:69]
	s_barrier
	s_setprio 0
	s_add_u32 s2, s30, 0x8000
	s_addc_u32 s3, s31, 0
	s_add_i32 s63, s63, s38
	v_lshl_add_u64 v[144:145], s[2:3], 0, v[132:133]
	s_mov_b32 m0, s63
	ds_read_b128 v[186:189], v150 offset:49152
	ds_read_b128 v[190:193], v150 offset:50176
	ds_read_b128 v[194:197], v150 offset:51200
	ds_read_b128 v[198:201], v150 offset:52224
	ds_read_b128 v[202:205], v150 offset:53248
	ds_read_b128 v[206:209], v150 offset:54272
	ds_read_b128 v[210:213], v150 offset:55296
	ds_read_b128 v[214:217], v150 offset:56320
	global_load_lds_dwordx4 v[144:145], off
	s_add_i32 m0, s63, 0x2000
	v_lshl_add_u64 v[144:145], s[2:3], 0, v[136:137]
	s_add_u32 s2, s30, 0xc000
	s_addc_u32 s3, s31, 0
	s_add_i32 s30, s64, s38
	global_load_lds_dwordx4 v[144:145], off
	v_lshl_add_u64 v[144:145], s[2:3], 0, v[132:133]
	s_mov_b32 m0, s30
	s_nop 0
	global_load_lds_dwordx4 v[144:145], off
	v_lshl_add_u64 v[144:145], s[2:3], 0, v[136:137]
	s_add_i32 m0, s30, 0x2000
	s_nop 0
	global_load_lds_dwordx4 v[144:145], off
	v_lshl_add_u64 v[144:145], s[28:29], 0, v[130:131]
	s_mov_b32 m0, s44
	s_nop 0
	global_load_lds_dwordx4 v[144:145], off
	v_lshl_add_u64 v[144:145], s[28:29], 0, v[134:135]
	s_mov_b32 m0, s45
	s_nop 0
	global_load_lds_dwordx4 v[144:145], off
	s_waitcnt vmcnt(8)
	s_waitcnt lgkmcnt(0)
	s_setprio 2
	s_barrier
	v_mfma_f32_16x16x32_bf16 v[62:65], v[152:155], v[186:189], v[62:65]
	v_mfma_f32_16x16x32_bf16 v[58:61], v[160:163], v[186:189], v[58:61]
	v_mfma_f32_16x16x32_bf16 v[50:53], v[152:155], v[194:197], v[50:53]
	v_mfma_f32_16x16x32_bf16 v[42:45], v[160:163], v[194:197], v[42:45]
	v_mfma_f32_16x16x32_bf16 v[34:37], v[152:155], v[202:205], v[34:37]
	v_mfma_f32_16x16x32_bf16 v[26:29], v[160:163], v[202:205], v[26:29]
	v_mfma_f32_16x16x32_bf16 v[18:21], v[152:155], v[210:213], v[18:21]
	v_mfma_f32_16x16x32_bf16 v[10:13], v[160:163], v[210:213], v[10:13]
	v_mfma_f32_16x16x32_bf16 v[62:65], v[156:159], v[190:193], v[62:65]
	v_mfma_f32_16x16x32_bf16 v[58:61], v[164:167], v[190:193], v[58:61]
	v_mfma_f32_16x16x32_bf16 v[50:53], v[156:159], v[198:201], v[50:53]
	v_mfma_f32_16x16x32_bf16 v[42:45], v[164:167], v[198:201], v[42:45]
	v_mfma_f32_16x16x32_bf16 v[34:37], v[156:159], v[206:209], v[34:37]
	v_mfma_f32_16x16x32_bf16 v[26:29], v[164:167], v[206:209], v[26:29]
	v_mfma_f32_16x16x32_bf16 v[18:21], v[156:159], v[214:217], v[18:21]
	v_mfma_f32_16x16x32_bf16 v[10:13], v[164:167], v[214:217], v[10:13]
	v_mfma_f32_16x16x32_bf16 v[54:57], v[168:171], v[186:189], v[54:57]
	v_mfma_f32_16x16x32_bf16 v[46:49], v[178:181], v[186:189], v[46:49]
	v_mfma_f32_16x16x32_bf16 v[38:41], v[168:171], v[194:197], v[38:41]
	v_mfma_f32_16x16x32_bf16 v[30:33], v[178:181], v[194:197], v[30:33]
	v_mfma_f32_16x16x32_bf16 v[22:25], v[168:171], v[202:205], v[22:25]
	v_mfma_f32_16x16x32_bf16 v[14:17], v[178:181], v[202:205], v[14:17]
	v_mfma_f32_16x16x32_bf16 v[6:9], v[168:171], v[210:213], v[6:9]
	v_mfma_f32_16x16x32_bf16 v[2:5], v[178:181], v[210:213], v[2:5]
	v_mfma_f32_16x16x32_bf16 v[54:57], v[172:175], v[190:193], v[54:57]
	v_mfma_f32_16x16x32_bf16 v[46:49], v[182:185], v[190:193], v[46:49]
	v_mfma_f32_16x16x32_bf16 v[38:41], v[172:175], v[198:201], v[38:41]
	v_mfma_f32_16x16x32_bf16 v[30:33], v[182:185], v[198:201], v[30:33]
	v_mfma_f32_16x16x32_bf16 v[22:25], v[172:175], v[206:209], v[22:25]
	v_mfma_f32_16x16x32_bf16 v[14:17], v[182:185], v[206:209], v[14:17]
	v_mfma_f32_16x16x32_bf16 v[6:9], v[172:175], v[214:217], v[6:9]
	v_mfma_f32_16x16x32_bf16 v[2:5], v[182:185], v[214:217], v[2:5]
	s_barrier
	s_setprio 0
	s_add_i32 s62, s62, 2
	s_add_u32 s26, s26, 0x10000
	s_addc_u32 s27, s27, 0
	s_add_u32 s60, s60, 0x10000
	s_addc_u32 s61, s61, 0
	s_cmp_gt_u32 s62, 41
	s_cbranch_scc0 .LBB0_1444
	s_branch .Lpk1444_exit
.LBB0_1444:
	ds_read_b128 v[152:155], v148
	ds_read_b128 v[156:159], v148 offset:1024
	ds_read_b128 v[160:163], v148 offset:2048
	ds_read_b128 v[164:167], v148 offset:3072
	ds_read_b128 v[168:171], v149
	ds_read_b128 v[172:175], v149 offset:1024
	ds_read_b128 v[178:181], v149 offset:2048
	ds_read_b128 v[182:185], v149 offset:3072
	s_add_u32 s2, s26, 0x4000
	s_addc_u32 s3, s27, 0
	s_cmp_eq_u32 s62, 40
	s_cselect_b32 s2, s57, s2
	s_cselect_b32 s3, s56, s3
	s_cselect_b32 s31, s58, s61
	s_cselect_b32 s30, s59, s60
	s_add_u32 s28, s2, 0x8000
	s_addc_u32 s29, s3, 0
	v_lshl_add_u64 v[144:145], s[26:27], 0, v[138:139]
	s_add_i32 m0, s39, 0xc000
	ds_read_b128 v[186:189], v150
	ds_read_b128 v[190:193], v150 offset:1024
	ds_read_b128 v[194:197], v150 offset:2048
	ds_read_b128 v[198:201], v150 offset:3072
	ds_read_b128 v[202:205], v150 offset:4096
	ds_read_b128 v[206:209], v150 offset:5120
	ds_read_b128 v[210:213], v150 offset:6144
	ds_read_b128 v[214:217], v150 offset:7168
	global_load_lds_dwordx4 v[144:145], off
	v_lshl_add_u64 v[144:145], s[26:27], 0, v[140:141]
	s_add_i32 m0, s39, 0xe000
	s_nop 0
	global_load_lds_dwordx4 v[144:145], off
	s_waitcnt vmcnt(8)
	s_waitcnt lgkmcnt(0)
	s_setprio 2
	s_barrier
	v_mfma_f32_16x16x32_bf16 v[126:129], v[152:155], v[186:189], v[126:129]
	v_mfma_f32_16x16x32_bf16 v[122:125], v[160:163], v[186:189], v[122:125]
	v_mfma_f32_16x16x32_bf16 v[114:117], v[152:155], v[194:197], v[114:117]
	v_mfma_f32_16x16x32_bf16 v[106:109], v[160:163], v[194:197], v[106:109]
	v_mfma_f32_16x16x32_bf16 v[98:101], v[152:155], v[202:205], v[98:101]
	v_mfma_f32_16x16x32_bf16 v[90:93], v[160:163], v[202:205], v[90:93]
	v_mfma_f32_16x16x32_bf16 v[82:85], v[152:155], v[210:213], v[82:85]
	v_mfma_f32_16x16x32_bf16 v[74:77], v[160:163], v[210:213], v[74:77]
	v_mfma_f32_16x16x32_bf16 v[126:129], v[156:159], v[190:193], v[126:129]
	v_mfma_f32_16x16x32_bf16 v[122:125], v[164:167], v[190:193], v[122:125]
	v_mfma_f32_16x16x32_bf16 v[114:117], v[156:159], v[198:201], v[114:117]
	v_mfma_f32_16x16x32_bf16 v[106:109], v[164:167], v[198:201], v[106:109]
	v_mfma_f32_16x16x32_bf16 v[98:101], v[156:159], v[206:209], v[98:101]
	v_mfma_f32_16x16x32_bf16 v[90:93], v[164:167], v[206:209], v[90:93]
	v_mfma_f32_16x16x32_bf16 v[82:85], v[156:159], v[214:217], v[82:85]
	v_mfma_f32_16x16x32_bf16 v[74:77], v[164:167], v[214:217], v[74:77]
	v_mfma_f32_16x16x32_bf16 v[118:121], v[168:171], v[186:189], v[118:121]
	v_mfma_f32_16x16x32_bf16 v[110:113], v[178:181], v[186:189], v[110:113]
	v_mfma_f32_16x16x32_bf16 v[102:105], v[168:171], v[194:197], v[102:105]
	v_mfma_f32_16x16x32_bf16 v[94:97], v[178:181], v[194:197], v[94:97]
	v_mfma_f32_16x16x32_bf16 v[86:89], v[168:171], v[202:205], v[86:89]
	v_mfma_f32_16x16x32_bf16 v[78:81], v[178:181], v[202:205], v[78:81]
	v_mfma_f32_16x16x32_bf16 v[70:73], v[168:171], v[210:213], v[70:73]
	v_mfma_f32_16x16x32_bf16 v[66:69], v[178:181], v[210:213], v[66:69]
	v_mfma_f32_16x16x32_bf16 v[118:121], v[172:175], v[190:193], v[118:121]
	v_mfma_f32_16x16x32_bf16 v[110:113], v[182:185], v[190:193], v[110:113]
	v_mfma_f32_16x16x32_bf16 v[102:105], v[172:175], v[198:201], v[102:105]
	v_mfma_f32_16x16x32_bf16 v[94:97], v[182:185], v[198:201], v[94:97]
	v_mfma_f32_16x16x32_bf16 v[86:89], v[172:175], v[206:209], v[86:89]
	v_mfma_f32_16x16x32_bf16 v[78:81], v[182:185], v[206:209], v[78:81]
	v_mfma_f32_16x16x32_bf16 v[70:73], v[172:175], v[214:217], v[70:73]
	v_mfma_f32_16x16x32_bf16 v[66:69], v[182:185], v[214:217], v[66:69]
	s_barrier
	s_setprio 0
	s_add_i32 s63, s46, s38
	v_lshl_add_u64 v[144:145], s[30:31], 0, v[132:133]
	s_mov_b32 m0, s63
	ds_read_b128 v[186:189], v150 offset:16384
	ds_read_b128 v[190:193], v150 offset:17408
	ds_read_b128 v[194:197], v150 offset:18432
	ds_read_b128 v[198:201], v150 offset:19456
	ds_read_b128 v[202:205], v150 offset:20480
	ds_read_b128 v[206:209], v150 offset:21504
	ds_read_b128 v[210:213], v150 offset:22528
	ds_read_b128 v[214:217], v150 offset:23552
	global_load_lds_dwordx4 v[144:145], off
	s_add_i32 m0, s63, 0x2000
	s_add_u32 s64, s30, 0x4000
	v_lshl_add_u64 v[144:145], s[30:31], 0, v[136:137]
	s_addc_u32 s65, s31, 0
	s_add_i32 s63, s47, s38
	global_load_lds_dwordx4 v[144:145], off
	v_lshl_add_u64 v[144:145], s[64:65], 0, v[132:133]
	s_mov_b32 m0, s63
	s_nop 0
	global_load_lds_dwordx4 v[144:145], off
	v_lshl_add_u64 v[144:145], s[64:65], 0, v[136:137]
	s_add_i32 m0, s63, 0x2000
	s_nop 0
	global_load_lds_dwordx4 v[144:145], off
	v_lshl_add_u64 v[144:145], s[2:3], 0, v[130:131]
	s_mov_b32 m0, s39
	s_nop 0
	global_load_lds_dwordx4 v[144:145], off
	v_lshl_add_u64 v[144:145], s[2:3], 0, v[134:135]
	s_mov_b32 m0, s40
	s_nop 0
	global_load_lds_dwordx4 v[144:145], off
	s_waitcnt vmcnt(8)
	s_waitcnt lgkmcnt(0)
	s_setprio 2
	s_barrier
	v_mfma_f32_16x16x32_bf16 v[62:65], v[152:155], v[186:189], v[62:65]
	v_mfma_f32_16x16x32_bf16 v[58:61], v[160:163], v[186:189], v[58:61]
	v_mfma_f32_16x16x32_bf16 v[50:53], v[152:155], v[194:197], v[50:53]
	v_mfma_f32_16x16x32_bf16 v[42:45], v[160:163], v[194:197], v[42:45]
	v_mfma_f32_16x16x32_bf16 v[34:37], v[152:155], v[202:205], v[34:37]
	v_mfma_f32_16x16x32_bf16 v[26:29], v[160:163], v[202:205], v[26:29]
	v_mfma_f32_16x16x32_bf16 v[18:21], v[152:155], v[210:213], v[18:21]
	v_mfma_f32_16x16x32_bf16 v[10:13], v[160:163], v[210:213], v[10:13]
	v_mfma_f32_16x16x32_bf16 v[62:65], v[156:159], v[190:193], v[62:65]
	v_mfma_f32_16x16x32_bf16 v[58:61], v[164:167], v[190:193], v[58:61]
	v_mfma_f32_16x16x32_bf16 v[50:53], v[156:159], v[198:201], v[50:53]
	v_mfma_f32_16x16x32_bf16 v[42:45], v[164:167], v[198:201], v[42:45]
	v_mfma_f32_16x16x32_bf16 v[34:37], v[156:159], v[206:209], v[34:37]
	v_mfma_f32_16x16x32_bf16 v[26:29], v[164:167], v[206:209], v[26:29]
	v_mfma_f32_16x16x32_bf16 v[18:21], v[156:159], v[214:217], v[18:21]
	v_mfma_f32_16x16x32_bf16 v[10:13], v[164:167], v[214:217], v[10:13]
	v_mfma_f32_16x16x32_bf16 v[54:57], v[168:171], v[186:189], v[54:57]
	v_mfma_f32_16x16x32_bf16 v[46:49], v[178:181], v[186:189], v[46:49]
	v_mfma_f32_16x16x32_bf16 v[38:41], v[168:171], v[194:197], v[38:41]
	v_mfma_f32_16x16x32_bf16 v[30:33], v[178:181], v[194:197], v[30:33]
	v_mfma_f32_16x16x32_bf16 v[22:25], v[168:171], v[202:205], v[22:25]
	v_mfma_f32_16x16x32_bf16 v[14:17], v[178:181], v[202:205], v[14:17]
	v_mfma_f32_16x16x32_bf16 v[6:9], v[168:171], v[210:213], v[6:9]
	v_mfma_f32_16x16x32_bf16 v[2:5], v[178:181], v[210:213], v[2:5]
	v_mfma_f32_16x16x32_bf16 v[54:57], v[172:175], v[190:193], v[54:57]
	v_mfma_f32_16x16x32_bf16 v[46:49], v[182:185], v[190:193], v[46:49]
	v_mfma_f32_16x16x32_bf16 v[38:41], v[172:175], v[198:201], v[38:41]
	v_mfma_f32_16x16x32_bf16 v[30:33], v[182:185], v[198:201], v[30:33]
	v_mfma_f32_16x16x32_bf16 v[22:25], v[172:175], v[206:209], v[22:25]
	v_mfma_f32_16x16x32_bf16 v[14:17], v[182:185], v[206:209], v[14:17]
	v_mfma_f32_16x16x32_bf16 v[6:9], v[172:175], v[214:217], v[6:9]
	v_mfma_f32_16x16x32_bf16 v[2:5], v[182:185], v[214:217], v[2:5]
	s_barrier
	s_setprio 0
	s_add_i32 s63, 0, 0x18000
	v_add_u32_e32 v144, s63, v146
	s_add_i32 s64, 0, 0x1c000
	ds_read_b128 v[152:155], v144
	ds_read_b128 v[156:159], v144 offset:1024
	ds_read_b128 v[160:163], v144 offset:2048
	ds_read_b128 v[164:167], v144 offset:3072
	v_add_u32_e32 v144, s64, v146
	ds_read_b128 v[168:171], v144
	ds_read_b128 v[172:175], v144 offset:1024
	ds_read_b128 v[178:181], v144 offset:2048
	ds_read_b128 v[182:185], v144 offset:3072
	s_add_u32 s2, s2, 0x4000
	s_addc_u32 s3, s3, 0
	s_mov_b32 m0, s41
	v_lshl_add_u64 v[144:145], s[2:3], 0, v[130:131]
	ds_read_b128 v[186:189], v150 offset:32768
	ds_read_b128 v[190:193], v150 offset:33792
	ds_read_b128 v[194:197], v150 offset:34816
	ds_read_b128 v[198:201], v150 offset:35840
	ds_read_b128 v[202:205], v150 offset:36864
	ds_read_b128 v[206:209], v150 offset:37888
	ds_read_b128 v[210:213], v150 offset:38912
	ds_read_b128 v[214:217], v150 offset:39936
	global_load_lds_dwordx4 v[144:145], off
	v_lshl_add_u64 v[144:145], s[2:3], 0, v[134:135]
	s_mov_b32 m0, s42
	s_nop 0
	global_load_lds_dwordx4 v[144:145], off
	s_waitcnt vmcnt(8)
	s_waitcnt lgkmcnt(0)
	s_setprio 2
	s_barrier
	v_mfma_f32_16x16x32_bf16 v[126:129], v[152:155], v[186:189], v[126:129]
	v_mfma_f32_16x16x32_bf16 v[122:125], v[160:163], v[186:189], v[122:125]
	v_mfma_f32_16x16x32_bf16 v[114:117], v[152:155], v[194:197], v[114:117]
	v_mfma_f32_16x16x32_bf16 v[106:109], v[160:163], v[194:197], v[106:109]
	v_mfma_f32_16x16x32_bf16 v[98:101], v[152:155], v[202:205], v[98:101]
	v_mfma_f32_16x16x32_bf16 v[90:93], v[160:163], v[202:205], v[90:93]
	v_mfma_f32_16x16x32_bf16 v[82:85], v[152:155], v[210:213], v[82:85]
	v_mfma_f32_16x16x32_bf16 v[74:77], v[160:163], v[210:213], v[74:77]
	v_mfma_f32_16x16x32_bf16 v[126:129], v[156:159], v[190:193], v[126:129]
	v_mfma_f32_16x16x32_bf16 v[122:125], v[164:167], v[190:193], v[122:125]
	v_mfma_f32_16x16x32_bf16 v[114:117], v[156:159], v[198:201], v[114:117]
	v_mfma_f32_16x16x32_bf16 v[106:109], v[164:167], v[198:201], v[106:109]
	v_mfma_f32_16x16x32_bf16 v[98:101], v[156:159], v[206:209], v[98:101]
	v_mfma_f32_16x16x32_bf16 v[90:93], v[164:167], v[206:209], v[90:93]
	v_mfma_f32_16x16x32_bf16 v[82:85], v[156:159], v[214:217], v[82:85]
	v_mfma_f32_16x16x32_bf16 v[74:77], v[164:167], v[214:217], v[74:77]
	v_mfma_f32_16x16x32_bf16 v[118:121], v[168:171], v[186:189], v[118:121]
	v_mfma_f32_16x16x32_bf16 v[110:113], v[178:181], v[186:189], v[110:113]
	v_mfma_f32_16x16x32_bf16 v[102:105], v[168:171], v[194:197], v[102:105]
	v_mfma_f32_16x16x32_bf16 v[94:97], v[178:181], v[194:197], v[94:97]
	v_mfma_f32_16x16x32_bf16 v[86:89], v[168:171], v[202:205], v[86:89]
	v_mfma_f32_16x16x32_bf16 v[78:81], v[178:181], v[202:205], v[78:81]
	v_mfma_f32_16x16x32_bf16 v[70:73], v[168:171], v[210:213], v[70:73]
	v_mfma_f32_16x16x32_bf16 v[66:69], v[178:181], v[210:213], v[66:69]
	v_mfma_f32_16x16x32_bf16 v[118:121], v[172:175], v[190:193], v[118:121]
	v_mfma_f32_16x16x32_bf16 v[110:113], v[182:185], v[190:193], v[110:113]
	v_mfma_f32_16x16x32_bf16 v[102:105], v[172:175], v[198:201], v[102:105]
	v_mfma_f32_16x16x32_bf16 v[94:97], v[182:185], v[198:201], v[94:97]
	v_mfma_f32_16x16x32_bf16 v[86:89], v[172:175], v[206:209], v[86:89]
	v_mfma_f32_16x16x32_bf16 v[78:81], v[182:185], v[206:209], v[78:81]
	v_mfma_f32_16x16x32_bf16 v[70:73], v[172:175], v[214:217], v[70:73]
	v_mfma_f32_16x16x32_bf16 v[66:69], v[182:185], v[214:217], v[66:69]
	s_barrier
	s_setprio 0
	s_add_u32 s2, s30, 0x8000
	s_addc_u32 s3, s31, 0
	s_add_i32 s63, s63, s38
	v_lshl_add_u64 v[144:145], s[2:3], 0, v[132:133]
	s_mov_b32 m0, s63
	ds_read_b128 v[186:189], v150 offset:49152
	ds_read_b128 v[190:193], v150 offset:50176
	ds_read_b128 v[194:197], v150 offset:51200
	ds_read_b128 v[198:201], v150 offset:52224
	ds_read_b128 v[202:205], v150 offset:53248
	ds_read_b128 v[206:209], v150 offset:54272
	ds_read_b128 v[210:213], v150 offset:55296
	ds_read_b128 v[214:217], v150 offset:56320
	global_load_lds_dwordx4 v[144:145], off
	s_add_i32 m0, s63, 0x2000
	v_lshl_add_u64 v[144:145], s[2:3], 0, v[136:137]
	s_add_u32 s2, s30, 0xc000
	s_addc_u32 s3, s31, 0
	s_add_i32 s30, s64, s38
	global_load_lds_dwordx4 v[144:145], off
	v_lshl_add_u64 v[144:145], s[2:3], 0, v[132:133]
	s_mov_b32 m0, s30
	s_nop 0
	global_load_lds_dwordx4 v[144:145], off
	v_lshl_add_u64 v[144:145], s[2:3], 0, v[136:137]
	s_add_i32 m0, s30, 0x2000
	s_nop 0
	global_load_lds_dwordx4 v[144:145], off
	v_lshl_add_u64 v[144:145], s[28:29], 0, v[130:131]
	s_mov_b32 m0, s44
	s_nop 0
	global_load_lds_dwordx4 v[144:145], off
	v_lshl_add_u64 v[144:145], s[28:29], 0, v[134:135]
	s_mov_b32 m0, s45
	s_nop 0
	global_load_lds_dwordx4 v[144:145], off
	s_waitcnt vmcnt(8)
	s_waitcnt lgkmcnt(0)
	s_setprio 2
	s_barrier
	v_mfma_f32_16x16x32_bf16 v[62:65], v[152:155], v[186:189], v[62:65]
	v_mfma_f32_16x16x32_bf16 v[58:61], v[160:163], v[186:189], v[58:61]
	v_mfma_f32_16x16x32_bf16 v[50:53], v[152:155], v[194:197], v[50:53]
	v_mfma_f32_16x16x32_bf16 v[42:45], v[160:163], v[194:197], v[42:45]
	v_mfma_f32_16x16x32_bf16 v[34:37], v[152:155], v[202:205], v[34:37]
	v_mfma_f32_16x16x32_bf16 v[26:29], v[160:163], v[202:205], v[26:29]
	v_mfma_f32_16x16x32_bf16 v[18:21], v[152:155], v[210:213], v[18:21]
	v_mfma_f32_16x16x32_bf16 v[10:13], v[160:163], v[210:213], v[10:13]
	v_mfma_f32_16x16x32_bf16 v[62:65], v[156:159], v[190:193], v[62:65]
	v_mfma_f32_16x16x32_bf16 v[58:61], v[164:167], v[190:193], v[58:61]
	v_mfma_f32_16x16x32_bf16 v[50:53], v[156:159], v[198:201], v[50:53]
	v_mfma_f32_16x16x32_bf16 v[42:45], v[164:167], v[198:201], v[42:45]
	v_mfma_f32_16x16x32_bf16 v[34:37], v[156:159], v[206:209], v[34:37]
	v_mfma_f32_16x16x32_bf16 v[26:29], v[164:167], v[206:209], v[26:29]
	v_mfma_f32_16x16x32_bf16 v[18:21], v[156:159], v[214:217], v[18:21]
	v_mfma_f32_16x16x32_bf16 v[10:13], v[164:167], v[214:217], v[10:13]
	v_mfma_f32_16x16x32_bf16 v[54:57], v[168:171], v[186:189], v[54:57]
	v_mfma_f32_16x16x32_bf16 v[46:49], v[178:181], v[186:189], v[46:49]
	v_mfma_f32_16x16x32_bf16 v[38:41], v[168:171], v[194:197], v[38:41]
	v_mfma_f32_16x16x32_bf16 v[30:33], v[178:181], v[194:197], v[30:33]
	v_mfma_f32_16x16x32_bf16 v[22:25], v[168:171], v[202:205], v[22:25]
	v_mfma_f32_16x16x32_bf16 v[14:17], v[178:181], v[202:205], v[14:17]
	v_mfma_f32_16x16x32_bf16 v[6:9], v[168:171], v[210:213], v[6:9]
	v_mfma_f32_16x16x32_bf16 v[2:5], v[178:181], v[210:213], v[2:5]
	v_mfma_f32_16x16x32_bf16 v[54:57], v[172:175], v[190:193], v[54:57]
	v_mfma_f32_16x16x32_bf16 v[46:49], v[182:185], v[190:193], v[46:49]
	v_mfma_f32_16x16x32_bf16 v[38:41], v[172:175], v[198:201], v[38:41]
	v_mfma_f32_16x16x32_bf16 v[30:33], v[182:185], v[198:201], v[30:33]
	v_mfma_f32_16x16x32_bf16 v[22:25], v[172:175], v[206:209], v[22:25]
	v_mfma_f32_16x16x32_bf16 v[14:17], v[182:185], v[206:209], v[14:17]
	v_mfma_f32_16x16x32_bf16 v[6:9], v[172:175], v[214:217], v[6:9]
	v_mfma_f32_16x16x32_bf16 v[2:5], v[182:185], v[214:217], v[2:5]
	s_barrier
	s_setprio 0
	s_add_i32 s62, s62, 2
	s_add_u32 s26, s26, 0x10000
	s_addc_u32 s27, s27, 0
	s_add_u32 s60, s60, 0x10000
	s_addc_u32 s61, s61, 0
	s_cmp_gt_u32 s62, 41
	s_cbranch_scc0 .LBB0_1444
